# peer_out expert-row addressing: 64-bit v_mad_i64_i32 per row replaced by 32-bit v_mad_u32_u24 offset + SGPR table base (global_load saddr form); sgpr 102, vgpr 256
# baseline (speedup 1.0000x reference)
; DI int otid() { int t = __builtin_amdgcn_workitem_id_x(); asm volatile("" : "+v"(t)); return t; }
; DI float bflo(unsigned w) { return __uint_as_float(w << 16); }
; DI float bfhi(unsigned w) { return __uint_as_float(w & 0xffff0000u); }
; DI void phase_peer_out(const Params& p, char* lds) {
;   char* ws = p.ws;
;   const int tid = otid(), lane = tid & 63, wave = tid >> 6, hb = lane >> 5, l5 = lane & 31;
;   int* sidx = (int*)lds + wave * 384; float* sw = (float*)(sidx + 128);
;   const u16* H = (const u16*)(ws + OFF_H); const unsigned* TV = (const unsigned*)(ws + OFF_TOPV);
;   const unsigned char* U6 = (const unsigned char*)(ws + OFF_U8) + 24 * l5; const unsigned char* V6 = (const unsigned char*)(ws + OFF_V8) + 24 * l5;
;   const float* USC = (const float*)(ws + OFF_USC); const float* VSC = (const float*)(ws + OFF_VSC);
;   const float* g3 = p.in[23]; const float* b3 = p.in[24];
;   int ci = 0, cj = 0; const bool cval = lane < 50;
;   if (cval) { int rem = lane, i = 0; while (true) { const int cnt = 16 / (i + 1); if (rem < cnt) break; rem -= cnt; ++i; } ci = i; cj = rem; }
;   const int flat = ci * 16 + cj;
;   for (int t = blockIdx.x * 8 + wave; t < T_TOK; t += gridDim.x * 8) {
;     f32x2 x2[16];
; #pragma unroll
;     for (int i = 0; i < 4; ++i) {
;       const uint4 hv = *(const uint4*)(H + (size_t)t * 1024 + 32 * l5 + 8 * i);
;       x2[4 * i] = f32x2{bflo(hv.x), bfhi(hv.x)}; x2[4 * i + 1] = f32x2{bflo(hv.y), bfhi(hv.y)}; x2[4 * i + 2] = f32x2{bflo(hv.z), bfhi(hv.z)}; x2[4 * i + 3] = f32x2{bflo(hv.w), bfhi(hv.w)};
;     }
;     float hval[8]; int hidx[8];
; #pragma unroll
;     for (int hq = 0; hq < 8; ++hq) {
;       const unsigned ka = TV[(size_t)t * 256 + (2 * hq) * 16 + ci], kb = TV[(size_t)t * 256 + (2 * hq + 1) * 16 + cj];
;       const float va = __uint_as_float(ka & 0xFFFFFF80u), vb = __uint_as_float(kb & 0xFFFFFF80u);
;       const int ia = 127 - (int)(ka & 127u), ib = 127 - (int)(kb & 127u);
;       hval[hq] = cval ? va + vb : -INFINITY; hidx[hq] = ia * 128 + ib;
;     }
.LBB0_1184:
	s_or_b64 exec, exec, s[2:3]
	v_ashrrev_i32_e32 v1, 6, v222
	v_readlane_b32 s0, v250, 27
	s_nop 1
	v_add_u32_e32 v60, s0, v1
	s_mov_b32 s0, 0x10000
	v_cmp_gt_i32_e64 s[0:1], s0, v60
	s_and_saveexec_b64 s[2:3], s[0:1]
	s_cbranch_execz .LBB0_1211
	s_movk_i32 s0, 0x600
	v_and_b32_e32 v5, 31, v222
	v_mul_lo_u32 v1, v1, s0
	v_readlane_b32 s0, v250, 52
	v_mul_u32_u24_e32 v2, 24, v5
	v_mov_b32_e32 v3, 0
	v_readlane_b32 s1, v250, 53
	v_add_u32_e32 v110, 0, v1
	v_lshl_add_u32 v1, v58, 4, v56
	v_lshl_add_u64 v[62:63], s[0:1], 0, v[2:3]
	v_readlane_b32 s0, v250, 54
	v_readlane_b32 s1, v250, 55
	v_sub_u32_e32 v111, 0xff, v1
	v_and_b32_e32 v1, 64, v223
	v_lshl_add_u64 v[64:65], s[0:1], 0, v[2:3]
	v_mov_b32_e32 v251, v2
	v_readlane_b32 s98, v250, 52
	v_readlane_b32 s99, v250, 53
	v_readlane_b32 s100, v250, 54
	v_readlane_b32 s101, v250, 55
	v_lshlrev_b32_e32 v2, 6, v5
	v_lshrrev_b32_e32 v4, 5, v0
	v_lshl_add_u64 v[66:67], s[24:25], 0, v[2:3]
	v_add_u32_e32 v7, 64, v1
	v_cmp_gt_u32_e64 s[0:1], 32, v0
	v_lshl_add_u32 v112, v0, 2, v110
	v_xor_b32_e32 v0, 32, v223
	v_readlane_b32 s16, v250, 30
	v_cmp_lt_i32_e64 s[2:3], v0, v7
	v_readlane_b32 s17, v250, 31
	v_readlane_b32 s18, v250, 32
	v_readlane_b32 s19, v250, 33
	v_cndmask_b32_e64 v0, v223, v0, s[2:3]
	v_lshlrev_b32_e32 v2, 7, v5
	v_readlane_b32 s30, v250, 44
	v_readlane_b32 s31, v250, 45
	v_readlane_b32 s16, v250, 56
	v_lshl_add_u32 v6, v5, 2, v110
	v_lshlrev_b32_e32 v8, 8, v4
	v_lshlrev_b32_e32 v113, 2, v0
	v_lshl_add_u64 v[0:1], s[30:31], 0, v[2:3]
	v_lshlrev_b32_e32 v4, 6, v4
	v_mov_b32_e32 v5, v3
	v_readlane_b32 s17, v250, 57
	v_lshl_add_u64 v[68:69], v[0:1], 0, v[4:5]
	v_readlane_b32 s18, v250, 58
	v_lshl_add_u64 v[0:1], s[16:17], 0, v[2:3]
	v_lshl_add_u64 v[70:71], v[0:1], 0, v[4:5]
	v_xor_b32_e32 v0, 8, v223
	v_cmp_lt_i32_e64 s[2:3], v0, v7
	v_readlane_b32 s19, v250, 59
	v_readlane_b32 s20, v250, 34
	v_cndmask_b32_e64 v0, v223, v0, s[2:3]
	v_lshlrev_b32_e32 v114, 2, v0
	v_xor_b32_e32 v0, 4, v223
	v_cmp_lt_i32_e64 s[2:3], v0, v7
	v_readlane_b32 s21, v250, 35
	v_readlane_b32 s22, v250, 36
	v_cndmask_b32_e64 v0, v223, v0, s[2:3]
	v_lshlrev_b32_e32 v115, 2, v0
	v_xor_b32_e32 v0, 2, v223
	v_cmp_lt_i32_e64 s[2:3], v0, v7
	v_readlane_b32 s23, v250, 37
	v_readlane_b32 s24, v250, 38
	v_cndmask_b32_e64 v0, v223, v0, s[2:3]
	v_lshlrev_b32_e32 v116, 2, v0
	v_xor_b32_e32 v0, 1, v223
	v_cmp_lt_i32_e64 s[2:3], v0, v7
	v_readlane_b32 s25, v250, 39
	v_readlane_b32 s26, v250, 40
	v_cndmask_b32_e64 v0, v223, v0, s[2:3]
	v_lshlrev_b32_e32 v117, 2, v0
	v_and_b32_e32 v0, 16, v222
	v_cmp_eq_u32_e64 s[2:3], 0, v0
	v_xor_b32_e32 v0, 16, v223
	v_cmp_lt_i32_e64 s[4:5], v0, v7
	v_readlane_b32 s27, v250, 41
	v_readlane_b32 s28, v250, 42
	v_cndmask_b32_e64 v0, v223, v0, s[4:5]
	v_lshlrev_b32_e32 v118, 2, v0
	v_and_b32_e32 v0, 8, v222
	v_cmp_eq_u32_e64 s[4:5], 0, v0
	v_and_b32_e32 v0, 4, v222
	v_cmp_eq_u32_e64 s[6:7], 0, v0
	v_and_b32_e32 v0, 2, v222
	v_cmp_eq_u32_e64 s[8:9], 0, v0
	v_and_b32_e32 v0, 1, v222
	v_readlane_b32 s29, v250, 43
	v_cmp_eq_u32_e64 s[10:11], 0, v0
	v_lshl_add_u64 v[0:1], s[18:19], 0, v[2:3]
	v_mov_b32_e32 v59, v3
	v_ashrrev_i32_e32 v57, 31, v56
	v_lshl_add_u64 v[72:73], v[0:1], 0, v[4:5]
	s_mov_b64 s[18:19], 0
	v_mov_b32_e32 v119, 0xff800000
	v_bfrev_b32_e32 v120, 1
	s_movk_i32 s21, 0xff00
	s_movk_i32 s22, 0x3fff
	s_movk_i32 s23, 0x300
	v_add_u32_e32 v121, v6, v8
	s_mov_b32 s24, 0x378e98ab
	s_mov_b32 s25, 0x3b7cd369
	s_mov_b32 s26, 0xbcc618b2
	s_mov_b32 s27, 0x3dda74e4
	s_mov_b32 s28, 0x3f228afd
	s_mov_b32 s29, 0x3e03c728
	s_mov_b32 s30, 0xbfb8aa3b
	s_mov_b32 s31, 0x42ce8ed0
	s_mov_b32 s33, 0xc2b17218
	v_mov_b32_e32 v122, 0x3ba10414
	s_brev_b32 s34, -2
	s_mov_b32 s20, 0x3f9837f0
	v_mov_b32_e32 v123, 0x3727c5ac
	s_mov_b32 s35, 0x800000
	s_mov_b32 s36, 0xffff
	v_mov_b32_e32 v124, 0xb9c68948
	v_mov_b32_e32 v125, 0x7f800000
	v_ashrrev_i32_e32 v61, 31, v60
	v_mov_b32_e32 v248, v60
	v_mov_b32_e32 v249, v61
	v_lshlrev_b64 v[36:37], 10, v[248:249]
	v_lshl_add_u64 v[36:37], s[14:15], 0, v[36:37]
	v_lshl_add_u64 v[34:35], v[56:57], 2, v[36:37]
	v_lshl_add_u64 v[32:33], v[58:59], 2, v[36:37]
	global_load_dword v231, v[34:35], off offset:64
	global_load_dword v230, v[32:33], off
	v_lshlrev_b64 v[248:249], 11, v[248:249]
	v_lshl_add_u64 v[36:37], v[66:67], 0, v[248:249]
	global_load_dwordx4 v[232:235], v[36:37], off offset:48
	global_load_dwordx4 v[236:239], v[36:37], off offset:32
	global_load_dwordx4 v[240:243], v[36:37], off offset:16
	global_load_dwordx4 v[244:247], v[36:37], off
	global_load_dword v228, v[32:33], off offset:128
	global_load_dword v226, v[32:33], off offset:256
	global_load_dword v224, v[32:33], off offset:384
	global_load_dword v222, v[32:33], off offset:512
	global_load_dword v220, v[32:33], off offset:640
	global_load_dword v218, v[32:33], off offset:768
	global_load_dword v216, v[32:33], off offset:896
	global_load_dword v229, v[34:35], off offset:192
	global_load_dword v227, v[34:35], off offset:320
	global_load_dword v225, v[34:35], off offset:448
	global_load_dword v223, v[34:35], off offset:576
	global_load_dword v221, v[34:35], off offset:704
	global_load_dword v219, v[34:35], off offset:832
	global_load_dword v217, v[34:35], off offset:960
	s_waitcnt vmcnt(0)
	global_load_dwordx4 v[184:187], v[68:69], off
	global_load_dwordx4 v[188:191], v[68:69], off offset:16
	global_load_dwordx4 v[192:195], v[68:69], off offset:32
	global_load_dwordx4 v[196:199], v[68:69], off offset:48
	global_load_dwordx4 v[200:203], v[70:71], off
	global_load_dwordx4 v[204:207], v[70:71], off offset:16
	global_load_dwordx4 v[208:211], v[70:71], off offset:32
	global_load_dwordx4 v[212:215], v[70:71], off offset:48
	s_waitcnt vmcnt(0)
	s_branch .LBB0_1187
; DI void phase_peer_out(const Params& p, char* lds) {
;     ...
;     float coefv[2];
; #pragma unroll
;     for (int grp = 0; grp < 2; ++grp) {
;       const float dt = sw[grp * 64 + lane] * USC[el[grp]];
;       const float ge = 0.5f * dt * (1.f + erff(dt * 0.7071067811865476f));
;       coefv[grp] = gl[grp] * ge * VSC[el[grp]];
;     }
;     f32x2 o2[16];
; #pragma unroll
;     for (int i = 0; i < 16; ++i) o2[i] = f32x2{0.f, 0.f};
; #pragma unroll
;     for (int kb = 0; kb < 8; ++kb) {
;       v6u qb[8];
; #pragma unroll
;       for (int k = 0; k < 8; ++k) {
;         const int e0 = __builtin_amdgcn_readlane(el[0], kb * 8 + k), e1 = __builtin_amdgcn_readlane(el[1], kb * 8 + k);
;         qb[k] = load6(V6 + (size_t)(hb ? e1 : e0) * 768);
;       }
; #pragma unroll
;       for (int k = 0; k < 8; ++k) {
;         const float c0 = __uint_as_float(__builtin_amdgcn_readlane(__float_as_uint(coefv[0]), kb * 8 + k)), c1 = __uint_as_float(__builtin_amdgcn_readlane(__float_as_uint(coefv[1]), kb * 8 + k));
;         const float cf = hb ? c1 : c0;
;         const f32x2 c2 = {cf, cf};
;         const v32f f = __builtin_amdgcn_cvt_scalef32_pk32_f32_fp6(qb[k], 1.0f);
; #pragma unroll
;         for (int i = 0; i < 16; ++i) o2[i] = f32x2{f[2 * i], f[2 * i + 1]} * c2 + o2[i];
;       }
.LBB0_1186:
	s_or_b64 exec, exec, s[12:13]
	v_lshl_add_u64 v[0:1], v[0:1], 2, s[56:57]
	global_load_dword v12, v[0:1], off
	v_readlane_b32 s12, v108, 0
	v_readlane_b32 s13, v107, 0
	v_readlane_b32 s16, v108, 1
	v_mov_b32_e32 v1, s12
	v_mov_b32_e32 v0, s13
	v_cndmask_b32_e64 v0, v0, v1, s[0:1]
	v_mad_u32_u24 v0, v0, s23, v251
	v_readlane_b32 s12, v107, 1
	v_add_f32_e32 v5, v128, v5
	global_load_dwordx2 v[132:133], v0, s[100:101] offset:16
	global_load_dwordx4 v[128:131], v0, s[100:101]
	v_mov_b32_e32 v0, s12
	v_mov_b32_e32 v1, s16
	v_cndmask_b32_e64 v0, v0, v1, s[0:1]
	v_readlane_b32 s17, v108, 2
	v_readlane_b32 s37, v107, 2
	v_mad_u32_u24 v0, v0, s23, v251
	global_load_dwordx2 v[138:139], v0, s[100:101] offset:16
	global_load_dwordx4 v[134:137], v0, s[100:101]
	v_mov_b32_e32 v0, s37
	v_mov_b32_e32 v1, s17
	v_cndmask_b32_e64 v0, v0, v1, s[0:1]
	v_add_f32_e32 v3, v3, v4
	v_mad_u32_u24 v0, v0, s23, v251
	v_bfi_b32 v7, s34, v8, v7
	v_mul_f32_e32 v8, 0.5, v10
	v_bfi_b32 v4, s34, v11, v9
	v_readlane_b32 s38, v108, 3
	v_readlane_b32 s39, v107, 3
	v_rcp_f32_e32 v10, v5
	v_rcp_f32_e32 v3, v3
	global_load_dwordx2 v[144:145], v0, s[100:101] offset:16
	global_load_dwordx4 v[140:143], v0, s[100:101]
	v_readlane_b32 s40, v108, 4
	v_readlane_b32 s41, v107, 4
	v_readlane_b32 s42, v108, 5
	v_readlane_b32 s43, v107, 5
	v_readlane_b32 s44, v108, 6
	v_readlane_b32 s45, v107, 6
	v_add_f32_e32 v5, 1.0, v7
	v_add_f32_e32 v4, 1.0, v4
	v_mov_b32_e32 v7, s39
	v_mov_b32_e32 v9, s38
	v_mul_f32_e32 v6, 0.5, v6
	v_mov_b32_e32 v11, s41
	v_mov_b32_e32 v13, s40
	v_mov_b32_e32 v14, s43
	v_mov_b32_e32 v15, s42
	v_mov_b32_e32 v16, s45
	v_mov_b32_e32 v17, s44
	v_mul_f32_e32 v19, v8, v4
	v_cndmask_b32_e64 v4, v7, v9, s[0:1]
	v_mul_f32_e32 v18, v6, v5
	v_cndmask_b32_e64 v5, v11, v13, s[0:1]
	v_cndmask_b32_e64 v6, v14, v15, s[0:1]
	v_cndmask_b32_e64 v8, v16, v17, s[0:1]
	v_mad_u32_u24 v0, v4, s23, v251
	v_mad_u32_u24 v4, v5, s23, v251
	v_mad_u32_u24 v6, v6, s23, v251
	v_mad_u32_u24 v8, v8, s23, v251
	global_load_dwordx4 v[146:149], v0, s[100:101]
	global_load_dwordx2 v[150:151], v0, s[100:101] offset:16
	global_load_dwordx4 v[50:53], v4, s[100:101]
	global_load_dwordx2 v[54:55], v4, s[100:101] offset:16
	global_load_dwordx4 v[44:47], v6, s[100:101]
	global_load_dwordx2 v[48:49], v6, s[100:101] offset:16
	global_load_dwordx4 v[38:41], v8, s[100:101]
	v_mul_f32_e32 v0, v126, v10
	v_mul_f32_e32 v1, v127, v3
	v_mul_f32_e32 v0, v0, v18
	v_mul_f32_e32 v1, v1, v19
	v_readlane_b32 s12, v108, 7
	v_readlane_b32 s13, v107, 7
	s_waitcnt vmcnt(14)
	v_mul_f32_e32 v106, v2, v0
	s_waitcnt vmcnt(13)
	v_mul_f32_e32 v109, v12, v1
	v_mov_b32_e32 v0, s13
	v_mov_b32_e32 v1, s12
	v_cndmask_b32_e64 v0, v0, v1, s[0:1]
	v_mad_u32_u24 v0, v0, s23, v251
	global_load_dwordx2 v[36:37], v0, s[100:101] offset:16
	global_load_dwordx2 v[42:43], v8, s[100:101] offset:16
	global_load_dwordx4 v[32:35], v0, s[100:101]
	v_readlane_b32 s12, v106, 0
	v_readlane_b32 s13, v109, 0
	s_nop 0
	v_mov_b32_e32 v1, s12
	v_mov_b32_e32 v0, s13
	v_cndmask_b32_e64 v126, v0, v1, s[0:1]
	s_waitcnt vmcnt(14)
	v_cvt_scalef32_pk32_f32_fp6 v[0:31], v[128:133], 1.0
	v_readlane_b32 s12, v106, 1
	v_readlane_b32 s13, v109, 1
	v_pk_fma_f32 v[128:129], v[0:1], v[126:127], 0 op_sel_hi:[1,0,0]
	v_mov_b32_e32 v1, s12
	v_mov_b32_e32 v0, s13
	v_pk_fma_f32 v[130:131], v[2:3], v[126:127], 0 op_sel_hi:[1,0,0]
	v_pk_fma_f32 v[132:133], v[4:5], v[126:127], 0 op_sel_hi:[1,0,0]
	v_pk_fma_f32 v[152:153], v[6:7], v[126:127], 0 op_sel_hi:[1,0,0]
	v_pk_fma_f32 v[154:155], v[8:9], v[126:127], 0 op_sel_hi:[1,0,0]
	v_pk_fma_f32 v[156:157], v[10:11], v[126:127], 0 op_sel_hi:[1,0,0]
	v_pk_fma_f32 v[158:159], v[12:13], v[126:127], 0 op_sel_hi:[1,0,0]
	v_pk_fma_f32 v[160:161], v[14:15], v[126:127], 0 op_sel_hi:[1,0,0]
	v_pk_fma_f32 v[162:163], v[16:17], v[126:127], 0 op_sel_hi:[1,0,0]
	v_pk_fma_f32 v[164:165], v[18:19], v[126:127], 0 op_sel_hi:[1,0,0]
	v_pk_fma_f32 v[166:167], v[20:21], v[126:127], 0 op_sel_hi:[1,0,0]
	v_pk_fma_f32 v[168:169], v[22:23], v[126:127], 0 op_sel_hi:[1,0,0]
	v_pk_fma_f32 v[170:171], v[24:25], v[126:127], 0 op_sel_hi:[1,0,0]
	v_pk_fma_f32 v[172:173], v[26:27], v[126:127], 0 op_sel_hi:[1,0,0]
	v_pk_fma_f32 v[174:175], v[28:29], v[126:127], 0 op_sel_hi:[1,0,0]
	v_pk_fma_f32 v[126:127], v[30:31], v[126:127], 0 op_sel_hi:[1,0,0]
	v_cndmask_b32_e64 v176, v0, v1, s[0:1]
	s_waitcnt vmcnt(12)
	v_cvt_scalef32_pk32_f32_fp6 v[0:31], v[134:139], 1.0
	v_readlane_b32 s12, v106, 2
	v_readlane_b32 s13, v109, 2
	v_pk_fma_f32 v[128:129], v[0:1], v[176:177], v[128:129] op_sel_hi:[1,0,1]
	v_mov_b32_e32 v1, s12
	v_mov_b32_e32 v0, s13
	v_pk_fma_f32 v[130:131], v[2:3], v[176:177], v[130:131] op_sel_hi:[1,0,1]
	v_pk_fma_f32 v[132:133], v[4:5], v[176:177], v[132:133] op_sel_hi:[1,0,1]
	v_pk_fma_f32 v[134:135], v[6:7], v[176:177], v[152:153] op_sel_hi:[1,0,1]
	v_pk_fma_f32 v[136:137], v[8:9], v[176:177], v[154:155] op_sel_hi:[1,0,1]
	v_pk_fma_f32 v[138:139], v[10:11], v[176:177], v[156:157] op_sel_hi:[1,0,1]
	v_pk_fma_f32 v[152:153], v[12:13], v[176:177], v[158:159] op_sel_hi:[1,0,1]
	v_pk_fma_f32 v[154:155], v[14:15], v[176:177], v[160:161] op_sel_hi:[1,0,1]
	v_pk_fma_f32 v[156:157], v[16:17], v[176:177], v[162:163] op_sel_hi:[1,0,1]
	v_pk_fma_f32 v[158:159], v[18:19], v[176:177], v[164:165] op_sel_hi:[1,0,1]
	v_pk_fma_f32 v[160:161], v[20:21], v[176:177], v[166:167] op_sel_hi:[1,0,1]
	v_pk_fma_f32 v[162:163], v[22:23], v[176:177], v[168:169] op_sel_hi:[1,0,1]
	v_pk_fma_f32 v[164:165], v[24:25], v[176:177], v[170:171] op_sel_hi:[1,0,1]
	v_pk_fma_f32 v[166:167], v[26:27], v[176:177], v[172:173] op_sel_hi:[1,0,1]
	v_pk_fma_f32 v[168:169], v[28:29], v[176:177], v[174:175] op_sel_hi:[1,0,1]
	v_pk_fma_f32 v[126:127], v[30:31], v[176:177], v[126:127] op_sel_hi:[1,0,1]
	v_cndmask_b32_e64 v170, v0, v1, s[0:1]
	s_waitcnt vmcnt(10)
; DI void phase_peer_out(const Params& p, char* lds) {
;     ...
;     for (int kb = 0; kb < 8; ++kb) {
;       v6u qb[8];
; #pragma unroll
;       for (int k = 0; k < 8; ++k) {
;         const int e0 = __builtin_amdgcn_readlane(el[0], kb * 8 + k), e1 = __builtin_amdgcn_readlane(el[1], kb * 8 + k);
;         qb[k] = load6(V6 + (size_t)(hb ? e1 : e0) * 768);
;       }
; #pragma unroll
;       for (int k = 0; k < 8; ++k) {
;         const float c0 = __uint_as_float(__builtin_amdgcn_readlane(__float_as_uint(coefv[0]), kb * 8 + k)), c1 = __uint_as_float(__builtin_amdgcn_readlane(__float_as_uint(coefv[1]), kb * 8 + k));
;         const float cf = hb ? c1 : c0;
;         const f32x2 c2 = {cf, cf};
;         const v32f f = __builtin_amdgcn_cvt_scalef32_pk32_f32_fp6(qb[k], 1.0f);
; #pragma unroll
;         for (int i = 0; i < 16; ++i) o2[i] = f32x2{f[2 * i], f[2 * i + 1]} * c2 + o2[i];
;       }
;     }
	v_cvt_scalef32_pk32_f32_fp6 v[0:31], v[140:145], 1.0
	v_readlane_b32 s12, v106, 3
	v_readlane_b32 s13, v109, 3
	v_pk_fma_f32 v[128:129], v[0:1], v[170:171], v[128:129] op_sel_hi:[1,0,1]
	v_mov_b32_e32 v1, s12
	v_mov_b32_e32 v0, s13
	v_pk_fma_f32 v[130:131], v[2:3], v[170:171], v[130:131] op_sel_hi:[1,0,1]
	v_pk_fma_f32 v[132:133], v[4:5], v[170:171], v[132:133] op_sel_hi:[1,0,1]
	v_pk_fma_f32 v[134:135], v[6:7], v[170:171], v[134:135] op_sel_hi:[1,0,1]
	v_pk_fma_f32 v[136:137], v[8:9], v[170:171], v[136:137] op_sel_hi:[1,0,1]
	v_pk_fma_f32 v[138:139], v[10:11], v[170:171], v[138:139] op_sel_hi:[1,0,1]
	v_pk_fma_f32 v[140:141], v[12:13], v[170:171], v[152:153] op_sel_hi:[1,0,1]
	v_pk_fma_f32 v[142:143], v[14:15], v[170:171], v[154:155] op_sel_hi:[1,0,1]
	v_pk_fma_f32 v[144:145], v[16:17], v[170:171], v[156:157] op_sel_hi:[1,0,1]
	v_pk_fma_f32 v[152:153], v[18:19], v[170:171], v[158:159] op_sel_hi:[1,0,1]
	v_pk_fma_f32 v[154:155], v[20:21], v[170:171], v[160:161] op_sel_hi:[1,0,1]
	v_pk_fma_f32 v[156:157], v[22:23], v[170:171], v[162:163] op_sel_hi:[1,0,1]
	v_pk_fma_f32 v[158:159], v[24:25], v[170:171], v[164:165] op_sel_hi:[1,0,1]
	v_pk_fma_f32 v[160:161], v[26:27], v[170:171], v[166:167] op_sel_hi:[1,0,1]
	v_pk_fma_f32 v[162:163], v[28:29], v[170:171], v[168:169] op_sel_hi:[1,0,1]
	v_pk_fma_f32 v[126:127], v[30:31], v[170:171], v[126:127] op_sel_hi:[1,0,1]
	v_cndmask_b32_e64 v164, v0, v1, s[0:1]
	s_waitcnt vmcnt(8)
	v_cvt_scalef32_pk32_f32_fp6 v[0:31], v[146:151], 1.0
	v_readlane_b32 s12, v106, 4
	v_readlane_b32 s13, v109, 4
	v_pk_fma_f32 v[128:129], v[0:1], v[164:165], v[128:129] op_sel_hi:[1,0,1]
	v_mov_b32_e32 v1, s12
	v_mov_b32_e32 v0, s13
	v_pk_fma_f32 v[130:131], v[2:3], v[164:165], v[130:131] op_sel_hi:[1,0,1]
	v_pk_fma_f32 v[132:133], v[4:5], v[164:165], v[132:133] op_sel_hi:[1,0,1]
	v_pk_fma_f32 v[134:135], v[6:7], v[164:165], v[134:135] op_sel_hi:[1,0,1]
	v_pk_fma_f32 v[136:137], v[8:9], v[164:165], v[136:137] op_sel_hi:[1,0,1]
	v_pk_fma_f32 v[138:139], v[10:11], v[164:165], v[138:139] op_sel_hi:[1,0,1]
	v_pk_fma_f32 v[140:141], v[12:13], v[164:165], v[140:141] op_sel_hi:[1,0,1]
	v_pk_fma_f32 v[142:143], v[14:15], v[164:165], v[142:143] op_sel_hi:[1,0,1]
	v_pk_fma_f32 v[144:145], v[16:17], v[164:165], v[144:145] op_sel_hi:[1,0,1]
	v_pk_fma_f32 v[146:147], v[18:19], v[164:165], v[152:153] op_sel_hi:[1,0,1]
	v_pk_fma_f32 v[148:149], v[20:21], v[164:165], v[154:155] op_sel_hi:[1,0,1]
	v_pk_fma_f32 v[150:151], v[22:23], v[164:165], v[156:157] op_sel_hi:[1,0,1]
	v_pk_fma_f32 v[152:153], v[24:25], v[164:165], v[158:159] op_sel_hi:[1,0,1]
	v_pk_fma_f32 v[154:155], v[26:27], v[164:165], v[160:161] op_sel_hi:[1,0,1]
	v_pk_fma_f32 v[156:157], v[28:29], v[164:165], v[162:163] op_sel_hi:[1,0,1]
	v_pk_fma_f32 v[126:127], v[30:31], v[164:165], v[126:127] op_sel_hi:[1,0,1]
	v_cndmask_b32_e64 v158, v0, v1, s[0:1]
	s_waitcnt vmcnt(6)
	v_cvt_scalef32_pk32_f32_fp6 v[0:31], v[50:55], 1.0
	v_readlane_b32 s12, v106, 5
	v_readlane_b32 s13, v109, 5
	v_pk_fma_f32 v[50:51], v[0:1], v[158:159], v[128:129] op_sel_hi:[1,0,1]
	v_mov_b32_e32 v1, s12
	v_mov_b32_e32 v0, s13
	v_pk_fma_f32 v[52:53], v[2:3], v[158:159], v[130:131] op_sel_hi:[1,0,1]
	v_pk_fma_f32 v[54:55], v[4:5], v[158:159], v[132:133] op_sel_hi:[1,0,1]
	v_pk_fma_f32 v[128:129], v[6:7], v[158:159], v[134:135] op_sel_hi:[1,0,1]
	v_pk_fma_f32 v[130:131], v[8:9], v[158:159], v[136:137] op_sel_hi:[1,0,1]
	v_pk_fma_f32 v[132:133], v[10:11], v[158:159], v[138:139] op_sel_hi:[1,0,1]
	v_pk_fma_f32 v[134:135], v[12:13], v[158:159], v[140:141] op_sel_hi:[1,0,1]
	v_pk_fma_f32 v[136:137], v[14:15], v[158:159], v[142:143] op_sel_hi:[1,0,1]
	v_pk_fma_f32 v[138:139], v[16:17], v[158:159], v[144:145] op_sel_hi:[1,0,1]
	v_pk_fma_f32 v[140:141], v[18:19], v[158:159], v[146:147] op_sel_hi:[1,0,1]
	v_pk_fma_f32 v[142:143], v[20:21], v[158:159], v[148:149] op_sel_hi:[1,0,1]
	v_pk_fma_f32 v[144:145], v[22:23], v[158:159], v[150:151] op_sel_hi:[1,0,1]
	v_pk_fma_f32 v[146:147], v[24:25], v[158:159], v[152:153] op_sel_hi:[1,0,1]
	v_pk_fma_f32 v[148:149], v[26:27], v[158:159], v[154:155] op_sel_hi:[1,0,1]
	v_pk_fma_f32 v[150:151], v[28:29], v[158:159], v[156:157] op_sel_hi:[1,0,1]
	v_pk_fma_f32 v[126:127], v[30:31], v[158:159], v[126:127] op_sel_hi:[1,0,1]
	v_cndmask_b32_e64 v152, v0, v1, s[0:1]
	s_waitcnt vmcnt(4)
	v_cvt_scalef32_pk32_f32_fp6 v[0:31], v[44:49], 1.0
	v_readlane_b32 s12, v106, 6
	v_readlane_b32 s13, v109, 6
	v_pk_fma_f32 v[44:45], v[0:1], v[152:153], v[50:51] op_sel_hi:[1,0,1]
	v_mov_b32_e32 v1, s12
	v_mov_b32_e32 v0, s13
	v_pk_fma_f32 v[46:47], v[2:3], v[152:153], v[52:53] op_sel_hi:[1,0,1]
	v_pk_fma_f32 v[48:49], v[4:5], v[152:153], v[54:55] op_sel_hi:[1,0,1]
	v_pk_fma_f32 v[50:51], v[6:7], v[152:153], v[128:129] op_sel_hi:[1,0,1]
	v_pk_fma_f32 v[52:53], v[8:9], v[152:153], v[130:131] op_sel_hi:[1,0,1]
	v_pk_fma_f32 v[54:55], v[10:11], v[152:153], v[132:133] op_sel_hi:[1,0,1]
	v_pk_fma_f32 v[128:129], v[12:13], v[152:153], v[134:135] op_sel_hi:[1,0,1]
	v_pk_fma_f32 v[130:131], v[14:15], v[152:153], v[136:137] op_sel_hi:[1,0,1]
	v_pk_fma_f32 v[132:133], v[16:17], v[152:153], v[138:139] op_sel_hi:[1,0,1]
	v_pk_fma_f32 v[134:135], v[18:19], v[152:153], v[140:141] op_sel_hi:[1,0,1]
	v_pk_fma_f32 v[136:137], v[20:21], v[152:153], v[142:143] op_sel_hi:[1,0,1]
	v_pk_fma_f32 v[138:139], v[22:23], v[152:153], v[144:145] op_sel_hi:[1,0,1]
	v_pk_fma_f32 v[140:141], v[24:25], v[152:153], v[146:147] op_sel_hi:[1,0,1]
	v_pk_fma_f32 v[142:143], v[26:27], v[152:153], v[148:149] op_sel_hi:[1,0,1]
	v_pk_fma_f32 v[144:145], v[28:29], v[152:153], v[150:151] op_sel_hi:[1,0,1]
	v_pk_fma_f32 v[126:127], v[30:31], v[152:153], v[126:127] op_sel_hi:[1,0,1]
	v_cndmask_b32_e64 v146, v0, v1, s[0:1]
	s_waitcnt vmcnt(1)
; DI void phase_peer_out(const Params& p, char* lds) {
;     ...
;     for (int kb = 0; kb < 8; ++kb) {
;       v6u qb[8];
; #pragma unroll
;       for (int k = 0; k < 8; ++k) {
;         const int e0 = __builtin_amdgcn_readlane(el[0], kb * 8 + k), e1 = __builtin_amdgcn_readlane(el[1], kb * 8 + k);
;         qb[k] = load6(V6 + (size_t)(hb ? e1 : e0) * 768);
;       }
; #pragma unroll
;       for (int k = 0; k < 8; ++k) {
;         const float c0 = __uint_as_float(__builtin_amdgcn_readlane(__float_as_uint(coefv[0]), kb * 8 + k)), c1 = __uint_as_float(__builtin_amdgcn_readlane(__float_as_uint(coefv[1]), kb * 8 + k));
;         const float cf = hb ? c1 : c0;
;         const f32x2 c2 = {cf, cf};
;         const v32f f = __builtin_amdgcn_cvt_scalef32_pk32_f32_fp6(qb[k], 1.0f);
; #pragma unroll
;         for (int i = 0; i < 16; ++i) o2[i] = f32x2{f[2 * i], f[2 * i + 1]} * c2 + o2[i];
;       }
;     }
	v_cvt_scalef32_pk32_f32_fp6 v[0:31], v[38:43], 1.0
	v_readlane_b32 s12, v106, 7
	v_readlane_b32 s13, v109, 7
	v_pk_fma_f32 v[38:39], v[0:1], v[146:147], v[44:45] op_sel_hi:[1,0,1]
	v_mov_b32_e32 v1, s12
	v_mov_b32_e32 v0, s13
	v_readlane_b32 s12, v108, 8
	v_readlane_b32 s13, v107, 8
	v_pk_fma_f32 v[40:41], v[2:3], v[146:147], v[46:47] op_sel_hi:[1,0,1]
	v_pk_fma_f32 v[42:43], v[4:5], v[146:147], v[48:49] op_sel_hi:[1,0,1]
	v_pk_fma_f32 v[44:45], v[6:7], v[146:147], v[50:51] op_sel_hi:[1,0,1]
	v_pk_fma_f32 v[46:47], v[8:9], v[146:147], v[52:53] op_sel_hi:[1,0,1]
	v_pk_fma_f32 v[48:49], v[10:11], v[146:147], v[54:55] op_sel_hi:[1,0,1]
	v_pk_fma_f32 v[50:51], v[12:13], v[146:147], v[128:129] op_sel_hi:[1,0,1]
	v_pk_fma_f32 v[52:53], v[14:15], v[146:147], v[130:131] op_sel_hi:[1,0,1]
	v_pk_fma_f32 v[54:55], v[16:17], v[146:147], v[132:133] op_sel_hi:[1,0,1]
	v_pk_fma_f32 v[132:133], v[18:19], v[146:147], v[134:135] op_sel_hi:[1,0,1]
	v_pk_fma_f32 v[134:135], v[20:21], v[146:147], v[136:137] op_sel_hi:[1,0,1]
	v_pk_fma_f32 v[136:137], v[22:23], v[146:147], v[138:139] op_sel_hi:[1,0,1]
	v_pk_fma_f32 v[138:139], v[24:25], v[146:147], v[140:141] op_sel_hi:[1,0,1]
	v_pk_fma_f32 v[140:141], v[26:27], v[146:147], v[142:143] op_sel_hi:[1,0,1]
	v_pk_fma_f32 v[142:143], v[28:29], v[146:147], v[144:145] op_sel_hi:[1,0,1]
	v_pk_fma_f32 v[144:145], v[30:31], v[146:147], v[126:127] op_sel_hi:[1,0,1]
	v_cndmask_b32_e64 v146, v0, v1, s[0:1]
	v_mov_b32_e32 v0, s13
	v_mov_b32_e32 v1, s12
	v_cndmask_b32_e64 v0, v0, v1, s[0:1]
	v_mad_u32_u24 v130, v0, s23, v251
	s_waitcnt vmcnt(0)
	v_cvt_scalef32_pk32_f32_fp6 v[0:31], v[32:37], 1.0
	v_readlane_b32 s12, v108, 9
	v_readlane_b32 s13, v107, 9
	v_pk_fma_f32 v[150:151], v[0:1], v[146:147], v[38:39] op_sel_hi:[1,0,1]
	v_mov_b32_e32 v1, s12
	v_mov_b32_e32 v0, s13
	v_cndmask_b32_e64 v0, v0, v1, s[0:1]
	v_mad_u32_u24 v0, v0, s23, v251
	v_readlane_b32 s12, v108, 10
	v_readlane_b32 s13, v107, 10
	global_load_dwordx4 v[126:129], v130, s[100:101]
	v_pk_fma_f32 v[168:169], v[18:19], v[146:147], v[132:133] op_sel_hi:[1,0,1]
	global_load_dwordx2 v[130:131], v130, s[100:101] offset:16
	v_pk_fma_f32 v[170:171], v[20:21], v[146:147], v[134:135] op_sel_hi:[1,0,1]
	v_pk_fma_f32 v[172:173], v[22:23], v[146:147], v[136:137] op_sel_hi:[1,0,1]
	global_load_dwordx2 v[136:137], v0, s[100:101] offset:16
	global_load_dwordx4 v[132:135], v0, s[100:101]
	v_mov_b32_e32 v0, s13
	v_mov_b32_e32 v1, s12
	v_cndmask_b32_e64 v0, v0, v1, s[0:1]
	v_mad_u32_u24 v0, v0, s23, v251
	v_readlane_b32 s12, v108, 11
	v_readlane_b32 s13, v107, 11
	v_pk_fma_f32 v[152:153], v[2:3], v[146:147], v[40:41] op_sel_hi:[1,0,1]
	v_mov_b32_e32 v3, s12
	v_mov_b32_e32 v2, s13
	v_cndmask_b32_e64 v2, v2, v3, s[0:1]
	v_mad_u32_u24 v2, v2, s23, v251
	v_readlane_b32 s12, v108, 12
	v_readlane_b32 s13, v107, 12
	v_pk_fma_f32 v[154:155], v[4:5], v[146:147], v[42:43] op_sel_hi:[1,0,1]
	v_pk_fma_f32 v[156:157], v[6:7], v[146:147], v[44:45] op_sel_hi:[1,0,1]
	v_pk_fma_f32 v[158:159], v[8:9], v[146:147], v[46:47] op_sel_hi:[1,0,1]
	v_pk_fma_f32 v[160:161], v[10:11], v[146:147], v[48:49] op_sel_hi:[1,0,1]
	v_pk_fma_f32 v[162:163], v[12:13], v[146:147], v[50:51] op_sel_hi:[1,0,1]
	v_pk_fma_f32 v[164:165], v[14:15], v[146:147], v[52:53] op_sel_hi:[1,0,1]
	v_pk_fma_f32 v[166:167], v[16:17], v[146:147], v[54:55] op_sel_hi:[1,0,1]
	v_pk_fma_f32 v[174:175], v[24:25], v[146:147], v[138:139] op_sel_hi:[1,0,1]
	v_pk_fma_f32 v[176:177], v[26:27], v[146:147], v[140:141] op_sel_hi:[1,0,1]
	v_pk_fma_f32 v[178:179], v[28:29], v[146:147], v[142:143] op_sel_hi:[1,0,1]
	v_pk_fma_f32 v[180:181], v[30:31], v[146:147], v[144:145] op_sel_hi:[1,0,1]
	global_load_dwordx4 v[138:141], v0, s[100:101]
	global_load_dwordx2 v[142:143], v0, s[100:101] offset:16
	global_load_dwordx4 v[144:147], v2, s[100:101]
	v_mov_b32_e32 v0, s13
	v_mov_b32_e32 v1, s12
	v_cndmask_b32_e64 v0, v0, v1, s[0:1]
	v_mad_u32_u24 v0, v0, s23, v251
	v_readlane_b32 s12, v108, 13
	v_readlane_b32 s13, v107, 13
	global_load_dwordx2 v[148:149], v2, s[100:101] offset:16
	global_load_dwordx4 v[50:53], v0, s[100:101]
	v_mov_b32_e32 v2, s13
	v_mov_b32_e32 v3, s12
	v_cndmask_b32_e64 v2, v2, v3, s[0:1]
	v_mad_u32_u24 v2, v2, s23, v251
	v_readlane_b32 s12, v108, 14
	v_readlane_b32 s13, v107, 14
	global_load_dwordx2 v[54:55], v0, s[100:101] offset:16
	global_load_dwordx4 v[44:47], v2, s[100:101]
	v_mov_b32_e32 v0, s13
	v_mov_b32_e32 v1, s12
	v_cndmask_b32_e64 v0, v0, v1, s[0:1]
	v_mad_u32_u24 v0, v0, s23, v251
	v_readlane_b32 s12, v108, 15
	v_readlane_b32 s13, v107, 15
	global_load_dwordx2 v[48:49], v2, s[100:101] offset:16
	global_load_dwordx4 v[38:41], v0, s[100:101]
	v_mov_b32_e32 v2, s13
	v_mov_b32_e32 v3, s12
	v_cndmask_b32_e64 v2, v2, v3, s[0:1]
	v_mad_u32_u24 v2, v2, s23, v251
	global_load_dwordx2 v[36:37], v2, s[100:101] offset:16
	global_load_dwordx2 v[42:43], v0, s[100:101] offset:16
	global_load_dwordx4 v[32:35], v2, s[100:101]
	v_readlane_b32 s12, v106, 8
	v_readlane_b32 s13, v109, 8
	s_nop 0
	v_mov_b32_e32 v1, s12
	v_mov_b32_e32 v0, s13
	v_cndmask_b32_e64 v182, v0, v1, s[0:1]
	v_readlane_b32 s12, v106, 9
	v_readlane_b32 s13, v109, 9
	s_waitcnt vmcnt(14)
; DI void phase_peer_out(const Params& p, char* lds) {
;     ...
;     for (int kb = 0; kb < 8; ++kb) {
;       v6u qb[8];
; #pragma unroll
;       for (int k = 0; k < 8; ++k) {
;         const int e0 = __builtin_amdgcn_readlane(el[0], kb * 8 + k), e1 = __builtin_amdgcn_readlane(el[1], kb * 8 + k);
;         qb[k] = load6(V6 + (size_t)(hb ? e1 : e0) * 768);
;       }
; #pragma unroll
;       for (int k = 0; k < 8; ++k) {
;         const float c0 = __uint_as_float(__builtin_amdgcn_readlane(__float_as_uint(coefv[0]), kb * 8 + k)), c1 = __uint_as_float(__builtin_amdgcn_readlane(__float_as_uint(coefv[1]), kb * 8 + k));
;         const float cf = hb ? c1 : c0;
;         const f32x2 c2 = {cf, cf};
;         const v32f f = __builtin_amdgcn_cvt_scalef32_pk32_f32_fp6(qb[k], 1.0f);
; #pragma unroll
;         for (int i = 0; i < 16; ++i) o2[i] = f32x2{f[2 * i], f[2 * i + 1]} * c2 + o2[i];
;       }
;     }
	v_cvt_scalef32_pk32_f32_fp6 v[0:31], v[126:131], 1.0
	v_pk_fma_f32 v[126:127], v[0:1], v[182:183], v[150:151] op_sel_hi:[1,0,1]
	v_mov_b32_e32 v0, s13
	v_mov_b32_e32 v1, s12
	v_pk_fma_f32 v[128:129], v[2:3], v[182:183], v[152:153] op_sel_hi:[1,0,1]
	v_pk_fma_f32 v[130:131], v[4:5], v[182:183], v[154:155] op_sel_hi:[1,0,1]
	v_pk_fma_f32 v[150:151], v[6:7], v[182:183], v[156:157] op_sel_hi:[1,0,1]
	v_pk_fma_f32 v[152:153], v[8:9], v[182:183], v[158:159] op_sel_hi:[1,0,1]
	v_pk_fma_f32 v[154:155], v[10:11], v[182:183], v[160:161] op_sel_hi:[1,0,1]
	v_pk_fma_f32 v[156:157], v[12:13], v[182:183], v[162:163] op_sel_hi:[1,0,1]
	v_pk_fma_f32 v[158:159], v[14:15], v[182:183], v[164:165] op_sel_hi:[1,0,1]
	v_pk_fma_f32 v[160:161], v[16:17], v[182:183], v[166:167] op_sel_hi:[1,0,1]
	v_pk_fma_f32 v[162:163], v[18:19], v[182:183], v[168:169] op_sel_hi:[1,0,1]
	v_pk_fma_f32 v[164:165], v[20:21], v[182:183], v[170:171] op_sel_hi:[1,0,1]
	v_pk_fma_f32 v[166:167], v[22:23], v[182:183], v[172:173] op_sel_hi:[1,0,1]
	v_pk_fma_f32 v[168:169], v[24:25], v[182:183], v[174:175] op_sel_hi:[1,0,1]
	v_pk_fma_f32 v[170:171], v[26:27], v[182:183], v[176:177] op_sel_hi:[1,0,1]
	v_pk_fma_f32 v[172:173], v[28:29], v[182:183], v[178:179] op_sel_hi:[1,0,1]
	v_pk_fma_f32 v[174:175], v[30:31], v[182:183], v[180:181] op_sel_hi:[1,0,1]
	v_cndmask_b32_e64 v176, v0, v1, s[0:1]
	s_waitcnt vmcnt(12)
	v_cvt_scalef32_pk32_f32_fp6 v[0:31], v[132:137], 1.0
	v_readlane_b32 s12, v106, 10
	v_readlane_b32 s13, v109, 10
	v_pk_fma_f32 v[126:127], v[0:1], v[176:177], v[126:127] op_sel_hi:[1,0,1]
	v_mov_b32_e32 v1, s12
	v_mov_b32_e32 v0, s13
	v_pk_fma_f32 v[128:129], v[2:3], v[176:177], v[128:129] op_sel_hi:[1,0,1]
	v_pk_fma_f32 v[130:131], v[4:5], v[176:177], v[130:131] op_sel_hi:[1,0,1]
	v_pk_fma_f32 v[132:133], v[6:7], v[176:177], v[150:151] op_sel_hi:[1,0,1]
	v_pk_fma_f32 v[134:135], v[8:9], v[176:177], v[152:153] op_sel_hi:[1,0,1]
	v_pk_fma_f32 v[136:137], v[10:11], v[176:177], v[154:155] op_sel_hi:[1,0,1]
	v_pk_fma_f32 v[150:151], v[12:13], v[176:177], v[156:157] op_sel_hi:[1,0,1]
	v_pk_fma_f32 v[152:153], v[14:15], v[176:177], v[158:159] op_sel_hi:[1,0,1]
	v_pk_fma_f32 v[154:155], v[16:17], v[176:177], v[160:161] op_sel_hi:[1,0,1]
	v_pk_fma_f32 v[156:157], v[18:19], v[176:177], v[162:163] op_sel_hi:[1,0,1]
	v_pk_fma_f32 v[158:159], v[20:21], v[176:177], v[164:165] op_sel_hi:[1,0,1]
	v_pk_fma_f32 v[160:161], v[22:23], v[176:177], v[166:167] op_sel_hi:[1,0,1]
	v_pk_fma_f32 v[162:163], v[24:25], v[176:177], v[168:169] op_sel_hi:[1,0,1]
	v_pk_fma_f32 v[164:165], v[26:27], v[176:177], v[170:171] op_sel_hi:[1,0,1]
	v_pk_fma_f32 v[166:167], v[28:29], v[176:177], v[172:173] op_sel_hi:[1,0,1]
	v_pk_fma_f32 v[168:169], v[30:31], v[176:177], v[174:175] op_sel_hi:[1,0,1]
	v_cndmask_b32_e64 v170, v0, v1, s[0:1]
	s_waitcnt vmcnt(10)
	v_cvt_scalef32_pk32_f32_fp6 v[0:31], v[138:143], 1.0
	v_readlane_b32 s12, v106, 11
	v_readlane_b32 s13, v109, 11
	v_pk_fma_f32 v[126:127], v[0:1], v[170:171], v[126:127] op_sel_hi:[1,0,1]
	v_mov_b32_e32 v1, s12
	v_mov_b32_e32 v0, s13
	v_pk_fma_f32 v[128:129], v[2:3], v[170:171], v[128:129] op_sel_hi:[1,0,1]
	v_pk_fma_f32 v[130:131], v[4:5], v[170:171], v[130:131] op_sel_hi:[1,0,1]
	v_pk_fma_f32 v[132:133], v[6:7], v[170:171], v[132:133] op_sel_hi:[1,0,1]
	v_pk_fma_f32 v[134:135], v[8:9], v[170:171], v[134:135] op_sel_hi:[1,0,1]
	v_pk_fma_f32 v[136:137], v[10:11], v[170:171], v[136:137] op_sel_hi:[1,0,1]
	v_pk_fma_f32 v[138:139], v[12:13], v[170:171], v[150:151] op_sel_hi:[1,0,1]
	v_pk_fma_f32 v[140:141], v[14:15], v[170:171], v[152:153] op_sel_hi:[1,0,1]
	v_pk_fma_f32 v[142:143], v[16:17], v[170:171], v[154:155] op_sel_hi:[1,0,1]
	v_pk_fma_f32 v[150:151], v[18:19], v[170:171], v[156:157] op_sel_hi:[1,0,1]
	v_pk_fma_f32 v[152:153], v[20:21], v[170:171], v[158:159] op_sel_hi:[1,0,1]
	v_pk_fma_f32 v[154:155], v[22:23], v[170:171], v[160:161] op_sel_hi:[1,0,1]
	v_pk_fma_f32 v[156:157], v[24:25], v[170:171], v[162:163] op_sel_hi:[1,0,1]
	v_pk_fma_f32 v[158:159], v[26:27], v[170:171], v[164:165] op_sel_hi:[1,0,1]
	v_pk_fma_f32 v[160:161], v[28:29], v[170:171], v[166:167] op_sel_hi:[1,0,1]
	v_pk_fma_f32 v[162:163], v[30:31], v[170:171], v[168:169] op_sel_hi:[1,0,1]
	v_cndmask_b32_e64 v164, v0, v1, s[0:1]
	s_waitcnt vmcnt(8)
	v_cvt_scalef32_pk32_f32_fp6 v[0:31], v[144:149], 1.0
	v_readlane_b32 s12, v106, 12
	v_readlane_b32 s13, v109, 12
	v_pk_fma_f32 v[126:127], v[0:1], v[164:165], v[126:127] op_sel_hi:[1,0,1]
	v_mov_b32_e32 v1, s12
	v_mov_b32_e32 v0, s13
	v_pk_fma_f32 v[128:129], v[2:3], v[164:165], v[128:129] op_sel_hi:[1,0,1]
	v_pk_fma_f32 v[130:131], v[4:5], v[164:165], v[130:131] op_sel_hi:[1,0,1]
	v_pk_fma_f32 v[132:133], v[6:7], v[164:165], v[132:133] op_sel_hi:[1,0,1]
	v_pk_fma_f32 v[134:135], v[8:9], v[164:165], v[134:135] op_sel_hi:[1,0,1]
	v_pk_fma_f32 v[136:137], v[10:11], v[164:165], v[136:137] op_sel_hi:[1,0,1]
	v_pk_fma_f32 v[138:139], v[12:13], v[164:165], v[138:139] op_sel_hi:[1,0,1]
	v_pk_fma_f32 v[140:141], v[14:15], v[164:165], v[140:141] op_sel_hi:[1,0,1]
	v_pk_fma_f32 v[142:143], v[16:17], v[164:165], v[142:143] op_sel_hi:[1,0,1]
	v_pk_fma_f32 v[144:145], v[18:19], v[164:165], v[150:151] op_sel_hi:[1,0,1]
	v_pk_fma_f32 v[146:147], v[20:21], v[164:165], v[152:153] op_sel_hi:[1,0,1]
	v_pk_fma_f32 v[148:149], v[22:23], v[164:165], v[154:155] op_sel_hi:[1,0,1]
	v_pk_fma_f32 v[150:151], v[24:25], v[164:165], v[156:157] op_sel_hi:[1,0,1]
	v_pk_fma_f32 v[152:153], v[26:27], v[164:165], v[158:159] op_sel_hi:[1,0,1]
	v_pk_fma_f32 v[154:155], v[28:29], v[164:165], v[160:161] op_sel_hi:[1,0,1]
	v_pk_fma_f32 v[156:157], v[30:31], v[164:165], v[162:163] op_sel_hi:[1,0,1]
	v_cndmask_b32_e64 v158, v0, v1, s[0:1]
	s_waitcnt vmcnt(6)
; DI void phase_peer_out(const Params& p, char* lds) {
;     ...
;     for (int kb = 0; kb < 8; ++kb) {
;       v6u qb[8];
; #pragma unroll
;       for (int k = 0; k < 8; ++k) {
;         const int e0 = __builtin_amdgcn_readlane(el[0], kb * 8 + k), e1 = __builtin_amdgcn_readlane(el[1], kb * 8 + k);
;         qb[k] = load6(V6 + (size_t)(hb ? e1 : e0) * 768);
;       }
; #pragma unroll
;       for (int k = 0; k < 8; ++k) {
;         const float c0 = __uint_as_float(__builtin_amdgcn_readlane(__float_as_uint(coefv[0]), kb * 8 + k)), c1 = __uint_as_float(__builtin_amdgcn_readlane(__float_as_uint(coefv[1]), kb * 8 + k));
;         const float cf = hb ? c1 : c0;
;         const f32x2 c2 = {cf, cf};
;         const v32f f = __builtin_amdgcn_cvt_scalef32_pk32_f32_fp6(qb[k], 1.0f);
; #pragma unroll
;         for (int i = 0; i < 16; ++i) o2[i] = f32x2{f[2 * i], f[2 * i + 1]} * c2 + o2[i];
;       }
;     }
	v_cvt_scalef32_pk32_f32_fp6 v[0:31], v[50:55], 1.0
	v_readlane_b32 s12, v106, 13
	v_readlane_b32 s13, v109, 13
	v_pk_fma_f32 v[50:51], v[0:1], v[158:159], v[126:127] op_sel_hi:[1,0,1]
	v_mov_b32_e32 v1, s12
	v_mov_b32_e32 v0, s13
	v_pk_fma_f32 v[52:53], v[2:3], v[158:159], v[128:129] op_sel_hi:[1,0,1]
	v_pk_fma_f32 v[54:55], v[4:5], v[158:159], v[130:131] op_sel_hi:[1,0,1]
	v_pk_fma_f32 v[126:127], v[6:7], v[158:159], v[132:133] op_sel_hi:[1,0,1]
	v_pk_fma_f32 v[128:129], v[8:9], v[158:159], v[134:135] op_sel_hi:[1,0,1]
	v_pk_fma_f32 v[130:131], v[10:11], v[158:159], v[136:137] op_sel_hi:[1,0,1]
	v_pk_fma_f32 v[132:133], v[12:13], v[158:159], v[138:139] op_sel_hi:[1,0,1]
	v_pk_fma_f32 v[134:135], v[14:15], v[158:159], v[140:141] op_sel_hi:[1,0,1]
	v_pk_fma_f32 v[136:137], v[16:17], v[158:159], v[142:143] op_sel_hi:[1,0,1]
	v_pk_fma_f32 v[138:139], v[18:19], v[158:159], v[144:145] op_sel_hi:[1,0,1]
	v_pk_fma_f32 v[140:141], v[20:21], v[158:159], v[146:147] op_sel_hi:[1,0,1]
	v_pk_fma_f32 v[142:143], v[22:23], v[158:159], v[148:149] op_sel_hi:[1,0,1]
	v_pk_fma_f32 v[144:145], v[24:25], v[158:159], v[150:151] op_sel_hi:[1,0,1]
	v_pk_fma_f32 v[146:147], v[26:27], v[158:159], v[152:153] op_sel_hi:[1,0,1]
	v_pk_fma_f32 v[148:149], v[28:29], v[158:159], v[154:155] op_sel_hi:[1,0,1]
	v_pk_fma_f32 v[150:151], v[30:31], v[158:159], v[156:157] op_sel_hi:[1,0,1]
	v_cndmask_b32_e64 v152, v0, v1, s[0:1]
	s_waitcnt vmcnt(4)
	v_cvt_scalef32_pk32_f32_fp6 v[0:31], v[44:49], 1.0
	v_readlane_b32 s12, v106, 14
	v_readlane_b32 s13, v109, 14
	v_pk_fma_f32 v[44:45], v[0:1], v[152:153], v[50:51] op_sel_hi:[1,0,1]
	v_mov_b32_e32 v1, s12
	v_mov_b32_e32 v0, s13
	v_pk_fma_f32 v[46:47], v[2:3], v[152:153], v[52:53] op_sel_hi:[1,0,1]
	v_pk_fma_f32 v[48:49], v[4:5], v[152:153], v[54:55] op_sel_hi:[1,0,1]
	v_pk_fma_f32 v[50:51], v[6:7], v[152:153], v[126:127] op_sel_hi:[1,0,1]
	v_pk_fma_f32 v[52:53], v[8:9], v[152:153], v[128:129] op_sel_hi:[1,0,1]
	v_pk_fma_f32 v[54:55], v[10:11], v[152:153], v[130:131] op_sel_hi:[1,0,1]
	v_pk_fma_f32 v[126:127], v[12:13], v[152:153], v[132:133] op_sel_hi:[1,0,1]
	v_pk_fma_f32 v[128:129], v[14:15], v[152:153], v[134:135] op_sel_hi:[1,0,1]
	v_pk_fma_f32 v[130:131], v[16:17], v[152:153], v[136:137] op_sel_hi:[1,0,1]
	v_pk_fma_f32 v[132:133], v[18:19], v[152:153], v[138:139] op_sel_hi:[1,0,1]
	v_pk_fma_f32 v[134:135], v[20:21], v[152:153], v[140:141] op_sel_hi:[1,0,1]
	v_pk_fma_f32 v[136:137], v[22:23], v[152:153], v[142:143] op_sel_hi:[1,0,1]
	v_pk_fma_f32 v[138:139], v[24:25], v[152:153], v[144:145] op_sel_hi:[1,0,1]
	v_pk_fma_f32 v[140:141], v[26:27], v[152:153], v[146:147] op_sel_hi:[1,0,1]
	v_pk_fma_f32 v[142:143], v[28:29], v[152:153], v[148:149] op_sel_hi:[1,0,1]
	v_pk_fma_f32 v[144:145], v[30:31], v[152:153], v[150:151] op_sel_hi:[1,0,1]
	v_cndmask_b32_e64 v146, v0, v1, s[0:1]
	s_waitcnt vmcnt(1)
	v_cvt_scalef32_pk32_f32_fp6 v[0:31], v[38:43], 1.0
	v_readlane_b32 s12, v106, 15
	v_readlane_b32 s13, v109, 15
	v_pk_fma_f32 v[38:39], v[0:1], v[146:147], v[44:45] op_sel_hi:[1,0,1]
	v_mov_b32_e32 v1, s12
	v_mov_b32_e32 v0, s13
	v_readlane_b32 s12, v108, 16
	v_readlane_b32 s13, v107, 16
	v_pk_fma_f32 v[40:41], v[2:3], v[146:147], v[46:47] op_sel_hi:[1,0,1]
	v_pk_fma_f32 v[42:43], v[4:5], v[146:147], v[48:49] op_sel_hi:[1,0,1]
	v_pk_fma_f32 v[44:45], v[6:7], v[146:147], v[50:51] op_sel_hi:[1,0,1]
	v_pk_fma_f32 v[46:47], v[8:9], v[146:147], v[52:53] op_sel_hi:[1,0,1]
	v_pk_fma_f32 v[48:49], v[10:11], v[146:147], v[54:55] op_sel_hi:[1,0,1]
	v_pk_fma_f32 v[50:51], v[12:13], v[146:147], v[126:127] op_sel_hi:[1,0,1]
	v_pk_fma_f32 v[52:53], v[14:15], v[146:147], v[128:129] op_sel_hi:[1,0,1]
	v_pk_fma_f32 v[54:55], v[16:17], v[146:147], v[130:131] op_sel_hi:[1,0,1]
	v_pk_fma_f32 v[132:133], v[18:19], v[146:147], v[132:133] op_sel_hi:[1,0,1]
	v_pk_fma_f32 v[134:135], v[20:21], v[146:147], v[134:135] op_sel_hi:[1,0,1]
	v_pk_fma_f32 v[136:137], v[22:23], v[146:147], v[136:137] op_sel_hi:[1,0,1]
	v_pk_fma_f32 v[138:139], v[24:25], v[146:147], v[138:139] op_sel_hi:[1,0,1]
	v_pk_fma_f32 v[140:141], v[26:27], v[146:147], v[140:141] op_sel_hi:[1,0,1]
	v_pk_fma_f32 v[142:143], v[28:29], v[146:147], v[142:143] op_sel_hi:[1,0,1]
	v_pk_fma_f32 v[144:145], v[30:31], v[146:147], v[144:145] op_sel_hi:[1,0,1]
	v_cndmask_b32_e64 v146, v0, v1, s[0:1]
	v_mov_b32_e32 v0, s13
	v_mov_b32_e32 v1, s12
	v_cndmask_b32_e64 v0, v0, v1, s[0:1]
	v_mad_u32_u24 v130, v0, s23, v251
	s_waitcnt vmcnt(0)
; DI void phase_peer_out(const Params& p, char* lds) {
;     ...
;     for (int kb = 0; kb < 8; ++kb) {
;       v6u qb[8];
; #pragma unroll
;       for (int k = 0; k < 8; ++k) {
;         const int e0 = __builtin_amdgcn_readlane(el[0], kb * 8 + k), e1 = __builtin_amdgcn_readlane(el[1], kb * 8 + k);
;         qb[k] = load6(V6 + (size_t)(hb ? e1 : e0) * 768);
;       }
; #pragma unroll
;       for (int k = 0; k < 8; ++k) {
;         const float c0 = __uint_as_float(__builtin_amdgcn_readlane(__float_as_uint(coefv[0]), kb * 8 + k)), c1 = __uint_as_float(__builtin_amdgcn_readlane(__float_as_uint(coefv[1]), kb * 8 + k));
;         const float cf = hb ? c1 : c0;
;         const f32x2 c2 = {cf, cf};
;         const v32f f = __builtin_amdgcn_cvt_scalef32_pk32_f32_fp6(qb[k], 1.0f);
; #pragma unroll
;         for (int i = 0; i < 16; ++i) o2[i] = f32x2{f[2 * i], f[2 * i + 1]} * c2 + o2[i];
;       }
;     }
	v_cvt_scalef32_pk32_f32_fp6 v[0:31], v[32:37], 1.0
	v_readlane_b32 s12, v108, 17
	v_readlane_b32 s13, v107, 17
	v_pk_fma_f32 v[150:151], v[0:1], v[146:147], v[38:39] op_sel_hi:[1,0,1]
	v_mov_b32_e32 v1, s12
	v_mov_b32_e32 v0, s13
	v_cndmask_b32_e64 v0, v0, v1, s[0:1]
	v_mad_u32_u24 v0, v0, s23, v251
	v_readlane_b32 s12, v108, 18
	v_readlane_b32 s13, v107, 18
	global_load_dwordx4 v[126:129], v130, s[100:101]
	v_pk_fma_f32 v[168:169], v[18:19], v[146:147], v[132:133] op_sel_hi:[1,0,1]
	global_load_dwordx2 v[130:131], v130, s[100:101] offset:16
	v_pk_fma_f32 v[170:171], v[20:21], v[146:147], v[134:135] op_sel_hi:[1,0,1]
	v_pk_fma_f32 v[172:173], v[22:23], v[146:147], v[136:137] op_sel_hi:[1,0,1]
	global_load_dwordx2 v[136:137], v0, s[100:101] offset:16
	global_load_dwordx4 v[132:135], v0, s[100:101]
	v_mov_b32_e32 v0, s13
	v_mov_b32_e32 v1, s12
	v_cndmask_b32_e64 v0, v0, v1, s[0:1]
	v_mad_u32_u24 v0, v0, s23, v251
	v_readlane_b32 s12, v108, 19
	v_readlane_b32 s13, v107, 19
	v_pk_fma_f32 v[152:153], v[2:3], v[146:147], v[40:41] op_sel_hi:[1,0,1]
	v_mov_b32_e32 v3, s12
	v_mov_b32_e32 v2, s13
	v_cndmask_b32_e64 v2, v2, v3, s[0:1]
	v_mad_u32_u24 v2, v2, s23, v251
	v_readlane_b32 s12, v108, 20
	v_readlane_b32 s13, v107, 20
	v_pk_fma_f32 v[154:155], v[4:5], v[146:147], v[42:43] op_sel_hi:[1,0,1]
	v_pk_fma_f32 v[156:157], v[6:7], v[146:147], v[44:45] op_sel_hi:[1,0,1]
	v_pk_fma_f32 v[158:159], v[8:9], v[146:147], v[46:47] op_sel_hi:[1,0,1]
	v_pk_fma_f32 v[160:161], v[10:11], v[146:147], v[48:49] op_sel_hi:[1,0,1]
	v_pk_fma_f32 v[162:163], v[12:13], v[146:147], v[50:51] op_sel_hi:[1,0,1]
	v_pk_fma_f32 v[164:165], v[14:15], v[146:147], v[52:53] op_sel_hi:[1,0,1]
	v_pk_fma_f32 v[166:167], v[16:17], v[146:147], v[54:55] op_sel_hi:[1,0,1]
	v_pk_fma_f32 v[174:175], v[24:25], v[146:147], v[138:139] op_sel_hi:[1,0,1]
	v_pk_fma_f32 v[176:177], v[26:27], v[146:147], v[140:141] op_sel_hi:[1,0,1]
	v_pk_fma_f32 v[178:179], v[28:29], v[146:147], v[142:143] op_sel_hi:[1,0,1]
	v_pk_fma_f32 v[180:181], v[30:31], v[146:147], v[144:145] op_sel_hi:[1,0,1]
	global_load_dwordx4 v[138:141], v0, s[100:101]
	global_load_dwordx2 v[142:143], v0, s[100:101] offset:16
	global_load_dwordx4 v[144:147], v2, s[100:101]
	v_mov_b32_e32 v0, s13
	v_mov_b32_e32 v1, s12
	v_cndmask_b32_e64 v0, v0, v1, s[0:1]
	v_mad_u32_u24 v0, v0, s23, v251
	v_readlane_b32 s12, v108, 21
	v_readlane_b32 s13, v107, 21
	global_load_dwordx2 v[148:149], v2, s[100:101] offset:16
	global_load_dwordx4 v[50:53], v0, s[100:101]
	v_mov_b32_e32 v2, s13
	v_mov_b32_e32 v3, s12
	v_cndmask_b32_e64 v2, v2, v3, s[0:1]
	v_mad_u32_u24 v2, v2, s23, v251
	v_readlane_b32 s12, v108, 22
	v_readlane_b32 s13, v107, 22
	global_load_dwordx2 v[54:55], v0, s[100:101] offset:16
	global_load_dwordx4 v[44:47], v2, s[100:101]
	v_mov_b32_e32 v0, s13
	v_mov_b32_e32 v1, s12
	v_cndmask_b32_e64 v0, v0, v1, s[0:1]
	v_mad_u32_u24 v0, v0, s23, v251
	v_readlane_b32 s12, v108, 23
	v_readlane_b32 s13, v107, 23
	global_load_dwordx2 v[48:49], v2, s[100:101] offset:16
	global_load_dwordx4 v[38:41], v0, s[100:101]
	v_mov_b32_e32 v2, s13
	v_mov_b32_e32 v3, s12
	v_cndmask_b32_e64 v2, v2, v3, s[0:1]
	v_mad_u32_u24 v2, v2, s23, v251
	global_load_dwordx2 v[36:37], v2, s[100:101] offset:16
	global_load_dwordx2 v[42:43], v0, s[100:101] offset:16
	global_load_dwordx4 v[32:35], v2, s[100:101]
	v_readlane_b32 s12, v106, 16
	v_readlane_b32 s13, v109, 16
	s_nop 0
	v_mov_b32_e32 v1, s12
	v_mov_b32_e32 v0, s13
	v_cndmask_b32_e64 v182, v0, v1, s[0:1]
	v_readlane_b32 s12, v106, 17
	v_readlane_b32 s13, v109, 17
	s_waitcnt vmcnt(14)
	v_cvt_scalef32_pk32_f32_fp6 v[0:31], v[126:131], 1.0
	v_pk_fma_f32 v[126:127], v[0:1], v[182:183], v[150:151] op_sel_hi:[1,0,1]
	v_mov_b32_e32 v0, s13
	v_mov_b32_e32 v1, s12
	v_pk_fma_f32 v[128:129], v[2:3], v[182:183], v[152:153] op_sel_hi:[1,0,1]
	v_pk_fma_f32 v[130:131], v[4:5], v[182:183], v[154:155] op_sel_hi:[1,0,1]
	v_pk_fma_f32 v[150:151], v[6:7], v[182:183], v[156:157] op_sel_hi:[1,0,1]
	v_pk_fma_f32 v[152:153], v[8:9], v[182:183], v[158:159] op_sel_hi:[1,0,1]
	v_pk_fma_f32 v[154:155], v[10:11], v[182:183], v[160:161] op_sel_hi:[1,0,1]
	v_pk_fma_f32 v[156:157], v[12:13], v[182:183], v[162:163] op_sel_hi:[1,0,1]
	v_pk_fma_f32 v[158:159], v[14:15], v[182:183], v[164:165] op_sel_hi:[1,0,1]
	v_pk_fma_f32 v[160:161], v[16:17], v[182:183], v[166:167] op_sel_hi:[1,0,1]
	v_pk_fma_f32 v[162:163], v[18:19], v[182:183], v[168:169] op_sel_hi:[1,0,1]
	v_pk_fma_f32 v[164:165], v[20:21], v[182:183], v[170:171] op_sel_hi:[1,0,1]
	v_pk_fma_f32 v[166:167], v[22:23], v[182:183], v[172:173] op_sel_hi:[1,0,1]
	v_pk_fma_f32 v[168:169], v[24:25], v[182:183], v[174:175] op_sel_hi:[1,0,1]
	v_pk_fma_f32 v[170:171], v[26:27], v[182:183], v[176:177] op_sel_hi:[1,0,1]
	v_pk_fma_f32 v[172:173], v[28:29], v[182:183], v[178:179] op_sel_hi:[1,0,1]
	v_pk_fma_f32 v[174:175], v[30:31], v[182:183], v[180:181] op_sel_hi:[1,0,1]
	v_cndmask_b32_e64 v176, v0, v1, s[0:1]
	s_waitcnt vmcnt(12)
; DI void phase_peer_out(const Params& p, char* lds) {
;     ...
;     for (int kb = 0; kb < 8; ++kb) {
;       v6u qb[8];
; #pragma unroll
;       for (int k = 0; k < 8; ++k) {
;         const int e0 = __builtin_amdgcn_readlane(el[0], kb * 8 + k), e1 = __builtin_amdgcn_readlane(el[1], kb * 8 + k);
;         qb[k] = load6(V6 + (size_t)(hb ? e1 : e0) * 768);
;       }
; #pragma unroll
;       for (int k = 0; k < 8; ++k) {
;         const float c0 = __uint_as_float(__builtin_amdgcn_readlane(__float_as_uint(coefv[0]), kb * 8 + k)), c1 = __uint_as_float(__builtin_amdgcn_readlane(__float_as_uint(coefv[1]), kb * 8 + k));
;         const float cf = hb ? c1 : c0;
;         const f32x2 c2 = {cf, cf};
;         const v32f f = __builtin_amdgcn_cvt_scalef32_pk32_f32_fp6(qb[k], 1.0f);
; #pragma unroll
;         for (int i = 0; i < 16; ++i) o2[i] = f32x2{f[2 * i], f[2 * i + 1]} * c2 + o2[i];
;       }
;     }
	v_cvt_scalef32_pk32_f32_fp6 v[0:31], v[132:137], 1.0
	v_readlane_b32 s12, v106, 18
	v_readlane_b32 s13, v109, 18
	v_pk_fma_f32 v[126:127], v[0:1], v[176:177], v[126:127] op_sel_hi:[1,0,1]
	v_mov_b32_e32 v1, s12
	v_mov_b32_e32 v0, s13
	v_pk_fma_f32 v[128:129], v[2:3], v[176:177], v[128:129] op_sel_hi:[1,0,1]
	v_pk_fma_f32 v[130:131], v[4:5], v[176:177], v[130:131] op_sel_hi:[1,0,1]
	v_pk_fma_f32 v[132:133], v[6:7], v[176:177], v[150:151] op_sel_hi:[1,0,1]
	v_pk_fma_f32 v[134:135], v[8:9], v[176:177], v[152:153] op_sel_hi:[1,0,1]
	v_pk_fma_f32 v[136:137], v[10:11], v[176:177], v[154:155] op_sel_hi:[1,0,1]
	v_pk_fma_f32 v[150:151], v[12:13], v[176:177], v[156:157] op_sel_hi:[1,0,1]
	v_pk_fma_f32 v[152:153], v[14:15], v[176:177], v[158:159] op_sel_hi:[1,0,1]
	v_pk_fma_f32 v[154:155], v[16:17], v[176:177], v[160:161] op_sel_hi:[1,0,1]
	v_pk_fma_f32 v[156:157], v[18:19], v[176:177], v[162:163] op_sel_hi:[1,0,1]
	v_pk_fma_f32 v[158:159], v[20:21], v[176:177], v[164:165] op_sel_hi:[1,0,1]
	v_pk_fma_f32 v[160:161], v[22:23], v[176:177], v[166:167] op_sel_hi:[1,0,1]
	v_pk_fma_f32 v[162:163], v[24:25], v[176:177], v[168:169] op_sel_hi:[1,0,1]
	v_pk_fma_f32 v[164:165], v[26:27], v[176:177], v[170:171] op_sel_hi:[1,0,1]
	v_pk_fma_f32 v[166:167], v[28:29], v[176:177], v[172:173] op_sel_hi:[1,0,1]
	v_pk_fma_f32 v[168:169], v[30:31], v[176:177], v[174:175] op_sel_hi:[1,0,1]
	v_cndmask_b32_e64 v170, v0, v1, s[0:1]
	s_waitcnt vmcnt(10)
	v_cvt_scalef32_pk32_f32_fp6 v[0:31], v[138:143], 1.0
	v_readlane_b32 s12, v106, 19
	v_readlane_b32 s13, v109, 19
	v_pk_fma_f32 v[126:127], v[0:1], v[170:171], v[126:127] op_sel_hi:[1,0,1]
	v_mov_b32_e32 v1, s12
	v_mov_b32_e32 v0, s13
	v_pk_fma_f32 v[128:129], v[2:3], v[170:171], v[128:129] op_sel_hi:[1,0,1]
	v_pk_fma_f32 v[130:131], v[4:5], v[170:171], v[130:131] op_sel_hi:[1,0,1]
	v_pk_fma_f32 v[132:133], v[6:7], v[170:171], v[132:133] op_sel_hi:[1,0,1]
	v_pk_fma_f32 v[134:135], v[8:9], v[170:171], v[134:135] op_sel_hi:[1,0,1]
	v_pk_fma_f32 v[136:137], v[10:11], v[170:171], v[136:137] op_sel_hi:[1,0,1]
	v_pk_fma_f32 v[138:139], v[12:13], v[170:171], v[150:151] op_sel_hi:[1,0,1]
	v_pk_fma_f32 v[140:141], v[14:15], v[170:171], v[152:153] op_sel_hi:[1,0,1]
	v_pk_fma_f32 v[142:143], v[16:17], v[170:171], v[154:155] op_sel_hi:[1,0,1]
	v_pk_fma_f32 v[150:151], v[18:19], v[170:171], v[156:157] op_sel_hi:[1,0,1]
	v_pk_fma_f32 v[152:153], v[20:21], v[170:171], v[158:159] op_sel_hi:[1,0,1]
	v_pk_fma_f32 v[154:155], v[22:23], v[170:171], v[160:161] op_sel_hi:[1,0,1]
	v_pk_fma_f32 v[156:157], v[24:25], v[170:171], v[162:163] op_sel_hi:[1,0,1]
	v_pk_fma_f32 v[158:159], v[26:27], v[170:171], v[164:165] op_sel_hi:[1,0,1]
	v_pk_fma_f32 v[160:161], v[28:29], v[170:171], v[166:167] op_sel_hi:[1,0,1]
	v_pk_fma_f32 v[162:163], v[30:31], v[170:171], v[168:169] op_sel_hi:[1,0,1]
	v_cndmask_b32_e64 v164, v0, v1, s[0:1]
	s_waitcnt vmcnt(8)
	v_cvt_scalef32_pk32_f32_fp6 v[0:31], v[144:149], 1.0
	v_readlane_b32 s12, v106, 20
	v_readlane_b32 s13, v109, 20
	v_pk_fma_f32 v[126:127], v[0:1], v[164:165], v[126:127] op_sel_hi:[1,0,1]
	v_mov_b32_e32 v1, s12
	v_mov_b32_e32 v0, s13
	v_pk_fma_f32 v[128:129], v[2:3], v[164:165], v[128:129] op_sel_hi:[1,0,1]
	v_pk_fma_f32 v[130:131], v[4:5], v[164:165], v[130:131] op_sel_hi:[1,0,1]
	v_pk_fma_f32 v[132:133], v[6:7], v[164:165], v[132:133] op_sel_hi:[1,0,1]
	v_pk_fma_f32 v[134:135], v[8:9], v[164:165], v[134:135] op_sel_hi:[1,0,1]
	v_pk_fma_f32 v[136:137], v[10:11], v[164:165], v[136:137] op_sel_hi:[1,0,1]
	v_pk_fma_f32 v[138:139], v[12:13], v[164:165], v[138:139] op_sel_hi:[1,0,1]
	v_pk_fma_f32 v[140:141], v[14:15], v[164:165], v[140:141] op_sel_hi:[1,0,1]
	v_pk_fma_f32 v[142:143], v[16:17], v[164:165], v[142:143] op_sel_hi:[1,0,1]
	v_pk_fma_f32 v[144:145], v[18:19], v[164:165], v[150:151] op_sel_hi:[1,0,1]
	v_pk_fma_f32 v[146:147], v[20:21], v[164:165], v[152:153] op_sel_hi:[1,0,1]
	v_pk_fma_f32 v[148:149], v[22:23], v[164:165], v[154:155] op_sel_hi:[1,0,1]
	v_pk_fma_f32 v[150:151], v[24:25], v[164:165], v[156:157] op_sel_hi:[1,0,1]
	v_pk_fma_f32 v[152:153], v[26:27], v[164:165], v[158:159] op_sel_hi:[1,0,1]
	v_pk_fma_f32 v[154:155], v[28:29], v[164:165], v[160:161] op_sel_hi:[1,0,1]
	v_pk_fma_f32 v[156:157], v[30:31], v[164:165], v[162:163] op_sel_hi:[1,0,1]
	v_cndmask_b32_e64 v158, v0, v1, s[0:1]
	s_waitcnt vmcnt(6)
	v_cvt_scalef32_pk32_f32_fp6 v[0:31], v[50:55], 1.0
	v_readlane_b32 s12, v106, 21
	v_readlane_b32 s13, v109, 21
	v_pk_fma_f32 v[50:51], v[0:1], v[158:159], v[126:127] op_sel_hi:[1,0,1]
	v_mov_b32_e32 v1, s12
	v_mov_b32_e32 v0, s13
	v_pk_fma_f32 v[52:53], v[2:3], v[158:159], v[128:129] op_sel_hi:[1,0,1]
	v_pk_fma_f32 v[54:55], v[4:5], v[158:159], v[130:131] op_sel_hi:[1,0,1]
	v_pk_fma_f32 v[126:127], v[6:7], v[158:159], v[132:133] op_sel_hi:[1,0,1]
	v_pk_fma_f32 v[128:129], v[8:9], v[158:159], v[134:135] op_sel_hi:[1,0,1]
	v_pk_fma_f32 v[130:131], v[10:11], v[158:159], v[136:137] op_sel_hi:[1,0,1]
	v_pk_fma_f32 v[132:133], v[12:13], v[158:159], v[138:139] op_sel_hi:[1,0,1]
	v_pk_fma_f32 v[134:135], v[14:15], v[158:159], v[140:141] op_sel_hi:[1,0,1]
	v_pk_fma_f32 v[136:137], v[16:17], v[158:159], v[142:143] op_sel_hi:[1,0,1]
	v_pk_fma_f32 v[138:139], v[18:19], v[158:159], v[144:145] op_sel_hi:[1,0,1]
	v_pk_fma_f32 v[140:141], v[20:21], v[158:159], v[146:147] op_sel_hi:[1,0,1]
	v_pk_fma_f32 v[142:143], v[22:23], v[158:159], v[148:149] op_sel_hi:[1,0,1]
	v_pk_fma_f32 v[144:145], v[24:25], v[158:159], v[150:151] op_sel_hi:[1,0,1]
	v_pk_fma_f32 v[146:147], v[26:27], v[158:159], v[152:153] op_sel_hi:[1,0,1]
	v_pk_fma_f32 v[148:149], v[28:29], v[158:159], v[154:155] op_sel_hi:[1,0,1]
	v_pk_fma_f32 v[150:151], v[30:31], v[158:159], v[156:157] op_sel_hi:[1,0,1]
	v_cndmask_b32_e64 v152, v0, v1, s[0:1]
	s_waitcnt vmcnt(4)
; DI void phase_peer_out(const Params& p, char* lds) {
;     ...
;     for (int kb = 0; kb < 8; ++kb) {
;       v6u qb[8];
; #pragma unroll
;       for (int k = 0; k < 8; ++k) {
;         const int e0 = __builtin_amdgcn_readlane(el[0], kb * 8 + k), e1 = __builtin_amdgcn_readlane(el[1], kb * 8 + k);
;         qb[k] = load6(V6 + (size_t)(hb ? e1 : e0) * 768);
;       }
; #pragma unroll
;       for (int k = 0; k < 8; ++k) {
;         const float c0 = __uint_as_float(__builtin_amdgcn_readlane(__float_as_uint(coefv[0]), kb * 8 + k)), c1 = __uint_as_float(__builtin_amdgcn_readlane(__float_as_uint(coefv[1]), kb * 8 + k));
;         const float cf = hb ? c1 : c0;
;         const f32x2 c2 = {cf, cf};
;         const v32f f = __builtin_amdgcn_cvt_scalef32_pk32_f32_fp6(qb[k], 1.0f);
; #pragma unroll
;         for (int i = 0; i < 16; ++i) o2[i] = f32x2{f[2 * i], f[2 * i + 1]} * c2 + o2[i];
;       }
;     }
	v_cvt_scalef32_pk32_f32_fp6 v[0:31], v[44:49], 1.0
	v_readlane_b32 s12, v106, 22
	v_readlane_b32 s13, v109, 22
	v_pk_fma_f32 v[44:45], v[0:1], v[152:153], v[50:51] op_sel_hi:[1,0,1]
	v_mov_b32_e32 v1, s12
	v_mov_b32_e32 v0, s13
	v_pk_fma_f32 v[46:47], v[2:3], v[152:153], v[52:53] op_sel_hi:[1,0,1]
	v_pk_fma_f32 v[48:49], v[4:5], v[152:153], v[54:55] op_sel_hi:[1,0,1]
	v_pk_fma_f32 v[50:51], v[6:7], v[152:153], v[126:127] op_sel_hi:[1,0,1]
	v_pk_fma_f32 v[52:53], v[8:9], v[152:153], v[128:129] op_sel_hi:[1,0,1]
	v_pk_fma_f32 v[54:55], v[10:11], v[152:153], v[130:131] op_sel_hi:[1,0,1]
	v_pk_fma_f32 v[126:127], v[12:13], v[152:153], v[132:133] op_sel_hi:[1,0,1]
	v_pk_fma_f32 v[128:129], v[14:15], v[152:153], v[134:135] op_sel_hi:[1,0,1]
	v_pk_fma_f32 v[130:131], v[16:17], v[152:153], v[136:137] op_sel_hi:[1,0,1]
	v_pk_fma_f32 v[132:133], v[18:19], v[152:153], v[138:139] op_sel_hi:[1,0,1]
	v_pk_fma_f32 v[134:135], v[20:21], v[152:153], v[140:141] op_sel_hi:[1,0,1]
	v_pk_fma_f32 v[136:137], v[22:23], v[152:153], v[142:143] op_sel_hi:[1,0,1]
	v_pk_fma_f32 v[138:139], v[24:25], v[152:153], v[144:145] op_sel_hi:[1,0,1]
	v_pk_fma_f32 v[140:141], v[26:27], v[152:153], v[146:147] op_sel_hi:[1,0,1]
	v_pk_fma_f32 v[142:143], v[28:29], v[152:153], v[148:149] op_sel_hi:[1,0,1]
	v_pk_fma_f32 v[144:145], v[30:31], v[152:153], v[150:151] op_sel_hi:[1,0,1]
	v_cndmask_b32_e64 v146, v0, v1, s[0:1]
	s_waitcnt vmcnt(1)
	v_cvt_scalef32_pk32_f32_fp6 v[0:31], v[38:43], 1.0
	v_readlane_b32 s12, v106, 23
	v_readlane_b32 s13, v109, 23
	v_pk_fma_f32 v[38:39], v[0:1], v[146:147], v[44:45] op_sel_hi:[1,0,1]
	v_mov_b32_e32 v1, s12
	v_mov_b32_e32 v0, s13
	v_readlane_b32 s12, v108, 24
	v_readlane_b32 s13, v107, 24
	v_pk_fma_f32 v[40:41], v[2:3], v[146:147], v[46:47] op_sel_hi:[1,0,1]
	v_pk_fma_f32 v[42:43], v[4:5], v[146:147], v[48:49] op_sel_hi:[1,0,1]
	v_pk_fma_f32 v[44:45], v[6:7], v[146:147], v[50:51] op_sel_hi:[1,0,1]
	v_pk_fma_f32 v[46:47], v[8:9], v[146:147], v[52:53] op_sel_hi:[1,0,1]
	v_pk_fma_f32 v[48:49], v[10:11], v[146:147], v[54:55] op_sel_hi:[1,0,1]
	v_pk_fma_f32 v[50:51], v[12:13], v[146:147], v[126:127] op_sel_hi:[1,0,1]
	v_pk_fma_f32 v[52:53], v[14:15], v[146:147], v[128:129] op_sel_hi:[1,0,1]
	v_pk_fma_f32 v[54:55], v[16:17], v[146:147], v[130:131] op_sel_hi:[1,0,1]
	v_pk_fma_f32 v[132:133], v[18:19], v[146:147], v[132:133] op_sel_hi:[1,0,1]
	v_pk_fma_f32 v[134:135], v[20:21], v[146:147], v[134:135] op_sel_hi:[1,0,1]
	v_pk_fma_f32 v[136:137], v[22:23], v[146:147], v[136:137] op_sel_hi:[1,0,1]
	v_pk_fma_f32 v[138:139], v[24:25], v[146:147], v[138:139] op_sel_hi:[1,0,1]
	v_pk_fma_f32 v[140:141], v[26:27], v[146:147], v[140:141] op_sel_hi:[1,0,1]
	v_pk_fma_f32 v[142:143], v[28:29], v[146:147], v[142:143] op_sel_hi:[1,0,1]
	v_pk_fma_f32 v[144:145], v[30:31], v[146:147], v[144:145] op_sel_hi:[1,0,1]
	v_cndmask_b32_e64 v146, v0, v1, s[0:1]
	v_mov_b32_e32 v0, s13
	v_mov_b32_e32 v1, s12
	v_cndmask_b32_e64 v0, v0, v1, s[0:1]
	v_mad_u32_u24 v130, v0, s23, v251
	s_waitcnt vmcnt(0)
	v_cvt_scalef32_pk32_f32_fp6 v[0:31], v[32:37], 1.0
	v_readlane_b32 s12, v108, 25
	v_readlane_b32 s13, v107, 25
	v_pk_fma_f32 v[150:151], v[0:1], v[146:147], v[38:39] op_sel_hi:[1,0,1]
	v_mov_b32_e32 v1, s12
	v_mov_b32_e32 v0, s13
	v_cndmask_b32_e64 v0, v0, v1, s[0:1]
	v_mad_u32_u24 v0, v0, s23, v251
	v_readlane_b32 s12, v108, 26
	v_readlane_b32 s13, v107, 26
	global_load_dwordx4 v[126:129], v130, s[100:101]
	v_pk_fma_f32 v[168:169], v[18:19], v[146:147], v[132:133] op_sel_hi:[1,0,1]
	global_load_dwordx2 v[130:131], v130, s[100:101] offset:16
	v_pk_fma_f32 v[170:171], v[20:21], v[146:147], v[134:135] op_sel_hi:[1,0,1]
	v_pk_fma_f32 v[172:173], v[22:23], v[146:147], v[136:137] op_sel_hi:[1,0,1]
	global_load_dwordx2 v[136:137], v0, s[100:101] offset:16
	global_load_dwordx4 v[132:135], v0, s[100:101]
	v_mov_b32_e32 v0, s13
	v_mov_b32_e32 v1, s12
	v_cndmask_b32_e64 v0, v0, v1, s[0:1]
	v_mad_u32_u24 v0, v0, s23, v251
	v_readlane_b32 s12, v108, 27
	v_readlane_b32 s13, v107, 27
	v_pk_fma_f32 v[152:153], v[2:3], v[146:147], v[40:41] op_sel_hi:[1,0,1]
	v_mov_b32_e32 v3, s12
	v_mov_b32_e32 v2, s13
	v_cndmask_b32_e64 v2, v2, v3, s[0:1]
	v_mad_u32_u24 v2, v2, s23, v251
	v_readlane_b32 s12, v108, 28
	v_readlane_b32 s13, v107, 28
	v_pk_fma_f32 v[154:155], v[4:5], v[146:147], v[42:43] op_sel_hi:[1,0,1]
	v_pk_fma_f32 v[156:157], v[6:7], v[146:147], v[44:45] op_sel_hi:[1,0,1]
	v_pk_fma_f32 v[158:159], v[8:9], v[146:147], v[46:47] op_sel_hi:[1,0,1]
	v_pk_fma_f32 v[160:161], v[10:11], v[146:147], v[48:49] op_sel_hi:[1,0,1]
	v_pk_fma_f32 v[162:163], v[12:13], v[146:147], v[50:51] op_sel_hi:[1,0,1]
	v_pk_fma_f32 v[164:165], v[14:15], v[146:147], v[52:53] op_sel_hi:[1,0,1]
	v_pk_fma_f32 v[166:167], v[16:17], v[146:147], v[54:55] op_sel_hi:[1,0,1]
	v_pk_fma_f32 v[174:175], v[24:25], v[146:147], v[138:139] op_sel_hi:[1,0,1]
	v_pk_fma_f32 v[176:177], v[26:27], v[146:147], v[140:141] op_sel_hi:[1,0,1]
	v_pk_fma_f32 v[178:179], v[28:29], v[146:147], v[142:143] op_sel_hi:[1,0,1]
	v_pk_fma_f32 v[180:181], v[30:31], v[146:147], v[144:145] op_sel_hi:[1,0,1]
	global_load_dwordx4 v[138:141], v0, s[100:101]
	global_load_dwordx2 v[142:143], v0, s[100:101] offset:16
	global_load_dwordx4 v[144:147], v2, s[100:101]
	v_mov_b32_e32 v0, s13
	v_mov_b32_e32 v1, s12
	v_cndmask_b32_e64 v0, v0, v1, s[0:1]
	v_mad_u32_u24 v0, v0, s23, v251
	v_readlane_b32 s12, v108, 29
	v_readlane_b32 s13, v107, 29
	global_load_dwordx2 v[148:149], v2, s[100:101] offset:16
	global_load_dwordx4 v[50:53], v0, s[100:101]
	v_mov_b32_e32 v2, s13
	v_mov_b32_e32 v3, s12
	v_cndmask_b32_e64 v2, v2, v3, s[0:1]
	v_mad_u32_u24 v2, v2, s23, v251
	v_readlane_b32 s12, v108, 30
	v_readlane_b32 s13, v107, 30
	global_load_dwordx2 v[54:55], v0, s[100:101] offset:16
	global_load_dwordx4 v[44:47], v2, s[100:101]
	v_mov_b32_e32 v0, s13
	v_mov_b32_e32 v1, s12
	v_cndmask_b32_e64 v0, v0, v1, s[0:1]
	v_mad_u32_u24 v0, v0, s23, v251
	v_readlane_b32 s12, v108, 31
	v_readlane_b32 s13, v107, 31
	global_load_dwordx2 v[48:49], v2, s[100:101] offset:16
	global_load_dwordx4 v[38:41], v0, s[100:101]
	v_mov_b32_e32 v2, s13
	v_mov_b32_e32 v3, s12
	v_cndmask_b32_e64 v2, v2, v3, s[0:1]
	v_mad_u32_u24 v2, v2, s23, v251
	global_load_dwordx2 v[36:37], v2, s[100:101] offset:16
	global_load_dwordx2 v[42:43], v0, s[100:101] offset:16
	global_load_dwordx4 v[32:35], v2, s[100:101]
	v_readlane_b32 s12, v106, 24
	v_readlane_b32 s13, v109, 24
	s_nop 0
	v_mov_b32_e32 v1, s12
	v_mov_b32_e32 v0, s13
	v_cndmask_b32_e64 v182, v0, v1, s[0:1]
	v_readlane_b32 s12, v106, 25
	v_readlane_b32 s13, v109, 25
	s_waitcnt vmcnt(14)
; DI void phase_peer_out(const Params& p, char* lds) {
;     ...
;     for (int kb = 0; kb < 8; ++kb) {
;       v6u qb[8];
; #pragma unroll
;       for (int k = 0; k < 8; ++k) {
;         const int e0 = __builtin_amdgcn_readlane(el[0], kb * 8 + k), e1 = __builtin_amdgcn_readlane(el[1], kb * 8 + k);
;         qb[k] = load6(V6 + (size_t)(hb ? e1 : e0) * 768);
;       }
; #pragma unroll
;       for (int k = 0; k < 8; ++k) {
;         const float c0 = __uint_as_float(__builtin_amdgcn_readlane(__float_as_uint(coefv[0]), kb * 8 + k)), c1 = __uint_as_float(__builtin_amdgcn_readlane(__float_as_uint(coefv[1]), kb * 8 + k));
;         const float cf = hb ? c1 : c0;
;         const f32x2 c2 = {cf, cf};
;         const v32f f = __builtin_amdgcn_cvt_scalef32_pk32_f32_fp6(qb[k], 1.0f);
; #pragma unroll
;         for (int i = 0; i < 16; ++i) o2[i] = f32x2{f[2 * i], f[2 * i + 1]} * c2 + o2[i];
;       }
;     }
	v_cvt_scalef32_pk32_f32_fp6 v[0:31], v[126:131], 1.0
	v_pk_fma_f32 v[126:127], v[0:1], v[182:183], v[150:151] op_sel_hi:[1,0,1]
	v_mov_b32_e32 v0, s13
	v_mov_b32_e32 v1, s12
	v_pk_fma_f32 v[128:129], v[2:3], v[182:183], v[152:153] op_sel_hi:[1,0,1]
	v_pk_fma_f32 v[130:131], v[4:5], v[182:183], v[154:155] op_sel_hi:[1,0,1]
	v_pk_fma_f32 v[150:151], v[6:7], v[182:183], v[156:157] op_sel_hi:[1,0,1]
	v_pk_fma_f32 v[152:153], v[8:9], v[182:183], v[158:159] op_sel_hi:[1,0,1]
	v_pk_fma_f32 v[154:155], v[10:11], v[182:183], v[160:161] op_sel_hi:[1,0,1]
	v_pk_fma_f32 v[156:157], v[12:13], v[182:183], v[162:163] op_sel_hi:[1,0,1]
	v_pk_fma_f32 v[158:159], v[14:15], v[182:183], v[164:165] op_sel_hi:[1,0,1]
	v_pk_fma_f32 v[160:161], v[16:17], v[182:183], v[166:167] op_sel_hi:[1,0,1]
	v_pk_fma_f32 v[162:163], v[18:19], v[182:183], v[168:169] op_sel_hi:[1,0,1]
	v_pk_fma_f32 v[164:165], v[20:21], v[182:183], v[170:171] op_sel_hi:[1,0,1]
	v_pk_fma_f32 v[166:167], v[22:23], v[182:183], v[172:173] op_sel_hi:[1,0,1]
	v_pk_fma_f32 v[168:169], v[24:25], v[182:183], v[174:175] op_sel_hi:[1,0,1]
	v_pk_fma_f32 v[170:171], v[26:27], v[182:183], v[176:177] op_sel_hi:[1,0,1]
	v_pk_fma_f32 v[172:173], v[28:29], v[182:183], v[178:179] op_sel_hi:[1,0,1]
	v_pk_fma_f32 v[174:175], v[30:31], v[182:183], v[180:181] op_sel_hi:[1,0,1]
	v_cndmask_b32_e64 v176, v0, v1, s[0:1]
	s_waitcnt vmcnt(12)
	v_cvt_scalef32_pk32_f32_fp6 v[0:31], v[132:137], 1.0
	v_readlane_b32 s12, v106, 26
	v_readlane_b32 s13, v109, 26
	v_pk_fma_f32 v[126:127], v[0:1], v[176:177], v[126:127] op_sel_hi:[1,0,1]
	v_mov_b32_e32 v1, s12
	v_mov_b32_e32 v0, s13
	v_pk_fma_f32 v[128:129], v[2:3], v[176:177], v[128:129] op_sel_hi:[1,0,1]
	v_pk_fma_f32 v[130:131], v[4:5], v[176:177], v[130:131] op_sel_hi:[1,0,1]
	v_pk_fma_f32 v[132:133], v[6:7], v[176:177], v[150:151] op_sel_hi:[1,0,1]
	v_pk_fma_f32 v[134:135], v[8:9], v[176:177], v[152:153] op_sel_hi:[1,0,1]
	v_pk_fma_f32 v[136:137], v[10:11], v[176:177], v[154:155] op_sel_hi:[1,0,1]
	v_pk_fma_f32 v[150:151], v[12:13], v[176:177], v[156:157] op_sel_hi:[1,0,1]
	v_pk_fma_f32 v[152:153], v[14:15], v[176:177], v[158:159] op_sel_hi:[1,0,1]
	v_pk_fma_f32 v[154:155], v[16:17], v[176:177], v[160:161] op_sel_hi:[1,0,1]
	v_pk_fma_f32 v[156:157], v[18:19], v[176:177], v[162:163] op_sel_hi:[1,0,1]
	v_pk_fma_f32 v[158:159], v[20:21], v[176:177], v[164:165] op_sel_hi:[1,0,1]
	v_pk_fma_f32 v[160:161], v[22:23], v[176:177], v[166:167] op_sel_hi:[1,0,1]
	v_pk_fma_f32 v[162:163], v[24:25], v[176:177], v[168:169] op_sel_hi:[1,0,1]
	v_pk_fma_f32 v[164:165], v[26:27], v[176:177], v[170:171] op_sel_hi:[1,0,1]
	v_pk_fma_f32 v[166:167], v[28:29], v[176:177], v[172:173] op_sel_hi:[1,0,1]
	v_pk_fma_f32 v[168:169], v[30:31], v[176:177], v[174:175] op_sel_hi:[1,0,1]
	v_cndmask_b32_e64 v170, v0, v1, s[0:1]
	s_waitcnt vmcnt(10)
	v_cvt_scalef32_pk32_f32_fp6 v[0:31], v[138:143], 1.0
	v_readlane_b32 s12, v106, 27
	v_readlane_b32 s13, v109, 27
	v_pk_fma_f32 v[126:127], v[0:1], v[170:171], v[126:127] op_sel_hi:[1,0,1]
	v_mov_b32_e32 v1, s12
	v_mov_b32_e32 v0, s13
	v_pk_fma_f32 v[128:129], v[2:3], v[170:171], v[128:129] op_sel_hi:[1,0,1]
	v_pk_fma_f32 v[130:131], v[4:5], v[170:171], v[130:131] op_sel_hi:[1,0,1]
	v_pk_fma_f32 v[132:133], v[6:7], v[170:171], v[132:133] op_sel_hi:[1,0,1]
	v_pk_fma_f32 v[134:135], v[8:9], v[170:171], v[134:135] op_sel_hi:[1,0,1]
	v_pk_fma_f32 v[136:137], v[10:11], v[170:171], v[136:137] op_sel_hi:[1,0,1]
	v_pk_fma_f32 v[138:139], v[12:13], v[170:171], v[150:151] op_sel_hi:[1,0,1]
	v_pk_fma_f32 v[140:141], v[14:15], v[170:171], v[152:153] op_sel_hi:[1,0,1]
	v_pk_fma_f32 v[142:143], v[16:17], v[170:171], v[154:155] op_sel_hi:[1,0,1]
	v_pk_fma_f32 v[150:151], v[18:19], v[170:171], v[156:157] op_sel_hi:[1,0,1]
	v_pk_fma_f32 v[152:153], v[20:21], v[170:171], v[158:159] op_sel_hi:[1,0,1]
	v_pk_fma_f32 v[154:155], v[22:23], v[170:171], v[160:161] op_sel_hi:[1,0,1]
	v_pk_fma_f32 v[156:157], v[24:25], v[170:171], v[162:163] op_sel_hi:[1,0,1]
	v_pk_fma_f32 v[158:159], v[26:27], v[170:171], v[164:165] op_sel_hi:[1,0,1]
	v_pk_fma_f32 v[160:161], v[28:29], v[170:171], v[166:167] op_sel_hi:[1,0,1]
	v_pk_fma_f32 v[162:163], v[30:31], v[170:171], v[168:169] op_sel_hi:[1,0,1]
	v_cndmask_b32_e64 v164, v0, v1, s[0:1]
	s_waitcnt vmcnt(8)
	v_cvt_scalef32_pk32_f32_fp6 v[0:31], v[144:149], 1.0
	v_readlane_b32 s12, v106, 28
	v_readlane_b32 s13, v109, 28
	v_pk_fma_f32 v[126:127], v[0:1], v[164:165], v[126:127] op_sel_hi:[1,0,1]
	v_mov_b32_e32 v1, s12
	v_mov_b32_e32 v0, s13
	v_pk_fma_f32 v[128:129], v[2:3], v[164:165], v[128:129] op_sel_hi:[1,0,1]
	v_pk_fma_f32 v[130:131], v[4:5], v[164:165], v[130:131] op_sel_hi:[1,0,1]
	v_pk_fma_f32 v[132:133], v[6:7], v[164:165], v[132:133] op_sel_hi:[1,0,1]
	v_pk_fma_f32 v[134:135], v[8:9], v[164:165], v[134:135] op_sel_hi:[1,0,1]
	v_pk_fma_f32 v[136:137], v[10:11], v[164:165], v[136:137] op_sel_hi:[1,0,1]
	v_pk_fma_f32 v[138:139], v[12:13], v[164:165], v[138:139] op_sel_hi:[1,0,1]
	v_pk_fma_f32 v[140:141], v[14:15], v[164:165], v[140:141] op_sel_hi:[1,0,1]
	v_pk_fma_f32 v[142:143], v[16:17], v[164:165], v[142:143] op_sel_hi:[1,0,1]
	v_pk_fma_f32 v[144:145], v[18:19], v[164:165], v[150:151] op_sel_hi:[1,0,1]
	v_pk_fma_f32 v[146:147], v[20:21], v[164:165], v[152:153] op_sel_hi:[1,0,1]
	v_pk_fma_f32 v[148:149], v[22:23], v[164:165], v[154:155] op_sel_hi:[1,0,1]
	v_pk_fma_f32 v[150:151], v[24:25], v[164:165], v[156:157] op_sel_hi:[1,0,1]
	v_pk_fma_f32 v[152:153], v[26:27], v[164:165], v[158:159] op_sel_hi:[1,0,1]
	v_pk_fma_f32 v[154:155], v[28:29], v[164:165], v[160:161] op_sel_hi:[1,0,1]
	v_pk_fma_f32 v[156:157], v[30:31], v[164:165], v[162:163] op_sel_hi:[1,0,1]
	v_cndmask_b32_e64 v158, v0, v1, s[0:1]
	s_waitcnt vmcnt(6)
; DI void phase_peer_out(const Params& p, char* lds) {
;     ...
;     for (int kb = 0; kb < 8; ++kb) {
;       v6u qb[8];
; #pragma unroll
;       for (int k = 0; k < 8; ++k) {
;         const int e0 = __builtin_amdgcn_readlane(el[0], kb * 8 + k), e1 = __builtin_amdgcn_readlane(el[1], kb * 8 + k);
;         qb[k] = load6(V6 + (size_t)(hb ? e1 : e0) * 768);
;       }
; #pragma unroll
;       for (int k = 0; k < 8; ++k) {
;         const float c0 = __uint_as_float(__builtin_amdgcn_readlane(__float_as_uint(coefv[0]), kb * 8 + k)), c1 = __uint_as_float(__builtin_amdgcn_readlane(__float_as_uint(coefv[1]), kb * 8 + k));
;         const float cf = hb ? c1 : c0;
;         const f32x2 c2 = {cf, cf};
;         const v32f f = __builtin_amdgcn_cvt_scalef32_pk32_f32_fp6(qb[k], 1.0f);
; #pragma unroll
;         for (int i = 0; i < 16; ++i) o2[i] = f32x2{f[2 * i], f[2 * i + 1]} * c2 + o2[i];
;       }
;     }
	v_cvt_scalef32_pk32_f32_fp6 v[0:31], v[50:55], 1.0
	v_readlane_b32 s12, v106, 29
	v_readlane_b32 s13, v109, 29
	v_pk_fma_f32 v[50:51], v[0:1], v[158:159], v[126:127] op_sel_hi:[1,0,1]
	v_mov_b32_e32 v1, s12
	v_mov_b32_e32 v0, s13
	v_pk_fma_f32 v[52:53], v[2:3], v[158:159], v[128:129] op_sel_hi:[1,0,1]
	v_pk_fma_f32 v[54:55], v[4:5], v[158:159], v[130:131] op_sel_hi:[1,0,1]
	v_pk_fma_f32 v[126:127], v[6:7], v[158:159], v[132:133] op_sel_hi:[1,0,1]
	v_pk_fma_f32 v[128:129], v[8:9], v[158:159], v[134:135] op_sel_hi:[1,0,1]
	v_pk_fma_f32 v[130:131], v[10:11], v[158:159], v[136:137] op_sel_hi:[1,0,1]
	v_pk_fma_f32 v[132:133], v[12:13], v[158:159], v[138:139] op_sel_hi:[1,0,1]
	v_pk_fma_f32 v[134:135], v[14:15], v[158:159], v[140:141] op_sel_hi:[1,0,1]
	v_pk_fma_f32 v[136:137], v[16:17], v[158:159], v[142:143] op_sel_hi:[1,0,1]
	v_pk_fma_f32 v[138:139], v[18:19], v[158:159], v[144:145] op_sel_hi:[1,0,1]
	v_pk_fma_f32 v[140:141], v[20:21], v[158:159], v[146:147] op_sel_hi:[1,0,1]
	v_pk_fma_f32 v[142:143], v[22:23], v[158:159], v[148:149] op_sel_hi:[1,0,1]
	v_pk_fma_f32 v[144:145], v[24:25], v[158:159], v[150:151] op_sel_hi:[1,0,1]
	v_pk_fma_f32 v[146:147], v[26:27], v[158:159], v[152:153] op_sel_hi:[1,0,1]
	v_pk_fma_f32 v[148:149], v[28:29], v[158:159], v[154:155] op_sel_hi:[1,0,1]
	v_pk_fma_f32 v[150:151], v[30:31], v[158:159], v[156:157] op_sel_hi:[1,0,1]
	v_cndmask_b32_e64 v152, v0, v1, s[0:1]
	s_waitcnt vmcnt(4)
	v_cvt_scalef32_pk32_f32_fp6 v[0:31], v[44:49], 1.0
	v_readlane_b32 s12, v106, 30
	v_readlane_b32 s13, v109, 30
	v_pk_fma_f32 v[44:45], v[0:1], v[152:153], v[50:51] op_sel_hi:[1,0,1]
	v_mov_b32_e32 v1, s12
	v_mov_b32_e32 v0, s13
	v_pk_fma_f32 v[46:47], v[2:3], v[152:153], v[52:53] op_sel_hi:[1,0,1]
	v_pk_fma_f32 v[48:49], v[4:5], v[152:153], v[54:55] op_sel_hi:[1,0,1]
	v_pk_fma_f32 v[50:51], v[6:7], v[152:153], v[126:127] op_sel_hi:[1,0,1]
	v_pk_fma_f32 v[52:53], v[8:9], v[152:153], v[128:129] op_sel_hi:[1,0,1]
	v_pk_fma_f32 v[54:55], v[10:11], v[152:153], v[130:131] op_sel_hi:[1,0,1]
	v_pk_fma_f32 v[126:127], v[12:13], v[152:153], v[132:133] op_sel_hi:[1,0,1]
	v_pk_fma_f32 v[128:129], v[14:15], v[152:153], v[134:135] op_sel_hi:[1,0,1]
	v_pk_fma_f32 v[130:131], v[16:17], v[152:153], v[136:137] op_sel_hi:[1,0,1]
	v_pk_fma_f32 v[132:133], v[18:19], v[152:153], v[138:139] op_sel_hi:[1,0,1]
	v_pk_fma_f32 v[134:135], v[20:21], v[152:153], v[140:141] op_sel_hi:[1,0,1]
	v_pk_fma_f32 v[136:137], v[22:23], v[152:153], v[142:143] op_sel_hi:[1,0,1]
	v_pk_fma_f32 v[138:139], v[24:25], v[152:153], v[144:145] op_sel_hi:[1,0,1]
	v_pk_fma_f32 v[140:141], v[26:27], v[152:153], v[146:147] op_sel_hi:[1,0,1]
	v_pk_fma_f32 v[142:143], v[28:29], v[152:153], v[148:149] op_sel_hi:[1,0,1]
	v_pk_fma_f32 v[144:145], v[30:31], v[152:153], v[150:151] op_sel_hi:[1,0,1]
	v_cndmask_b32_e64 v146, v0, v1, s[0:1]
	s_waitcnt vmcnt(1)
	v_cvt_scalef32_pk32_f32_fp6 v[0:31], v[38:43], 1.0
	v_readlane_b32 s12, v106, 31
	v_readlane_b32 s13, v109, 31
	v_pk_fma_f32 v[38:39], v[0:1], v[146:147], v[44:45] op_sel_hi:[1,0,1]
	v_mov_b32_e32 v1, s12
	v_mov_b32_e32 v0, s13
	v_readlane_b32 s12, v108, 32
	v_readlane_b32 s13, v107, 32
	v_pk_fma_f32 v[40:41], v[2:3], v[146:147], v[46:47] op_sel_hi:[1,0,1]
	v_pk_fma_f32 v[42:43], v[4:5], v[146:147], v[48:49] op_sel_hi:[1,0,1]
	v_pk_fma_f32 v[44:45], v[6:7], v[146:147], v[50:51] op_sel_hi:[1,0,1]
	v_pk_fma_f32 v[46:47], v[8:9], v[146:147], v[52:53] op_sel_hi:[1,0,1]
	v_pk_fma_f32 v[48:49], v[10:11], v[146:147], v[54:55] op_sel_hi:[1,0,1]
	v_pk_fma_f32 v[50:51], v[12:13], v[146:147], v[126:127] op_sel_hi:[1,0,1]
	v_pk_fma_f32 v[52:53], v[14:15], v[146:147], v[128:129] op_sel_hi:[1,0,1]
	v_pk_fma_f32 v[54:55], v[16:17], v[146:147], v[130:131] op_sel_hi:[1,0,1]
	v_pk_fma_f32 v[132:133], v[18:19], v[146:147], v[132:133] op_sel_hi:[1,0,1]
	v_pk_fma_f32 v[134:135], v[20:21], v[146:147], v[134:135] op_sel_hi:[1,0,1]
	v_pk_fma_f32 v[136:137], v[22:23], v[146:147], v[136:137] op_sel_hi:[1,0,1]
	v_pk_fma_f32 v[138:139], v[24:25], v[146:147], v[138:139] op_sel_hi:[1,0,1]
	v_pk_fma_f32 v[140:141], v[26:27], v[146:147], v[140:141] op_sel_hi:[1,0,1]
	v_pk_fma_f32 v[142:143], v[28:29], v[146:147], v[142:143] op_sel_hi:[1,0,1]
	v_pk_fma_f32 v[144:145], v[30:31], v[146:147], v[144:145] op_sel_hi:[1,0,1]
	v_cndmask_b32_e64 v146, v0, v1, s[0:1]
	v_mov_b32_e32 v0, s13
	v_mov_b32_e32 v1, s12
	v_cndmask_b32_e64 v0, v0, v1, s[0:1]
	v_mad_u32_u24 v130, v0, s23, v251
	s_waitcnt vmcnt(0)
; DI void phase_peer_out(const Params& p, char* lds) {
;     ...
;     for (int kb = 0; kb < 8; ++kb) {
;       v6u qb[8];
; #pragma unroll
;       for (int k = 0; k < 8; ++k) {
;         const int e0 = __builtin_amdgcn_readlane(el[0], kb * 8 + k), e1 = __builtin_amdgcn_readlane(el[1], kb * 8 + k);
;         qb[k] = load6(V6 + (size_t)(hb ? e1 : e0) * 768);
;       }
; #pragma unroll
;       for (int k = 0; k < 8; ++k) {
;         const float c0 = __uint_as_float(__builtin_amdgcn_readlane(__float_as_uint(coefv[0]), kb * 8 + k)), c1 = __uint_as_float(__builtin_amdgcn_readlane(__float_as_uint(coefv[1]), kb * 8 + k));
;         const float cf = hb ? c1 : c0;
;         const f32x2 c2 = {cf, cf};
;         const v32f f = __builtin_amdgcn_cvt_scalef32_pk32_f32_fp6(qb[k], 1.0f);
; #pragma unroll
;         for (int i = 0; i < 16; ++i) o2[i] = f32x2{f[2 * i], f[2 * i + 1]} * c2 + o2[i];
;       }
;     }
	v_cvt_scalef32_pk32_f32_fp6 v[0:31], v[32:37], 1.0
	v_readlane_b32 s12, v108, 33
	v_readlane_b32 s13, v107, 33
	v_pk_fma_f32 v[150:151], v[0:1], v[146:147], v[38:39] op_sel_hi:[1,0,1]
	v_mov_b32_e32 v1, s12
	v_mov_b32_e32 v0, s13
	v_cndmask_b32_e64 v0, v0, v1, s[0:1]
	v_mad_u32_u24 v0, v0, s23, v251
	v_readlane_b32 s12, v108, 34
	v_readlane_b32 s13, v107, 34
	global_load_dwordx4 v[126:129], v130, s[100:101]
	v_pk_fma_f32 v[168:169], v[18:19], v[146:147], v[132:133] op_sel_hi:[1,0,1]
	global_load_dwordx2 v[130:131], v130, s[100:101] offset:16
	v_pk_fma_f32 v[170:171], v[20:21], v[146:147], v[134:135] op_sel_hi:[1,0,1]
	v_pk_fma_f32 v[172:173], v[22:23], v[146:147], v[136:137] op_sel_hi:[1,0,1]
	global_load_dwordx2 v[136:137], v0, s[100:101] offset:16
	global_load_dwordx4 v[132:135], v0, s[100:101]
	v_mov_b32_e32 v0, s13
	v_mov_b32_e32 v1, s12
	v_cndmask_b32_e64 v0, v0, v1, s[0:1]
	v_mad_u32_u24 v0, v0, s23, v251
	v_readlane_b32 s12, v108, 35
	v_readlane_b32 s13, v107, 35
	v_pk_fma_f32 v[152:153], v[2:3], v[146:147], v[40:41] op_sel_hi:[1,0,1]
	v_mov_b32_e32 v3, s12
	v_mov_b32_e32 v2, s13
	v_cndmask_b32_e64 v2, v2, v3, s[0:1]
	v_mad_u32_u24 v2, v2, s23, v251
	v_readlane_b32 s12, v108, 36
	v_readlane_b32 s13, v107, 36
	v_pk_fma_f32 v[154:155], v[4:5], v[146:147], v[42:43] op_sel_hi:[1,0,1]
	v_pk_fma_f32 v[156:157], v[6:7], v[146:147], v[44:45] op_sel_hi:[1,0,1]
	v_pk_fma_f32 v[158:159], v[8:9], v[146:147], v[46:47] op_sel_hi:[1,0,1]
	v_pk_fma_f32 v[160:161], v[10:11], v[146:147], v[48:49] op_sel_hi:[1,0,1]
	v_pk_fma_f32 v[162:163], v[12:13], v[146:147], v[50:51] op_sel_hi:[1,0,1]
	v_pk_fma_f32 v[164:165], v[14:15], v[146:147], v[52:53] op_sel_hi:[1,0,1]
	v_pk_fma_f32 v[166:167], v[16:17], v[146:147], v[54:55] op_sel_hi:[1,0,1]
	v_pk_fma_f32 v[174:175], v[24:25], v[146:147], v[138:139] op_sel_hi:[1,0,1]
	v_pk_fma_f32 v[176:177], v[26:27], v[146:147], v[140:141] op_sel_hi:[1,0,1]
	v_pk_fma_f32 v[178:179], v[28:29], v[146:147], v[142:143] op_sel_hi:[1,0,1]
	v_pk_fma_f32 v[180:181], v[30:31], v[146:147], v[144:145] op_sel_hi:[1,0,1]
	global_load_dwordx4 v[138:141], v0, s[100:101]
	global_load_dwordx2 v[142:143], v0, s[100:101] offset:16
	global_load_dwordx4 v[144:147], v2, s[100:101]
	v_mov_b32_e32 v0, s13
	v_mov_b32_e32 v1, s12
	v_cndmask_b32_e64 v0, v0, v1, s[0:1]
	v_mad_u32_u24 v0, v0, s23, v251
	v_readlane_b32 s12, v108, 37
	v_readlane_b32 s13, v107, 37
	global_load_dwordx2 v[148:149], v2, s[100:101] offset:16
	global_load_dwordx4 v[50:53], v0, s[100:101]
	v_mov_b32_e32 v2, s13
	v_mov_b32_e32 v3, s12
	v_cndmask_b32_e64 v2, v2, v3, s[0:1]
	v_mad_u32_u24 v2, v2, s23, v251
	v_readlane_b32 s12, v108, 38
	v_readlane_b32 s13, v107, 38
	global_load_dwordx2 v[54:55], v0, s[100:101] offset:16
	global_load_dwordx4 v[44:47], v2, s[100:101]
	v_mov_b32_e32 v0, s13
	v_mov_b32_e32 v1, s12
	v_cndmask_b32_e64 v0, v0, v1, s[0:1]
	v_mad_u32_u24 v0, v0, s23, v251
	v_readlane_b32 s12, v108, 39
	v_readlane_b32 s13, v107, 39
	global_load_dwordx2 v[48:49], v2, s[100:101] offset:16
	global_load_dwordx4 v[38:41], v0, s[100:101]
	v_mov_b32_e32 v2, s13
	v_mov_b32_e32 v3, s12
	v_cndmask_b32_e64 v2, v2, v3, s[0:1]
	v_mad_u32_u24 v2, v2, s23, v251
	global_load_dwordx2 v[36:37], v2, s[100:101] offset:16
	global_load_dwordx2 v[42:43], v0, s[100:101] offset:16
	global_load_dwordx4 v[32:35], v2, s[100:101]
	v_readlane_b32 s12, v106, 32
	v_readlane_b32 s13, v109, 32
	s_nop 0
	v_mov_b32_e32 v1, s12
	v_mov_b32_e32 v0, s13
	v_cndmask_b32_e64 v182, v0, v1, s[0:1]
	v_readlane_b32 s12, v106, 33
	v_readlane_b32 s13, v109, 33
	s_waitcnt vmcnt(14)
	v_cvt_scalef32_pk32_f32_fp6 v[0:31], v[126:131], 1.0
	v_pk_fma_f32 v[126:127], v[0:1], v[182:183], v[150:151] op_sel_hi:[1,0,1]
	v_mov_b32_e32 v0, s13
	v_mov_b32_e32 v1, s12
	v_pk_fma_f32 v[128:129], v[2:3], v[182:183], v[152:153] op_sel_hi:[1,0,1]
	v_pk_fma_f32 v[130:131], v[4:5], v[182:183], v[154:155] op_sel_hi:[1,0,1]
	v_pk_fma_f32 v[150:151], v[6:7], v[182:183], v[156:157] op_sel_hi:[1,0,1]
	v_pk_fma_f32 v[152:153], v[8:9], v[182:183], v[158:159] op_sel_hi:[1,0,1]
	v_pk_fma_f32 v[154:155], v[10:11], v[182:183], v[160:161] op_sel_hi:[1,0,1]
	v_pk_fma_f32 v[156:157], v[12:13], v[182:183], v[162:163] op_sel_hi:[1,0,1]
	v_pk_fma_f32 v[158:159], v[14:15], v[182:183], v[164:165] op_sel_hi:[1,0,1]
	v_pk_fma_f32 v[160:161], v[16:17], v[182:183], v[166:167] op_sel_hi:[1,0,1]
	v_pk_fma_f32 v[162:163], v[18:19], v[182:183], v[168:169] op_sel_hi:[1,0,1]
	v_pk_fma_f32 v[164:165], v[20:21], v[182:183], v[170:171] op_sel_hi:[1,0,1]
	v_pk_fma_f32 v[166:167], v[22:23], v[182:183], v[172:173] op_sel_hi:[1,0,1]
	v_pk_fma_f32 v[168:169], v[24:25], v[182:183], v[174:175] op_sel_hi:[1,0,1]
	v_pk_fma_f32 v[170:171], v[26:27], v[182:183], v[176:177] op_sel_hi:[1,0,1]
	v_pk_fma_f32 v[172:173], v[28:29], v[182:183], v[178:179] op_sel_hi:[1,0,1]
	v_pk_fma_f32 v[174:175], v[30:31], v[182:183], v[180:181] op_sel_hi:[1,0,1]
	v_cndmask_b32_e64 v176, v0, v1, s[0:1]
	s_waitcnt vmcnt(12)
; DI void phase_peer_out(const Params& p, char* lds) {
;     ...
;     for (int kb = 0; kb < 8; ++kb) {
;       v6u qb[8];
; #pragma unroll
;       for (int k = 0; k < 8; ++k) {
;         const int e0 = __builtin_amdgcn_readlane(el[0], kb * 8 + k), e1 = __builtin_amdgcn_readlane(el[1], kb * 8 + k);
;         qb[k] = load6(V6 + (size_t)(hb ? e1 : e0) * 768);
;       }
; #pragma unroll
;       for (int k = 0; k < 8; ++k) {
;         const float c0 = __uint_as_float(__builtin_amdgcn_readlane(__float_as_uint(coefv[0]), kb * 8 + k)), c1 = __uint_as_float(__builtin_amdgcn_readlane(__float_as_uint(coefv[1]), kb * 8 + k));
;         const float cf = hb ? c1 : c0;
;         const f32x2 c2 = {cf, cf};
;         const v32f f = __builtin_amdgcn_cvt_scalef32_pk32_f32_fp6(qb[k], 1.0f);
; #pragma unroll
;         for (int i = 0; i < 16; ++i) o2[i] = f32x2{f[2 * i], f[2 * i + 1]} * c2 + o2[i];
;       }
;     }
	v_cvt_scalef32_pk32_f32_fp6 v[0:31], v[132:137], 1.0
	v_readlane_b32 s12, v106, 34
	v_readlane_b32 s13, v109, 34
	v_pk_fma_f32 v[126:127], v[0:1], v[176:177], v[126:127] op_sel_hi:[1,0,1]
	v_mov_b32_e32 v1, s12
	v_mov_b32_e32 v0, s13
	v_pk_fma_f32 v[128:129], v[2:3], v[176:177], v[128:129] op_sel_hi:[1,0,1]
	v_pk_fma_f32 v[130:131], v[4:5], v[176:177], v[130:131] op_sel_hi:[1,0,1]
	v_pk_fma_f32 v[132:133], v[6:7], v[176:177], v[150:151] op_sel_hi:[1,0,1]
	v_pk_fma_f32 v[134:135], v[8:9], v[176:177], v[152:153] op_sel_hi:[1,0,1]
	v_pk_fma_f32 v[136:137], v[10:11], v[176:177], v[154:155] op_sel_hi:[1,0,1]
	v_pk_fma_f32 v[150:151], v[12:13], v[176:177], v[156:157] op_sel_hi:[1,0,1]
	v_pk_fma_f32 v[152:153], v[14:15], v[176:177], v[158:159] op_sel_hi:[1,0,1]
	v_pk_fma_f32 v[154:155], v[16:17], v[176:177], v[160:161] op_sel_hi:[1,0,1]
	v_pk_fma_f32 v[156:157], v[18:19], v[176:177], v[162:163] op_sel_hi:[1,0,1]
	v_pk_fma_f32 v[158:159], v[20:21], v[176:177], v[164:165] op_sel_hi:[1,0,1]
	v_pk_fma_f32 v[160:161], v[22:23], v[176:177], v[166:167] op_sel_hi:[1,0,1]
	v_pk_fma_f32 v[162:163], v[24:25], v[176:177], v[168:169] op_sel_hi:[1,0,1]
	v_pk_fma_f32 v[164:165], v[26:27], v[176:177], v[170:171] op_sel_hi:[1,0,1]
	v_pk_fma_f32 v[166:167], v[28:29], v[176:177], v[172:173] op_sel_hi:[1,0,1]
	v_pk_fma_f32 v[168:169], v[30:31], v[176:177], v[174:175] op_sel_hi:[1,0,1]
	v_cndmask_b32_e64 v170, v0, v1, s[0:1]
	s_waitcnt vmcnt(10)
	v_cvt_scalef32_pk32_f32_fp6 v[0:31], v[138:143], 1.0
	v_readlane_b32 s12, v106, 35
	v_readlane_b32 s13, v109, 35
	v_pk_fma_f32 v[126:127], v[0:1], v[170:171], v[126:127] op_sel_hi:[1,0,1]
	v_mov_b32_e32 v1, s12
	v_mov_b32_e32 v0, s13
	v_pk_fma_f32 v[128:129], v[2:3], v[170:171], v[128:129] op_sel_hi:[1,0,1]
	v_pk_fma_f32 v[130:131], v[4:5], v[170:171], v[130:131] op_sel_hi:[1,0,1]
	v_pk_fma_f32 v[132:133], v[6:7], v[170:171], v[132:133] op_sel_hi:[1,0,1]
	v_pk_fma_f32 v[134:135], v[8:9], v[170:171], v[134:135] op_sel_hi:[1,0,1]
	v_pk_fma_f32 v[136:137], v[10:11], v[170:171], v[136:137] op_sel_hi:[1,0,1]
	v_pk_fma_f32 v[138:139], v[12:13], v[170:171], v[150:151] op_sel_hi:[1,0,1]
	v_pk_fma_f32 v[140:141], v[14:15], v[170:171], v[152:153] op_sel_hi:[1,0,1]
	v_pk_fma_f32 v[142:143], v[16:17], v[170:171], v[154:155] op_sel_hi:[1,0,1]
	v_pk_fma_f32 v[150:151], v[18:19], v[170:171], v[156:157] op_sel_hi:[1,0,1]
	v_pk_fma_f32 v[152:153], v[20:21], v[170:171], v[158:159] op_sel_hi:[1,0,1]
	v_pk_fma_f32 v[154:155], v[22:23], v[170:171], v[160:161] op_sel_hi:[1,0,1]
	v_pk_fma_f32 v[156:157], v[24:25], v[170:171], v[162:163] op_sel_hi:[1,0,1]
	v_pk_fma_f32 v[158:159], v[26:27], v[170:171], v[164:165] op_sel_hi:[1,0,1]
	v_pk_fma_f32 v[160:161], v[28:29], v[170:171], v[166:167] op_sel_hi:[1,0,1]
	v_pk_fma_f32 v[162:163], v[30:31], v[170:171], v[168:169] op_sel_hi:[1,0,1]
	v_cndmask_b32_e64 v164, v0, v1, s[0:1]
	s_waitcnt vmcnt(8)
	v_cvt_scalef32_pk32_f32_fp6 v[0:31], v[144:149], 1.0
	v_readlane_b32 s12, v106, 36
	v_readlane_b32 s13, v109, 36
	v_pk_fma_f32 v[126:127], v[0:1], v[164:165], v[126:127] op_sel_hi:[1,0,1]
	v_mov_b32_e32 v1, s12
	v_mov_b32_e32 v0, s13
	v_pk_fma_f32 v[128:129], v[2:3], v[164:165], v[128:129] op_sel_hi:[1,0,1]
	v_pk_fma_f32 v[130:131], v[4:5], v[164:165], v[130:131] op_sel_hi:[1,0,1]
	v_pk_fma_f32 v[132:133], v[6:7], v[164:165], v[132:133] op_sel_hi:[1,0,1]
	v_pk_fma_f32 v[134:135], v[8:9], v[164:165], v[134:135] op_sel_hi:[1,0,1]
	v_pk_fma_f32 v[136:137], v[10:11], v[164:165], v[136:137] op_sel_hi:[1,0,1]
	v_pk_fma_f32 v[138:139], v[12:13], v[164:165], v[138:139] op_sel_hi:[1,0,1]
	v_pk_fma_f32 v[140:141], v[14:15], v[164:165], v[140:141] op_sel_hi:[1,0,1]
	v_pk_fma_f32 v[142:143], v[16:17], v[164:165], v[142:143] op_sel_hi:[1,0,1]
	v_pk_fma_f32 v[144:145], v[18:19], v[164:165], v[150:151] op_sel_hi:[1,0,1]
	v_pk_fma_f32 v[146:147], v[20:21], v[164:165], v[152:153] op_sel_hi:[1,0,1]
	v_pk_fma_f32 v[148:149], v[22:23], v[164:165], v[154:155] op_sel_hi:[1,0,1]
	v_pk_fma_f32 v[150:151], v[24:25], v[164:165], v[156:157] op_sel_hi:[1,0,1]
	v_pk_fma_f32 v[152:153], v[26:27], v[164:165], v[158:159] op_sel_hi:[1,0,1]
	v_pk_fma_f32 v[154:155], v[28:29], v[164:165], v[160:161] op_sel_hi:[1,0,1]
	v_pk_fma_f32 v[156:157], v[30:31], v[164:165], v[162:163] op_sel_hi:[1,0,1]
	v_cndmask_b32_e64 v158, v0, v1, s[0:1]
	s_waitcnt vmcnt(6)
	v_cvt_scalef32_pk32_f32_fp6 v[0:31], v[50:55], 1.0
	v_readlane_b32 s12, v106, 37
	v_readlane_b32 s13, v109, 37
	v_pk_fma_f32 v[50:51], v[0:1], v[158:159], v[126:127] op_sel_hi:[1,0,1]
	v_mov_b32_e32 v1, s12
	v_mov_b32_e32 v0, s13
	v_pk_fma_f32 v[52:53], v[2:3], v[158:159], v[128:129] op_sel_hi:[1,0,1]
	v_pk_fma_f32 v[54:55], v[4:5], v[158:159], v[130:131] op_sel_hi:[1,0,1]
	v_pk_fma_f32 v[126:127], v[6:7], v[158:159], v[132:133] op_sel_hi:[1,0,1]
	v_pk_fma_f32 v[128:129], v[8:9], v[158:159], v[134:135] op_sel_hi:[1,0,1]
	v_pk_fma_f32 v[130:131], v[10:11], v[158:159], v[136:137] op_sel_hi:[1,0,1]
	v_pk_fma_f32 v[132:133], v[12:13], v[158:159], v[138:139] op_sel_hi:[1,0,1]
	v_pk_fma_f32 v[134:135], v[14:15], v[158:159], v[140:141] op_sel_hi:[1,0,1]
	v_pk_fma_f32 v[136:137], v[16:17], v[158:159], v[142:143] op_sel_hi:[1,0,1]
	v_pk_fma_f32 v[138:139], v[18:19], v[158:159], v[144:145] op_sel_hi:[1,0,1]
	v_pk_fma_f32 v[140:141], v[20:21], v[158:159], v[146:147] op_sel_hi:[1,0,1]
	v_pk_fma_f32 v[142:143], v[22:23], v[158:159], v[148:149] op_sel_hi:[1,0,1]
	v_pk_fma_f32 v[144:145], v[24:25], v[158:159], v[150:151] op_sel_hi:[1,0,1]
	v_pk_fma_f32 v[146:147], v[26:27], v[158:159], v[152:153] op_sel_hi:[1,0,1]
	v_pk_fma_f32 v[148:149], v[28:29], v[158:159], v[154:155] op_sel_hi:[1,0,1]
	v_pk_fma_f32 v[150:151], v[30:31], v[158:159], v[156:157] op_sel_hi:[1,0,1]
	v_cndmask_b32_e64 v152, v0, v1, s[0:1]
	s_waitcnt vmcnt(4)
; DI void phase_peer_out(const Params& p, char* lds) {
;     ...
;     for (int kb = 0; kb < 8; ++kb) {
;       v6u qb[8];
; #pragma unroll
;       for (int k = 0; k < 8; ++k) {
;         const int e0 = __builtin_amdgcn_readlane(el[0], kb * 8 + k), e1 = __builtin_amdgcn_readlane(el[1], kb * 8 + k);
;         qb[k] = load6(V6 + (size_t)(hb ? e1 : e0) * 768);
;       }
; #pragma unroll
;       for (int k = 0; k < 8; ++k) {
;         const float c0 = __uint_as_float(__builtin_amdgcn_readlane(__float_as_uint(coefv[0]), kb * 8 + k)), c1 = __uint_as_float(__builtin_amdgcn_readlane(__float_as_uint(coefv[1]), kb * 8 + k));
;         const float cf = hb ? c1 : c0;
;         const f32x2 c2 = {cf, cf};
;         const v32f f = __builtin_amdgcn_cvt_scalef32_pk32_f32_fp6(qb[k], 1.0f);
; #pragma unroll
;         for (int i = 0; i < 16; ++i) o2[i] = f32x2{f[2 * i], f[2 * i + 1]} * c2 + o2[i];
;       }
;     }
	v_cvt_scalef32_pk32_f32_fp6 v[0:31], v[44:49], 1.0
	v_readlane_b32 s12, v106, 38
	v_readlane_b32 s13, v109, 38
	v_pk_fma_f32 v[44:45], v[0:1], v[152:153], v[50:51] op_sel_hi:[1,0,1]
	v_mov_b32_e32 v1, s12
	v_mov_b32_e32 v0, s13
	v_pk_fma_f32 v[46:47], v[2:3], v[152:153], v[52:53] op_sel_hi:[1,0,1]
	v_pk_fma_f32 v[48:49], v[4:5], v[152:153], v[54:55] op_sel_hi:[1,0,1]
	v_pk_fma_f32 v[50:51], v[6:7], v[152:153], v[126:127] op_sel_hi:[1,0,1]
	v_pk_fma_f32 v[52:53], v[8:9], v[152:153], v[128:129] op_sel_hi:[1,0,1]
	v_pk_fma_f32 v[54:55], v[10:11], v[152:153], v[130:131] op_sel_hi:[1,0,1]
	v_pk_fma_f32 v[126:127], v[12:13], v[152:153], v[132:133] op_sel_hi:[1,0,1]
	v_pk_fma_f32 v[128:129], v[14:15], v[152:153], v[134:135] op_sel_hi:[1,0,1]
	v_pk_fma_f32 v[130:131], v[16:17], v[152:153], v[136:137] op_sel_hi:[1,0,1]
	v_pk_fma_f32 v[132:133], v[18:19], v[152:153], v[138:139] op_sel_hi:[1,0,1]
	v_pk_fma_f32 v[134:135], v[20:21], v[152:153], v[140:141] op_sel_hi:[1,0,1]
	v_pk_fma_f32 v[136:137], v[22:23], v[152:153], v[142:143] op_sel_hi:[1,0,1]
	v_pk_fma_f32 v[138:139], v[24:25], v[152:153], v[144:145] op_sel_hi:[1,0,1]
	v_pk_fma_f32 v[140:141], v[26:27], v[152:153], v[146:147] op_sel_hi:[1,0,1]
	v_pk_fma_f32 v[142:143], v[28:29], v[152:153], v[148:149] op_sel_hi:[1,0,1]
	v_pk_fma_f32 v[144:145], v[30:31], v[152:153], v[150:151] op_sel_hi:[1,0,1]
	v_cndmask_b32_e64 v146, v0, v1, s[0:1]
	s_waitcnt vmcnt(1)
	v_cvt_scalef32_pk32_f32_fp6 v[0:31], v[38:43], 1.0
	v_readlane_b32 s12, v106, 39
	v_readlane_b32 s13, v109, 39
	v_pk_fma_f32 v[38:39], v[0:1], v[146:147], v[44:45] op_sel_hi:[1,0,1]
	v_mov_b32_e32 v1, s12
	v_mov_b32_e32 v0, s13
	v_readlane_b32 s12, v108, 40
	v_readlane_b32 s13, v107, 40
	v_pk_fma_f32 v[40:41], v[2:3], v[146:147], v[46:47] op_sel_hi:[1,0,1]
	v_pk_fma_f32 v[42:43], v[4:5], v[146:147], v[48:49] op_sel_hi:[1,0,1]
	v_pk_fma_f32 v[44:45], v[6:7], v[146:147], v[50:51] op_sel_hi:[1,0,1]
	v_pk_fma_f32 v[46:47], v[8:9], v[146:147], v[52:53] op_sel_hi:[1,0,1]
	v_pk_fma_f32 v[48:49], v[10:11], v[146:147], v[54:55] op_sel_hi:[1,0,1]
	v_pk_fma_f32 v[50:51], v[12:13], v[146:147], v[126:127] op_sel_hi:[1,0,1]
	v_pk_fma_f32 v[52:53], v[14:15], v[146:147], v[128:129] op_sel_hi:[1,0,1]
	v_pk_fma_f32 v[54:55], v[16:17], v[146:147], v[130:131] op_sel_hi:[1,0,1]
	v_pk_fma_f32 v[132:133], v[18:19], v[146:147], v[132:133] op_sel_hi:[1,0,1]
	v_pk_fma_f32 v[134:135], v[20:21], v[146:147], v[134:135] op_sel_hi:[1,0,1]
	v_pk_fma_f32 v[136:137], v[22:23], v[146:147], v[136:137] op_sel_hi:[1,0,1]
	v_pk_fma_f32 v[138:139], v[24:25], v[146:147], v[138:139] op_sel_hi:[1,0,1]
	v_pk_fma_f32 v[140:141], v[26:27], v[146:147], v[140:141] op_sel_hi:[1,0,1]
	v_pk_fma_f32 v[142:143], v[28:29], v[146:147], v[142:143] op_sel_hi:[1,0,1]
	v_pk_fma_f32 v[144:145], v[30:31], v[146:147], v[144:145] op_sel_hi:[1,0,1]
	v_cndmask_b32_e64 v146, v0, v1, s[0:1]
	v_mov_b32_e32 v0, s13
	v_mov_b32_e32 v1, s12
	v_cndmask_b32_e64 v0, v0, v1, s[0:1]
	v_mad_u32_u24 v130, v0, s23, v251
	s_waitcnt vmcnt(0)
	v_cvt_scalef32_pk32_f32_fp6 v[0:31], v[32:37], 1.0
	v_readlane_b32 s12, v108, 41
	v_readlane_b32 s13, v107, 41
	v_pk_fma_f32 v[150:151], v[0:1], v[146:147], v[38:39] op_sel_hi:[1,0,1]
	v_mov_b32_e32 v1, s12
	v_mov_b32_e32 v0, s13
	v_cndmask_b32_e64 v0, v0, v1, s[0:1]
	v_mad_u32_u24 v0, v0, s23, v251
	v_readlane_b32 s12, v108, 42
	v_readlane_b32 s13, v107, 42
	global_load_dwordx4 v[126:129], v130, s[100:101]
	v_pk_fma_f32 v[168:169], v[18:19], v[146:147], v[132:133] op_sel_hi:[1,0,1]
	global_load_dwordx2 v[130:131], v130, s[100:101] offset:16
	v_pk_fma_f32 v[170:171], v[20:21], v[146:147], v[134:135] op_sel_hi:[1,0,1]
	v_pk_fma_f32 v[172:173], v[22:23], v[146:147], v[136:137] op_sel_hi:[1,0,1]
	global_load_dwordx2 v[136:137], v0, s[100:101] offset:16
	global_load_dwordx4 v[132:135], v0, s[100:101]
	v_mov_b32_e32 v0, s13
	v_mov_b32_e32 v1, s12
	v_cndmask_b32_e64 v0, v0, v1, s[0:1]
	v_mad_u32_u24 v0, v0, s23, v251
	v_readlane_b32 s12, v108, 43
	v_readlane_b32 s13, v107, 43
	v_pk_fma_f32 v[152:153], v[2:3], v[146:147], v[40:41] op_sel_hi:[1,0,1]
	v_mov_b32_e32 v3, s12
	v_mov_b32_e32 v2, s13
	v_cndmask_b32_e64 v2, v2, v3, s[0:1]
	v_mad_u32_u24 v2, v2, s23, v251
	v_readlane_b32 s12, v108, 44
	v_readlane_b32 s13, v107, 44
	v_pk_fma_f32 v[154:155], v[4:5], v[146:147], v[42:43] op_sel_hi:[1,0,1]
	v_pk_fma_f32 v[156:157], v[6:7], v[146:147], v[44:45] op_sel_hi:[1,0,1]
	v_pk_fma_f32 v[158:159], v[8:9], v[146:147], v[46:47] op_sel_hi:[1,0,1]
	v_pk_fma_f32 v[160:161], v[10:11], v[146:147], v[48:49] op_sel_hi:[1,0,1]
	v_pk_fma_f32 v[162:163], v[12:13], v[146:147], v[50:51] op_sel_hi:[1,0,1]
	v_pk_fma_f32 v[164:165], v[14:15], v[146:147], v[52:53] op_sel_hi:[1,0,1]
	v_pk_fma_f32 v[166:167], v[16:17], v[146:147], v[54:55] op_sel_hi:[1,0,1]
	v_pk_fma_f32 v[174:175], v[24:25], v[146:147], v[138:139] op_sel_hi:[1,0,1]
	v_pk_fma_f32 v[176:177], v[26:27], v[146:147], v[140:141] op_sel_hi:[1,0,1]
	v_pk_fma_f32 v[178:179], v[28:29], v[146:147], v[142:143] op_sel_hi:[1,0,1]
	v_pk_fma_f32 v[180:181], v[30:31], v[146:147], v[144:145] op_sel_hi:[1,0,1]
	global_load_dwordx4 v[138:141], v0, s[100:101]
	global_load_dwordx2 v[142:143], v0, s[100:101] offset:16
	global_load_dwordx4 v[144:147], v2, s[100:101]
	v_mov_b32_e32 v0, s13
	v_mov_b32_e32 v1, s12
	v_cndmask_b32_e64 v0, v0, v1, s[0:1]
	v_mad_u32_u24 v0, v0, s23, v251
	v_readlane_b32 s12, v108, 45
	v_readlane_b32 s13, v107, 45
	global_load_dwordx2 v[148:149], v2, s[100:101] offset:16
	global_load_dwordx4 v[50:53], v0, s[100:101]
	v_mov_b32_e32 v2, s13
	v_mov_b32_e32 v3, s12
	v_cndmask_b32_e64 v2, v2, v3, s[0:1]
	v_mad_u32_u24 v2, v2, s23, v251
	v_readlane_b32 s12, v108, 46
	v_readlane_b32 s13, v107, 46
	global_load_dwordx2 v[54:55], v0, s[100:101] offset:16
	global_load_dwordx4 v[44:47], v2, s[100:101]
	v_mov_b32_e32 v0, s13
	v_mov_b32_e32 v1, s12
	v_cndmask_b32_e64 v0, v0, v1, s[0:1]
	v_mad_u32_u24 v0, v0, s23, v251
	v_readlane_b32 s12, v108, 47
	v_readlane_b32 s13, v107, 47
	global_load_dwordx2 v[48:49], v2, s[100:101] offset:16
	global_load_dwordx4 v[38:41], v0, s[100:101]
	v_mov_b32_e32 v2, s13
	v_mov_b32_e32 v3, s12
	v_cndmask_b32_e64 v2, v2, v3, s[0:1]
	v_mad_u32_u24 v2, v2, s23, v251
	global_load_dwordx2 v[36:37], v2, s[100:101] offset:16
	global_load_dwordx2 v[42:43], v0, s[100:101] offset:16
	global_load_dwordx4 v[32:35], v2, s[100:101]
	v_readlane_b32 s12, v106, 40
	v_readlane_b32 s13, v109, 40
	s_nop 0
	v_mov_b32_e32 v1, s12
	v_mov_b32_e32 v0, s13
	v_cndmask_b32_e64 v182, v0, v1, s[0:1]
	v_readlane_b32 s12, v106, 41
	v_readlane_b32 s13, v109, 41
	s_waitcnt vmcnt(14)
; DI void phase_peer_out(const Params& p, char* lds) {
;     ...
;     for (int kb = 0; kb < 8; ++kb) {
;       v6u qb[8];
; #pragma unroll
;       for (int k = 0; k < 8; ++k) {
;         const int e0 = __builtin_amdgcn_readlane(el[0], kb * 8 + k), e1 = __builtin_amdgcn_readlane(el[1], kb * 8 + k);
;         qb[k] = load6(V6 + (size_t)(hb ? e1 : e0) * 768);
;       }
; #pragma unroll
;       for (int k = 0; k < 8; ++k) {
;         const float c0 = __uint_as_float(__builtin_amdgcn_readlane(__float_as_uint(coefv[0]), kb * 8 + k)), c1 = __uint_as_float(__builtin_amdgcn_readlane(__float_as_uint(coefv[1]), kb * 8 + k));
;         const float cf = hb ? c1 : c0;
;         const f32x2 c2 = {cf, cf};
;         const v32f f = __builtin_amdgcn_cvt_scalef32_pk32_f32_fp6(qb[k], 1.0f);
; #pragma unroll
;         for (int i = 0; i < 16; ++i) o2[i] = f32x2{f[2 * i], f[2 * i + 1]} * c2 + o2[i];
;       }
;     }
	v_cvt_scalef32_pk32_f32_fp6 v[0:31], v[126:131], 1.0
	v_pk_fma_f32 v[126:127], v[0:1], v[182:183], v[150:151] op_sel_hi:[1,0,1]
	v_mov_b32_e32 v0, s13
	v_mov_b32_e32 v1, s12
	v_pk_fma_f32 v[128:129], v[2:3], v[182:183], v[152:153] op_sel_hi:[1,0,1]
	v_pk_fma_f32 v[130:131], v[4:5], v[182:183], v[154:155] op_sel_hi:[1,0,1]
	v_pk_fma_f32 v[150:151], v[6:7], v[182:183], v[156:157] op_sel_hi:[1,0,1]
	v_pk_fma_f32 v[152:153], v[8:9], v[182:183], v[158:159] op_sel_hi:[1,0,1]
	v_pk_fma_f32 v[154:155], v[10:11], v[182:183], v[160:161] op_sel_hi:[1,0,1]
	v_pk_fma_f32 v[156:157], v[12:13], v[182:183], v[162:163] op_sel_hi:[1,0,1]
	v_pk_fma_f32 v[158:159], v[14:15], v[182:183], v[164:165] op_sel_hi:[1,0,1]
	v_pk_fma_f32 v[160:161], v[16:17], v[182:183], v[166:167] op_sel_hi:[1,0,1]
	v_pk_fma_f32 v[162:163], v[18:19], v[182:183], v[168:169] op_sel_hi:[1,0,1]
	v_pk_fma_f32 v[164:165], v[20:21], v[182:183], v[170:171] op_sel_hi:[1,0,1]
	v_pk_fma_f32 v[166:167], v[22:23], v[182:183], v[172:173] op_sel_hi:[1,0,1]
	v_pk_fma_f32 v[168:169], v[24:25], v[182:183], v[174:175] op_sel_hi:[1,0,1]
	v_pk_fma_f32 v[170:171], v[26:27], v[182:183], v[176:177] op_sel_hi:[1,0,1]
	v_pk_fma_f32 v[172:173], v[28:29], v[182:183], v[178:179] op_sel_hi:[1,0,1]
	v_pk_fma_f32 v[174:175], v[30:31], v[182:183], v[180:181] op_sel_hi:[1,0,1]
	v_cndmask_b32_e64 v176, v0, v1, s[0:1]
	s_waitcnt vmcnt(12)
	v_cvt_scalef32_pk32_f32_fp6 v[0:31], v[132:137], 1.0
	v_readlane_b32 s12, v106, 42
	v_readlane_b32 s13, v109, 42
	v_pk_fma_f32 v[126:127], v[0:1], v[176:177], v[126:127] op_sel_hi:[1,0,1]
	v_mov_b32_e32 v1, s12
	v_mov_b32_e32 v0, s13
	v_pk_fma_f32 v[128:129], v[2:3], v[176:177], v[128:129] op_sel_hi:[1,0,1]
	v_pk_fma_f32 v[130:131], v[4:5], v[176:177], v[130:131] op_sel_hi:[1,0,1]
	v_pk_fma_f32 v[132:133], v[6:7], v[176:177], v[150:151] op_sel_hi:[1,0,1]
	v_pk_fma_f32 v[134:135], v[8:9], v[176:177], v[152:153] op_sel_hi:[1,0,1]
	v_pk_fma_f32 v[136:137], v[10:11], v[176:177], v[154:155] op_sel_hi:[1,0,1]
	v_pk_fma_f32 v[150:151], v[12:13], v[176:177], v[156:157] op_sel_hi:[1,0,1]
	v_pk_fma_f32 v[152:153], v[14:15], v[176:177], v[158:159] op_sel_hi:[1,0,1]
	v_pk_fma_f32 v[154:155], v[16:17], v[176:177], v[160:161] op_sel_hi:[1,0,1]
	v_pk_fma_f32 v[156:157], v[18:19], v[176:177], v[162:163] op_sel_hi:[1,0,1]
	v_pk_fma_f32 v[158:159], v[20:21], v[176:177], v[164:165] op_sel_hi:[1,0,1]
	v_pk_fma_f32 v[160:161], v[22:23], v[176:177], v[166:167] op_sel_hi:[1,0,1]
	v_pk_fma_f32 v[162:163], v[24:25], v[176:177], v[168:169] op_sel_hi:[1,0,1]
	v_pk_fma_f32 v[164:165], v[26:27], v[176:177], v[170:171] op_sel_hi:[1,0,1]
	v_pk_fma_f32 v[166:167], v[28:29], v[176:177], v[172:173] op_sel_hi:[1,0,1]
	v_pk_fma_f32 v[168:169], v[30:31], v[176:177], v[174:175] op_sel_hi:[1,0,1]
	v_cndmask_b32_e64 v170, v0, v1, s[0:1]
	s_waitcnt vmcnt(10)
	v_cvt_scalef32_pk32_f32_fp6 v[0:31], v[138:143], 1.0
	v_readlane_b32 s12, v106, 43
	v_readlane_b32 s13, v109, 43
	v_pk_fma_f32 v[126:127], v[0:1], v[170:171], v[126:127] op_sel_hi:[1,0,1]
	v_mov_b32_e32 v1, s12
	v_mov_b32_e32 v0, s13
	v_pk_fma_f32 v[128:129], v[2:3], v[170:171], v[128:129] op_sel_hi:[1,0,1]
	v_pk_fma_f32 v[130:131], v[4:5], v[170:171], v[130:131] op_sel_hi:[1,0,1]
	v_pk_fma_f32 v[132:133], v[6:7], v[170:171], v[132:133] op_sel_hi:[1,0,1]
	v_pk_fma_f32 v[134:135], v[8:9], v[170:171], v[134:135] op_sel_hi:[1,0,1]
	v_pk_fma_f32 v[136:137], v[10:11], v[170:171], v[136:137] op_sel_hi:[1,0,1]
	v_pk_fma_f32 v[138:139], v[12:13], v[170:171], v[150:151] op_sel_hi:[1,0,1]
	v_pk_fma_f32 v[140:141], v[14:15], v[170:171], v[152:153] op_sel_hi:[1,0,1]
	v_pk_fma_f32 v[142:143], v[16:17], v[170:171], v[154:155] op_sel_hi:[1,0,1]
	v_pk_fma_f32 v[150:151], v[18:19], v[170:171], v[156:157] op_sel_hi:[1,0,1]
	v_pk_fma_f32 v[152:153], v[20:21], v[170:171], v[158:159] op_sel_hi:[1,0,1]
	v_pk_fma_f32 v[154:155], v[22:23], v[170:171], v[160:161] op_sel_hi:[1,0,1]
	v_pk_fma_f32 v[156:157], v[24:25], v[170:171], v[162:163] op_sel_hi:[1,0,1]
	v_pk_fma_f32 v[158:159], v[26:27], v[170:171], v[164:165] op_sel_hi:[1,0,1]
	v_pk_fma_f32 v[160:161], v[28:29], v[170:171], v[166:167] op_sel_hi:[1,0,1]
	v_pk_fma_f32 v[162:163], v[30:31], v[170:171], v[168:169] op_sel_hi:[1,0,1]
	v_cndmask_b32_e64 v164, v0, v1, s[0:1]
	s_waitcnt vmcnt(8)
	v_cvt_scalef32_pk32_f32_fp6 v[0:31], v[144:149], 1.0
	v_readlane_b32 s12, v106, 44
	v_readlane_b32 s13, v109, 44
	v_pk_fma_f32 v[126:127], v[0:1], v[164:165], v[126:127] op_sel_hi:[1,0,1]
	v_mov_b32_e32 v1, s12
	v_mov_b32_e32 v0, s13
	v_pk_fma_f32 v[128:129], v[2:3], v[164:165], v[128:129] op_sel_hi:[1,0,1]
	v_pk_fma_f32 v[130:131], v[4:5], v[164:165], v[130:131] op_sel_hi:[1,0,1]
	v_pk_fma_f32 v[132:133], v[6:7], v[164:165], v[132:133] op_sel_hi:[1,0,1]
	v_pk_fma_f32 v[134:135], v[8:9], v[164:165], v[134:135] op_sel_hi:[1,0,1]
	v_pk_fma_f32 v[136:137], v[10:11], v[164:165], v[136:137] op_sel_hi:[1,0,1]
	v_pk_fma_f32 v[138:139], v[12:13], v[164:165], v[138:139] op_sel_hi:[1,0,1]
	v_pk_fma_f32 v[140:141], v[14:15], v[164:165], v[140:141] op_sel_hi:[1,0,1]
	v_pk_fma_f32 v[142:143], v[16:17], v[164:165], v[142:143] op_sel_hi:[1,0,1]
	v_pk_fma_f32 v[144:145], v[18:19], v[164:165], v[150:151] op_sel_hi:[1,0,1]
	v_pk_fma_f32 v[146:147], v[20:21], v[164:165], v[152:153] op_sel_hi:[1,0,1]
	v_pk_fma_f32 v[148:149], v[22:23], v[164:165], v[154:155] op_sel_hi:[1,0,1]
	v_pk_fma_f32 v[150:151], v[24:25], v[164:165], v[156:157] op_sel_hi:[1,0,1]
	v_pk_fma_f32 v[152:153], v[26:27], v[164:165], v[158:159] op_sel_hi:[1,0,1]
	v_pk_fma_f32 v[154:155], v[28:29], v[164:165], v[160:161] op_sel_hi:[1,0,1]
	v_pk_fma_f32 v[156:157], v[30:31], v[164:165], v[162:163] op_sel_hi:[1,0,1]
	v_cndmask_b32_e64 v158, v0, v1, s[0:1]
	s_waitcnt vmcnt(6)
; DI void phase_peer_out(const Params& p, char* lds) {
;     ...
;     for (int kb = 0; kb < 8; ++kb) {
;       v6u qb[8];
; #pragma unroll
;       for (int k = 0; k < 8; ++k) {
;         const int e0 = __builtin_amdgcn_readlane(el[0], kb * 8 + k), e1 = __builtin_amdgcn_readlane(el[1], kb * 8 + k);
;         qb[k] = load6(V6 + (size_t)(hb ? e1 : e0) * 768);
;       }
; #pragma unroll
;       for (int k = 0; k < 8; ++k) {
;         const float c0 = __uint_as_float(__builtin_amdgcn_readlane(__float_as_uint(coefv[0]), kb * 8 + k)), c1 = __uint_as_float(__builtin_amdgcn_readlane(__float_as_uint(coefv[1]), kb * 8 + k));
;         const float cf = hb ? c1 : c0;
;         const f32x2 c2 = {cf, cf};
;         const v32f f = __builtin_amdgcn_cvt_scalef32_pk32_f32_fp6(qb[k], 1.0f);
; #pragma unroll
;         for (int i = 0; i < 16; ++i) o2[i] = f32x2{f[2 * i], f[2 * i + 1]} * c2 + o2[i];
;       }
;     }
	v_cvt_scalef32_pk32_f32_fp6 v[0:31], v[50:55], 1.0
	v_readlane_b32 s12, v106, 45
	v_readlane_b32 s13, v109, 45
	v_pk_fma_f32 v[50:51], v[0:1], v[158:159], v[126:127] op_sel_hi:[1,0,1]
	v_mov_b32_e32 v1, s12
	v_mov_b32_e32 v0, s13
	v_pk_fma_f32 v[52:53], v[2:3], v[158:159], v[128:129] op_sel_hi:[1,0,1]
	v_pk_fma_f32 v[54:55], v[4:5], v[158:159], v[130:131] op_sel_hi:[1,0,1]
	v_pk_fma_f32 v[126:127], v[6:7], v[158:159], v[132:133] op_sel_hi:[1,0,1]
	v_pk_fma_f32 v[128:129], v[8:9], v[158:159], v[134:135] op_sel_hi:[1,0,1]
	v_pk_fma_f32 v[130:131], v[10:11], v[158:159], v[136:137] op_sel_hi:[1,0,1]
	v_pk_fma_f32 v[132:133], v[12:13], v[158:159], v[138:139] op_sel_hi:[1,0,1]
	v_pk_fma_f32 v[134:135], v[14:15], v[158:159], v[140:141] op_sel_hi:[1,0,1]
	v_pk_fma_f32 v[136:137], v[16:17], v[158:159], v[142:143] op_sel_hi:[1,0,1]
	v_pk_fma_f32 v[138:139], v[18:19], v[158:159], v[144:145] op_sel_hi:[1,0,1]
	v_pk_fma_f32 v[140:141], v[20:21], v[158:159], v[146:147] op_sel_hi:[1,0,1]
	v_pk_fma_f32 v[142:143], v[22:23], v[158:159], v[148:149] op_sel_hi:[1,0,1]
	v_pk_fma_f32 v[144:145], v[24:25], v[158:159], v[150:151] op_sel_hi:[1,0,1]
	v_pk_fma_f32 v[146:147], v[26:27], v[158:159], v[152:153] op_sel_hi:[1,0,1]
	v_pk_fma_f32 v[148:149], v[28:29], v[158:159], v[154:155] op_sel_hi:[1,0,1]
	v_pk_fma_f32 v[150:151], v[30:31], v[158:159], v[156:157] op_sel_hi:[1,0,1]
	v_cndmask_b32_e64 v152, v0, v1, s[0:1]
	s_waitcnt vmcnt(4)
	v_cvt_scalef32_pk32_f32_fp6 v[0:31], v[44:49], 1.0
	v_readlane_b32 s12, v106, 46
	v_readlane_b32 s13, v109, 46
	v_pk_fma_f32 v[44:45], v[0:1], v[152:153], v[50:51] op_sel_hi:[1,0,1]
	v_mov_b32_e32 v1, s12
	v_mov_b32_e32 v0, s13
	v_pk_fma_f32 v[46:47], v[2:3], v[152:153], v[52:53] op_sel_hi:[1,0,1]
	v_pk_fma_f32 v[48:49], v[4:5], v[152:153], v[54:55] op_sel_hi:[1,0,1]
	v_pk_fma_f32 v[50:51], v[6:7], v[152:153], v[126:127] op_sel_hi:[1,0,1]
	v_pk_fma_f32 v[52:53], v[8:9], v[152:153], v[128:129] op_sel_hi:[1,0,1]
	v_pk_fma_f32 v[54:55], v[10:11], v[152:153], v[130:131] op_sel_hi:[1,0,1]
	v_pk_fma_f32 v[126:127], v[12:13], v[152:153], v[132:133] op_sel_hi:[1,0,1]
	v_pk_fma_f32 v[128:129], v[14:15], v[152:153], v[134:135] op_sel_hi:[1,0,1]
	v_pk_fma_f32 v[130:131], v[16:17], v[152:153], v[136:137] op_sel_hi:[1,0,1]
	v_pk_fma_f32 v[132:133], v[18:19], v[152:153], v[138:139] op_sel_hi:[1,0,1]
	v_pk_fma_f32 v[134:135], v[20:21], v[152:153], v[140:141] op_sel_hi:[1,0,1]
	v_pk_fma_f32 v[136:137], v[22:23], v[152:153], v[142:143] op_sel_hi:[1,0,1]
	v_pk_fma_f32 v[138:139], v[24:25], v[152:153], v[144:145] op_sel_hi:[1,0,1]
	v_pk_fma_f32 v[140:141], v[26:27], v[152:153], v[146:147] op_sel_hi:[1,0,1]
	v_pk_fma_f32 v[142:143], v[28:29], v[152:153], v[148:149] op_sel_hi:[1,0,1]
	v_pk_fma_f32 v[144:145], v[30:31], v[152:153], v[150:151] op_sel_hi:[1,0,1]
	v_cndmask_b32_e64 v146, v0, v1, s[0:1]
	s_waitcnt vmcnt(1)
	v_cvt_scalef32_pk32_f32_fp6 v[0:31], v[38:43], 1.0
	v_readlane_b32 s12, v106, 47
	v_readlane_b32 s13, v109, 47
	v_pk_fma_f32 v[38:39], v[0:1], v[146:147], v[44:45] op_sel_hi:[1,0,1]
	v_mov_b32_e32 v1, s12
	v_mov_b32_e32 v0, s13
	v_readlane_b32 s12, v108, 48
	v_readlane_b32 s13, v107, 48
	v_pk_fma_f32 v[40:41], v[2:3], v[146:147], v[46:47] op_sel_hi:[1,0,1]
	v_pk_fma_f32 v[42:43], v[4:5], v[146:147], v[48:49] op_sel_hi:[1,0,1]
	v_pk_fma_f32 v[44:45], v[6:7], v[146:147], v[50:51] op_sel_hi:[1,0,1]
	v_pk_fma_f32 v[46:47], v[8:9], v[146:147], v[52:53] op_sel_hi:[1,0,1]
	v_pk_fma_f32 v[48:49], v[10:11], v[146:147], v[54:55] op_sel_hi:[1,0,1]
	v_pk_fma_f32 v[50:51], v[12:13], v[146:147], v[126:127] op_sel_hi:[1,0,1]
	v_pk_fma_f32 v[52:53], v[14:15], v[146:147], v[128:129] op_sel_hi:[1,0,1]
	v_pk_fma_f32 v[54:55], v[16:17], v[146:147], v[130:131] op_sel_hi:[1,0,1]
	v_pk_fma_f32 v[132:133], v[18:19], v[146:147], v[132:133] op_sel_hi:[1,0,1]
	v_pk_fma_f32 v[134:135], v[20:21], v[146:147], v[134:135] op_sel_hi:[1,0,1]
	v_pk_fma_f32 v[136:137], v[22:23], v[146:147], v[136:137] op_sel_hi:[1,0,1]
	v_pk_fma_f32 v[138:139], v[24:25], v[146:147], v[138:139] op_sel_hi:[1,0,1]
	v_pk_fma_f32 v[140:141], v[26:27], v[146:147], v[140:141] op_sel_hi:[1,0,1]
	v_pk_fma_f32 v[142:143], v[28:29], v[146:147], v[142:143] op_sel_hi:[1,0,1]
	v_pk_fma_f32 v[144:145], v[30:31], v[146:147], v[144:145] op_sel_hi:[1,0,1]
	v_cndmask_b32_e64 v146, v0, v1, s[0:1]
	v_mov_b32_e32 v0, s13
	v_mov_b32_e32 v1, s12
	v_cndmask_b32_e64 v0, v0, v1, s[0:1]
	v_mad_u32_u24 v130, v0, s23, v251
	s_waitcnt vmcnt(0)
; DI void phase_peer_out(const Params& p, char* lds) {
;     ...
;     for (int kb = 0; kb < 8; ++kb) {
;       v6u qb[8];
; #pragma unroll
;       for (int k = 0; k < 8; ++k) {
;         const int e0 = __builtin_amdgcn_readlane(el[0], kb * 8 + k), e1 = __builtin_amdgcn_readlane(el[1], kb * 8 + k);
;         qb[k] = load6(V6 + (size_t)(hb ? e1 : e0) * 768);
;       }
; #pragma unroll
;       for (int k = 0; k < 8; ++k) {
;         const float c0 = __uint_as_float(__builtin_amdgcn_readlane(__float_as_uint(coefv[0]), kb * 8 + k)), c1 = __uint_as_float(__builtin_amdgcn_readlane(__float_as_uint(coefv[1]), kb * 8 + k));
;         const float cf = hb ? c1 : c0;
;         const f32x2 c2 = {cf, cf};
;         const v32f f = __builtin_amdgcn_cvt_scalef32_pk32_f32_fp6(qb[k], 1.0f);
; #pragma unroll
;         for (int i = 0; i < 16; ++i) o2[i] = f32x2{f[2 * i], f[2 * i + 1]} * c2 + o2[i];
;       }
;     }
	v_cvt_scalef32_pk32_f32_fp6 v[0:31], v[32:37], 1.0
	v_readlane_b32 s12, v108, 49
	v_readlane_b32 s13, v107, 49
	v_pk_fma_f32 v[150:151], v[0:1], v[146:147], v[38:39] op_sel_hi:[1,0,1]
	v_mov_b32_e32 v1, s12
	v_mov_b32_e32 v0, s13
	v_cndmask_b32_e64 v0, v0, v1, s[0:1]
	v_mad_u32_u24 v0, v0, s23, v251
	v_readlane_b32 s12, v108, 50
	v_readlane_b32 s13, v107, 50
	global_load_dwordx4 v[126:129], v130, s[100:101]
	v_pk_fma_f32 v[168:169], v[18:19], v[146:147], v[132:133] op_sel_hi:[1,0,1]
	global_load_dwordx2 v[130:131], v130, s[100:101] offset:16
	v_pk_fma_f32 v[170:171], v[20:21], v[146:147], v[134:135] op_sel_hi:[1,0,1]
	v_pk_fma_f32 v[172:173], v[22:23], v[146:147], v[136:137] op_sel_hi:[1,0,1]
	global_load_dwordx2 v[136:137], v0, s[100:101] offset:16
	global_load_dwordx4 v[132:135], v0, s[100:101]
	v_mov_b32_e32 v0, s13
	v_mov_b32_e32 v1, s12
	v_cndmask_b32_e64 v0, v0, v1, s[0:1]
	v_mad_u32_u24 v0, v0, s23, v251
	v_readlane_b32 s12, v108, 51
	v_readlane_b32 s13, v107, 51
	v_pk_fma_f32 v[152:153], v[2:3], v[146:147], v[40:41] op_sel_hi:[1,0,1]
	v_mov_b32_e32 v3, s12
	v_mov_b32_e32 v2, s13
	v_cndmask_b32_e64 v2, v2, v3, s[0:1]
	v_mad_u32_u24 v2, v2, s23, v251
	v_readlane_b32 s12, v108, 52
	v_readlane_b32 s13, v107, 52
	v_pk_fma_f32 v[154:155], v[4:5], v[146:147], v[42:43] op_sel_hi:[1,0,1]
	v_pk_fma_f32 v[156:157], v[6:7], v[146:147], v[44:45] op_sel_hi:[1,0,1]
	v_pk_fma_f32 v[158:159], v[8:9], v[146:147], v[46:47] op_sel_hi:[1,0,1]
	v_pk_fma_f32 v[160:161], v[10:11], v[146:147], v[48:49] op_sel_hi:[1,0,1]
	v_pk_fma_f32 v[162:163], v[12:13], v[146:147], v[50:51] op_sel_hi:[1,0,1]
	v_pk_fma_f32 v[164:165], v[14:15], v[146:147], v[52:53] op_sel_hi:[1,0,1]
	v_pk_fma_f32 v[166:167], v[16:17], v[146:147], v[54:55] op_sel_hi:[1,0,1]
	v_pk_fma_f32 v[174:175], v[24:25], v[146:147], v[138:139] op_sel_hi:[1,0,1]
	v_pk_fma_f32 v[176:177], v[26:27], v[146:147], v[140:141] op_sel_hi:[1,0,1]
	v_pk_fma_f32 v[178:179], v[28:29], v[146:147], v[142:143] op_sel_hi:[1,0,1]
	v_pk_fma_f32 v[180:181], v[30:31], v[146:147], v[144:145] op_sel_hi:[1,0,1]
	global_load_dwordx4 v[138:141], v0, s[100:101]
	global_load_dwordx2 v[142:143], v0, s[100:101] offset:16
	global_load_dwordx4 v[144:147], v2, s[100:101]
	v_mov_b32_e32 v0, s13
	v_mov_b32_e32 v1, s12
	v_cndmask_b32_e64 v0, v0, v1, s[0:1]
	v_mad_u32_u24 v0, v0, s23, v251
	v_readlane_b32 s12, v108, 53
	v_readlane_b32 s13, v107, 53
	global_load_dwordx2 v[148:149], v2, s[100:101] offset:16
	global_load_dwordx4 v[50:53], v0, s[100:101]
	v_mov_b32_e32 v2, s13
	v_mov_b32_e32 v3, s12
	v_cndmask_b32_e64 v2, v2, v3, s[0:1]
	v_mad_u32_u24 v2, v2, s23, v251
	v_readlane_b32 s12, v108, 54
	v_readlane_b32 s13, v107, 54
	global_load_dwordx2 v[54:55], v0, s[100:101] offset:16
	global_load_dwordx4 v[44:47], v2, s[100:101]
	v_mov_b32_e32 v0, s13
	v_mov_b32_e32 v1, s12
	v_cndmask_b32_e64 v0, v0, v1, s[0:1]
	v_mad_u32_u24 v0, v0, s23, v251
	v_readlane_b32 s12, v108, 55
	v_readlane_b32 s13, v107, 55
	global_load_dwordx2 v[48:49], v2, s[100:101] offset:16
	global_load_dwordx4 v[38:41], v0, s[100:101]
	v_mov_b32_e32 v2, s13
	v_mov_b32_e32 v3, s12
	v_cndmask_b32_e64 v2, v2, v3, s[0:1]
	v_mad_u32_u24 v2, v2, s23, v251
	global_load_dwordx2 v[36:37], v2, s[100:101] offset:16
	global_load_dwordx2 v[42:43], v0, s[100:101] offset:16
	global_load_dwordx4 v[32:35], v2, s[100:101]
	v_readlane_b32 s12, v106, 48
	v_readlane_b32 s13, v109, 48
	s_nop 0
	v_mov_b32_e32 v1, s12
	v_mov_b32_e32 v0, s13
	v_cndmask_b32_e64 v182, v0, v1, s[0:1]
	v_readlane_b32 s12, v106, 49
	v_readlane_b32 s13, v109, 49
	s_waitcnt vmcnt(14)
	v_cvt_scalef32_pk32_f32_fp6 v[0:31], v[126:131], 1.0
	v_pk_fma_f32 v[126:127], v[0:1], v[182:183], v[150:151] op_sel_hi:[1,0,1]
	v_mov_b32_e32 v0, s13
	v_mov_b32_e32 v1, s12
	v_pk_fma_f32 v[128:129], v[2:3], v[182:183], v[152:153] op_sel_hi:[1,0,1]
	v_pk_fma_f32 v[130:131], v[4:5], v[182:183], v[154:155] op_sel_hi:[1,0,1]
	v_pk_fma_f32 v[150:151], v[6:7], v[182:183], v[156:157] op_sel_hi:[1,0,1]
	v_pk_fma_f32 v[152:153], v[8:9], v[182:183], v[158:159] op_sel_hi:[1,0,1]
	v_pk_fma_f32 v[154:155], v[10:11], v[182:183], v[160:161] op_sel_hi:[1,0,1]
	v_pk_fma_f32 v[156:157], v[12:13], v[182:183], v[162:163] op_sel_hi:[1,0,1]
	v_pk_fma_f32 v[158:159], v[14:15], v[182:183], v[164:165] op_sel_hi:[1,0,1]
	v_pk_fma_f32 v[160:161], v[16:17], v[182:183], v[166:167] op_sel_hi:[1,0,1]
	v_pk_fma_f32 v[162:163], v[18:19], v[182:183], v[168:169] op_sel_hi:[1,0,1]
	v_pk_fma_f32 v[164:165], v[20:21], v[182:183], v[170:171] op_sel_hi:[1,0,1]
	v_pk_fma_f32 v[166:167], v[22:23], v[182:183], v[172:173] op_sel_hi:[1,0,1]
	v_pk_fma_f32 v[168:169], v[24:25], v[182:183], v[174:175] op_sel_hi:[1,0,1]
	v_pk_fma_f32 v[170:171], v[26:27], v[182:183], v[176:177] op_sel_hi:[1,0,1]
	v_pk_fma_f32 v[172:173], v[28:29], v[182:183], v[178:179] op_sel_hi:[1,0,1]
	v_pk_fma_f32 v[174:175], v[30:31], v[182:183], v[180:181] op_sel_hi:[1,0,1]
	v_cndmask_b32_e64 v176, v0, v1, s[0:1]
	s_waitcnt vmcnt(12)
; DI void phase_peer_out(const Params& p, char* lds) {
;     ...
;     for (int kb = 0; kb < 8; ++kb) {
;       v6u qb[8];
; #pragma unroll
;       for (int k = 0; k < 8; ++k) {
;         const int e0 = __builtin_amdgcn_readlane(el[0], kb * 8 + k), e1 = __builtin_amdgcn_readlane(el[1], kb * 8 + k);
;         qb[k] = load6(V6 + (size_t)(hb ? e1 : e0) * 768);
;       }
; #pragma unroll
;       for (int k = 0; k < 8; ++k) {
;         const float c0 = __uint_as_float(__builtin_amdgcn_readlane(__float_as_uint(coefv[0]), kb * 8 + k)), c1 = __uint_as_float(__builtin_amdgcn_readlane(__float_as_uint(coefv[1]), kb * 8 + k));
;         const float cf = hb ? c1 : c0;
;         const f32x2 c2 = {cf, cf};
;         const v32f f = __builtin_amdgcn_cvt_scalef32_pk32_f32_fp6(qb[k], 1.0f);
; #pragma unroll
;         for (int i = 0; i < 16; ++i) o2[i] = f32x2{f[2 * i], f[2 * i + 1]} * c2 + o2[i];
;       }
;     }
	v_cvt_scalef32_pk32_f32_fp6 v[0:31], v[132:137], 1.0
	v_readlane_b32 s12, v106, 50
	v_readlane_b32 s13, v109, 50
	v_pk_fma_f32 v[126:127], v[0:1], v[176:177], v[126:127] op_sel_hi:[1,0,1]
	v_mov_b32_e32 v1, s12
	v_mov_b32_e32 v0, s13
	v_pk_fma_f32 v[128:129], v[2:3], v[176:177], v[128:129] op_sel_hi:[1,0,1]
	v_pk_fma_f32 v[130:131], v[4:5], v[176:177], v[130:131] op_sel_hi:[1,0,1]
	v_pk_fma_f32 v[132:133], v[6:7], v[176:177], v[150:151] op_sel_hi:[1,0,1]
	v_pk_fma_f32 v[134:135], v[8:9], v[176:177], v[152:153] op_sel_hi:[1,0,1]
	v_pk_fma_f32 v[136:137], v[10:11], v[176:177], v[154:155] op_sel_hi:[1,0,1]
	v_pk_fma_f32 v[150:151], v[12:13], v[176:177], v[156:157] op_sel_hi:[1,0,1]
	v_pk_fma_f32 v[152:153], v[14:15], v[176:177], v[158:159] op_sel_hi:[1,0,1]
	v_pk_fma_f32 v[154:155], v[16:17], v[176:177], v[160:161] op_sel_hi:[1,0,1]
	v_pk_fma_f32 v[156:157], v[18:19], v[176:177], v[162:163] op_sel_hi:[1,0,1]
	v_pk_fma_f32 v[158:159], v[20:21], v[176:177], v[164:165] op_sel_hi:[1,0,1]
	v_pk_fma_f32 v[160:161], v[22:23], v[176:177], v[166:167] op_sel_hi:[1,0,1]
	v_pk_fma_f32 v[162:163], v[24:25], v[176:177], v[168:169] op_sel_hi:[1,0,1]
	v_pk_fma_f32 v[164:165], v[26:27], v[176:177], v[170:171] op_sel_hi:[1,0,1]
	v_pk_fma_f32 v[166:167], v[28:29], v[176:177], v[172:173] op_sel_hi:[1,0,1]
	v_pk_fma_f32 v[168:169], v[30:31], v[176:177], v[174:175] op_sel_hi:[1,0,1]
	v_cndmask_b32_e64 v170, v0, v1, s[0:1]
	s_waitcnt vmcnt(10)
	v_cvt_scalef32_pk32_f32_fp6 v[0:31], v[138:143], 1.0
	v_readlane_b32 s12, v106, 51
	v_readlane_b32 s13, v109, 51
	v_pk_fma_f32 v[126:127], v[0:1], v[170:171], v[126:127] op_sel_hi:[1,0,1]
	v_mov_b32_e32 v1, s12
	v_mov_b32_e32 v0, s13
	v_pk_fma_f32 v[128:129], v[2:3], v[170:171], v[128:129] op_sel_hi:[1,0,1]
	v_pk_fma_f32 v[130:131], v[4:5], v[170:171], v[130:131] op_sel_hi:[1,0,1]
	v_pk_fma_f32 v[132:133], v[6:7], v[170:171], v[132:133] op_sel_hi:[1,0,1]
	v_pk_fma_f32 v[134:135], v[8:9], v[170:171], v[134:135] op_sel_hi:[1,0,1]
	v_pk_fma_f32 v[136:137], v[10:11], v[170:171], v[136:137] op_sel_hi:[1,0,1]
	v_pk_fma_f32 v[138:139], v[12:13], v[170:171], v[150:151] op_sel_hi:[1,0,1]
	v_pk_fma_f32 v[140:141], v[14:15], v[170:171], v[152:153] op_sel_hi:[1,0,1]
	v_pk_fma_f32 v[142:143], v[16:17], v[170:171], v[154:155] op_sel_hi:[1,0,1]
	v_pk_fma_f32 v[150:151], v[18:19], v[170:171], v[156:157] op_sel_hi:[1,0,1]
	v_pk_fma_f32 v[152:153], v[20:21], v[170:171], v[158:159] op_sel_hi:[1,0,1]
	v_pk_fma_f32 v[154:155], v[22:23], v[170:171], v[160:161] op_sel_hi:[1,0,1]
	v_pk_fma_f32 v[156:157], v[24:25], v[170:171], v[162:163] op_sel_hi:[1,0,1]
	v_pk_fma_f32 v[158:159], v[26:27], v[170:171], v[164:165] op_sel_hi:[1,0,1]
	v_pk_fma_f32 v[160:161], v[28:29], v[170:171], v[166:167] op_sel_hi:[1,0,1]
	v_pk_fma_f32 v[162:163], v[30:31], v[170:171], v[168:169] op_sel_hi:[1,0,1]
	v_cndmask_b32_e64 v164, v0, v1, s[0:1]
	s_waitcnt vmcnt(8)
	v_cvt_scalef32_pk32_f32_fp6 v[0:31], v[144:149], 1.0
	v_readlane_b32 s12, v106, 52
	v_readlane_b32 s13, v109, 52
	v_pk_fma_f32 v[126:127], v[0:1], v[164:165], v[126:127] op_sel_hi:[1,0,1]
	v_mov_b32_e32 v1, s12
	v_mov_b32_e32 v0, s13
	v_pk_fma_f32 v[128:129], v[2:3], v[164:165], v[128:129] op_sel_hi:[1,0,1]
	v_pk_fma_f32 v[130:131], v[4:5], v[164:165], v[130:131] op_sel_hi:[1,0,1]
	v_pk_fma_f32 v[132:133], v[6:7], v[164:165], v[132:133] op_sel_hi:[1,0,1]
	v_pk_fma_f32 v[134:135], v[8:9], v[164:165], v[134:135] op_sel_hi:[1,0,1]
	v_pk_fma_f32 v[136:137], v[10:11], v[164:165], v[136:137] op_sel_hi:[1,0,1]
	v_pk_fma_f32 v[138:139], v[12:13], v[164:165], v[138:139] op_sel_hi:[1,0,1]
	v_pk_fma_f32 v[140:141], v[14:15], v[164:165], v[140:141] op_sel_hi:[1,0,1]
	v_pk_fma_f32 v[142:143], v[16:17], v[164:165], v[142:143] op_sel_hi:[1,0,1]
	v_pk_fma_f32 v[144:145], v[18:19], v[164:165], v[150:151] op_sel_hi:[1,0,1]
	v_pk_fma_f32 v[146:147], v[20:21], v[164:165], v[152:153] op_sel_hi:[1,0,1]
	v_pk_fma_f32 v[148:149], v[22:23], v[164:165], v[154:155] op_sel_hi:[1,0,1]
	v_pk_fma_f32 v[150:151], v[24:25], v[164:165], v[156:157] op_sel_hi:[1,0,1]
	v_pk_fma_f32 v[152:153], v[26:27], v[164:165], v[158:159] op_sel_hi:[1,0,1]
	v_pk_fma_f32 v[154:155], v[28:29], v[164:165], v[160:161] op_sel_hi:[1,0,1]
	v_pk_fma_f32 v[156:157], v[30:31], v[164:165], v[162:163] op_sel_hi:[1,0,1]
	v_cndmask_b32_e64 v158, v0, v1, s[0:1]
	s_waitcnt vmcnt(6)
	v_cvt_scalef32_pk32_f32_fp6 v[0:31], v[50:55], 1.0
	v_readlane_b32 s12, v106, 53
	v_readlane_b32 s13, v109, 53
	v_pk_fma_f32 v[50:51], v[0:1], v[158:159], v[126:127] op_sel_hi:[1,0,1]
	v_mov_b32_e32 v1, s12
	v_mov_b32_e32 v0, s13
	v_pk_fma_f32 v[52:53], v[2:3], v[158:159], v[128:129] op_sel_hi:[1,0,1]
	v_pk_fma_f32 v[54:55], v[4:5], v[158:159], v[130:131] op_sel_hi:[1,0,1]
	v_pk_fma_f32 v[126:127], v[6:7], v[158:159], v[132:133] op_sel_hi:[1,0,1]
	v_pk_fma_f32 v[128:129], v[8:9], v[158:159], v[134:135] op_sel_hi:[1,0,1]
	v_pk_fma_f32 v[130:131], v[10:11], v[158:159], v[136:137] op_sel_hi:[1,0,1]
	v_pk_fma_f32 v[132:133], v[12:13], v[158:159], v[138:139] op_sel_hi:[1,0,1]
	v_pk_fma_f32 v[134:135], v[14:15], v[158:159], v[140:141] op_sel_hi:[1,0,1]
	v_pk_fma_f32 v[136:137], v[16:17], v[158:159], v[142:143] op_sel_hi:[1,0,1]
	v_pk_fma_f32 v[138:139], v[18:19], v[158:159], v[144:145] op_sel_hi:[1,0,1]
	v_pk_fma_f32 v[140:141], v[20:21], v[158:159], v[146:147] op_sel_hi:[1,0,1]
	v_pk_fma_f32 v[142:143], v[22:23], v[158:159], v[148:149] op_sel_hi:[1,0,1]
	v_pk_fma_f32 v[144:145], v[24:25], v[158:159], v[150:151] op_sel_hi:[1,0,1]
	v_pk_fma_f32 v[146:147], v[26:27], v[158:159], v[152:153] op_sel_hi:[1,0,1]
	v_pk_fma_f32 v[148:149], v[28:29], v[158:159], v[154:155] op_sel_hi:[1,0,1]
	v_pk_fma_f32 v[150:151], v[30:31], v[158:159], v[156:157] op_sel_hi:[1,0,1]
	v_cndmask_b32_e64 v152, v0, v1, s[0:1]
	s_waitcnt vmcnt(4)
; DI void phase_peer_out(const Params& p, char* lds) {
;     ...
;     for (int kb = 0; kb < 8; ++kb) {
;       v6u qb[8];
; #pragma unroll
;       for (int k = 0; k < 8; ++k) {
;         const int e0 = __builtin_amdgcn_readlane(el[0], kb * 8 + k), e1 = __builtin_amdgcn_readlane(el[1], kb * 8 + k);
;         qb[k] = load6(V6 + (size_t)(hb ? e1 : e0) * 768);
;       }
; #pragma unroll
;       for (int k = 0; k < 8; ++k) {
;         const float c0 = __uint_as_float(__builtin_amdgcn_readlane(__float_as_uint(coefv[0]), kb * 8 + k)), c1 = __uint_as_float(__builtin_amdgcn_readlane(__float_as_uint(coefv[1]), kb * 8 + k));
;         const float cf = hb ? c1 : c0;
;         const f32x2 c2 = {cf, cf};
;         const v32f f = __builtin_amdgcn_cvt_scalef32_pk32_f32_fp6(qb[k], 1.0f);
; #pragma unroll
;         for (int i = 0; i < 16; ++i) o2[i] = f32x2{f[2 * i], f[2 * i + 1]} * c2 + o2[i];
;       }
;     }
	v_cvt_scalef32_pk32_f32_fp6 v[0:31], v[44:49], 1.0
	v_readlane_b32 s12, v106, 54
	v_readlane_b32 s13, v109, 54
	v_pk_fma_f32 v[44:45], v[0:1], v[152:153], v[50:51] op_sel_hi:[1,0,1]
	v_mov_b32_e32 v1, s12
	v_mov_b32_e32 v0, s13
	v_pk_fma_f32 v[46:47], v[2:3], v[152:153], v[52:53] op_sel_hi:[1,0,1]
	v_pk_fma_f32 v[48:49], v[4:5], v[152:153], v[54:55] op_sel_hi:[1,0,1]
	v_pk_fma_f32 v[50:51], v[6:7], v[152:153], v[126:127] op_sel_hi:[1,0,1]
	v_pk_fma_f32 v[52:53], v[8:9], v[152:153], v[128:129] op_sel_hi:[1,0,1]
	v_pk_fma_f32 v[54:55], v[10:11], v[152:153], v[130:131] op_sel_hi:[1,0,1]
	v_pk_fma_f32 v[126:127], v[12:13], v[152:153], v[132:133] op_sel_hi:[1,0,1]
	v_pk_fma_f32 v[128:129], v[14:15], v[152:153], v[134:135] op_sel_hi:[1,0,1]
	v_pk_fma_f32 v[130:131], v[16:17], v[152:153], v[136:137] op_sel_hi:[1,0,1]
	v_pk_fma_f32 v[132:133], v[18:19], v[152:153], v[138:139] op_sel_hi:[1,0,1]
	v_pk_fma_f32 v[134:135], v[20:21], v[152:153], v[140:141] op_sel_hi:[1,0,1]
	v_pk_fma_f32 v[136:137], v[22:23], v[152:153], v[142:143] op_sel_hi:[1,0,1]
	v_pk_fma_f32 v[138:139], v[24:25], v[152:153], v[144:145] op_sel_hi:[1,0,1]
	v_pk_fma_f32 v[140:141], v[26:27], v[152:153], v[146:147] op_sel_hi:[1,0,1]
	v_pk_fma_f32 v[142:143], v[28:29], v[152:153], v[148:149] op_sel_hi:[1,0,1]
	v_pk_fma_f32 v[144:145], v[30:31], v[152:153], v[150:151] op_sel_hi:[1,0,1]
	v_cndmask_b32_e64 v146, v0, v1, s[0:1]
	s_waitcnt vmcnt(1)
	v_cvt_scalef32_pk32_f32_fp6 v[0:31], v[38:43], 1.0
	v_readlane_b32 s12, v106, 55
	v_readlane_b32 s13, v109, 55
	v_pk_fma_f32 v[38:39], v[0:1], v[146:147], v[44:45] op_sel_hi:[1,0,1]
	v_mov_b32_e32 v1, s12
	v_mov_b32_e32 v0, s13
	v_readlane_b32 s12, v108, 56
	v_readlane_b32 s13, v107, 56
	v_pk_fma_f32 v[40:41], v[2:3], v[146:147], v[46:47] op_sel_hi:[1,0,1]
	v_pk_fma_f32 v[42:43], v[4:5], v[146:147], v[48:49] op_sel_hi:[1,0,1]
	v_pk_fma_f32 v[44:45], v[6:7], v[146:147], v[50:51] op_sel_hi:[1,0,1]
	v_pk_fma_f32 v[46:47], v[8:9], v[146:147], v[52:53] op_sel_hi:[1,0,1]
	v_pk_fma_f32 v[48:49], v[10:11], v[146:147], v[54:55] op_sel_hi:[1,0,1]
	v_pk_fma_f32 v[50:51], v[12:13], v[146:147], v[126:127] op_sel_hi:[1,0,1]
	v_pk_fma_f32 v[52:53], v[14:15], v[146:147], v[128:129] op_sel_hi:[1,0,1]
	v_pk_fma_f32 v[54:55], v[16:17], v[146:147], v[130:131] op_sel_hi:[1,0,1]
	v_pk_fma_f32 v[132:133], v[18:19], v[146:147], v[132:133] op_sel_hi:[1,0,1]
	v_pk_fma_f32 v[134:135], v[20:21], v[146:147], v[134:135] op_sel_hi:[1,0,1]
	v_pk_fma_f32 v[136:137], v[22:23], v[146:147], v[136:137] op_sel_hi:[1,0,1]
	v_pk_fma_f32 v[138:139], v[24:25], v[146:147], v[138:139] op_sel_hi:[1,0,1]
	v_pk_fma_f32 v[140:141], v[26:27], v[146:147], v[140:141] op_sel_hi:[1,0,1]
	v_pk_fma_f32 v[142:143], v[28:29], v[146:147], v[142:143] op_sel_hi:[1,0,1]
	v_pk_fma_f32 v[144:145], v[30:31], v[146:147], v[144:145] op_sel_hi:[1,0,1]
	v_cndmask_b32_e64 v146, v0, v1, s[0:1]
	v_mov_b32_e32 v0, s13
	v_mov_b32_e32 v1, s12
	v_cndmask_b32_e64 v0, v0, v1, s[0:1]
	v_mad_u32_u24 v130, v0, s23, v251
	s_waitcnt vmcnt(0)
	v_cvt_scalef32_pk32_f32_fp6 v[0:31], v[32:37], 1.0
	v_readlane_b32 s12, v108, 57
	v_readlane_b32 s13, v107, 57
	v_pk_fma_f32 v[150:151], v[0:1], v[146:147], v[38:39] op_sel_hi:[1,0,1]
	v_mov_b32_e32 v1, s12
	v_mov_b32_e32 v0, s13
	v_cndmask_b32_e64 v0, v0, v1, s[0:1]
	v_mad_u32_u24 v0, v0, s23, v251
	v_readlane_b32 s12, v108, 58
	v_readlane_b32 s13, v107, 58
	global_load_dwordx4 v[126:129], v130, s[100:101]
	v_pk_fma_f32 v[168:169], v[18:19], v[146:147], v[132:133] op_sel_hi:[1,0,1]
	global_load_dwordx2 v[130:131], v130, s[100:101] offset:16
	v_pk_fma_f32 v[170:171], v[20:21], v[146:147], v[134:135] op_sel_hi:[1,0,1]
	v_pk_fma_f32 v[172:173], v[22:23], v[146:147], v[136:137] op_sel_hi:[1,0,1]
	global_load_dwordx2 v[136:137], v0, s[100:101] offset:16
	global_load_dwordx4 v[132:135], v0, s[100:101]
	v_mov_b32_e32 v0, s13
	v_mov_b32_e32 v1, s12
	v_cndmask_b32_e64 v0, v0, v1, s[0:1]
	v_mad_u32_u24 v0, v0, s23, v251
	v_readlane_b32 s12, v108, 59
	v_readlane_b32 s13, v107, 59
	v_pk_fma_f32 v[152:153], v[2:3], v[146:147], v[40:41] op_sel_hi:[1,0,1]
	v_mov_b32_e32 v3, s12
	v_mov_b32_e32 v2, s13
	v_cndmask_b32_e64 v2, v2, v3, s[0:1]
	v_mad_u32_u24 v2, v2, s23, v251
	v_readlane_b32 s12, v108, 60
	v_readlane_b32 s13, v107, 60
	v_pk_fma_f32 v[154:155], v[4:5], v[146:147], v[42:43] op_sel_hi:[1,0,1]
	v_pk_fma_f32 v[156:157], v[6:7], v[146:147], v[44:45] op_sel_hi:[1,0,1]
	v_pk_fma_f32 v[158:159], v[8:9], v[146:147], v[46:47] op_sel_hi:[1,0,1]
	v_pk_fma_f32 v[160:161], v[10:11], v[146:147], v[48:49] op_sel_hi:[1,0,1]
	v_pk_fma_f32 v[162:163], v[12:13], v[146:147], v[50:51] op_sel_hi:[1,0,1]
	v_pk_fma_f32 v[164:165], v[14:15], v[146:147], v[52:53] op_sel_hi:[1,0,1]
	v_pk_fma_f32 v[166:167], v[16:17], v[146:147], v[54:55] op_sel_hi:[1,0,1]
	v_pk_fma_f32 v[174:175], v[24:25], v[146:147], v[138:139] op_sel_hi:[1,0,1]
	v_pk_fma_f32 v[176:177], v[26:27], v[146:147], v[140:141] op_sel_hi:[1,0,1]
	v_pk_fma_f32 v[178:179], v[28:29], v[146:147], v[142:143] op_sel_hi:[1,0,1]
	v_pk_fma_f32 v[180:181], v[30:31], v[146:147], v[144:145] op_sel_hi:[1,0,1]
	global_load_dwordx4 v[138:141], v0, s[100:101]
	global_load_dwordx2 v[142:143], v0, s[100:101] offset:16
	global_load_dwordx4 v[144:147], v2, s[100:101]
	v_mov_b32_e32 v0, s13
	v_mov_b32_e32 v1, s12
	v_cndmask_b32_e64 v0, v0, v1, s[0:1]
	v_mad_u32_u24 v0, v0, s23, v251
	v_readlane_b32 s12, v108, 61
	v_readlane_b32 s13, v107, 61
	global_load_dwordx2 v[148:149], v2, s[100:101] offset:16
	global_load_dwordx4 v[50:53], v0, s[100:101]
	v_mov_b32_e32 v2, s13
	v_mov_b32_e32 v3, s12
	v_cndmask_b32_e64 v2, v2, v3, s[0:1]
	v_mad_u32_u24 v2, v2, s23, v251
	v_readlane_b32 s12, v108, 62
	v_readlane_b32 s13, v107, 62
	global_load_dwordx2 v[54:55], v0, s[100:101] offset:16
	global_load_dwordx4 v[44:47], v2, s[100:101]
	v_mov_b32_e32 v0, s13
	v_mov_b32_e32 v1, s12
	v_cndmask_b32_e64 v0, v0, v1, s[0:1]
	v_mad_u32_u24 v0, v0, s23, v251
	v_readlane_b32 s12, v108, 63
	v_readlane_b32 s13, v107, 63
	global_load_dwordx2 v[48:49], v2, s[100:101] offset:16
	global_load_dwordx4 v[38:41], v0, s[100:101]
	v_mov_b32_e32 v2, s13
	v_mov_b32_e32 v3, s12
	v_cndmask_b32_e64 v2, v2, v3, s[0:1]
	v_mad_u32_u24 v2, v2, s23, v251
	global_load_dwordx2 v[36:37], v2, s[100:101] offset:16
	global_load_dwordx2 v[42:43], v0, s[100:101] offset:16
	global_load_dwordx4 v[32:35], v2, s[100:101]
	v_readlane_b32 s12, v106, 56
	v_readlane_b32 s13, v109, 56
	s_nop 0
	v_mov_b32_e32 v1, s12
	v_mov_b32_e32 v0, s13
	v_cndmask_b32_e64 v108, v0, v1, s[0:1]
	v_readlane_b32 s12, v106, 57
	v_readlane_b32 s13, v109, 57
	s_waitcnt vmcnt(14)
; DI void phase_peer_out(const Params& p, char* lds) {
;     ...
;     for (int kb = 0; kb < 8; ++kb) {
;       v6u qb[8];
; #pragma unroll
;       for (int k = 0; k < 8; ++k) {
;         const int e0 = __builtin_amdgcn_readlane(el[0], kb * 8 + k), e1 = __builtin_amdgcn_readlane(el[1], kb * 8 + k);
;         qb[k] = load6(V6 + (size_t)(hb ? e1 : e0) * 768);
;       }
; #pragma unroll
;       for (int k = 0; k < 8; ++k) {
;         const float c0 = __uint_as_float(__builtin_amdgcn_readlane(__float_as_uint(coefv[0]), kb * 8 + k)), c1 = __uint_as_float(__builtin_amdgcn_readlane(__float_as_uint(coefv[1]), kb * 8 + k));
;         const float cf = hb ? c1 : c0;
;         const f32x2 c2 = {cf, cf};
;         const v32f f = __builtin_amdgcn_cvt_scalef32_pk32_f32_fp6(qb[k], 1.0f);
; #pragma unroll
;         for (int i = 0; i < 16; ++i) o2[i] = f32x2{f[2 * i], f[2 * i + 1]} * c2 + o2[i];
;       }
;     }
	v_cvt_scalef32_pk32_f32_fp6 v[0:31], v[126:131], 1.0
	v_pk_fma_f32 v[126:127], v[0:1], v[108:109], v[150:151] op_sel_hi:[1,0,1]
	v_mov_b32_e32 v0, s13
	v_mov_b32_e32 v1, s12
	v_pk_fma_f32 v[128:129], v[2:3], v[108:109], v[152:153] op_sel_hi:[1,0,1]
	v_pk_fma_f32 v[130:131], v[4:5], v[108:109], v[154:155] op_sel_hi:[1,0,1]
	v_pk_fma_f32 v[150:151], v[6:7], v[108:109], v[156:157] op_sel_hi:[1,0,1]
	v_pk_fma_f32 v[152:153], v[8:9], v[108:109], v[158:159] op_sel_hi:[1,0,1]
	v_pk_fma_f32 v[154:155], v[10:11], v[108:109], v[160:161] op_sel_hi:[1,0,1]
	v_pk_fma_f32 v[156:157], v[12:13], v[108:109], v[162:163] op_sel_hi:[1,0,1]
	v_pk_fma_f32 v[158:159], v[14:15], v[108:109], v[164:165] op_sel_hi:[1,0,1]
	v_pk_fma_f32 v[160:161], v[16:17], v[108:109], v[166:167] op_sel_hi:[1,0,1]
	v_pk_fma_f32 v[162:163], v[18:19], v[108:109], v[168:169] op_sel_hi:[1,0,1]
	v_pk_fma_f32 v[164:165], v[20:21], v[108:109], v[170:171] op_sel_hi:[1,0,1]
	v_pk_fma_f32 v[166:167], v[22:23], v[108:109], v[172:173] op_sel_hi:[1,0,1]
	v_pk_fma_f32 v[168:169], v[24:25], v[108:109], v[174:175] op_sel_hi:[1,0,1]
	v_pk_fma_f32 v[170:171], v[26:27], v[108:109], v[176:177] op_sel_hi:[1,0,1]
	v_pk_fma_f32 v[172:173], v[28:29], v[108:109], v[178:179] op_sel_hi:[1,0,1]
	v_pk_fma_f32 v[174:175], v[30:31], v[108:109], v[180:181] op_sel_hi:[1,0,1]
	v_cndmask_b32_e64 v108, v0, v1, s[0:1]
	s_waitcnt vmcnt(12)
	v_cvt_scalef32_pk32_f32_fp6 v[0:31], v[132:137], 1.0
	v_readlane_b32 s12, v106, 58
	v_readlane_b32 s13, v109, 58
	v_pk_fma_f32 v[126:127], v[0:1], v[108:109], v[126:127] op_sel_hi:[1,0,1]
	v_mov_b32_e32 v1, s12
	v_mov_b32_e32 v0, s13
	v_pk_fma_f32 v[128:129], v[2:3], v[108:109], v[128:129] op_sel_hi:[1,0,1]
	v_pk_fma_f32 v[130:131], v[4:5], v[108:109], v[130:131] op_sel_hi:[1,0,1]
	v_pk_fma_f32 v[132:133], v[6:7], v[108:109], v[150:151] op_sel_hi:[1,0,1]
	v_pk_fma_f32 v[134:135], v[8:9], v[108:109], v[152:153] op_sel_hi:[1,0,1]
	v_pk_fma_f32 v[136:137], v[10:11], v[108:109], v[154:155] op_sel_hi:[1,0,1]
	v_pk_fma_f32 v[150:151], v[12:13], v[108:109], v[156:157] op_sel_hi:[1,0,1]
	v_pk_fma_f32 v[152:153], v[14:15], v[108:109], v[158:159] op_sel_hi:[1,0,1]
	v_pk_fma_f32 v[154:155], v[16:17], v[108:109], v[160:161] op_sel_hi:[1,0,1]
	v_pk_fma_f32 v[156:157], v[18:19], v[108:109], v[162:163] op_sel_hi:[1,0,1]
	v_pk_fma_f32 v[158:159], v[20:21], v[108:109], v[164:165] op_sel_hi:[1,0,1]
	v_pk_fma_f32 v[160:161], v[22:23], v[108:109], v[166:167] op_sel_hi:[1,0,1]
	v_pk_fma_f32 v[162:163], v[24:25], v[108:109], v[168:169] op_sel_hi:[1,0,1]
	v_pk_fma_f32 v[164:165], v[26:27], v[108:109], v[170:171] op_sel_hi:[1,0,1]
	v_pk_fma_f32 v[166:167], v[28:29], v[108:109], v[172:173] op_sel_hi:[1,0,1]
	v_pk_fma_f32 v[168:169], v[30:31], v[108:109], v[174:175] op_sel_hi:[1,0,1]
	v_cndmask_b32_e64 v108, v0, v1, s[0:1]
	s_waitcnt vmcnt(10)
	v_cvt_scalef32_pk32_f32_fp6 v[0:31], v[138:143], 1.0
	v_readlane_b32 s12, v106, 59
	v_readlane_b32 s13, v109, 59
	v_pk_fma_f32 v[126:127], v[0:1], v[108:109], v[126:127] op_sel_hi:[1,0,1]
	v_mov_b32_e32 v1, s12
	v_mov_b32_e32 v0, s13
	v_pk_fma_f32 v[128:129], v[2:3], v[108:109], v[128:129] op_sel_hi:[1,0,1]
	v_pk_fma_f32 v[130:131], v[4:5], v[108:109], v[130:131] op_sel_hi:[1,0,1]
	v_pk_fma_f32 v[132:133], v[6:7], v[108:109], v[132:133] op_sel_hi:[1,0,1]
	v_pk_fma_f32 v[134:135], v[8:9], v[108:109], v[134:135] op_sel_hi:[1,0,1]
	v_pk_fma_f32 v[136:137], v[10:11], v[108:109], v[136:137] op_sel_hi:[1,0,1]
	v_pk_fma_f32 v[138:139], v[12:13], v[108:109], v[150:151] op_sel_hi:[1,0,1]
	v_pk_fma_f32 v[140:141], v[14:15], v[108:109], v[152:153] op_sel_hi:[1,0,1]
	v_pk_fma_f32 v[142:143], v[16:17], v[108:109], v[154:155] op_sel_hi:[1,0,1]
	v_pk_fma_f32 v[150:151], v[18:19], v[108:109], v[156:157] op_sel_hi:[1,0,1]
	v_pk_fma_f32 v[152:153], v[20:21], v[108:109], v[158:159] op_sel_hi:[1,0,1]
	v_pk_fma_f32 v[154:155], v[22:23], v[108:109], v[160:161] op_sel_hi:[1,0,1]
	v_pk_fma_f32 v[156:157], v[24:25], v[108:109], v[162:163] op_sel_hi:[1,0,1]
	v_pk_fma_f32 v[158:159], v[26:27], v[108:109], v[164:165] op_sel_hi:[1,0,1]
	v_pk_fma_f32 v[160:161], v[28:29], v[108:109], v[166:167] op_sel_hi:[1,0,1]
	v_pk_fma_f32 v[162:163], v[30:31], v[108:109], v[168:169] op_sel_hi:[1,0,1]
	v_cndmask_b32_e64 v108, v0, v1, s[0:1]
	s_waitcnt vmcnt(8)
	v_cvt_scalef32_pk32_f32_fp6 v[0:31], v[144:149], 1.0
	v_readlane_b32 s12, v106, 60
	v_readlane_b32 s13, v109, 60
	v_pk_fma_f32 v[126:127], v[0:1], v[108:109], v[126:127] op_sel_hi:[1,0,1]
	v_mov_b32_e32 v1, s12
	v_mov_b32_e32 v0, s13
	v_pk_fma_f32 v[128:129], v[2:3], v[108:109], v[128:129] op_sel_hi:[1,0,1]
	v_pk_fma_f32 v[130:131], v[4:5], v[108:109], v[130:131] op_sel_hi:[1,0,1]
	v_pk_fma_f32 v[132:133], v[6:7], v[108:109], v[132:133] op_sel_hi:[1,0,1]
	v_pk_fma_f32 v[134:135], v[8:9], v[108:109], v[134:135] op_sel_hi:[1,0,1]
	v_pk_fma_f32 v[136:137], v[10:11], v[108:109], v[136:137] op_sel_hi:[1,0,1]
	v_pk_fma_f32 v[138:139], v[12:13], v[108:109], v[138:139] op_sel_hi:[1,0,1]
	v_pk_fma_f32 v[140:141], v[14:15], v[108:109], v[140:141] op_sel_hi:[1,0,1]
	v_pk_fma_f32 v[142:143], v[16:17], v[108:109], v[142:143] op_sel_hi:[1,0,1]
	v_pk_fma_f32 v[144:145], v[18:19], v[108:109], v[150:151] op_sel_hi:[1,0,1]
	v_pk_fma_f32 v[146:147], v[20:21], v[108:109], v[152:153] op_sel_hi:[1,0,1]
	v_pk_fma_f32 v[148:149], v[22:23], v[108:109], v[154:155] op_sel_hi:[1,0,1]
	v_pk_fma_f32 v[150:151], v[24:25], v[108:109], v[156:157] op_sel_hi:[1,0,1]
	v_pk_fma_f32 v[152:153], v[26:27], v[108:109], v[158:159] op_sel_hi:[1,0,1]
	v_pk_fma_f32 v[154:155], v[28:29], v[108:109], v[160:161] op_sel_hi:[1,0,1]
	v_pk_fma_f32 v[156:157], v[30:31], v[108:109], v[162:163] op_sel_hi:[1,0,1]
	v_cndmask_b32_e64 v108, v0, v1, s[0:1]
	s_waitcnt vmcnt(6)
; DI void phase_peer_out(const Params& p, char* lds) {
;     ...
;     for (int kb = 0; kb < 8; ++kb) {
;       v6u qb[8];
; #pragma unroll
;       for (int k = 0; k < 8; ++k) {
;         const int e0 = __builtin_amdgcn_readlane(el[0], kb * 8 + k), e1 = __builtin_amdgcn_readlane(el[1], kb * 8 + k);
;         qb[k] = load6(V6 + (size_t)(hb ? e1 : e0) * 768);
;       }
; #pragma unroll
;       for (int k = 0; k < 8; ++k) {
;         const float c0 = __uint_as_float(__builtin_amdgcn_readlane(__float_as_uint(coefv[0]), kb * 8 + k)), c1 = __uint_as_float(__builtin_amdgcn_readlane(__float_as_uint(coefv[1]), kb * 8 + k));
;         const float cf = hb ? c1 : c0;
;         const f32x2 c2 = {cf, cf};
;         const v32f f = __builtin_amdgcn_cvt_scalef32_pk32_f32_fp6(qb[k], 1.0f);
; #pragma unroll
;         for (int i = 0; i < 16; ++i) o2[i] = f32x2{f[2 * i], f[2 * i + 1]} * c2 + o2[i];
;       }
;     }
;     float s = 0.f;
; #pragma unroll
;     for (int i = 0; i < 16; ++i) {
;       o2[i].x += __shfl_xor(o2[i].x, 32); o2[i].y += __shfl_xor(o2[i].y, 32);
;       o2[i] = x2[i] * f32x2{ALPHA, ALPHA} + o2[i]; s += o2[i].x + o2[i].y;
	v_cvt_scalef32_pk32_f32_fp6 v[0:31], v[50:55], 1.0
	v_readlane_b32 s12, v106, 61
	v_readlane_b32 s13, v109, 61
	v_pk_fma_f32 v[50:51], v[0:1], v[108:109], v[126:127] op_sel_hi:[1,0,1]
	v_mov_b32_e32 v1, s12
	v_mov_b32_e32 v0, s13
	v_pk_fma_f32 v[52:53], v[2:3], v[108:109], v[128:129] op_sel_hi:[1,0,1]
	v_pk_fma_f32 v[54:55], v[4:5], v[108:109], v[130:131] op_sel_hi:[1,0,1]
	v_pk_fma_f32 v[126:127], v[6:7], v[108:109], v[132:133] op_sel_hi:[1,0,1]
	v_pk_fma_f32 v[128:129], v[8:9], v[108:109], v[134:135] op_sel_hi:[1,0,1]
	v_pk_fma_f32 v[130:131], v[10:11], v[108:109], v[136:137] op_sel_hi:[1,0,1]
	v_pk_fma_f32 v[132:133], v[12:13], v[108:109], v[138:139] op_sel_hi:[1,0,1]
	v_pk_fma_f32 v[134:135], v[14:15], v[108:109], v[140:141] op_sel_hi:[1,0,1]
	v_pk_fma_f32 v[136:137], v[16:17], v[108:109], v[142:143] op_sel_hi:[1,0,1]
	v_pk_fma_f32 v[138:139], v[18:19], v[108:109], v[144:145] op_sel_hi:[1,0,1]
	v_pk_fma_f32 v[140:141], v[20:21], v[108:109], v[146:147] op_sel_hi:[1,0,1]
	v_pk_fma_f32 v[142:143], v[22:23], v[108:109], v[148:149] op_sel_hi:[1,0,1]
	v_pk_fma_f32 v[144:145], v[24:25], v[108:109], v[150:151] op_sel_hi:[1,0,1]
	v_pk_fma_f32 v[146:147], v[26:27], v[108:109], v[152:153] op_sel_hi:[1,0,1]
	v_pk_fma_f32 v[148:149], v[28:29], v[108:109], v[154:155] op_sel_hi:[1,0,1]
	v_pk_fma_f32 v[150:151], v[30:31], v[108:109], v[156:157] op_sel_hi:[1,0,1]
	v_cndmask_b32_e64 v108, v0, v1, s[0:1]
	s_waitcnt vmcnt(4)
	v_cvt_scalef32_pk32_f32_fp6 v[0:31], v[44:49], 1.0
	v_readlane_b32 s12, v106, 62
	v_readlane_b32 s13, v109, 62
	v_pk_fma_f32 v[44:45], v[0:1], v[108:109], v[50:51] op_sel_hi:[1,0,1]
	v_mov_b32_e32 v1, s12
	v_mov_b32_e32 v0, s13
	v_pk_fma_f32 v[46:47], v[2:3], v[108:109], v[52:53] op_sel_hi:[1,0,1]
	v_pk_fma_f32 v[48:49], v[4:5], v[108:109], v[54:55] op_sel_hi:[1,0,1]
	v_pk_fma_f32 v[50:51], v[6:7], v[108:109], v[126:127] op_sel_hi:[1,0,1]
	v_pk_fma_f32 v[52:53], v[8:9], v[108:109], v[128:129] op_sel_hi:[1,0,1]
	v_pk_fma_f32 v[54:55], v[10:11], v[108:109], v[130:131] op_sel_hi:[1,0,1]
	v_pk_fma_f32 v[126:127], v[12:13], v[108:109], v[132:133] op_sel_hi:[1,0,1]
	v_pk_fma_f32 v[128:129], v[14:15], v[108:109], v[134:135] op_sel_hi:[1,0,1]
	v_pk_fma_f32 v[130:131], v[16:17], v[108:109], v[136:137] op_sel_hi:[1,0,1]
	v_pk_fma_f32 v[132:133], v[18:19], v[108:109], v[138:139] op_sel_hi:[1,0,1]
	v_pk_fma_f32 v[134:135], v[20:21], v[108:109], v[140:141] op_sel_hi:[1,0,1]
	v_pk_fma_f32 v[136:137], v[22:23], v[108:109], v[142:143] op_sel_hi:[1,0,1]
	v_pk_fma_f32 v[138:139], v[24:25], v[108:109], v[144:145] op_sel_hi:[1,0,1]
	v_pk_fma_f32 v[140:141], v[26:27], v[108:109], v[146:147] op_sel_hi:[1,0,1]
	v_pk_fma_f32 v[142:143], v[28:29], v[108:109], v[148:149] op_sel_hi:[1,0,1]
	v_pk_fma_f32 v[144:145], v[30:31], v[108:109], v[150:151] op_sel_hi:[1,0,1]
	v_cndmask_b32_e64 v108, v0, v1, s[0:1]
	s_waitcnt vmcnt(1)
	v_cvt_scalef32_pk32_f32_fp6 v[0:31], v[38:43], 1.0
	v_readlane_b32 s12, v106, 63
	v_readlane_b32 s13, v109, 63
	v_pk_fma_f32 v[38:39], v[0:1], v[108:109], v[44:45] op_sel_hi:[1,0,1]
	v_mov_b32_e32 v1, s12
	v_mov_b32_e32 v0, s13
	v_pk_fma_f32 v[40:41], v[2:3], v[108:109], v[46:47] op_sel_hi:[1,0,1]
	v_pk_fma_f32 v[42:43], v[4:5], v[108:109], v[48:49] op_sel_hi:[1,0,1]
	v_pk_fma_f32 v[44:45], v[6:7], v[108:109], v[50:51] op_sel_hi:[1,0,1]
	v_pk_fma_f32 v[46:47], v[8:9], v[108:109], v[52:53] op_sel_hi:[1,0,1]
	v_pk_fma_f32 v[48:49], v[10:11], v[108:109], v[54:55] op_sel_hi:[1,0,1]
	v_pk_fma_f32 v[50:51], v[12:13], v[108:109], v[126:127] op_sel_hi:[1,0,1]
	v_pk_fma_f32 v[52:53], v[14:15], v[108:109], v[128:129] op_sel_hi:[1,0,1]
	v_pk_fma_f32 v[54:55], v[16:17], v[108:109], v[130:131] op_sel_hi:[1,0,1]
	v_pk_fma_f32 v[126:127], v[18:19], v[108:109], v[132:133] op_sel_hi:[1,0,1]
	v_pk_fma_f32 v[128:129], v[20:21], v[108:109], v[134:135] op_sel_hi:[1,0,1]
	v_pk_fma_f32 v[130:131], v[22:23], v[108:109], v[136:137] op_sel_hi:[1,0,1]
	v_pk_fma_f32 v[132:133], v[24:25], v[108:109], v[138:139] op_sel_hi:[1,0,1]
	v_pk_fma_f32 v[134:135], v[26:27], v[108:109], v[140:141] op_sel_hi:[1,0,1]
	v_pk_fma_f32 v[136:137], v[28:29], v[108:109], v[142:143] op_sel_hi:[1,0,1]
	v_pk_fma_f32 v[138:139], v[30:31], v[108:109], v[144:145] op_sel_hi:[1,0,1]
	v_cndmask_b32_e64 v106, v0, v1, s[0:1]
	s_waitcnt vmcnt(0)
	v_cvt_scalef32_pk32_f32_fp6 v[0:31], v[32:37], 1.0
	v_pk_fma_f32 v[0:1], v[0:1], v[106:107], v[38:39] op_sel_hi:[1,0,1]
	v_pk_fma_f32 v[32:33], v[8:9], v[106:107], v[46:47] op_sel_hi:[1,0,1]
	ds_bpermute_b32 v8, v113, v0
	ds_bpermute_b32 v9, v113, v1
	v_pk_fma_f32 v[2:3], v[2:3], v[106:107], v[40:41] op_sel_hi:[1,0,1]
	v_pk_fma_f32 v[34:35], v[10:11], v[106:107], v[48:49] op_sel_hi:[1,0,1]
	ds_bpermute_b32 v10, v113, v2
	ds_bpermute_b32 v11, v113, v3
	s_waitcnt lgkmcnt(2)
	v_pk_add_f32 v[0:1], v[0:1], v[8:9]
	v_pk_fma_f32 v[36:37], v[12:13], v[106:107], v[50:51] op_sel_hi:[1,0,1]
	v_pk_fma_f32 v[12:13], v[94:95], s[20:21], v[0:1] op_sel_hi:[1,0,1]
	v_pk_fma_f32 v[4:5], v[4:5], v[106:107], v[42:43] op_sel_hi:[1,0,1]
	v_add_f32_e32 v0, v12, v13
	v_add_f32_e32 v8, 0, v0
	s_waitcnt lgkmcnt(0)
	v_pk_add_f32 v[0:1], v[2:3], v[10:11]
	v_pk_fma_f32 v[38:39], v[14:15], v[106:107], v[52:53] op_sel_hi:[1,0,1]
	v_pk_fma_f32 v[14:15], v[92:93], s[20:21], v[0:1] op_sel_hi:[1,0,1]
	ds_bpermute_b32 v0, v113, v4
	ds_bpermute_b32 v1, v113, v5
	v_pk_fma_f32 v[6:7], v[6:7], v[106:107], v[44:45] op_sel_hi:[1,0,1]
	v_add_f32_e32 v2, v14, v15
	v_add_f32_e32 v10, v2, v8
	ds_bpermute_b32 v2, v113, v6
	ds_bpermute_b32 v3, v113, v7
	s_waitcnt lgkmcnt(2)
; DI void phase_peer_out(const Params& p, char* lds) {
;     ...
;     float s = 0.f;
; #pragma unroll
;     for (int i = 0; i < 16; ++i) {
;       o2[i].x += __shfl_xor(o2[i].x, 32); o2[i].y += __shfl_xor(o2[i].y, 32);
;       o2[i] = x2[i] * f32x2{ALPHA, ALPHA} + o2[i]; s += o2[i].x + o2[i].y;
;     }
;     for (int o = 16; o; o >>= 1) s += __shfl_xor(s, o);
;     const float mu = s * (1.f / 1024.f);
;     float q = 0.f;
; #pragma unroll
;     for (int i = 0; i < 16; ++i) { const float a = o2[i].x - mu, bq = o2[i].y - mu; q += a * a + bq * bq; }
;     for (int o = 16; o; o >>= 1) q += __shfl_xor(q, o);
	v_pk_add_f32 v[0:1], v[4:5], v[0:1]
	v_pk_fma_f32 v[40:41], v[22:23], v[106:107], v[130:131] op_sel_hi:[1,0,1]
	v_pk_fma_f32 v[8:9], v[86:87], s[20:21], v[0:1] op_sel_hi:[1,0,1]
	v_pk_fma_f32 v[16:17], v[16:17], v[106:107], v[54:55] op_sel_hi:[1,0,1]
	v_add_f32_e32 v0, v8, v9
	v_add_f32_e32 v4, v0, v10
	s_waitcnt lgkmcnt(0)
	v_pk_add_f32 v[0:1], v[6:7], v[2:3]
	ds_bpermute_b32 v3, v113, v35
	v_pk_fma_f32 v[10:11], v[100:101], s[20:21], v[0:1] op_sel_hi:[1,0,1]
	ds_bpermute_b32 v0, v113, v32
	ds_bpermute_b32 v1, v113, v33
	v_add_f32_e32 v2, v10, v11
	v_add_f32_e32 v6, v2, v4
	ds_bpermute_b32 v2, v113, v34
	v_pk_fma_f32 v[42:43], v[26:27], v[106:107], v[134:135] op_sel_hi:[1,0,1]
	s_waitcnt lgkmcnt(1)
	v_pk_add_f32 v[0:1], v[32:33], v[0:1]
	v_pk_fma_f32 v[18:19], v[18:19], v[106:107], v[126:127] op_sel_hi:[1,0,1]
	v_pk_fma_f32 v[4:5], v[104:105], s[20:21], v[0:1] op_sel_hi:[1,0,1]
	v_pk_fma_f32 v[46:47], v[30:31], v[106:107], v[138:139] op_sel_hi:[1,0,1]
	v_add_f32_e32 v0, v4, v5
	v_add_f32_e32 v22, v0, v6
	s_waitcnt lgkmcnt(0)
	v_pk_add_f32 v[0:1], v[34:35], v[2:3]
	ds_bpermute_b32 v3, v113, v39
	v_pk_fma_f32 v[6:7], v[102:103], s[20:21], v[0:1] op_sel_hi:[1,0,1]
	ds_bpermute_b32 v0, v113, v36
	ds_bpermute_b32 v1, v113, v37
	v_add_f32_e32 v2, v6, v7
	v_add_f32_e32 v22, v2, v22
	ds_bpermute_b32 v2, v113, v38
	v_pk_fma_f32 v[44:45], v[28:29], v[106:107], v[136:137] op_sel_hi:[1,0,1]
	s_waitcnt lgkmcnt(1)
	v_pk_add_f32 v[0:1], v[36:37], v[0:1]
	v_pk_fma_f32 v[20:21], v[20:21], v[106:107], v[128:129] op_sel_hi:[1,0,1]
	v_pk_fma_f32 v[0:1], v[98:99], s[20:21], v[0:1] op_sel_hi:[1,0,1]
	s_waitcnt lgkmcnt(0)
	v_pk_add_f32 v[2:3], v[38:39], v[2:3]
	v_add_f32_e32 v23, v0, v1
	v_add_f32_e32 v26, v22, v23
	ds_bpermute_b32 v22, v113, v16
	ds_bpermute_b32 v23, v113, v17
	v_pk_fma_f32 v[2:3], v[96:97], s[20:21], v[2:3] op_sel_hi:[1,0,1]
	v_pk_fma_f32 v[24:25], v[24:25], v[106:107], v[132:133] op_sel_hi:[1,0,1]
	v_add_f32_e32 v27, v2, v3
	v_add_f32_e32 v30, v26, v27
	ds_bpermute_b32 v26, v113, v18
	ds_bpermute_b32 v27, v113, v19
	s_waitcnt lgkmcnt(2)
	v_pk_add_f32 v[16:17], v[16:17], v[22:23]
	ds_bpermute_b32 v33, v113, v47
	v_pk_fma_f32 v[28:29], v[90:91], s[20:21], v[16:17] op_sel_hi:[1,0,1]
	s_nop 0
	v_add_f32_e32 v16, v28, v29
	v_add_f32_e32 v22, v30, v16
	s_waitcnt lgkmcnt(1)
	v_pk_add_f32 v[16:17], v[18:19], v[26:27]
	ds_bpermute_b32 v18, v113, v40
	v_pk_fma_f32 v[30:31], v[88:89], s[20:21], v[16:17] op_sel_hi:[1,0,1]
	ds_bpermute_b32 v16, v113, v20
	ds_bpermute_b32 v17, v113, v21
	ds_bpermute_b32 v19, v113, v41
	v_add_f32_e32 v23, v30, v31
	v_add_f32_e32 v32, v22, v23
	s_waitcnt lgkmcnt(1)
	v_pk_add_f32 v[16:17], v[20:21], v[16:17]
	s_nop 0
	v_pk_fma_f32 v[22:23], v[84:85], s[20:21], v[16:17] op_sel_hi:[1,0,1]
	s_waitcnt lgkmcnt(0)
	v_pk_add_f32 v[16:17], v[40:41], v[18:19]
	v_mov_b32_e32 v18, v23
	v_pk_fma_f32 v[26:27], v[82:83], s[20:21], v[16:17] op_sel_hi:[1,0,1]
	v_mov_b32_e32 v16, v22
	v_mov_b32_e32 v17, v26
	v_mov_b32_e32 v19, v27
	v_pk_add_f32 v[16:17], v[16:17], v[18:19]
	ds_bpermute_b32 v18, v113, v24
	ds_bpermute_b32 v19, v113, v25
	ds_bpermute_b32 v20, v113, v42
	ds_bpermute_b32 v21, v113, v43
	v_add_f32_e32 v16, v32, v16
	v_add_f32_e32 v34, v16, v17
	s_waitcnt lgkmcnt(2)
	v_pk_add_f32 v[16:17], v[24:25], v[18:19]
	ds_bpermute_b32 v32, v113, v46
	v_pk_fma_f32 v[18:19], v[78:79], s[20:21], v[16:17] op_sel_hi:[1,0,1]
	s_waitcnt lgkmcnt(1)
	v_pk_add_f32 v[16:17], v[42:43], v[20:21]
	v_mov_b32_e32 v20, v19
	v_pk_fma_f32 v[24:25], v[76:77], s[20:21], v[16:17] op_sel_hi:[1,0,1]
	v_mov_b32_e32 v16, v18
	v_mov_b32_e32 v17, v24
	v_mov_b32_e32 v21, v25
	v_pk_add_f32 v[16:17], v[16:17], v[20:21]
	ds_bpermute_b32 v20, v113, v44
	ds_bpermute_b32 v21, v113, v45
	v_add_f32_e32 v16, v34, v16
	v_add_f32_e32 v36, v16, v17
	v_mov_b32_e32 v43, v22
	s_waitcnt lgkmcnt(0)
	v_pk_add_f32 v[16:17], v[44:45], v[20:21]
	v_pk_add_f32 v[20:21], v[46:47], v[32:33]
	v_pk_fma_f32 v[16:17], v[74:75], s[20:21], v[16:17] op_sel_hi:[1,0,1]
	v_pk_fma_f32 v[20:21], v[80:81], s[20:21], v[20:21] op_sel_hi:[1,0,1]
	v_mov_b32_e32 v32, v16
	v_mov_b32_e32 v33, v20
	v_mov_b32_e32 v34, v17
	v_mov_b32_e32 v35, v21
	v_pk_add_f32 v[32:33], v[32:33], v[34:35]
	v_mov_b32_e32 v44, v27
	v_add_f32_e32 v32, v36, v32
	v_add_f32_e32 v32, v32, v33
	v_mov_b32_e32 v45, v23
	s_nop 1
	v_add_f32_dpp v32, v32, v32 row_shr:1 row_mask:0xf bank_mask:0xf
	s_nop 1
	v_add_f32_dpp v32, v32, v32 row_shr:2 row_mask:0xf bank_mask:0xf
	s_nop 1
	v_add_f32_dpp v32, v32, v32 row_shr:4 row_mask:0xf bank_mask:0xf
	s_nop 1
	v_add_f32_dpp v32, v32, v32 row_shr:8 row_mask:0xf bank_mask:0xf
	s_nop 1
	v_add_f32_dpp v32, v32, v32 row_bcast:15 row_mask:0xa bank_mask:0xf
	s_nop 0
	v_readlane_b32 s90, v32, 63
	s_nop 1
	v_mov_b32_e32 v33, s90
	v_fmamk_f32 v35, v33, 0xba800000, v13
	v_fmamk_f32 v34, v33, 0xba800000, v12
	v_mul_f32_e32 v35, v35, v35
	v_fmamk_f32 v36, v33, 0xba800000, v15
	v_fmac_f32_e32 v35, v34, v34
	v_fmamk_f32 v34, v33, 0xba800000, v14
	v_mul_f32_e32 v36, v36, v36
	v_fmac_f32_e32 v36, v34, v34
	v_add_f32_e32 v34, v35, v36
	v_fmamk_f32 v36, v33, 0xba800000, v9
	v_fmamk_f32 v35, v33, 0xba800000, v8
	v_mul_f32_e32 v36, v36, v36
	v_fmac_f32_e32 v36, v35, v35
	v_add_f32_e32 v34, v36, v34
	v_fmamk_f32 v36, v33, 0xba800000, v11
	v_fmamk_f32 v35, v33, 0xba800000, v10
	v_mul_f32_e32 v36, v36, v36
	v_fmac_f32_e32 v36, v35, v35
	v_add_f32_e32 v34, v36, v34
	v_fmamk_f32 v36, v33, 0xba800000, v5
	v_fmamk_f32 v35, v33, 0xba800000, v4
	v_mul_f32_e32 v36, v36, v36
; DI void phase_peer_out(const Params& p, char* lds) {
;     ...
;   for (int t = blockIdx.x * 8 + wave; t < T_TOK; t += gridDim.x * 8) {
;     ...
;     for (int o = 16; o; o >>= 1) s += __shfl_xor(s, o);
;     const float mu = s * (1.f / 1024.f);
;     float q = 0.f;
; #pragma unroll
;     for (int i = 0; i < 16; ++i) { const float a = o2[i].x - mu, bq = o2[i].y - mu; q += a * a + bq * bq; }
;     for (int o = 16; o; o >>= 1) q += __shfl_xor(q, o);
;     const float rstd = rsqrtf(q * (1.f / 1024.f) + LN_EPS);
;     float* orow = p.out + (size_t)t * 1024 + 32 * l5 + 16 * hb;
; #pragma unroll
;     for (int q4 = 0; q4 < 4; ++q4) {
;       const float4 gg = *(const float4*)(g3 + 32 * l5 + 16 * hb + 4 * q4), bb = *(const float4*)(b3 + 32 * l5 + 16 * hb + 4 * q4);
;       const f32x2 a0 = hb ? o2[8 + 2 * q4] : o2[2 * q4], a1 = hb ? o2[8 + 2 * q4 + 1] : o2[2 * q4 + 1];
;       float4 o;
;       o.x = (a0.x - mu) * rstd * gg.x + bb.x; o.y = (a0.y - mu) * rstd * gg.y + bb.y;
;       o.z = (a1.x - mu) * rstd * gg.z + bb.z; o.w = (a1.y - mu) * rstd * gg.w + bb.w;
;       *(float4*)(orow + 4 * q4) = o;
;     }
;   }
	v_fmac_f32_e32 v36, v35, v35
	v_add_f32_e32 v34, v36, v34
	v_fmamk_f32 v36, v33, 0xba800000, v7
	v_fmamk_f32 v35, v33, 0xba800000, v6
	v_mul_f32_e32 v36, v36, v36
	v_fmac_f32_e32 v36, v35, v35
	v_add_f32_e32 v34, v36, v34
	v_fmamk_f32 v36, v33, 0xba800000, v1
	v_fmamk_f32 v35, v33, 0xba800000, v0
	v_mul_f32_e32 v36, v36, v36
	v_fmac_f32_e32 v36, v35, v35
	v_add_f32_e32 v34, v36, v34
	v_fmamk_f32 v36, v33, 0xba800000, v3
	v_fmamk_f32 v35, v33, 0xba800000, v2
	v_mul_f32_e32 v36, v36, v36
	v_fmac_f32_e32 v36, v35, v35
	v_add_f32_e32 v34, v36, v34
	v_fmamk_f32 v36, v33, 0xba800000, v29
	v_fmamk_f32 v35, v33, 0xba800000, v28
	v_mul_f32_e32 v36, v36, v36
	v_fmac_f32_e32 v36, v35, v35
	v_mul_f32_e32 v32, 0x3a800000, v33
	v_add_f32_e32 v42, v36, v34
	v_fmamk_f32 v34, v33, 0xba800000, v30
	v_fmamk_f32 v33, v33, 0xba800000, v31
	v_mul_f32_e32 v33, v33, v33
	v_fmac_f32_e32 v33, v34, v34
	v_add_f32_e32 v33, v33, v42
	v_mov_b32_e32 v42, v26
	v_pk_add_f32 v[44:45], v[44:45], v[32:33] op_sel_hi:[1,0] neg_lo:[0,1] neg_hi:[0,1]
	v_pk_add_f32 v[42:43], v[42:43], v[32:33] op_sel_hi:[1,0] neg_lo:[0,1] neg_hi:[0,1]
	v_pk_mul_f32 v[44:45], v[44:45], v[44:45]
	v_cndmask_b32_e64 v13, v29, v13, s[0:1]
	v_pk_fma_f32 v[42:43], v[42:43], v[42:43], v[44:45]
	v_mov_b32_e32 v44, v25
	v_add_f32_e32 v33, v43, v33
	v_add_f32_e32 v33, v42, v33
	v_mov_b32_e32 v45, v19
	v_mov_b32_e32 v42, v24
	v_mov_b32_e32 v43, v18
	v_pk_add_f32 v[44:45], v[44:45], v[32:33] op_sel_hi:[1,0] neg_lo:[0,1] neg_hi:[0,1]
	v_pk_add_f32 v[42:43], v[42:43], v[32:33] op_sel_hi:[1,0] neg_lo:[0,1] neg_hi:[0,1]
	v_pk_mul_f32 v[44:45], v[44:45], v[44:45]
	v_cndmask_b32_e64 v12, v28, v12, s[0:1]
	v_pk_fma_f32 v[42:43], v[42:43], v[42:43], v[44:45]
	v_mov_b32_e32 v44, v21
	v_add_f32_e32 v33, v43, v33
	v_add_f32_e32 v33, v42, v33
	v_mov_b32_e32 v45, v17
	v_mov_b32_e32 v42, v20
	v_mov_b32_e32 v43, v16
	v_pk_add_f32 v[44:45], v[44:45], v[32:33] op_sel_hi:[1,0] neg_lo:[0,1] neg_hi:[0,1]
	v_pk_add_f32 v[42:43], v[42:43], v[32:33] op_sel_hi:[1,0] neg_lo:[0,1] neg_hi:[0,1]
	v_pk_mul_f32 v[44:45], v[44:45], v[44:45]
	v_cndmask_b32_e64 v15, v31, v15, s[0:1]
	v_pk_fma_f32 v[42:43], v[42:43], v[42:43], v[44:45]
	v_cndmask_b32_e64 v14, v30, v14, s[0:1]
	v_add_f32_e32 v33, v43, v33
	v_add_f32_e32 v33, v42, v33
	v_lshlrev_b64 v[44:45], 12, v[60:61]
	v_lshl_add_u64 v[44:45], v[72:73], 0, v[44:45]
	v_cndmask_b32_e64 v9, v23, v9, s[0:1]
	v_cndmask_b32_e64 v8, v22, v8, s[0:1]
	v_cndmask_b32_e64 v11, v27, v11, s[0:1]
	v_cndmask_b32_e64 v10, v26, v10, s[0:1]
	v_cndmask_b32_e64 v5, v19, v5, s[0:1]
	v_cndmask_b32_e64 v4, v18, v4, s[0:1]
	v_cndmask_b32_e64 v7, v25, v7, s[0:1]
	v_cndmask_b32_e64 v6, v24, v6, s[0:1]
	v_cndmask_b32_e64 v1, v17, v1, s[0:1]
	v_cndmask_b32_e64 v0, v16, v0, s[0:1]
	v_cndmask_b32_e64 v3, v21, v3, s[0:1]
	v_cndmask_b32_e64 v2, v20, v2, s[0:1]
	v_add_u32_e32 v60, s53, v60
	s_nop 1
	v_add_f32_dpp v33, v33, v33 row_shr:1 row_mask:0xf bank_mask:0xf
	s_nop 1
	v_add_f32_dpp v33, v33, v33 row_shr:2 row_mask:0xf bank_mask:0xf
	s_nop 1
	v_add_f32_dpp v33, v33, v33 row_shr:4 row_mask:0xf bank_mask:0xf
	s_nop 1
	v_add_f32_dpp v33, v33, v33 row_shr:8 row_mask:0xf bank_mask:0xf
	s_nop 1
	v_add_f32_dpp v33, v33, v33 row_bcast:15 row_mask:0xa bank_mask:0xf
	s_nop 0
	v_readlane_b32 s90, v33, 63
	s_nop 1
	v_mov_b32_e32 v33, s90
	v_fmamk_f32 v33, v33, 0x3a800000, v123
	v_mul_f32_e32 v42, 0x4b800000, v33
	v_cmp_gt_f32_e64 s[12:13], s35, v33
	s_nop 1
	v_cndmask_b32_e64 v33, v33, v42, s[12:13]
	v_rsq_f32_e32 v33, v33
	s_nop 0
	v_mul_f32_e32 v42, 0x45800000, v33
	v_cndmask_b32_e64 v42, v33, v42, s[12:13]
	v_pk_add_f32 v[12:13], v[12:13], v[32:33] op_sel_hi:[1,0] neg_lo:[0,1] neg_hi:[0,1]
	v_pk_add_f32 v[14:15], v[14:15], v[32:33] op_sel_hi:[1,0] neg_lo:[0,1] neg_hi:[0,1]
	v_pk_mul_f32 v[12:13], v[12:13], v[42:43] op_sel_hi:[1,0]
	v_pk_mul_f32 v[14:15], v[14:15], v[42:43] op_sel_hi:[1,0]
	v_pk_add_f32 v[8:9], v[8:9], v[32:33] op_sel_hi:[1,0] neg_lo:[0,1] neg_hi:[0,1]
	v_pk_fma_f32 v[12:13], v[184:185], v[12:13], v[200:201]
	v_pk_fma_f32 v[14:15], v[186:187], v[14:15], v[202:203]
	global_store_dwordx4 v[44:45], v[12:15], off
	v_pk_add_f32 v[10:11], v[10:11], v[32:33] op_sel_hi:[1,0] neg_lo:[0,1] neg_hi:[0,1]
	v_pk_mul_f32 v[8:9], v[8:9], v[42:43] op_sel_hi:[1,0]
	v_pk_mul_f32 v[10:11], v[10:11], v[42:43] op_sel_hi:[1,0]
	v_pk_add_f32 v[4:5], v[4:5], v[32:33] op_sel_hi:[1,0] neg_lo:[0,1] neg_hi:[0,1]
	v_pk_add_f32 v[6:7], v[6:7], v[32:33] op_sel_hi:[1,0] neg_lo:[0,1] neg_hi:[0,1]
	v_pk_mul_f32 v[4:5], v[4:5], v[42:43] op_sel_hi:[1,0]
	v_pk_mul_f32 v[6:7], v[6:7], v[42:43] op_sel_hi:[1,0]
	v_pk_add_f32 v[0:1], v[0:1], v[32:33] op_sel_hi:[1,0] neg_lo:[0,1] neg_hi:[0,1]
	v_pk_add_f32 v[2:3], v[2:3], v[32:33] op_sel_hi:[1,0] neg_lo:[0,1] neg_hi:[0,1]
	v_pk_mul_f32 v[0:1], v[0:1], v[42:43] op_sel_hi:[1,0]
	v_pk_mul_f32 v[2:3], v[2:3], v[42:43] op_sel_hi:[1,0]
	v_cmp_lt_i32_e64 s[12:13], s36, v60
	s_or_b64 s[18:19], s[12:13], s[18:19]
	v_pk_fma_f32 v[8:9], v[188:189], v[8:9], v[204:205]
	v_pk_fma_f32 v[10:11], v[190:191], v[10:11], v[206:207]
	global_store_dwordx4 v[44:45], v[8:11], off offset:16
	v_pk_fma_f32 v[4:5], v[192:193], v[4:5], v[208:209]
	v_pk_fma_f32 v[6:7], v[194:195], v[6:7], v[210:211]
	global_store_dwordx4 v[44:45], v[4:7], off offset:32
	v_pk_fma_f32 v[0:1], v[0:1], v[196:197], v[212:213]
	v_pk_fma_f32 v[2:3], v[2:3], v[198:199], v[214:215]
	global_store_dwordx4 v[44:45], v[0:3], off offset:48
	s_andn2_b64 exec, exec, s[18:19]
	s_cbranch_execz .LBB0_1211

; DI void phase_peer_out(const Params& p, char* lds) {
;     ...
;     int el[2]; float gl[2];
; #pragma unroll
;     for (int grp = 0; grp < 2; ++grp) {
;       el[grp] = sidx[grp * 64 + lane];
;       const float sc = sw[grp * 64 + lane];
;       float mx = sc; for (int o = 8; o; o >>= 1) mx = fmaxf(mx, __shfl_xor(mx, o));
;       const float e = __expf(sc - mx);
;       float sm = e; for (int o = 8; o; o >>= 1) sm += __shfl_xor(sm, o);
;       gl[grp] = e * __builtin_amdgcn_rcpf(sm);
;     }
; #pragma unroll
;     for (int hf = 0; hf < 2; ++hf) {
;       float pd[32];
; #pragma unroll
;       for (int kb = 0; kb < 4; ++kb) {
;         v6u qb[8];
; #pragma unroll
;         for (int k = 0; k < 8; ++k) {
;           const int e0 = __builtin_amdgcn_readlane(el[0], hf * 32 + kb * 8 + k), e1 = __builtin_amdgcn_readlane(el[1], hf * 32 + kb * 8 + k);
;           qb[k] = load6(U6 + (size_t)(hb ? e1 : e0) * 768);
;         }
; #pragma unroll
;         for (int k = 0; k < 8; ++k) {
;           const v32f f = __builtin_amdgcn_cvt_scalef32_pk32_f32_fp6(qb[k], 1.0f);
;           f32x2 a = f32x2{f[0], f[1]} * x2[0];
; #pragma unroll
;           for (int i = 1; i < 16; ++i) a = f32x2{f[2 * i], f[2 * i + 1]} * x2[i] + a;
;           pd[kb * 8 + k] = a.x + a.y;
.LBB0_1203:
	s_or_b64 exec, exec, s[12:13]
	v_lshlrev_b32_e32 v94, 16, v12
	v_and_b32_e32 v95, 0xffff0000, v12
	ds_read_b32 v12, v112 offset:512
	v_lshlrev_b32_e32 v86, 16, v14
	v_and_b32_e32 v87, 0xffff0000, v14
	v_lshlrev_b32_e32 v104, 16, v8
	v_and_b32_e32 v105, 0xffff0000, v8
	s_waitcnt lgkmcnt(0)
	ds_bpermute_b32 v14, v114, v12
	v_lshlrev_b32_e32 v102, 16, v9
	v_and_b32_e32 v103, 0xffff0000, v9
	v_max_f32_e32 v9, v12, v12
	v_lshlrev_b32_e32 v90, 16, v4
	s_waitcnt lgkmcnt(0)
	v_max_f32_e32 v8, v14, v14
	v_max_f32_e32 v8, v9, v8
	ds_bpermute_b32 v9, v115, v8
	v_and_b32_e32 v91, 0xffff0000, v4
	v_lshlrev_b32_e32 v92, 16, v13
	v_and_b32_e32 v93, 0xffff0000, v13
	ds_read2st64_b32 v[106:107], v112 offset1:1
	ds_read_b32 v13, v112 offset:768
	s_waitcnt lgkmcnt(2)
	v_max_f32_e32 v9, v9, v9
	v_max_f32_e32 v8, v8, v9
	ds_bpermute_b32 v9, v116, v8
	v_lshlrev_b32_e32 v88, 16, v5
	v_and_b32_e32 v89, 0xffff0000, v5
	v_lshlrev_b32_e32 v84, 16, v6
	v_and_b32_e32 v85, 0xffff0000, v6
	s_waitcnt lgkmcnt(0)
	v_max_f32_e32 v4, v9, v9
	v_max_f32_e32 v4, v8, v4
	ds_bpermute_b32 v5, v117, v4
	ds_bpermute_b32 v6, v114, v13
	v_lshlrev_b32_e32 v78, 16, v0
	v_and_b32_e32 v79, 0xffff0000, v0
	v_readlane_b32 s12, v106, 0
	s_waitcnt lgkmcnt(1)
	v_max_f32_e32 v5, v5, v5
	v_max_f32_e32 v4, v4, v5
	v_sub_f32_e32 v4, v12, v4
	v_mul_f32_e32 v4, 0x3fb8aa3b, v4
	v_exp_f32_e32 v126, v4
	s_waitcnt lgkmcnt(0)
	v_max_f32_e32 v4, v6, v6
	v_max_f32_e32 v5, v13, v13
	v_max_f32_e32 v4, v5, v4
	ds_bpermute_b32 v5, v115, v4
	ds_bpermute_b32 v0, v114, v126
	v_readlane_b32 s13, v107, 0
	v_lshlrev_b32_e32 v76, 16, v1
	v_and_b32_e32 v77, 0xffff0000, v1
	s_waitcnt lgkmcnt(1)
	v_max_f32_e32 v5, v5, v5
	v_max_f32_e32 v4, v4, v5
	ds_bpermute_b32 v5, v116, v4
	s_waitcnt lgkmcnt(1)
	v_add_f32_e32 v6, v126, v0
	v_mov_b32_e32 v1, s12
	v_lshlrev_b32_e32 v82, 16, v7
	v_and_b32_e32 v83, 0xffff0000, v7
	s_waitcnt lgkmcnt(0)
	v_max_f32_e32 v0, v5, v5
	v_max_f32_e32 v4, v4, v0
	v_mov_b32_e32 v0, s13
	v_cndmask_b32_e64 v0, v0, v1, s[0:1]
	v_mad_u32_u24 v0, v0, s23, v251
	global_load_dwordx2 v[136:137], v0, s[98:99] offset:16
	global_load_dwordx4 v[132:135], v0, s[98:99]
	ds_bpermute_b32 v5, v117, v4
	v_readlane_b32 s12, v106, 1
	v_readlane_b32 s13, v107, 1
	ds_bpermute_b32 v7, v115, v6
	v_mov_b32_e32 v1, s12
	s_waitcnt lgkmcnt(1)
	v_max_f32_e32 v0, v5, v5
	v_max_f32_e32 v0, v4, v0
	v_sub_f32_e32 v0, v13, v0
	v_mul_f32_e32 v0, 0x3fb8aa3b, v0
	v_exp_f32_e32 v127, v0
	v_mov_b32_e32 v0, s13
	v_cndmask_b32_e64 v0, v0, v1, s[0:1]
	v_mad_u32_u24 v0, v0, s23, v251
	global_load_dwordx2 v[142:143], v0, s[98:99] offset:16
	global_load_dwordx4 v[138:141], v0, s[98:99]
	ds_bpermute_b32 v0, v114, v127
	v_readlane_b32 s12, v106, 2
	v_readlane_b32 s13, v107, 2
	v_lshlrev_b32_e32 v74, 16, v2
	v_mov_b32_e32 v1, s12
	s_waitcnt lgkmcnt(0)
	v_add_f32_e32 v129, v127, v0
	v_mov_b32_e32 v0, s13
	v_cndmask_b32_e64 v0, v0, v1, s[0:1]
	v_mad_u32_u24 v0, v0, s23, v251
	global_load_dwordx2 v[148:149], v0, s[98:99] offset:16
	global_load_dwordx4 v[144:147], v0, s[98:99]
	v_readlane_b32 s12, v106, 3
	v_readlane_b32 s13, v107, 3
	v_and_b32_e32 v75, 0xffff0000, v2
	v_mov_b32_e32 v1, s12
	v_mov_b32_e32 v0, s13
	v_cndmask_b32_e64 v0, v0, v1, s[0:1]
	v_mad_u32_u24 v0, v0, s23, v251
	global_load_dwordx2 v[154:155], v0, s[98:99] offset:16
	global_load_dwordx4 v[150:153], v0, s[98:99]
	v_readlane_b32 s12, v106, 4
	v_readlane_b32 s13, v107, 4
	v_add_f32_e32 v2, v6, v7
	v_mov_b32_e32 v1, s12
	v_mov_b32_e32 v0, s13
	v_cndmask_b32_e64 v0, v0, v1, s[0:1]
	v_mad_u32_u24 v0, v0, s23, v251
	global_load_dwordx2 v[54:55], v0, s[98:99] offset:16
	global_load_dwordx4 v[50:53], v0, s[98:99]
	v_readlane_b32 s12, v106, 5
	v_readlane_b32 s13, v107, 5
	ds_bpermute_b32 v6, v116, v2
	v_mov_b32_e32 v1, s12
	v_mov_b32_e32 v0, s13
	v_cndmask_b32_e64 v0, v0, v1, s[0:1]
	v_mad_u32_u24 v0, v0, s23, v251
	v_readlane_b32 s12, v106, 6
	v_readlane_b32 s13, v107, 6
	global_load_dwordx2 v[48:49], v0, s[98:99] offset:16
	global_load_dwordx4 v[44:47], v0, s[98:99]
	v_mov_b32_e32 v0, s13
	v_mov_b32_e32 v1, s12
	v_cndmask_b32_e64 v0, v0, v1, s[0:1]
	v_mad_u32_u24 v0, v0, s23, v251
	v_readlane_b32 s12, v106, 7
	v_readlane_b32 s13, v107, 7
	global_load_dwordx2 v[42:43], v0, s[98:99] offset:16
	global_load_dwordx4 v[38:41], v0, s[98:99]
	v_mov_b32_e32 v0, s13
	v_mov_b32_e32 v1, s12
	v_cndmask_b32_e64 v0, v0, v1, s[0:1]
	v_mad_u32_u24 v0, v0, s23, v251
	v_lshlrev_b32_e32 v100, 16, v15
	v_and_b32_e32 v101, 0xffff0000, v15
	v_lshlrev_b32_e32 v98, 16, v10
	v_and_b32_e32 v99, 0xffff0000, v10
	v_lshlrev_b32_e32 v96, 16, v11
	v_and_b32_e32 v97, 0xffff0000, v11
	v_lshlrev_b32_e32 v80, 16, v3
	v_and_b32_e32 v81, 0xffff0000, v3
	s_waitcnt lgkmcnt(0)
	v_add_f32_e32 v128, v2, v6
	global_load_dwordx2 v[36:37], v0, s[98:99] offset:16
	global_load_dwordx4 v[32:35], v0, s[98:99]
	v_readlane_b32 s12, v106, 8
	s_waitcnt vmcnt(14)
	v_cvt_scalef32_pk32_f32_fp6 v[0:31], v[132:137], 1.0
	v_pk_mul_f32 v[2:3], v[2:3], v[92:93]
	v_readlane_b32 s13, v107, 8
	v_pk_fma_f32 v[0:1], v[0:1], v[94:95], v[2:3]
	ds_bpermute_b32 v130, v115, v129
	v_pk_fma_f32 v[0:1], v[4:5], v[86:87], v[0:1]
	v_ashrrev_i32_e32 v109, 31, v106
	v_pk_fma_f32 v[0:1], v[6:7], v[100:101], v[0:1]
	v_mov_b32_e32 v108, v106
	v_pk_fma_f32 v[0:1], v[8:9], v[104:105], v[0:1]
	s_nop 0
	v_pk_fma_f32 v[0:1], v[10:11], v[102:103], v[0:1]
	s_nop 0
	v_pk_fma_f32 v[0:1], v[12:13], v[98:99], v[0:1]
	s_nop 0
	v_pk_fma_f32 v[0:1], v[14:15], v[96:97], v[0:1]
	s_nop 0
	v_pk_fma_f32 v[0:1], v[16:17], v[90:91], v[0:1]
	s_nop 0
	v_pk_fma_f32 v[0:1], v[18:19], v[88:89], v[0:1]
	s_nop 0
	v_pk_fma_f32 v[0:1], v[20:21], v[84:85], v[0:1]
	s_nop 0
	v_pk_fma_f32 v[0:1], v[22:23], v[82:83], v[0:1]
	s_nop 0
	v_pk_fma_f32 v[0:1], v[24:25], v[78:79], v[0:1]
	s_nop 0
	v_pk_fma_f32 v[0:1], v[26:27], v[76:77], v[0:1]
	s_nop 0
	v_pk_fma_f32 v[0:1], v[28:29], v[74:75], v[0:1]
	s_nop 0
	v_pk_fma_f32 v[0:1], v[30:31], v[80:81], v[0:1]
	s_nop 0
	v_add_f32_e32 v131, v0, v1
	s_waitcnt vmcnt(12)
; DI void phase_peer_out(const Params& p, char* lds) {
;     ...
; #pragma unroll
;         for (int k = 0; k < 8; ++k) {
;           const v32f f = __builtin_amdgcn_cvt_scalef32_pk32_f32_fp6(qb[k], 1.0f);
;           f32x2 a = f32x2{f[0], f[1]} * x2[0];
; #pragma unroll
;           for (int i = 1; i < 16; ++i) a = f32x2{f[2 * i], f[2 * i + 1]} * x2[i] + a;
;           pd[kb * 8 + k] = a.x + a.y;
	v_cvt_scalef32_pk32_f32_fp6 v[0:31], v[138:143], 1.0
	v_pk_mul_f32 v[2:3], v[2:3], v[92:93]
	s_nop 0
	v_pk_fma_f32 v[0:1], v[0:1], v[94:95], v[2:3]
	s_nop 0
	v_pk_fma_f32 v[0:1], v[4:5], v[86:87], v[0:1]
	s_nop 0
	v_pk_fma_f32 v[0:1], v[6:7], v[100:101], v[0:1]
	s_nop 0
	v_pk_fma_f32 v[0:1], v[8:9], v[104:105], v[0:1]
	s_nop 0
	v_pk_fma_f32 v[0:1], v[10:11], v[102:103], v[0:1]
	s_nop 0
	v_pk_fma_f32 v[0:1], v[12:13], v[98:99], v[0:1]
	s_nop 0
	v_pk_fma_f32 v[0:1], v[14:15], v[96:97], v[0:1]
	s_nop 0
	v_pk_fma_f32 v[0:1], v[16:17], v[90:91], v[0:1]
	s_nop 0
	v_pk_fma_f32 v[0:1], v[18:19], v[88:89], v[0:1]
	s_nop 0
	v_pk_fma_f32 v[0:1], v[20:21], v[84:85], v[0:1]
	s_nop 0
	v_pk_fma_f32 v[0:1], v[22:23], v[82:83], v[0:1]
	s_nop 0
	v_pk_fma_f32 v[0:1], v[24:25], v[78:79], v[0:1]
	s_nop 0
	v_pk_fma_f32 v[0:1], v[26:27], v[76:77], v[0:1]
	s_nop 0
	v_pk_fma_f32 v[0:1], v[28:29], v[74:75], v[0:1]
	s_nop 0
	v_pk_fma_f32 v[0:1], v[30:31], v[80:81], v[0:1]
	s_nop 0
	v_add_f32_e32 v132, v0, v1
	s_waitcnt vmcnt(10)
	v_cvt_scalef32_pk32_f32_fp6 v[0:31], v[144:149], 1.0
	v_pk_mul_f32 v[2:3], v[2:3], v[92:93]
	s_nop 0
	v_pk_fma_f32 v[0:1], v[0:1], v[94:95], v[2:3]
	s_nop 0
	v_pk_fma_f32 v[0:1], v[4:5], v[86:87], v[0:1]
	s_nop 0
	v_pk_fma_f32 v[0:1], v[6:7], v[100:101], v[0:1]
	s_nop 0
	v_pk_fma_f32 v[0:1], v[8:9], v[104:105], v[0:1]
	s_nop 0
	v_pk_fma_f32 v[0:1], v[10:11], v[102:103], v[0:1]
	s_nop 0
	v_pk_fma_f32 v[0:1], v[12:13], v[98:99], v[0:1]
	s_nop 0
	v_pk_fma_f32 v[0:1], v[14:15], v[96:97], v[0:1]
	s_nop 0
	v_pk_fma_f32 v[0:1], v[16:17], v[90:91], v[0:1]
	s_nop 0
	v_pk_fma_f32 v[0:1], v[18:19], v[88:89], v[0:1]
	s_nop 0
	v_pk_fma_f32 v[0:1], v[20:21], v[84:85], v[0:1]
	s_nop 0
	v_pk_fma_f32 v[0:1], v[22:23], v[82:83], v[0:1]
	s_nop 0
	v_pk_fma_f32 v[0:1], v[24:25], v[78:79], v[0:1]
	s_nop 0
	v_pk_fma_f32 v[0:1], v[26:27], v[76:77], v[0:1]
	s_nop 0
	v_pk_fma_f32 v[0:1], v[28:29], v[74:75], v[0:1]
	s_nop 0
	v_pk_fma_f32 v[0:1], v[30:31], v[80:81], v[0:1]
	s_nop 0
	v_add_f32_e32 v133, v0, v1
	s_waitcnt vmcnt(8)
	v_cvt_scalef32_pk32_f32_fp6 v[0:31], v[150:155], 1.0
	v_pk_mul_f32 v[2:3], v[2:3], v[92:93]
	s_nop 0
	v_pk_fma_f32 v[0:1], v[0:1], v[94:95], v[2:3]
	s_nop 0
	v_pk_fma_f32 v[0:1], v[4:5], v[86:87], v[0:1]
	s_nop 0
	v_pk_fma_f32 v[0:1], v[6:7], v[100:101], v[0:1]
	s_nop 0
	v_pk_fma_f32 v[0:1], v[8:9], v[104:105], v[0:1]
	s_nop 0
	v_pk_fma_f32 v[0:1], v[10:11], v[102:103], v[0:1]
	s_nop 0
	v_pk_fma_f32 v[0:1], v[12:13], v[98:99], v[0:1]
	s_nop 0
	v_pk_fma_f32 v[0:1], v[14:15], v[96:97], v[0:1]
	s_nop 0
	v_pk_fma_f32 v[0:1], v[16:17], v[90:91], v[0:1]
	s_nop 0
	v_pk_fma_f32 v[0:1], v[18:19], v[88:89], v[0:1]
	s_nop 0
	v_pk_fma_f32 v[0:1], v[20:21], v[84:85], v[0:1]
	s_nop 0
	v_pk_fma_f32 v[0:1], v[22:23], v[82:83], v[0:1]
	s_nop 0
	v_pk_fma_f32 v[0:1], v[24:25], v[78:79], v[0:1]
	s_nop 0
	v_pk_fma_f32 v[0:1], v[26:27], v[76:77], v[0:1]
	s_nop 0
	v_pk_fma_f32 v[0:1], v[28:29], v[74:75], v[0:1]
	s_nop 0
	v_pk_fma_f32 v[0:1], v[30:31], v[80:81], v[0:1]
	s_nop 0
	v_add_f32_e32 v134, v0, v1
	s_waitcnt vmcnt(6)
	v_cvt_scalef32_pk32_f32_fp6 v[0:31], v[50:55], 1.0
	v_pk_mul_f32 v[2:3], v[2:3], v[92:93]
	s_nop 0
	v_pk_fma_f32 v[0:1], v[0:1], v[94:95], v[2:3]
	s_nop 0
	v_pk_fma_f32 v[0:1], v[4:5], v[86:87], v[0:1]
	s_nop 0
	v_pk_fma_f32 v[0:1], v[6:7], v[100:101], v[0:1]
	s_nop 0
	v_pk_fma_f32 v[0:1], v[8:9], v[104:105], v[0:1]
	s_nop 0
	v_pk_fma_f32 v[0:1], v[10:11], v[102:103], v[0:1]
	s_nop 0
	v_pk_fma_f32 v[0:1], v[12:13], v[98:99], v[0:1]
	s_nop 0
	v_pk_fma_f32 v[0:1], v[14:15], v[96:97], v[0:1]
	s_nop 0
	v_pk_fma_f32 v[0:1], v[16:17], v[90:91], v[0:1]
	s_nop 0
	v_pk_fma_f32 v[0:1], v[18:19], v[88:89], v[0:1]
	s_nop 0
	v_pk_fma_f32 v[0:1], v[20:21], v[84:85], v[0:1]
	s_nop 0
	v_pk_fma_f32 v[0:1], v[22:23], v[82:83], v[0:1]
	s_nop 0
	v_pk_fma_f32 v[0:1], v[24:25], v[78:79], v[0:1]
	s_nop 0
	v_pk_fma_f32 v[0:1], v[26:27], v[76:77], v[0:1]
	s_nop 0
	v_pk_fma_f32 v[0:1], v[28:29], v[74:75], v[0:1]
	s_nop 0
	v_pk_fma_f32 v[0:1], v[30:31], v[80:81], v[0:1]
	s_nop 0
	v_add_f32_e32 v50, v0, v1
	s_waitcnt vmcnt(4)
	v_cvt_scalef32_pk32_f32_fp6 v[0:31], v[44:49], 1.0
	v_pk_mul_f32 v[2:3], v[2:3], v[92:93]
	s_nop 0
	v_pk_fma_f32 v[0:1], v[0:1], v[94:95], v[2:3]
	s_nop 0
	v_pk_fma_f32 v[0:1], v[4:5], v[86:87], v[0:1]
	s_nop 0
	v_pk_fma_f32 v[0:1], v[6:7], v[100:101], v[0:1]
	s_nop 0
	v_pk_fma_f32 v[0:1], v[8:9], v[104:105], v[0:1]
	s_nop 0
	v_pk_fma_f32 v[0:1], v[10:11], v[102:103], v[0:1]
	s_nop 0
	v_pk_fma_f32 v[0:1], v[12:13], v[98:99], v[0:1]
	s_nop 0
	v_pk_fma_f32 v[0:1], v[14:15], v[96:97], v[0:1]
	s_nop 0
	v_pk_fma_f32 v[0:1], v[16:17], v[90:91], v[0:1]
	s_nop 0
	v_pk_fma_f32 v[0:1], v[18:19], v[88:89], v[0:1]
	s_nop 0
	v_pk_fma_f32 v[0:1], v[20:21], v[84:85], v[0:1]
	s_nop 0
	v_pk_fma_f32 v[0:1], v[22:23], v[82:83], v[0:1]
	s_nop 0
	v_pk_fma_f32 v[0:1], v[24:25], v[78:79], v[0:1]
	s_nop 0
	v_pk_fma_f32 v[0:1], v[26:27], v[76:77], v[0:1]
	s_nop 0
	v_pk_fma_f32 v[0:1], v[28:29], v[74:75], v[0:1]
	s_nop 0
	v_pk_fma_f32 v[0:1], v[30:31], v[80:81], v[0:1]
	s_nop 0
	v_add_f32_e32 v51, v0, v1
	s_waitcnt vmcnt(2)
	v_cvt_scalef32_pk32_f32_fp6 v[0:31], v[38:43], 1.0
	v_pk_mul_f32 v[2:3], v[2:3], v[92:93]
	s_nop 0
	v_pk_fma_f32 v[0:1], v[0:1], v[94:95], v[2:3]
	s_nop 0
	v_pk_fma_f32 v[0:1], v[4:5], v[86:87], v[0:1]
	s_nop 0
	v_pk_fma_f32 v[0:1], v[6:7], v[100:101], v[0:1]
	s_nop 0
	v_pk_fma_f32 v[0:1], v[8:9], v[104:105], v[0:1]
	s_nop 0
	v_pk_fma_f32 v[0:1], v[10:11], v[102:103], v[0:1]
	s_nop 0
	v_pk_fma_f32 v[0:1], v[12:13], v[98:99], v[0:1]
	s_nop 0
	v_pk_fma_f32 v[0:1], v[14:15], v[96:97], v[0:1]
	s_nop 0
	v_pk_fma_f32 v[0:1], v[16:17], v[90:91], v[0:1]
	s_nop 0
	v_pk_fma_f32 v[0:1], v[18:19], v[88:89], v[0:1]
	s_nop 0
	v_pk_fma_f32 v[0:1], v[20:21], v[84:85], v[0:1]
	s_nop 0
	v_pk_fma_f32 v[0:1], v[22:23], v[82:83], v[0:1]
	s_nop 0
	v_pk_fma_f32 v[0:1], v[24:25], v[78:79], v[0:1]
	s_nop 0
	v_pk_fma_f32 v[0:1], v[26:27], v[76:77], v[0:1]
	s_nop 0
	v_pk_fma_f32 v[0:1], v[28:29], v[74:75], v[0:1]
	s_nop 0
	v_pk_fma_f32 v[0:1], v[30:31], v[80:81], v[0:1]
	s_nop 0
	v_add_f32_e32 v52, v0, v1
	s_waitcnt vmcnt(0)
; DI void phase_peer_out(const Params& p, char* lds) {
;     ...
;       for (int kb = 0; kb < 4; ++kb) {
;         v6u qb[8];
; #pragma unroll
;         for (int k = 0; k < 8; ++k) {
;           const int e0 = __builtin_amdgcn_readlane(el[0], hf * 32 + kb * 8 + k), e1 = __builtin_amdgcn_readlane(el[1], hf * 32 + kb * 8 + k);
;           qb[k] = load6(U6 + (size_t)(hb ? e1 : e0) * 768);
;         }
; #pragma unroll
;         for (int k = 0; k < 8; ++k) {
;           const v32f f = __builtin_amdgcn_cvt_scalef32_pk32_f32_fp6(qb[k], 1.0f);
;           f32x2 a = f32x2{f[0], f[1]} * x2[0];
; #pragma unroll
;           for (int i = 1; i < 16; ++i) a = f32x2{f[2 * i], f[2 * i + 1]} * x2[i] + a;
;           pd[kb * 8 + k] = a.x + a.y;
	v_cvt_scalef32_pk32_f32_fp6 v[0:31], v[32:37], 1.0
	v_mov_b32_e32 v32, s13
	v_mov_b32_e32 v33, s12
	v_cndmask_b32_e64 v32, v32, v33, s[0:1]
	v_mad_u32_u24 v32, v32, s23, v251
	global_load_dwordx2 v[140:141], v32, s[98:99] offset:16
	global_load_dwordx4 v[136:139], v32, s[98:99]
	v_pk_mul_f32 v[2:3], v[2:3], v[92:93]
	v_readlane_b32 s12, v106, 9
	v_readlane_b32 s13, v107, 9
	v_pk_fma_f32 v[0:1], v[0:1], v[94:95], v[2:3]
	v_mov_b32_e32 v3, s12
	v_mov_b32_e32 v2, s13
	v_cndmask_b32_e64 v2, v2, v3, s[0:1]
	v_mad_u32_u24 v2, v2, s23, v251
	v_pk_fma_f32 v[0:1], v[4:5], v[86:87], v[0:1]
	global_load_dwordx2 v[146:147], v2, s[98:99] offset:16
	global_load_dwordx4 v[142:145], v2, s[98:99]
	v_pk_fma_f32 v[0:1], v[6:7], v[100:101], v[0:1]
	v_readlane_b32 s12, v106, 10
	v_pk_fma_f32 v[0:1], v[8:9], v[104:105], v[0:1]
	v_readlane_b32 s13, v107, 10
	v_pk_fma_f32 v[0:1], v[10:11], v[102:103], v[0:1]
	s_nop 0
	v_pk_fma_f32 v[0:1], v[12:13], v[98:99], v[0:1]
	s_nop 0
	v_pk_fma_f32 v[0:1], v[14:15], v[96:97], v[0:1]
	s_nop 0
	v_pk_fma_f32 v[0:1], v[16:17], v[90:91], v[0:1]
	s_nop 0
	v_pk_fma_f32 v[0:1], v[18:19], v[88:89], v[0:1]
	s_nop 0
	v_pk_fma_f32 v[0:1], v[20:21], v[84:85], v[0:1]
	s_nop 0
	v_pk_fma_f32 v[0:1], v[22:23], v[82:83], v[0:1]
	s_nop 0
	v_pk_fma_f32 v[0:1], v[24:25], v[78:79], v[0:1]
	s_nop 0
	v_pk_fma_f32 v[0:1], v[26:27], v[76:77], v[0:1]
	s_nop 0
	v_pk_fma_f32 v[0:1], v[28:29], v[74:75], v[0:1]
	s_nop 0
	v_pk_fma_f32 v[0:1], v[30:31], v[80:81], v[0:1]
	s_nop 0
	v_add_f32_e32 v53, v0, v1
	v_mov_b32_e32 v0, s13
	v_mov_b32_e32 v1, s12
	v_cndmask_b32_e64 v0, v0, v1, s[0:1]
	v_mad_u32_u24 v0, v0, s23, v251
	global_load_dwordx2 v[152:153], v0, s[98:99] offset:16
	global_load_dwordx4 v[148:151], v0, s[98:99]
	v_readlane_b32 s12, v106, 11
	v_readlane_b32 s13, v107, 11
	s_nop 0
	v_mov_b32_e32 v1, s12
	v_mov_b32_e32 v0, s13
	v_cndmask_b32_e64 v0, v0, v1, s[0:1]
	v_mad_u32_u24 v0, v0, s23, v251
	global_load_dwordx2 v[158:159], v0, s[98:99] offset:16
	global_load_dwordx4 v[154:157], v0, s[98:99]
	v_readlane_b32 s12, v106, 12
	v_readlane_b32 s13, v107, 12
	s_nop 0
	v_mov_b32_e32 v1, s12
	v_mov_b32_e32 v0, s13
	v_cndmask_b32_e64 v0, v0, v1, s[0:1]
	v_mad_u32_u24 v0, v0, s23, v251
	global_load_dwordx2 v[164:165], v0, s[98:99] offset:16
	global_load_dwordx4 v[160:163], v0, s[98:99]
	v_readlane_b32 s12, v106, 13
	v_readlane_b32 s13, v107, 13
	s_nop 0
	v_mov_b32_e32 v1, s12
	v_mov_b32_e32 v0, s13
	v_cndmask_b32_e64 v0, v0, v1, s[0:1]
	v_mad_u32_u24 v0, v0, s23, v251
	v_readlane_b32 s12, v106, 14
	v_readlane_b32 s13, v107, 14
	global_load_dwordx2 v[48:49], v0, s[98:99] offset:16
	global_load_dwordx4 v[44:47], v0, s[98:99]
	v_mov_b32_e32 v0, s13
	v_mov_b32_e32 v1, s12
	v_cndmask_b32_e64 v0, v0, v1, s[0:1]
	v_mad_u32_u24 v0, v0, s23, v251
	v_readlane_b32 s12, v106, 15
	v_readlane_b32 s13, v107, 15
	global_load_dwordx2 v[42:43], v0, s[98:99] offset:16
	global_load_dwordx4 v[38:41], v0, s[98:99]
	v_mov_b32_e32 v0, s13
	v_mov_b32_e32 v1, s12
	v_cndmask_b32_e64 v0, v0, v1, s[0:1]
	v_mad_u32_u24 v0, v0, s23, v251
	global_load_dwordx2 v[36:37], v0, s[98:99] offset:16
	global_load_dwordx4 v[32:35], v0, s[98:99]
	s_waitcnt vmcnt(14)
	v_cvt_scalef32_pk32_f32_fp6 v[0:31], v[136:141], 1.0
	v_pk_mul_f32 v[2:3], v[2:3], v[92:93]
	v_readlane_b32 s12, v106, 16
	v_pk_fma_f32 v[0:1], v[0:1], v[94:95], v[2:3]
	v_readlane_b32 s13, v107, 16
	v_pk_fma_f32 v[0:1], v[4:5], v[86:87], v[0:1]
	s_nop 0
	v_pk_fma_f32 v[0:1], v[6:7], v[100:101], v[0:1]
	s_nop 0
	v_pk_fma_f32 v[0:1], v[8:9], v[104:105], v[0:1]
	s_nop 0
	v_pk_fma_f32 v[0:1], v[10:11], v[102:103], v[0:1]
	s_nop 0
	v_pk_fma_f32 v[0:1], v[12:13], v[98:99], v[0:1]
	s_nop 0
	v_pk_fma_f32 v[0:1], v[14:15], v[96:97], v[0:1]
	s_nop 0
	v_pk_fma_f32 v[0:1], v[16:17], v[90:91], v[0:1]
	s_nop 0
	v_pk_fma_f32 v[0:1], v[18:19], v[88:89], v[0:1]
	s_nop 0
	v_pk_fma_f32 v[0:1], v[20:21], v[84:85], v[0:1]
	s_nop 0
	v_pk_fma_f32 v[0:1], v[22:23], v[82:83], v[0:1]
	s_nop 0
	v_pk_fma_f32 v[0:1], v[24:25], v[78:79], v[0:1]
	s_nop 0
	v_pk_fma_f32 v[0:1], v[26:27], v[76:77], v[0:1]
	s_nop 0
	v_pk_fma_f32 v[0:1], v[28:29], v[74:75], v[0:1]
	s_nop 0
	v_pk_fma_f32 v[0:1], v[30:31], v[80:81], v[0:1]
	s_nop 0
	v_add_f32_e32 v54, v0, v1
	s_waitcnt vmcnt(12)
	v_cvt_scalef32_pk32_f32_fp6 v[0:31], v[142:147], 1.0
	v_pk_mul_f32 v[2:3], v[2:3], v[92:93]
	s_nop 0
	v_pk_fma_f32 v[0:1], v[0:1], v[94:95], v[2:3]
	s_nop 0
	v_pk_fma_f32 v[0:1], v[4:5], v[86:87], v[0:1]
	s_nop 0
	v_pk_fma_f32 v[0:1], v[6:7], v[100:101], v[0:1]
	s_nop 0
	v_pk_fma_f32 v[0:1], v[8:9], v[104:105], v[0:1]
	s_nop 0
	v_pk_fma_f32 v[0:1], v[10:11], v[102:103], v[0:1]
	s_nop 0
	v_pk_fma_f32 v[0:1], v[12:13], v[98:99], v[0:1]
	s_nop 0
	v_pk_fma_f32 v[0:1], v[14:15], v[96:97], v[0:1]
	s_nop 0
	v_pk_fma_f32 v[0:1], v[16:17], v[90:91], v[0:1]
	s_nop 0
	v_pk_fma_f32 v[0:1], v[18:19], v[88:89], v[0:1]
	s_nop 0
	v_pk_fma_f32 v[0:1], v[20:21], v[84:85], v[0:1]
	s_nop 0
	v_pk_fma_f32 v[0:1], v[22:23], v[82:83], v[0:1]
	s_nop 0
	v_pk_fma_f32 v[0:1], v[24:25], v[78:79], v[0:1]
	s_nop 0
	v_pk_fma_f32 v[0:1], v[26:27], v[76:77], v[0:1]
	s_nop 0
	v_pk_fma_f32 v[0:1], v[28:29], v[74:75], v[0:1]
	s_nop 0
	v_pk_fma_f32 v[0:1], v[30:31], v[80:81], v[0:1]
	s_nop 0
	v_add_f32_e32 v55, v0, v1
	s_waitcnt vmcnt(10)
; DI void phase_peer_out(const Params& p, char* lds) {
;     ...
; #pragma unroll
;         for (int k = 0; k < 8; ++k) {
;           const v32f f = __builtin_amdgcn_cvt_scalef32_pk32_f32_fp6(qb[k], 1.0f);
;           f32x2 a = f32x2{f[0], f[1]} * x2[0];
; #pragma unroll
;           for (int i = 1; i < 16; ++i) a = f32x2{f[2 * i], f[2 * i + 1]} * x2[i] + a;
;           pd[kb * 8 + k] = a.x + a.y;
	v_cvt_scalef32_pk32_f32_fp6 v[0:31], v[148:153], 1.0
	v_pk_mul_f32 v[2:3], v[2:3], v[92:93]
	s_nop 0
	v_pk_fma_f32 v[0:1], v[0:1], v[94:95], v[2:3]
	s_nop 0
	v_pk_fma_f32 v[0:1], v[4:5], v[86:87], v[0:1]
	s_nop 0
	v_pk_fma_f32 v[0:1], v[6:7], v[100:101], v[0:1]
	s_nop 0
	v_pk_fma_f32 v[0:1], v[8:9], v[104:105], v[0:1]
	s_nop 0
	v_pk_fma_f32 v[0:1], v[10:11], v[102:103], v[0:1]
	s_nop 0
	v_pk_fma_f32 v[0:1], v[12:13], v[98:99], v[0:1]
	s_nop 0
	v_pk_fma_f32 v[0:1], v[14:15], v[96:97], v[0:1]
	s_nop 0
	v_pk_fma_f32 v[0:1], v[16:17], v[90:91], v[0:1]
	s_nop 0
	v_pk_fma_f32 v[0:1], v[18:19], v[88:89], v[0:1]
	s_nop 0
	v_pk_fma_f32 v[0:1], v[20:21], v[84:85], v[0:1]
	s_nop 0
	v_pk_fma_f32 v[0:1], v[22:23], v[82:83], v[0:1]
	s_nop 0
	v_pk_fma_f32 v[0:1], v[24:25], v[78:79], v[0:1]
	s_nop 0
	v_pk_fma_f32 v[0:1], v[26:27], v[76:77], v[0:1]
	s_nop 0
	v_pk_fma_f32 v[0:1], v[28:29], v[74:75], v[0:1]
	s_nop 0
	v_pk_fma_f32 v[0:1], v[30:31], v[80:81], v[0:1]
	s_nop 0
	v_add_f32_e32 v135, v0, v1
	s_waitcnt vmcnt(8)
	v_cvt_scalef32_pk32_f32_fp6 v[0:31], v[154:159], 1.0
	v_pk_mul_f32 v[2:3], v[2:3], v[92:93]
	s_nop 0
	v_pk_fma_f32 v[0:1], v[0:1], v[94:95], v[2:3]
	s_nop 0
	v_pk_fma_f32 v[0:1], v[4:5], v[86:87], v[0:1]
	s_nop 0
	v_pk_fma_f32 v[0:1], v[6:7], v[100:101], v[0:1]
	s_nop 0
	v_pk_fma_f32 v[0:1], v[8:9], v[104:105], v[0:1]
	s_nop 0
	v_pk_fma_f32 v[0:1], v[10:11], v[102:103], v[0:1]
	s_nop 0
	v_pk_fma_f32 v[0:1], v[12:13], v[98:99], v[0:1]
	s_nop 0
	v_pk_fma_f32 v[0:1], v[14:15], v[96:97], v[0:1]
	s_nop 0
	v_pk_fma_f32 v[0:1], v[16:17], v[90:91], v[0:1]
	s_nop 0
	v_pk_fma_f32 v[0:1], v[18:19], v[88:89], v[0:1]
	s_nop 0
	v_pk_fma_f32 v[0:1], v[20:21], v[84:85], v[0:1]
	s_nop 0
	v_pk_fma_f32 v[0:1], v[22:23], v[82:83], v[0:1]
	s_nop 0
	v_pk_fma_f32 v[0:1], v[24:25], v[78:79], v[0:1]
	s_nop 0
	v_pk_fma_f32 v[0:1], v[26:27], v[76:77], v[0:1]
	s_nop 0
	v_pk_fma_f32 v[0:1], v[28:29], v[74:75], v[0:1]
	s_nop 0
	v_pk_fma_f32 v[0:1], v[30:31], v[80:81], v[0:1]
	s_nop 0
	v_add_f32_e32 v136, v0, v1
	s_waitcnt vmcnt(6)
	v_cvt_scalef32_pk32_f32_fp6 v[0:31], v[160:165], 1.0
	v_pk_mul_f32 v[2:3], v[2:3], v[92:93]
	s_nop 0
	v_pk_fma_f32 v[0:1], v[0:1], v[94:95], v[2:3]
	s_nop 0
	v_pk_fma_f32 v[0:1], v[4:5], v[86:87], v[0:1]
	s_nop 0
	v_pk_fma_f32 v[0:1], v[6:7], v[100:101], v[0:1]
	s_nop 0
	v_pk_fma_f32 v[0:1], v[8:9], v[104:105], v[0:1]
	s_nop 0
	v_pk_fma_f32 v[0:1], v[10:11], v[102:103], v[0:1]
	s_nop 0
	v_pk_fma_f32 v[0:1], v[12:13], v[98:99], v[0:1]
	s_nop 0
	v_pk_fma_f32 v[0:1], v[14:15], v[96:97], v[0:1]
	s_nop 0
	v_pk_fma_f32 v[0:1], v[16:17], v[90:91], v[0:1]
	s_nop 0
	v_pk_fma_f32 v[0:1], v[18:19], v[88:89], v[0:1]
	s_nop 0
	v_pk_fma_f32 v[0:1], v[20:21], v[84:85], v[0:1]
	s_nop 0
	v_pk_fma_f32 v[0:1], v[22:23], v[82:83], v[0:1]
	s_nop 0
	v_pk_fma_f32 v[0:1], v[24:25], v[78:79], v[0:1]
	s_nop 0
	v_pk_fma_f32 v[0:1], v[26:27], v[76:77], v[0:1]
	s_nop 0
	v_pk_fma_f32 v[0:1], v[28:29], v[74:75], v[0:1]
	s_nop 0
	v_pk_fma_f32 v[0:1], v[30:31], v[80:81], v[0:1]
	s_nop 0
	v_add_f32_e32 v137, v0, v1
	s_waitcnt vmcnt(4)
	v_cvt_scalef32_pk32_f32_fp6 v[0:31], v[44:49], 1.0
	v_pk_mul_f32 v[2:3], v[2:3], v[92:93]
	s_nop 0
	v_pk_fma_f32 v[0:1], v[0:1], v[94:95], v[2:3]
	s_nop 0
	v_pk_fma_f32 v[0:1], v[4:5], v[86:87], v[0:1]
	s_nop 0
	v_pk_fma_f32 v[0:1], v[6:7], v[100:101], v[0:1]
	s_nop 0
	v_pk_fma_f32 v[0:1], v[8:9], v[104:105], v[0:1]
	s_nop 0
	v_pk_fma_f32 v[0:1], v[10:11], v[102:103], v[0:1]
	s_nop 0
	v_pk_fma_f32 v[0:1], v[12:13], v[98:99], v[0:1]
	s_nop 0
	v_pk_fma_f32 v[0:1], v[14:15], v[96:97], v[0:1]
	s_nop 0
	v_pk_fma_f32 v[0:1], v[16:17], v[90:91], v[0:1]
	s_nop 0
	v_pk_fma_f32 v[0:1], v[18:19], v[88:89], v[0:1]
	s_nop 0
	v_pk_fma_f32 v[0:1], v[20:21], v[84:85], v[0:1]
	s_nop 0
	v_pk_fma_f32 v[0:1], v[22:23], v[82:83], v[0:1]
	s_nop 0
	v_pk_fma_f32 v[0:1], v[24:25], v[78:79], v[0:1]
	s_nop 0
	v_pk_fma_f32 v[0:1], v[26:27], v[76:77], v[0:1]
	s_nop 0
	v_pk_fma_f32 v[0:1], v[28:29], v[74:75], v[0:1]
	s_nop 0
	v_pk_fma_f32 v[0:1], v[30:31], v[80:81], v[0:1]
	s_nop 0
	v_add_f32_e32 v138, v0, v1
	s_waitcnt vmcnt(2)
	v_cvt_scalef32_pk32_f32_fp6 v[0:31], v[38:43], 1.0
	v_pk_mul_f32 v[2:3], v[2:3], v[92:93]
	s_nop 0
	v_pk_fma_f32 v[0:1], v[0:1], v[94:95], v[2:3]
	s_nop 0
	v_pk_fma_f32 v[0:1], v[4:5], v[86:87], v[0:1]
	s_nop 0
	v_pk_fma_f32 v[0:1], v[6:7], v[100:101], v[0:1]
	s_nop 0
	v_pk_fma_f32 v[0:1], v[8:9], v[104:105], v[0:1]
	s_nop 0
	v_pk_fma_f32 v[0:1], v[10:11], v[102:103], v[0:1]
	s_nop 0
	v_pk_fma_f32 v[0:1], v[12:13], v[98:99], v[0:1]
	s_nop 0
	v_pk_fma_f32 v[0:1], v[14:15], v[96:97], v[0:1]
	s_nop 0
	v_pk_fma_f32 v[0:1], v[16:17], v[90:91], v[0:1]
	s_nop 0
	v_pk_fma_f32 v[0:1], v[18:19], v[88:89], v[0:1]
	s_nop 0
	v_pk_fma_f32 v[0:1], v[20:21], v[84:85], v[0:1]
	s_nop 0
	v_pk_fma_f32 v[0:1], v[22:23], v[82:83], v[0:1]
	s_nop 0
	v_pk_fma_f32 v[0:1], v[24:25], v[78:79], v[0:1]
	s_nop 0
	v_pk_fma_f32 v[0:1], v[26:27], v[76:77], v[0:1]
	s_nop 0
	v_pk_fma_f32 v[0:1], v[28:29], v[74:75], v[0:1]
	s_nop 0
	v_pk_fma_f32 v[0:1], v[30:31], v[80:81], v[0:1]
	s_nop 0
	v_add_f32_e32 v139, v0, v1
	s_waitcnt vmcnt(0)
; DI void phase_peer_out(const Params& p, char* lds) {
;     ...
;       for (int kb = 0; kb < 4; ++kb) {
;         v6u qb[8];
; #pragma unroll
;         for (int k = 0; k < 8; ++k) {
;           const int e0 = __builtin_amdgcn_readlane(el[0], hf * 32 + kb * 8 + k), e1 = __builtin_amdgcn_readlane(el[1], hf * 32 + kb * 8 + k);
;           qb[k] = load6(U6 + (size_t)(hb ? e1 : e0) * 768);
;         }
; #pragma unroll
;         for (int k = 0; k < 8; ++k) {
;           const v32f f = __builtin_amdgcn_cvt_scalef32_pk32_f32_fp6(qb[k], 1.0f);
;           f32x2 a = f32x2{f[0], f[1]} * x2[0];
; #pragma unroll
;           for (int i = 1; i < 16; ++i) a = f32x2{f[2 * i], f[2 * i + 1]} * x2[i] + a;
;           pd[kb * 8 + k] = a.x + a.y;
	v_cvt_scalef32_pk32_f32_fp6 v[0:31], v[32:37], 1.0
	v_mov_b32_e32 v32, s13
	v_mov_b32_e32 v33, s12
	v_cndmask_b32_e64 v32, v32, v33, s[0:1]
	v_mad_u32_u24 v32, v32, s23, v251
	global_load_dwordx2 v[146:147], v32, s[98:99] offset:16
	global_load_dwordx4 v[142:145], v32, s[98:99]
	v_pk_mul_f32 v[2:3], v[2:3], v[92:93]
	v_readlane_b32 s12, v106, 17
	v_readlane_b32 s13, v107, 17
	v_pk_fma_f32 v[0:1], v[0:1], v[94:95], v[2:3]
	v_mov_b32_e32 v3, s12
	v_mov_b32_e32 v2, s13
	v_cndmask_b32_e64 v2, v2, v3, s[0:1]
	v_mad_u32_u24 v2, v2, s23, v251
	v_pk_fma_f32 v[0:1], v[4:5], v[86:87], v[0:1]
	global_load_dwordx2 v[152:153], v2, s[98:99] offset:16
	global_load_dwordx4 v[148:151], v2, s[98:99]
	v_pk_fma_f32 v[0:1], v[6:7], v[100:101], v[0:1]
	v_readlane_b32 s12, v106, 18
	v_pk_fma_f32 v[0:1], v[8:9], v[104:105], v[0:1]
	v_readlane_b32 s13, v107, 18
	v_pk_fma_f32 v[0:1], v[10:11], v[102:103], v[0:1]
	s_nop 0
	v_pk_fma_f32 v[0:1], v[12:13], v[98:99], v[0:1]
	s_nop 0
	v_pk_fma_f32 v[0:1], v[14:15], v[96:97], v[0:1]
	s_nop 0
	v_pk_fma_f32 v[0:1], v[16:17], v[90:91], v[0:1]
	s_nop 0
	v_pk_fma_f32 v[0:1], v[18:19], v[88:89], v[0:1]
	s_nop 0
	v_pk_fma_f32 v[0:1], v[20:21], v[84:85], v[0:1]
	s_nop 0
	v_pk_fma_f32 v[0:1], v[22:23], v[82:83], v[0:1]
	s_nop 0
	v_pk_fma_f32 v[0:1], v[24:25], v[78:79], v[0:1]
	s_nop 0
	v_pk_fma_f32 v[0:1], v[26:27], v[76:77], v[0:1]
	s_nop 0
	v_pk_fma_f32 v[0:1], v[28:29], v[74:75], v[0:1]
	s_nop 0
	v_pk_fma_f32 v[0:1], v[30:31], v[80:81], v[0:1]
	s_nop 0
	v_add_f32_e32 v140, v0, v1
	v_mov_b32_e32 v0, s13
	v_mov_b32_e32 v1, s12
	v_cndmask_b32_e64 v0, v0, v1, s[0:1]
	v_mad_u32_u24 v0, v0, s23, v251
	global_load_dwordx2 v[158:159], v0, s[98:99] offset:16
	global_load_dwordx4 v[154:157], v0, s[98:99]
	v_readlane_b32 s12, v106, 19
	v_readlane_b32 s13, v107, 19
	s_nop 0
	v_mov_b32_e32 v1, s12
	v_mov_b32_e32 v0, s13
	v_cndmask_b32_e64 v0, v0, v1, s[0:1]
	v_mad_u32_u24 v0, v0, s23, v251
	global_load_dwordx2 v[164:165], v0, s[98:99] offset:16
	global_load_dwordx4 v[160:163], v0, s[98:99]
	v_readlane_b32 s12, v106, 20
	v_readlane_b32 s13, v107, 20
	s_nop 0
	v_mov_b32_e32 v1, s12
	v_mov_b32_e32 v0, s13
	v_cndmask_b32_e64 v0, v0, v1, s[0:1]
	v_mad_u32_u24 v0, v0, s23, v251
	global_load_dwordx2 v[170:171], v0, s[98:99] offset:16
	global_load_dwordx4 v[166:169], v0, s[98:99]
	v_readlane_b32 s12, v106, 21
	v_readlane_b32 s13, v107, 21
	s_nop 0
	v_mov_b32_e32 v1, s12
	v_mov_b32_e32 v0, s13
	v_cndmask_b32_e64 v0, v0, v1, s[0:1]
	v_mad_u32_u24 v0, v0, s23, v251
	v_readlane_b32 s12, v106, 22
	v_readlane_b32 s13, v107, 22
	global_load_dwordx2 v[48:49], v0, s[98:99] offset:16
	global_load_dwordx4 v[44:47], v0, s[98:99]
	v_mov_b32_e32 v0, s13
	v_mov_b32_e32 v1, s12
	v_cndmask_b32_e64 v0, v0, v1, s[0:1]
	v_mad_u32_u24 v0, v0, s23, v251
	v_readlane_b32 s12, v106, 23
	v_readlane_b32 s13, v107, 23
	global_load_dwordx2 v[42:43], v0, s[98:99] offset:16
	global_load_dwordx4 v[38:41], v0, s[98:99]
	v_mov_b32_e32 v0, s13
	v_mov_b32_e32 v1, s12
	v_cndmask_b32_e64 v0, v0, v1, s[0:1]
	v_mad_u32_u24 v0, v0, s23, v251
	global_load_dwordx2 v[36:37], v0, s[98:99] offset:16
	global_load_dwordx4 v[32:35], v0, s[98:99]
	s_waitcnt vmcnt(14)
	v_cvt_scalef32_pk32_f32_fp6 v[0:31], v[142:147], 1.0
	v_pk_mul_f32 v[2:3], v[2:3], v[92:93]
	v_readlane_b32 s12, v106, 24
	v_pk_fma_f32 v[0:1], v[0:1], v[94:95], v[2:3]
	v_readlane_b32 s13, v107, 24
	v_pk_fma_f32 v[0:1], v[4:5], v[86:87], v[0:1]
	s_nop 0
	v_pk_fma_f32 v[0:1], v[6:7], v[100:101], v[0:1]
	s_nop 0
	v_pk_fma_f32 v[0:1], v[8:9], v[104:105], v[0:1]
	s_nop 0
	v_pk_fma_f32 v[0:1], v[10:11], v[102:103], v[0:1]
	s_nop 0
	v_pk_fma_f32 v[0:1], v[12:13], v[98:99], v[0:1]
	s_nop 0
	v_pk_fma_f32 v[0:1], v[14:15], v[96:97], v[0:1]
	s_nop 0
	v_pk_fma_f32 v[0:1], v[16:17], v[90:91], v[0:1]
	s_nop 0
	v_pk_fma_f32 v[0:1], v[18:19], v[88:89], v[0:1]
	s_nop 0
	v_pk_fma_f32 v[0:1], v[20:21], v[84:85], v[0:1]
	s_nop 0
	v_pk_fma_f32 v[0:1], v[22:23], v[82:83], v[0:1]
	s_nop 0
	v_pk_fma_f32 v[0:1], v[24:25], v[78:79], v[0:1]
	s_nop 0
	v_pk_fma_f32 v[0:1], v[26:27], v[76:77], v[0:1]
	s_nop 0
	v_pk_fma_f32 v[0:1], v[28:29], v[74:75], v[0:1]
	s_nop 0
	v_pk_fma_f32 v[0:1], v[30:31], v[80:81], v[0:1]
	s_nop 0
	v_add_f32_e32 v141, v0, v1
	s_waitcnt vmcnt(12)
	v_cvt_scalef32_pk32_f32_fp6 v[0:31], v[148:153], 1.0
	v_pk_mul_f32 v[2:3], v[2:3], v[92:93]
	s_nop 0
	v_pk_fma_f32 v[0:1], v[0:1], v[94:95], v[2:3]
	s_nop 0
	v_pk_fma_f32 v[0:1], v[4:5], v[86:87], v[0:1]
	s_nop 0
	v_pk_fma_f32 v[0:1], v[6:7], v[100:101], v[0:1]
	s_nop 0
	v_pk_fma_f32 v[0:1], v[8:9], v[104:105], v[0:1]
	s_nop 0
	v_pk_fma_f32 v[0:1], v[10:11], v[102:103], v[0:1]
	s_nop 0
	v_pk_fma_f32 v[0:1], v[12:13], v[98:99], v[0:1]
	s_nop 0
	v_pk_fma_f32 v[0:1], v[14:15], v[96:97], v[0:1]
	s_nop 0
	v_pk_fma_f32 v[0:1], v[16:17], v[90:91], v[0:1]
	s_nop 0
	v_pk_fma_f32 v[0:1], v[18:19], v[88:89], v[0:1]
	s_nop 0
	v_pk_fma_f32 v[0:1], v[20:21], v[84:85], v[0:1]
	s_nop 0
	v_pk_fma_f32 v[0:1], v[22:23], v[82:83], v[0:1]
	s_nop 0
	v_pk_fma_f32 v[0:1], v[24:25], v[78:79], v[0:1]
	s_nop 0
	v_pk_fma_f32 v[0:1], v[26:27], v[76:77], v[0:1]
	s_nop 0
	v_pk_fma_f32 v[0:1], v[28:29], v[74:75], v[0:1]
	s_nop 0
	v_pk_fma_f32 v[0:1], v[30:31], v[80:81], v[0:1]
	s_nop 0
	v_add_f32_e32 v142, v0, v1
	s_waitcnt vmcnt(10)
; DI void phase_peer_out(const Params& p, char* lds) {
;     ...
; #pragma unroll
;         for (int k = 0; k < 8; ++k) {
;           const v32f f = __builtin_amdgcn_cvt_scalef32_pk32_f32_fp6(qb[k], 1.0f);
;           f32x2 a = f32x2{f[0], f[1]} * x2[0];
; #pragma unroll
;           for (int i = 1; i < 16; ++i) a = f32x2{f[2 * i], f[2 * i + 1]} * x2[i] + a;
;           pd[kb * 8 + k] = a.x + a.y;
	v_cvt_scalef32_pk32_f32_fp6 v[0:31], v[154:159], 1.0
	v_pk_mul_f32 v[2:3], v[2:3], v[92:93]
	s_nop 0
	v_pk_fma_f32 v[0:1], v[0:1], v[94:95], v[2:3]
	s_nop 0
	v_pk_fma_f32 v[0:1], v[4:5], v[86:87], v[0:1]
	s_nop 0
	v_pk_fma_f32 v[0:1], v[6:7], v[100:101], v[0:1]
	s_nop 0
	v_pk_fma_f32 v[0:1], v[8:9], v[104:105], v[0:1]
	s_nop 0
	v_pk_fma_f32 v[0:1], v[10:11], v[102:103], v[0:1]
	s_nop 0
	v_pk_fma_f32 v[0:1], v[12:13], v[98:99], v[0:1]
	s_nop 0
	v_pk_fma_f32 v[0:1], v[14:15], v[96:97], v[0:1]
	s_nop 0
	v_pk_fma_f32 v[0:1], v[16:17], v[90:91], v[0:1]
	s_nop 0
	v_pk_fma_f32 v[0:1], v[18:19], v[88:89], v[0:1]
	s_nop 0
	v_pk_fma_f32 v[0:1], v[20:21], v[84:85], v[0:1]
	s_nop 0
	v_pk_fma_f32 v[0:1], v[22:23], v[82:83], v[0:1]
	s_nop 0
	v_pk_fma_f32 v[0:1], v[24:25], v[78:79], v[0:1]
	s_nop 0
	v_pk_fma_f32 v[0:1], v[26:27], v[76:77], v[0:1]
	s_nop 0
	v_pk_fma_f32 v[0:1], v[28:29], v[74:75], v[0:1]
	s_nop 0
	v_pk_fma_f32 v[0:1], v[30:31], v[80:81], v[0:1]
	s_nop 0
	v_add_f32_e32 v143, v0, v1
	s_waitcnt vmcnt(8)
	v_cvt_scalef32_pk32_f32_fp6 v[0:31], v[160:165], 1.0
	v_pk_mul_f32 v[2:3], v[2:3], v[92:93]
	s_nop 0
	v_pk_fma_f32 v[0:1], v[0:1], v[94:95], v[2:3]
	s_nop 0
	v_pk_fma_f32 v[0:1], v[4:5], v[86:87], v[0:1]
	s_nop 0
	v_pk_fma_f32 v[0:1], v[6:7], v[100:101], v[0:1]
	s_nop 0
	v_pk_fma_f32 v[0:1], v[8:9], v[104:105], v[0:1]
	s_nop 0
	v_pk_fma_f32 v[0:1], v[10:11], v[102:103], v[0:1]
	s_nop 0
	v_pk_fma_f32 v[0:1], v[12:13], v[98:99], v[0:1]
	s_nop 0
	v_pk_fma_f32 v[0:1], v[14:15], v[96:97], v[0:1]
	s_nop 0
	v_pk_fma_f32 v[0:1], v[16:17], v[90:91], v[0:1]
	s_nop 0
	v_pk_fma_f32 v[0:1], v[18:19], v[88:89], v[0:1]
	s_nop 0
	v_pk_fma_f32 v[0:1], v[20:21], v[84:85], v[0:1]
	s_nop 0
	v_pk_fma_f32 v[0:1], v[22:23], v[82:83], v[0:1]
	s_nop 0
	v_pk_fma_f32 v[0:1], v[24:25], v[78:79], v[0:1]
	s_nop 0
	v_pk_fma_f32 v[0:1], v[26:27], v[76:77], v[0:1]
	s_nop 0
	v_pk_fma_f32 v[0:1], v[28:29], v[74:75], v[0:1]
	s_nop 0
	v_pk_fma_f32 v[0:1], v[30:31], v[80:81], v[0:1]
	s_nop 0
	v_add_f32_e32 v144, v0, v1
	s_waitcnt vmcnt(6)
	v_cvt_scalef32_pk32_f32_fp6 v[0:31], v[166:171], 1.0
	v_pk_mul_f32 v[2:3], v[2:3], v[92:93]
	s_nop 0
	v_pk_fma_f32 v[0:1], v[0:1], v[94:95], v[2:3]
	s_nop 0
	v_pk_fma_f32 v[0:1], v[4:5], v[86:87], v[0:1]
	s_nop 0
	v_pk_fma_f32 v[0:1], v[6:7], v[100:101], v[0:1]
	s_nop 0
	v_pk_fma_f32 v[0:1], v[8:9], v[104:105], v[0:1]
	s_nop 0
	v_pk_fma_f32 v[0:1], v[10:11], v[102:103], v[0:1]
	s_nop 0
	v_pk_fma_f32 v[0:1], v[12:13], v[98:99], v[0:1]
	s_nop 0
	v_pk_fma_f32 v[0:1], v[14:15], v[96:97], v[0:1]
	s_nop 0
	v_pk_fma_f32 v[0:1], v[16:17], v[90:91], v[0:1]
	s_nop 0
	v_pk_fma_f32 v[0:1], v[18:19], v[88:89], v[0:1]
	s_nop 0
	v_pk_fma_f32 v[0:1], v[20:21], v[84:85], v[0:1]
	s_nop 0
	v_pk_fma_f32 v[0:1], v[22:23], v[82:83], v[0:1]
	s_nop 0
	v_pk_fma_f32 v[0:1], v[24:25], v[78:79], v[0:1]
	s_nop 0
	v_pk_fma_f32 v[0:1], v[26:27], v[76:77], v[0:1]
	s_nop 0
	v_pk_fma_f32 v[0:1], v[28:29], v[74:75], v[0:1]
	s_nop 0
	v_pk_fma_f32 v[0:1], v[30:31], v[80:81], v[0:1]
	s_nop 0
	v_add_f32_e32 v145, v0, v1
	s_waitcnt vmcnt(4)
	v_cvt_scalef32_pk32_f32_fp6 v[0:31], v[44:49], 1.0
	v_pk_mul_f32 v[2:3], v[2:3], v[92:93]
	s_nop 0
	v_pk_fma_f32 v[0:1], v[0:1], v[94:95], v[2:3]
	s_nop 0
	v_pk_fma_f32 v[0:1], v[4:5], v[86:87], v[0:1]
	s_nop 0
	v_pk_fma_f32 v[0:1], v[6:7], v[100:101], v[0:1]
	s_nop 0
	v_pk_fma_f32 v[0:1], v[8:9], v[104:105], v[0:1]
	s_nop 0
	v_pk_fma_f32 v[0:1], v[10:11], v[102:103], v[0:1]
	s_nop 0
	v_pk_fma_f32 v[0:1], v[12:13], v[98:99], v[0:1]
	s_nop 0
	v_pk_fma_f32 v[0:1], v[14:15], v[96:97], v[0:1]
	s_nop 0
	v_pk_fma_f32 v[0:1], v[16:17], v[90:91], v[0:1]
	s_nop 0
	v_pk_fma_f32 v[0:1], v[18:19], v[88:89], v[0:1]
	s_nop 0
	v_pk_fma_f32 v[0:1], v[20:21], v[84:85], v[0:1]
	s_nop 0
	v_pk_fma_f32 v[0:1], v[22:23], v[82:83], v[0:1]
	s_nop 0
	v_pk_fma_f32 v[0:1], v[24:25], v[78:79], v[0:1]
	s_nop 0
	v_pk_fma_f32 v[0:1], v[26:27], v[76:77], v[0:1]
	s_nop 0
	v_pk_fma_f32 v[0:1], v[28:29], v[74:75], v[0:1]
	s_nop 0
	v_pk_fma_f32 v[0:1], v[30:31], v[80:81], v[0:1]
	s_nop 0
	v_add_f32_e32 v146, v0, v1
	s_waitcnt vmcnt(2)
	v_cvt_scalef32_pk32_f32_fp6 v[0:31], v[38:43], 1.0
	v_pk_mul_f32 v[2:3], v[2:3], v[92:93]
	s_nop 0
	v_pk_fma_f32 v[0:1], v[0:1], v[94:95], v[2:3]
	s_nop 0
	v_pk_fma_f32 v[0:1], v[4:5], v[86:87], v[0:1]
	s_nop 0
	v_pk_fma_f32 v[0:1], v[6:7], v[100:101], v[0:1]
	s_nop 0
	v_pk_fma_f32 v[0:1], v[8:9], v[104:105], v[0:1]
	s_nop 0
	v_pk_fma_f32 v[0:1], v[10:11], v[102:103], v[0:1]
	s_nop 0
	v_pk_fma_f32 v[0:1], v[12:13], v[98:99], v[0:1]
	s_nop 0
	v_pk_fma_f32 v[0:1], v[14:15], v[96:97], v[0:1]
	s_nop 0
	v_pk_fma_f32 v[0:1], v[16:17], v[90:91], v[0:1]
	s_nop 0
	v_pk_fma_f32 v[0:1], v[18:19], v[88:89], v[0:1]
	s_nop 0
	v_pk_fma_f32 v[0:1], v[20:21], v[84:85], v[0:1]
	s_nop 0
	v_pk_fma_f32 v[0:1], v[22:23], v[82:83], v[0:1]
	s_nop 0
	v_pk_fma_f32 v[0:1], v[24:25], v[78:79], v[0:1]
	s_nop 0
	v_pk_fma_f32 v[0:1], v[26:27], v[76:77], v[0:1]
	s_nop 0
	v_pk_fma_f32 v[0:1], v[28:29], v[74:75], v[0:1]
	s_nop 0
	v_pk_fma_f32 v[0:1], v[30:31], v[80:81], v[0:1]
	s_nop 0
	v_add_f32_e32 v147, v0, v1
	s_waitcnt vmcnt(0)
; DI void phase_peer_out(const Params& p, char* lds) {
;     ...
;       for (int kb = 0; kb < 4; ++kb) {
;         v6u qb[8];
; #pragma unroll
;         for (int k = 0; k < 8; ++k) {
;           const int e0 = __builtin_amdgcn_readlane(el[0], hf * 32 + kb * 8 + k), e1 = __builtin_amdgcn_readlane(el[1], hf * 32 + kb * 8 + k);
;           qb[k] = load6(U6 + (size_t)(hb ? e1 : e0) * 768);
;         }
; #pragma unroll
;         for (int k = 0; k < 8; ++k) {
;           const v32f f = __builtin_amdgcn_cvt_scalef32_pk32_f32_fp6(qb[k], 1.0f);
;           f32x2 a = f32x2{f[0], f[1]} * x2[0];
; #pragma unroll
;           for (int i = 1; i < 16; ++i) a = f32x2{f[2 * i], f[2 * i + 1]} * x2[i] + a;
;           pd[kb * 8 + k] = a.x + a.y;
	v_cvt_scalef32_pk32_f32_fp6 v[0:31], v[32:37], 1.0
	v_mov_b32_e32 v32, s13
	v_mov_b32_e32 v33, s12
	v_cndmask_b32_e64 v32, v32, v33, s[0:1]
	v_mad_u32_u24 v32, v32, s23, v251
	global_load_dwordx2 v[154:155], v32, s[98:99] offset:16
	global_load_dwordx4 v[150:153], v32, s[98:99]
	v_pk_mul_f32 v[2:3], v[2:3], v[92:93]
	v_readlane_b32 s12, v106, 25
	v_readlane_b32 s13, v107, 25
	v_pk_fma_f32 v[0:1], v[0:1], v[94:95], v[2:3]
	v_mov_b32_e32 v3, s12
	v_mov_b32_e32 v2, s13
	v_cndmask_b32_e64 v2, v2, v3, s[0:1]
	v_mad_u32_u24 v2, v2, s23, v251
	v_pk_fma_f32 v[0:1], v[4:5], v[86:87], v[0:1]
	global_load_dwordx2 v[160:161], v2, s[98:99] offset:16
	global_load_dwordx4 v[156:159], v2, s[98:99]
	v_pk_fma_f32 v[0:1], v[6:7], v[100:101], v[0:1]
	v_readlane_b32 s12, v106, 26
	v_pk_fma_f32 v[0:1], v[8:9], v[104:105], v[0:1]
	v_readlane_b32 s13, v107, 26
	v_pk_fma_f32 v[0:1], v[10:11], v[102:103], v[0:1]
	s_nop 0
	v_pk_fma_f32 v[0:1], v[12:13], v[98:99], v[0:1]
	s_nop 0
	v_pk_fma_f32 v[0:1], v[14:15], v[96:97], v[0:1]
	s_nop 0
	v_pk_fma_f32 v[0:1], v[16:17], v[90:91], v[0:1]
	s_nop 0
	v_pk_fma_f32 v[0:1], v[18:19], v[88:89], v[0:1]
	s_nop 0
	v_pk_fma_f32 v[0:1], v[20:21], v[84:85], v[0:1]
	s_nop 0
	v_pk_fma_f32 v[0:1], v[22:23], v[82:83], v[0:1]
	s_nop 0
	v_pk_fma_f32 v[0:1], v[24:25], v[78:79], v[0:1]
	s_nop 0
	v_pk_fma_f32 v[0:1], v[26:27], v[76:77], v[0:1]
	s_nop 0
	v_pk_fma_f32 v[0:1], v[28:29], v[74:75], v[0:1]
	s_nop 0
	v_pk_fma_f32 v[0:1], v[30:31], v[80:81], v[0:1]
	s_nop 0
	v_add_f32_e32 v148, v0, v1
	v_mov_b32_e32 v0, s13
	v_mov_b32_e32 v1, s12
	v_cndmask_b32_e64 v0, v0, v1, s[0:1]
	v_mad_u32_u24 v0, v0, s23, v251
	global_load_dwordx2 v[166:167], v0, s[98:99] offset:16
	global_load_dwordx4 v[162:165], v0, s[98:99]
	v_readlane_b32 s12, v106, 27
	v_readlane_b32 s13, v107, 27
	s_nop 0
	v_mov_b32_e32 v1, s12
	v_mov_b32_e32 v0, s13
	v_cndmask_b32_e64 v0, v0, v1, s[0:1]
	v_mad_u32_u24 v0, v0, s23, v251
	global_load_dwordx2 v[172:173], v0, s[98:99] offset:16
	global_load_dwordx4 v[168:171], v0, s[98:99]
	v_readlane_b32 s12, v106, 28
	v_readlane_b32 s13, v107, 28
	s_nop 0
	v_mov_b32_e32 v1, s12
	v_mov_b32_e32 v0, s13
	v_cndmask_b32_e64 v0, v0, v1, s[0:1]
	v_mad_u32_u24 v0, v0, s23, v251
	global_load_dwordx2 v[178:179], v0, s[98:99] offset:16
	global_load_dwordx4 v[174:177], v0, s[98:99]
	v_readlane_b32 s12, v106, 29
	v_readlane_b32 s13, v107, 29
	s_nop 0
	v_mov_b32_e32 v1, s12
	v_mov_b32_e32 v0, s13
	v_cndmask_b32_e64 v0, v0, v1, s[0:1]
	v_mad_u32_u24 v0, v0, s23, v251
	v_readlane_b32 s12, v106, 30
	v_readlane_b32 s13, v107, 30
	global_load_dwordx2 v[48:49], v0, s[98:99] offset:16
	global_load_dwordx4 v[44:47], v0, s[98:99]
	v_mov_b32_e32 v0, s13
	v_mov_b32_e32 v1, s12
	v_cndmask_b32_e64 v0, v0, v1, s[0:1]
	v_mad_u32_u24 v0, v0, s23, v251
	v_readlane_b32 s12, v106, 31
	v_readlane_b32 s13, v107, 31
	global_load_dwordx2 v[42:43], v0, s[98:99] offset:16
	global_load_dwordx4 v[38:41], v0, s[98:99]
	v_mov_b32_e32 v0, s13
	v_mov_b32_e32 v1, s12
	v_cndmask_b32_e64 v0, v0, v1, s[0:1]
	v_mad_u32_u24 v0, v0, s23, v251
	global_load_dwordx2 v[36:37], v0, s[98:99] offset:16
	global_load_dwordx4 v[32:35], v0, s[98:99]
	s_waitcnt vmcnt(14)
	v_cvt_scalef32_pk32_f32_fp6 v[0:31], v[150:155], 1.0
	v_pk_mul_f32 v[2:3], v[2:3], v[92:93]
	v_readlane_b32 s12, v106, 32
	v_pk_fma_f32 v[0:1], v[0:1], v[94:95], v[2:3]
	v_readlane_b32 s13, v107, 32
	v_pk_fma_f32 v[0:1], v[4:5], v[86:87], v[0:1]
	s_nop 0
	v_pk_fma_f32 v[0:1], v[6:7], v[100:101], v[0:1]
	s_nop 0
	v_pk_fma_f32 v[0:1], v[8:9], v[104:105], v[0:1]
	s_nop 0
	v_pk_fma_f32 v[0:1], v[10:11], v[102:103], v[0:1]
	s_nop 0
	v_pk_fma_f32 v[0:1], v[12:13], v[98:99], v[0:1]
	s_nop 0
	v_pk_fma_f32 v[0:1], v[14:15], v[96:97], v[0:1]
	s_nop 0
	v_pk_fma_f32 v[0:1], v[16:17], v[90:91], v[0:1]
	s_nop 0
	v_pk_fma_f32 v[0:1], v[18:19], v[88:89], v[0:1]
	s_nop 0
	v_pk_fma_f32 v[0:1], v[20:21], v[84:85], v[0:1]
	s_nop 0
	v_pk_fma_f32 v[0:1], v[22:23], v[82:83], v[0:1]
	s_nop 0
	v_pk_fma_f32 v[0:1], v[24:25], v[78:79], v[0:1]
	s_nop 0
	v_pk_fma_f32 v[0:1], v[26:27], v[76:77], v[0:1]
	s_nop 0
	v_pk_fma_f32 v[0:1], v[28:29], v[74:75], v[0:1]
	s_nop 0
	v_pk_fma_f32 v[0:1], v[30:31], v[80:81], v[0:1]
	s_nop 0
	v_add_f32_e32 v149, v0, v1
	s_waitcnt vmcnt(12)
	v_cvt_scalef32_pk32_f32_fp6 v[0:31], v[156:161], 1.0
	v_pk_mul_f32 v[2:3], v[2:3], v[92:93]
	s_nop 0
	v_pk_fma_f32 v[0:1], v[0:1], v[94:95], v[2:3]
	s_nop 0
	v_pk_fma_f32 v[0:1], v[4:5], v[86:87], v[0:1]
	s_nop 0
	v_pk_fma_f32 v[0:1], v[6:7], v[100:101], v[0:1]
	s_nop 0
	v_pk_fma_f32 v[0:1], v[8:9], v[104:105], v[0:1]
	s_nop 0
	v_pk_fma_f32 v[0:1], v[10:11], v[102:103], v[0:1]
	s_nop 0
	v_pk_fma_f32 v[0:1], v[12:13], v[98:99], v[0:1]
	s_nop 0
	v_pk_fma_f32 v[0:1], v[14:15], v[96:97], v[0:1]
	s_nop 0
	v_pk_fma_f32 v[0:1], v[16:17], v[90:91], v[0:1]
	s_nop 0
	v_pk_fma_f32 v[0:1], v[18:19], v[88:89], v[0:1]
	s_nop 0
	v_pk_fma_f32 v[0:1], v[20:21], v[84:85], v[0:1]
	s_nop 0
	v_pk_fma_f32 v[0:1], v[22:23], v[82:83], v[0:1]
	s_nop 0
	v_pk_fma_f32 v[0:1], v[24:25], v[78:79], v[0:1]
	s_nop 0
	v_pk_fma_f32 v[0:1], v[26:27], v[76:77], v[0:1]
	s_nop 0
	v_pk_fma_f32 v[0:1], v[28:29], v[74:75], v[0:1]
	s_nop 0
	v_pk_fma_f32 v[0:1], v[30:31], v[80:81], v[0:1]
	s_nop 0
	v_add_f32_e32 v150, v0, v1
	s_waitcnt vmcnt(10)
; DI void phase_peer_out(const Params& p, char* lds) {
;     ...
; #pragma unroll
;         for (int k = 0; k < 8; ++k) {
;           const v32f f = __builtin_amdgcn_cvt_scalef32_pk32_f32_fp6(qb[k], 1.0f);
;           f32x2 a = f32x2{f[0], f[1]} * x2[0];
; #pragma unroll
;           for (int i = 1; i < 16; ++i) a = f32x2{f[2 * i], f[2 * i + 1]} * x2[i] + a;
;           pd[kb * 8 + k] = a.x + a.y;
	v_cvt_scalef32_pk32_f32_fp6 v[0:31], v[162:167], 1.0
	v_pk_mul_f32 v[2:3], v[2:3], v[92:93]
	s_nop 0
	v_pk_fma_f32 v[0:1], v[0:1], v[94:95], v[2:3]
	s_nop 0
	v_pk_fma_f32 v[0:1], v[4:5], v[86:87], v[0:1]
	s_nop 0
	v_pk_fma_f32 v[0:1], v[6:7], v[100:101], v[0:1]
	s_nop 0
	v_pk_fma_f32 v[0:1], v[8:9], v[104:105], v[0:1]
	s_nop 0
	v_pk_fma_f32 v[0:1], v[10:11], v[102:103], v[0:1]
	s_nop 0
	v_pk_fma_f32 v[0:1], v[12:13], v[98:99], v[0:1]
	s_nop 0
	v_pk_fma_f32 v[0:1], v[14:15], v[96:97], v[0:1]
	s_nop 0
	v_pk_fma_f32 v[0:1], v[16:17], v[90:91], v[0:1]
	s_nop 0
	v_pk_fma_f32 v[0:1], v[18:19], v[88:89], v[0:1]
	s_nop 0
	v_pk_fma_f32 v[0:1], v[20:21], v[84:85], v[0:1]
	s_nop 0
	v_pk_fma_f32 v[0:1], v[22:23], v[82:83], v[0:1]
	s_nop 0
	v_pk_fma_f32 v[0:1], v[24:25], v[78:79], v[0:1]
	s_nop 0
	v_pk_fma_f32 v[0:1], v[26:27], v[76:77], v[0:1]
	s_nop 0
	v_pk_fma_f32 v[0:1], v[28:29], v[74:75], v[0:1]
	s_nop 0
	v_pk_fma_f32 v[0:1], v[30:31], v[80:81], v[0:1]
	s_nop 0
	v_add_f32_e32 v151, v0, v1
	s_waitcnt vmcnt(8)
	v_cvt_scalef32_pk32_f32_fp6 v[0:31], v[168:173], 1.0
	v_pk_mul_f32 v[2:3], v[2:3], v[92:93]
	s_nop 0
	v_pk_fma_f32 v[0:1], v[0:1], v[94:95], v[2:3]
	s_nop 0
	v_pk_fma_f32 v[0:1], v[4:5], v[86:87], v[0:1]
	s_nop 0
	v_pk_fma_f32 v[0:1], v[6:7], v[100:101], v[0:1]
	s_nop 0
	v_pk_fma_f32 v[0:1], v[8:9], v[104:105], v[0:1]
	s_nop 0
	v_pk_fma_f32 v[0:1], v[10:11], v[102:103], v[0:1]
	s_nop 0
	v_pk_fma_f32 v[0:1], v[12:13], v[98:99], v[0:1]
	s_nop 0
	v_pk_fma_f32 v[0:1], v[14:15], v[96:97], v[0:1]
	s_nop 0
	v_pk_fma_f32 v[0:1], v[16:17], v[90:91], v[0:1]
	s_nop 0
	v_pk_fma_f32 v[0:1], v[18:19], v[88:89], v[0:1]
	s_nop 0
	v_pk_fma_f32 v[0:1], v[20:21], v[84:85], v[0:1]
	s_nop 0
	v_pk_fma_f32 v[0:1], v[22:23], v[82:83], v[0:1]
	s_nop 0
	v_pk_fma_f32 v[0:1], v[24:25], v[78:79], v[0:1]
	s_nop 0
	v_pk_fma_f32 v[0:1], v[26:27], v[76:77], v[0:1]
	s_nop 0
	v_pk_fma_f32 v[0:1], v[28:29], v[74:75], v[0:1]
	s_nop 0
	v_pk_fma_f32 v[0:1], v[30:31], v[80:81], v[0:1]
	s_nop 0
	v_add_f32_e32 v152, v0, v1
	s_waitcnt vmcnt(6)
	v_cvt_scalef32_pk32_f32_fp6 v[0:31], v[174:179], 1.0
	v_pk_mul_f32 v[2:3], v[2:3], v[92:93]
	s_nop 0
	v_pk_fma_f32 v[0:1], v[0:1], v[94:95], v[2:3]
	s_nop 0
	v_pk_fma_f32 v[0:1], v[4:5], v[86:87], v[0:1]
	s_nop 0
	v_pk_fma_f32 v[0:1], v[6:7], v[100:101], v[0:1]
	s_nop 0
	v_pk_fma_f32 v[0:1], v[8:9], v[104:105], v[0:1]
	s_nop 0
	v_pk_fma_f32 v[0:1], v[10:11], v[102:103], v[0:1]
	s_nop 0
	v_pk_fma_f32 v[0:1], v[12:13], v[98:99], v[0:1]
	s_nop 0
	v_pk_fma_f32 v[0:1], v[14:15], v[96:97], v[0:1]
	s_nop 0
	v_pk_fma_f32 v[0:1], v[16:17], v[90:91], v[0:1]
	s_nop 0
	v_pk_fma_f32 v[0:1], v[18:19], v[88:89], v[0:1]
	s_nop 0
	v_pk_fma_f32 v[0:1], v[20:21], v[84:85], v[0:1]
	s_nop 0
	v_pk_fma_f32 v[0:1], v[22:23], v[82:83], v[0:1]
	s_nop 0
	v_pk_fma_f32 v[0:1], v[24:25], v[78:79], v[0:1]
	s_nop 0
	v_pk_fma_f32 v[0:1], v[26:27], v[76:77], v[0:1]
	s_nop 0
	v_pk_fma_f32 v[0:1], v[28:29], v[74:75], v[0:1]
	s_nop 0
	v_pk_fma_f32 v[0:1], v[30:31], v[80:81], v[0:1]
	s_nop 0
	v_add_f32_e32 v153, v0, v1
	s_waitcnt vmcnt(4)
	v_cvt_scalef32_pk32_f32_fp6 v[0:31], v[44:49], 1.0
	v_pk_mul_f32 v[2:3], v[2:3], v[92:93]
	s_nop 0
	v_pk_fma_f32 v[0:1], v[0:1], v[94:95], v[2:3]
	s_nop 0
	v_pk_fma_f32 v[0:1], v[4:5], v[86:87], v[0:1]
	s_nop 0
	v_pk_fma_f32 v[0:1], v[6:7], v[100:101], v[0:1]
	s_nop 0
	v_pk_fma_f32 v[0:1], v[8:9], v[104:105], v[0:1]
	s_nop 0
	v_pk_fma_f32 v[0:1], v[10:11], v[102:103], v[0:1]
	s_nop 0
	v_pk_fma_f32 v[0:1], v[12:13], v[98:99], v[0:1]
	s_nop 0
	v_pk_fma_f32 v[0:1], v[14:15], v[96:97], v[0:1]
	s_nop 0
	v_pk_fma_f32 v[0:1], v[16:17], v[90:91], v[0:1]
	s_nop 0
	v_pk_fma_f32 v[0:1], v[18:19], v[88:89], v[0:1]
	s_nop 0
	v_pk_fma_f32 v[0:1], v[20:21], v[84:85], v[0:1]
	s_nop 0
	v_pk_fma_f32 v[0:1], v[22:23], v[82:83], v[0:1]
	s_nop 0
	v_pk_fma_f32 v[0:1], v[24:25], v[78:79], v[0:1]
	s_nop 0
	v_pk_fma_f32 v[0:1], v[26:27], v[76:77], v[0:1]
	s_nop 0
	v_pk_fma_f32 v[0:1], v[28:29], v[74:75], v[0:1]
	s_nop 0
	v_pk_fma_f32 v[0:1], v[30:31], v[80:81], v[0:1]
	s_nop 0
	v_add_f32_e32 v44, v0, v1
	s_waitcnt vmcnt(2)
	v_cvt_scalef32_pk32_f32_fp6 v[0:31], v[38:43], 1.0
	v_pk_mul_f32 v[2:3], v[2:3], v[92:93]
	s_nop 0
	v_pk_fma_f32 v[0:1], v[0:1], v[94:95], v[2:3]
	s_nop 0
	v_pk_fma_f32 v[0:1], v[4:5], v[86:87], v[0:1]
	s_nop 0
	v_pk_fma_f32 v[0:1], v[6:7], v[100:101], v[0:1]
	s_nop 0
	v_pk_fma_f32 v[0:1], v[8:9], v[104:105], v[0:1]
	s_nop 0
	v_pk_fma_f32 v[0:1], v[10:11], v[102:103], v[0:1]
	s_nop 0
	v_pk_fma_f32 v[0:1], v[12:13], v[98:99], v[0:1]
	s_nop 0
	v_pk_fma_f32 v[0:1], v[14:15], v[96:97], v[0:1]
	s_nop 0
	v_pk_fma_f32 v[0:1], v[16:17], v[90:91], v[0:1]
	s_nop 0
	v_pk_fma_f32 v[0:1], v[18:19], v[88:89], v[0:1]
	s_nop 0
	v_pk_fma_f32 v[0:1], v[20:21], v[84:85], v[0:1]
	s_nop 0
	v_pk_fma_f32 v[0:1], v[22:23], v[82:83], v[0:1]
	s_nop 0
	v_pk_fma_f32 v[0:1], v[24:25], v[78:79], v[0:1]
	s_nop 0
	v_pk_fma_f32 v[0:1], v[26:27], v[76:77], v[0:1]
	s_nop 0
	v_pk_fma_f32 v[0:1], v[28:29], v[74:75], v[0:1]
	s_nop 0
	v_pk_fma_f32 v[0:1], v[30:31], v[80:81], v[0:1]
	s_nop 0
	v_add_f32_e32 v38, v0, v1
	s_waitcnt vmcnt(0)
; DI void phase_peer_out(const Params& p, char* lds) {
;     ...
; #pragma unroll
;         for (int k = 0; k < 8; ++k) {
;           const int e0 = __builtin_amdgcn_readlane(el[0], hf * 32 + kb * 8 + k), e1 = __builtin_amdgcn_readlane(el[1], hf * 32 + kb * 8 + k);
;           qb[k] = load6(U6 + (size_t)(hb ? e1 : e0) * 768);
;     ...
; #pragma unroll
;       for (int off = 16; off >= 1; off >>= 1) {
;         const bool up = (lane & off) != 0;
; #pragma unroll
;         for (int i = 0; i < off; ++i) {
;           const float send = up ? pd[i] : pd[i + off];
;           const float keep = up ? pd[i + off] : pd[i];
;           pd[i] = keep + __shfl_xor(send, off);
;         }
;       }
	v_cvt_scalef32_pk32_f32_fp6 v[0:31], v[32:37], 1.0
	v_pk_mul_f32 v[2:3], v[2:3], v[92:93]
	s_nop 0
	v_pk_fma_f32 v[0:1], v[0:1], v[94:95], v[2:3]
	v_cndmask_b32_e64 v2, v131, v141, s[2:3]
	v_pk_fma_f32 v[0:1], v[4:5], v[86:87], v[0:1]
	ds_bpermute_b32 v2, v118, v2
	v_pk_fma_f32 v[0:1], v[6:7], v[100:101], v[0:1]
	v_cndmask_b32_e64 v4, v133, v143, s[2:3]
	v_pk_fma_f32 v[0:1], v[8:9], v[104:105], v[0:1]
	ds_bpermute_b32 v4, v118, v4
	v_pk_fma_f32 v[0:1], v[10:11], v[102:103], v[0:1]
	v_cndmask_b32_e64 v5, v134, v144, s[2:3]
	v_pk_fma_f32 v[0:1], v[12:13], v[98:99], v[0:1]
	ds_bpermute_b32 v5, v118, v5
	v_pk_fma_f32 v[0:1], v[14:15], v[96:97], v[0:1]
	v_cndmask_b32_e64 v3, v142, v132, s[2:3]
	v_pk_fma_f32 v[0:1], v[16:17], v[90:91], v[0:1]
	v_cndmask_b32_e64 v7, v51, v146, s[2:3]
	v_pk_fma_f32 v[0:1], v[18:19], v[88:89], v[0:1]
	ds_bpermute_b32 v7, v118, v7
	v_pk_fma_f32 v[0:1], v[20:21], v[84:85], v[0:1]
	v_cndmask_b32_e64 v8, v52, v147, s[2:3]
	v_pk_fma_f32 v[0:1], v[22:23], v[82:83], v[0:1]
	ds_bpermute_b32 v8, v118, v8
	v_pk_fma_f32 v[0:1], v[24:25], v[78:79], v[0:1]
	v_cndmask_b32_e64 v6, v145, v50, s[2:3]
	v_pk_fma_f32 v[0:1], v[26:27], v[76:77], v[0:1]
	v_cndmask_b32_e64 v10, v54, v149, s[2:3]
	v_pk_fma_f32 v[0:1], v[28:29], v[74:75], v[0:1]
	ds_bpermute_b32 v10, v118, v10
	v_pk_fma_f32 v[0:1], v[30:31], v[80:81], v[0:1]
	v_cndmask_b32_e64 v11, v55, v150, s[2:3]
	v_add_f32_e32 v0, v0, v1
	v_cndmask_b32_e64 v1, v141, v131, s[2:3]
	s_waitcnt lgkmcnt(5)
	v_add_f32_e32 v1, v1, v2
	v_cndmask_b32_e64 v2, v132, v142, s[2:3]
	ds_bpermute_b32 v2, v118, v2
	ds_bpermute_b32 v11, v118, v11
	v_cndmask_b32_e64 v9, v148, v53, s[2:3]
	v_cndmask_b32_e64 v13, v136, v152, s[2:3]
	ds_bpermute_b32 v13, v118, v13
	s_waitcnt lgkmcnt(2)
	v_add_f32_e32 v2, v3, v2
	v_cndmask_b32_e64 v3, v143, v133, s[2:3]
	v_add_f32_e32 v3, v3, v4
	v_cndmask_b32_e64 v4, v144, v134, s[2:3]
	v_add_f32_e32 v4, v4, v5
	v_cndmask_b32_e64 v5, v50, v145, s[2:3]
	ds_bpermute_b32 v5, v118, v5
	v_cndmask_b32_e64 v14, v137, v153, s[2:3]
	ds_bpermute_b32 v14, v118, v14
	v_cndmask_b32_e64 v12, v151, v135, s[2:3]
	v_cndmask_b32_e64 v16, v139, v38, s[2:3]
	s_waitcnt lgkmcnt(1)
	v_add_f32_e32 v5, v6, v5
	v_cndmask_b32_e64 v6, v146, v51, s[2:3]
	v_add_f32_e32 v6, v6, v7
	v_cndmask_b32_e64 v7, v147, v52, s[2:3]
	v_add_f32_e32 v7, v7, v8
	v_cndmask_b32_e64 v8, v53, v148, s[2:3]
	ds_bpermute_b32 v8, v118, v8
	ds_bpermute_b32 v16, v118, v16
	v_cndmask_b32_e64 v15, v44, v138, s[2:3]
	v_cndmask_b32_e64 v17, v140, v0, s[2:3]
	ds_bpermute_b32 v17, v118, v17
	s_waitcnt lgkmcnt(2)
	v_add_f32_e32 v8, v9, v8
	v_cndmask_b32_e64 v9, v149, v54, s[2:3]
	v_add_f32_e32 v9, v9, v10
	v_cndmask_b32_e64 v10, v150, v55, s[2:3]
	v_add_f32_e32 v10, v10, v11
	v_cndmask_b32_e64 v11, v135, v151, s[2:3]
	ds_bpermute_b32 v11, v118, v11
	v_cndmask_b32_e64 v0, v0, v140, s[2:3]
	s_waitcnt lgkmcnt(1)
	v_add_f32_e32 v0, v0, v17
	v_add_f32_e32 v50, v129, v130
	s_waitcnt lgkmcnt(0)
	v_add_f32_e32 v11, v12, v11
	v_cndmask_b32_e64 v12, v152, v136, s[2:3]
	v_add_f32_e32 v12, v12, v13
	v_cndmask_b32_e64 v13, v153, v137, s[2:3]
	v_add_f32_e32 v13, v13, v14
	v_cndmask_b32_e64 v14, v138, v44, s[2:3]
	ds_bpermute_b32 v14, v118, v14
	v_cndmask_b32_e64 v17, v3, v11, s[4:5]
	v_cndmask_b32_e64 v3, v11, v3, s[4:5]
	ds_bpermute_b32 v17, v114, v17
	s_waitcnt lgkmcnt(1)
	v_add_f32_e32 v14, v15, v14
	v_cndmask_b32_e64 v15, v38, v139, s[2:3]
	v_add_f32_e32 v15, v15, v16
	v_cndmask_b32_e64 v16, v1, v9, s[4:5]
	v_cndmask_b32_e64 v1, v9, v1, s[4:5]
	ds_bpermute_b32 v9, v114, v16
	v_cndmask_b32_e64 v16, v2, v10, s[4:5]
	v_cndmask_b32_e64 v2, v10, v2, s[4:5]
	v_cndmask_b32_e64 v10, v5, v13, s[4:5]
	ds_bpermute_b32 v10, v114, v10
	s_waitcnt lgkmcnt(1)
	v_add_f32_e32 v1, v1, v9
	v_cndmask_b32_e64 v9, v4, v12, s[4:5]
	v_cndmask_b32_e64 v11, v6, v14, s[4:5]
	ds_bpermute_b32 v9, v114, v9
	ds_bpermute_b32 v11, v114, v11
	v_cndmask_b32_e64 v5, v13, v5, s[4:5]
	v_cndmask_b32_e64 v4, v12, v4, s[4:5]
	s_waitcnt lgkmcnt(2)
	v_add_f32_e32 v5, v5, v10
	v_cndmask_b32_e64 v6, v14, v6, s[4:5]
	v_cndmask_b32_e64 v10, v8, v0, s[4:5]
	ds_bpermute_b32 v16, v114, v16
	s_waitcnt lgkmcnt(2)
	v_add_f32_e32 v4, v4, v9
	s_waitcnt lgkmcnt(1)
	v_add_f32_e32 v6, v6, v11
	v_cndmask_b32_e64 v9, v7, v15, s[4:5]
	ds_bpermute_b32 v10, v114, v10
	v_cndmask_b32_e64 v11, v1, v5, s[6:7]
	ds_bpermute_b32 v9, v114, v9
	ds_bpermute_b32 v11, v115, v11
	v_cndmask_b32_e64 v0, v0, v8, s[4:5]
	s_waitcnt lgkmcnt(3)
	v_add_f32_e32 v2, v2, v16
	v_cndmask_b32_e64 v7, v15, v7, s[4:5]
	s_waitcnt lgkmcnt(2)
	v_add_f32_e32 v8, v0, v10
	v_cndmask_b32_e64 v0, v5, v1, s[6:7]
	v_add_f32_e32 v3, v3, v17
	s_waitcnt lgkmcnt(1)
	v_add_f32_e32 v7, v7, v9
	s_waitcnt lgkmcnt(0)
	v_add_f32_e32 v5, v0, v11
	v_cndmask_b32_e64 v0, v2, v6, s[6:7]
	v_cndmask_b32_e64 v2, v6, v2, s[6:7]
	ds_bpermute_b32 v6, v115, v0
	v_cndmask_b32_e64 v0, v3, v7, s[6:7]
	ds_bpermute_b32 v9, v115, v0
	v_mov_b32_e32 v0, s13
	v_mov_b32_e32 v1, s12
	v_cndmask_b32_e64 v0, v0, v1, s[0:1]
	v_mad_u32_u24 v0, v0, s23, v251
	global_load_dwordx2 v[136:137], v0, s[98:99] offset:16
	global_load_dwordx4 v[132:135], v0, s[98:99]
	v_cndmask_b32_e64 v10, v4, v8, s[6:7]
	ds_bpermute_b32 v0, v115, v10
	v_cndmask_b32_e64 v1, v7, v3, s[6:7]
	s_waitcnt lgkmcnt(1)
	v_add_f32_e32 v3, v1, v9
	v_cndmask_b32_e64 v1, v8, v4, s[6:7]
	v_readlane_b32 s12, v106, 33
	s_waitcnt lgkmcnt(0)
	v_add_f32_e32 v4, v1, v0
	v_cndmask_b32_e64 v0, v5, v3, s[8:9]
	v_readlane_b32 s13, v107, 33
	v_add_f32_e32 v2, v2, v6
	ds_bpermute_b32 v6, v116, v0
	v_mov_b32_e32 v0, s13
	v_mov_b32_e32 v1, s12
	v_cndmask_b32_e64 v0, v0, v1, s[0:1]
	v_mad_u32_u24 v0, v0, s23, v251
	global_load_dwordx2 v[142:143], v0, s[98:99] offset:16
	global_load_dwordx4 v[138:141], v0, s[98:99]
	v_cndmask_b32_e64 v7, v2, v4, s[8:9]
	ds_bpermute_b32 v0, v116, v7
	v_cndmask_b32_e64 v1, v3, v5, s[8:9]
	s_waitcnt lgkmcnt(1)
; DI void phase_peer_out(const Params& p, char* lds) {
;     ...
;       for (int kb = 0; kb < 4; ++kb) {
;         v6u qb[8];
; #pragma unroll
;         for (int k = 0; k < 8; ++k) {
;           const int e0 = __builtin_amdgcn_readlane(el[0], hf * 32 + kb * 8 + k), e1 = __builtin_amdgcn_readlane(el[1], hf * 32 + kb * 8 + k);
;           qb[k] = load6(U6 + (size_t)(hb ? e1 : e0) * 768);
;         }
; #pragma unroll
;         for (int k = 0; k < 8; ++k) {
;           const v32f f = __builtin_amdgcn_cvt_scalef32_pk32_f32_fp6(qb[k], 1.0f);
;           f32x2 a = f32x2{f[0], f[1]} * x2[0];
; #pragma unroll
;           for (int i = 1; i < 16; ++i) a = f32x2{f[2 * i], f[2 * i + 1]} * x2[i] + a;
;           pd[kb * 8 + k] = a.x + a.y;
	v_add_f32_e32 v51, v1, v6
	v_cndmask_b32_e64 v1, v4, v2, s[8:9]
	v_readlane_b32 s12, v106, 34
	v_readlane_b32 s13, v107, 34
	s_waitcnt lgkmcnt(0)
	v_add_f32_e32 v52, v1, v0
	v_mov_b32_e32 v1, s12
	v_mov_b32_e32 v0, s13
	v_cndmask_b32_e64 v0, v0, v1, s[0:1]
	v_mad_u32_u24 v0, v0, s23, v251
	global_load_dwordx2 v[148:149], v0, s[98:99] offset:16
	global_load_dwordx4 v[144:147], v0, s[98:99]
	v_readlane_b32 s12, v106, 35
	v_readlane_b32 s13, v107, 35
	v_cndmask_b32_e64 v53, v51, v52, s[10:11]
	v_mov_b32_e32 v1, s12
	v_mov_b32_e32 v0, s13
	v_cndmask_b32_e64 v0, v0, v1, s[0:1]
	v_mad_u32_u24 v0, v0, s23, v251
	global_load_dwordx2 v[154:155], v0, s[98:99] offset:16
	global_load_dwordx4 v[150:153], v0, s[98:99]
	v_readlane_b32 s12, v106, 36
	v_readlane_b32 s13, v107, 36
	s_nop 0
	v_mov_b32_e32 v1, s12
	v_mov_b32_e32 v0, s13
	v_cndmask_b32_e64 v0, v0, v1, s[0:1]
	v_mad_u32_u24 v0, v0, s23, v251
	global_load_dwordx2 v[160:161], v0, s[98:99] offset:16
	global_load_dwordx4 v[156:159], v0, s[98:99]
	v_readlane_b32 s12, v106, 37
	v_readlane_b32 s13, v107, 37
	s_nop 0
	v_mov_b32_e32 v1, s12
	v_mov_b32_e32 v0, s13
	v_cndmask_b32_e64 v0, v0, v1, s[0:1]
	v_mad_u32_u24 v0, v0, s23, v251
	v_readlane_b32 s12, v106, 38
	v_readlane_b32 s13, v107, 38
	global_load_dwordx2 v[48:49], v0, s[98:99] offset:16
	global_load_dwordx4 v[44:47], v0, s[98:99]
	v_mov_b32_e32 v0, s13
	v_mov_b32_e32 v1, s12
	v_cndmask_b32_e64 v0, v0, v1, s[0:1]
	v_mad_u32_u24 v0, v0, s23, v251
	v_readlane_b32 s12, v106, 39
	v_readlane_b32 s13, v107, 39
	global_load_dwordx2 v[42:43], v0, s[98:99] offset:16
	global_load_dwordx4 v[38:41], v0, s[98:99]
	v_mov_b32_e32 v0, s13
	v_mov_b32_e32 v1, s12
	v_cndmask_b32_e64 v0, v0, v1, s[0:1]
	v_mad_u32_u24 v0, v0, s23, v251
	global_load_dwordx2 v[36:37], v0, s[98:99] offset:16
	global_load_dwordx4 v[32:35], v0, s[98:99]
	v_readlane_b32 s12, v106, 40
	v_readlane_b32 s13, v107, 40
	s_waitcnt vmcnt(14)
	v_cvt_scalef32_pk32_f32_fp6 v[0:31], v[132:137], 1.0
	v_pk_mul_f32 v[2:3], v[2:3], v[92:93]
	s_nop 0
	v_pk_fma_f32 v[0:1], v[0:1], v[94:95], v[2:3]
	s_nop 0
	v_pk_fma_f32 v[0:1], v[4:5], v[86:87], v[0:1]
	s_nop 0
	v_pk_fma_f32 v[0:1], v[6:7], v[100:101], v[0:1]
	s_nop 0
	v_pk_fma_f32 v[0:1], v[8:9], v[104:105], v[0:1]
	s_nop 0
	v_pk_fma_f32 v[0:1], v[10:11], v[102:103], v[0:1]
	s_nop 0
	v_pk_fma_f32 v[0:1], v[12:13], v[98:99], v[0:1]
	s_nop 0
	v_pk_fma_f32 v[0:1], v[14:15], v[96:97], v[0:1]
	s_nop 0
	v_pk_fma_f32 v[0:1], v[16:17], v[90:91], v[0:1]
	s_nop 0
	v_pk_fma_f32 v[0:1], v[18:19], v[88:89], v[0:1]
	s_nop 0
	v_pk_fma_f32 v[0:1], v[20:21], v[84:85], v[0:1]
	s_nop 0
	v_pk_fma_f32 v[0:1], v[22:23], v[82:83], v[0:1]
	s_nop 0
	v_pk_fma_f32 v[0:1], v[24:25], v[78:79], v[0:1]
	s_nop 0
	v_pk_fma_f32 v[0:1], v[26:27], v[76:77], v[0:1]
	s_nop 0
	v_pk_fma_f32 v[0:1], v[28:29], v[74:75], v[0:1]
	s_nop 0
	v_pk_fma_f32 v[0:1], v[30:31], v[80:81], v[0:1]
	s_nop 0
	v_add_f32_e32 v54, v0, v1
	s_waitcnt vmcnt(12)
	v_cvt_scalef32_pk32_f32_fp6 v[0:31], v[138:143], 1.0
	v_pk_mul_f32 v[2:3], v[2:3], v[92:93]
	s_nop 0
	v_pk_fma_f32 v[0:1], v[0:1], v[94:95], v[2:3]
	s_nop 0
	v_pk_fma_f32 v[0:1], v[4:5], v[86:87], v[0:1]
	s_nop 0
	v_pk_fma_f32 v[0:1], v[6:7], v[100:101], v[0:1]
	s_nop 0
	v_pk_fma_f32 v[0:1], v[8:9], v[104:105], v[0:1]
	s_nop 0
	v_pk_fma_f32 v[0:1], v[10:11], v[102:103], v[0:1]
	s_nop 0
	v_pk_fma_f32 v[0:1], v[12:13], v[98:99], v[0:1]
	s_nop 0
	v_pk_fma_f32 v[0:1], v[14:15], v[96:97], v[0:1]
	s_nop 0
	v_pk_fma_f32 v[0:1], v[16:17], v[90:91], v[0:1]
	s_nop 0
	v_pk_fma_f32 v[0:1], v[18:19], v[88:89], v[0:1]
	s_nop 0
	v_pk_fma_f32 v[0:1], v[20:21], v[84:85], v[0:1]
	s_nop 0
	v_pk_fma_f32 v[0:1], v[22:23], v[82:83], v[0:1]
	s_nop 0
	v_pk_fma_f32 v[0:1], v[24:25], v[78:79], v[0:1]
	s_nop 0
	v_pk_fma_f32 v[0:1], v[26:27], v[76:77], v[0:1]
	s_nop 0
	v_pk_fma_f32 v[0:1], v[28:29], v[74:75], v[0:1]
	s_nop 0
	v_pk_fma_f32 v[0:1], v[30:31], v[80:81], v[0:1]
	s_nop 0
	v_add_f32_e32 v55, v0, v1
	s_waitcnt vmcnt(10)
	v_cvt_scalef32_pk32_f32_fp6 v[0:31], v[144:149], 1.0
	v_pk_mul_f32 v[2:3], v[2:3], v[92:93]
	s_nop 0
	v_pk_fma_f32 v[0:1], v[0:1], v[94:95], v[2:3]
	s_nop 0
	v_pk_fma_f32 v[0:1], v[4:5], v[86:87], v[0:1]
	s_nop 0
	v_pk_fma_f32 v[0:1], v[6:7], v[100:101], v[0:1]
	s_nop 0
	v_pk_fma_f32 v[0:1], v[8:9], v[104:105], v[0:1]
	s_nop 0
	v_pk_fma_f32 v[0:1], v[10:11], v[102:103], v[0:1]
	s_nop 0
	v_pk_fma_f32 v[0:1], v[12:13], v[98:99], v[0:1]
	s_nop 0
	v_pk_fma_f32 v[0:1], v[14:15], v[96:97], v[0:1]
	s_nop 0
	v_pk_fma_f32 v[0:1], v[16:17], v[90:91], v[0:1]
	s_nop 0
	v_pk_fma_f32 v[0:1], v[18:19], v[88:89], v[0:1]
	s_nop 0
	v_pk_fma_f32 v[0:1], v[20:21], v[84:85], v[0:1]
	s_nop 0
	v_pk_fma_f32 v[0:1], v[22:23], v[82:83], v[0:1]
	s_nop 0
	v_pk_fma_f32 v[0:1], v[24:25], v[78:79], v[0:1]
	s_nop 0
	v_pk_fma_f32 v[0:1], v[26:27], v[76:77], v[0:1]
	s_nop 0
	v_pk_fma_f32 v[0:1], v[28:29], v[74:75], v[0:1]
	s_nop 0
	v_pk_fma_f32 v[0:1], v[30:31], v[80:81], v[0:1]
	s_nop 0
	v_add_f32_e32 v129, v0, v1
	s_waitcnt vmcnt(8)
	v_cvt_scalef32_pk32_f32_fp6 v[0:31], v[150:155], 1.0
	v_pk_mul_f32 v[2:3], v[2:3], v[92:93]
	s_nop 0
	v_pk_fma_f32 v[0:1], v[0:1], v[94:95], v[2:3]
	s_nop 0
	v_pk_fma_f32 v[0:1], v[4:5], v[86:87], v[0:1]
	s_nop 0
	v_pk_fma_f32 v[0:1], v[6:7], v[100:101], v[0:1]
	s_nop 0
	v_pk_fma_f32 v[0:1], v[8:9], v[104:105], v[0:1]
	s_nop 0
	v_pk_fma_f32 v[0:1], v[10:11], v[102:103], v[0:1]
	s_nop 0
	v_pk_fma_f32 v[0:1], v[12:13], v[98:99], v[0:1]
	s_nop 0
	v_pk_fma_f32 v[0:1], v[14:15], v[96:97], v[0:1]
	s_nop 0
	v_pk_fma_f32 v[0:1], v[16:17], v[90:91], v[0:1]
	s_nop 0
	v_pk_fma_f32 v[0:1], v[18:19], v[88:89], v[0:1]
	s_nop 0
	v_pk_fma_f32 v[0:1], v[20:21], v[84:85], v[0:1]
	s_nop 0
	v_pk_fma_f32 v[0:1], v[22:23], v[82:83], v[0:1]
	s_nop 0
	v_pk_fma_f32 v[0:1], v[24:25], v[78:79], v[0:1]
	s_nop 0
	v_pk_fma_f32 v[0:1], v[26:27], v[76:77], v[0:1]
	s_nop 0
	v_pk_fma_f32 v[0:1], v[28:29], v[74:75], v[0:1]
	s_nop 0
	v_pk_fma_f32 v[0:1], v[30:31], v[80:81], v[0:1]
	s_nop 0
	v_add_f32_e32 v130, v0, v1
	s_waitcnt vmcnt(6)
; DI void phase_peer_out(const Params& p, char* lds) {
;     ...
;       for (int kb = 0; kb < 4; ++kb) {
;         v6u qb[8];
; #pragma unroll
;         for (int k = 0; k < 8; ++k) {
;           const int e0 = __builtin_amdgcn_readlane(el[0], hf * 32 + kb * 8 + k), e1 = __builtin_amdgcn_readlane(el[1], hf * 32 + kb * 8 + k);
;           qb[k] = load6(U6 + (size_t)(hb ? e1 : e0) * 768);
;         }
; #pragma unroll
;         for (int k = 0; k < 8; ++k) {
;           const v32f f = __builtin_amdgcn_cvt_scalef32_pk32_f32_fp6(qb[k], 1.0f);
;           f32x2 a = f32x2{f[0], f[1]} * x2[0];
; #pragma unroll
;           for (int i = 1; i < 16; ++i) a = f32x2{f[2 * i], f[2 * i + 1]} * x2[i] + a;
;           pd[kb * 8 + k] = a.x + a.y;
	v_cvt_scalef32_pk32_f32_fp6 v[0:31], v[156:161], 1.0
	v_pk_mul_f32 v[2:3], v[2:3], v[92:93]
	s_nop 0
	v_pk_fma_f32 v[0:1], v[0:1], v[94:95], v[2:3]
	s_nop 0
	v_pk_fma_f32 v[0:1], v[4:5], v[86:87], v[0:1]
	s_nop 0
	v_pk_fma_f32 v[0:1], v[6:7], v[100:101], v[0:1]
	s_nop 0
	v_pk_fma_f32 v[0:1], v[8:9], v[104:105], v[0:1]
	s_nop 0
	v_pk_fma_f32 v[0:1], v[10:11], v[102:103], v[0:1]
	s_nop 0
	v_pk_fma_f32 v[0:1], v[12:13], v[98:99], v[0:1]
	s_nop 0
	v_pk_fma_f32 v[0:1], v[14:15], v[96:97], v[0:1]
	s_nop 0
	v_pk_fma_f32 v[0:1], v[16:17], v[90:91], v[0:1]
	s_nop 0
	v_pk_fma_f32 v[0:1], v[18:19], v[88:89], v[0:1]
	s_nop 0
	v_pk_fma_f32 v[0:1], v[20:21], v[84:85], v[0:1]
	s_nop 0
	v_pk_fma_f32 v[0:1], v[22:23], v[82:83], v[0:1]
	s_nop 0
	v_pk_fma_f32 v[0:1], v[24:25], v[78:79], v[0:1]
	s_nop 0
	v_pk_fma_f32 v[0:1], v[26:27], v[76:77], v[0:1]
	s_nop 0
	v_pk_fma_f32 v[0:1], v[28:29], v[74:75], v[0:1]
	s_nop 0
	v_pk_fma_f32 v[0:1], v[30:31], v[80:81], v[0:1]
	s_nop 0
	v_add_f32_e32 v131, v0, v1
	s_waitcnt vmcnt(4)
	v_cvt_scalef32_pk32_f32_fp6 v[0:31], v[44:49], 1.0
	v_pk_mul_f32 v[2:3], v[2:3], v[92:93]
	s_nop 0
	v_pk_fma_f32 v[0:1], v[0:1], v[94:95], v[2:3]
	s_nop 0
	v_pk_fma_f32 v[0:1], v[4:5], v[86:87], v[0:1]
	s_nop 0
	v_pk_fma_f32 v[0:1], v[6:7], v[100:101], v[0:1]
	s_nop 0
	v_pk_fma_f32 v[0:1], v[8:9], v[104:105], v[0:1]
	s_nop 0
	v_pk_fma_f32 v[0:1], v[10:11], v[102:103], v[0:1]
	s_nop 0
	v_pk_fma_f32 v[0:1], v[12:13], v[98:99], v[0:1]
	s_nop 0
	v_pk_fma_f32 v[0:1], v[14:15], v[96:97], v[0:1]
	s_nop 0
	v_pk_fma_f32 v[0:1], v[16:17], v[90:91], v[0:1]
	s_nop 0
	v_pk_fma_f32 v[0:1], v[18:19], v[88:89], v[0:1]
	s_nop 0
	v_pk_fma_f32 v[0:1], v[20:21], v[84:85], v[0:1]
	s_nop 0
	v_pk_fma_f32 v[0:1], v[22:23], v[82:83], v[0:1]
	s_nop 0
	v_pk_fma_f32 v[0:1], v[24:25], v[78:79], v[0:1]
	s_nop 0
	v_pk_fma_f32 v[0:1], v[26:27], v[76:77], v[0:1]
	s_nop 0
	v_pk_fma_f32 v[0:1], v[28:29], v[74:75], v[0:1]
	s_nop 0
	v_pk_fma_f32 v[0:1], v[30:31], v[80:81], v[0:1]
	s_nop 0
	v_add_f32_e32 v132, v0, v1
	s_waitcnt vmcnt(2)
	v_cvt_scalef32_pk32_f32_fp6 v[0:31], v[38:43], 1.0
	v_pk_mul_f32 v[2:3], v[2:3], v[92:93]
	s_nop 0
	v_pk_fma_f32 v[0:1], v[0:1], v[94:95], v[2:3]
	s_nop 0
	v_pk_fma_f32 v[0:1], v[4:5], v[86:87], v[0:1]
	s_nop 0
	v_pk_fma_f32 v[0:1], v[6:7], v[100:101], v[0:1]
	s_nop 0
	v_pk_fma_f32 v[0:1], v[8:9], v[104:105], v[0:1]
	s_nop 0
	v_pk_fma_f32 v[0:1], v[10:11], v[102:103], v[0:1]
	s_nop 0
	v_pk_fma_f32 v[0:1], v[12:13], v[98:99], v[0:1]
	s_nop 0
	v_pk_fma_f32 v[0:1], v[14:15], v[96:97], v[0:1]
	s_nop 0
	v_pk_fma_f32 v[0:1], v[16:17], v[90:91], v[0:1]
	s_nop 0
	v_pk_fma_f32 v[0:1], v[18:19], v[88:89], v[0:1]
	s_nop 0
	v_pk_fma_f32 v[0:1], v[20:21], v[84:85], v[0:1]
	s_nop 0
	v_pk_fma_f32 v[0:1], v[22:23], v[82:83], v[0:1]
	s_nop 0
	v_pk_fma_f32 v[0:1], v[24:25], v[78:79], v[0:1]
	s_nop 0
	v_pk_fma_f32 v[0:1], v[26:27], v[76:77], v[0:1]
	s_nop 0
	v_pk_fma_f32 v[0:1], v[28:29], v[74:75], v[0:1]
	s_nop 0
	v_pk_fma_f32 v[0:1], v[30:31], v[80:81], v[0:1]
	s_nop 0
	v_add_f32_e32 v133, v0, v1
	s_waitcnt vmcnt(0)
	v_cvt_scalef32_pk32_f32_fp6 v[0:31], v[32:37], 1.0
	v_mov_b32_e32 v32, s13
	v_mov_b32_e32 v33, s12
	v_cndmask_b32_e64 v32, v32, v33, s[0:1]
	v_mad_u32_u24 v32, v32, s23, v251
	global_load_dwordx2 v[140:141], v32, s[98:99] offset:16
	global_load_dwordx4 v[136:139], v32, s[98:99]
	v_pk_mul_f32 v[2:3], v[2:3], v[92:93]
	v_readlane_b32 s12, v106, 41
	v_readlane_b32 s13, v107, 41
	v_pk_fma_f32 v[0:1], v[0:1], v[94:95], v[2:3]
	v_mov_b32_e32 v3, s12
	v_mov_b32_e32 v2, s13
	v_cndmask_b32_e64 v2, v2, v3, s[0:1]
	v_mad_u32_u24 v2, v2, s23, v251
	v_pk_fma_f32 v[0:1], v[4:5], v[86:87], v[0:1]
	global_load_dwordx2 v[146:147], v2, s[98:99] offset:16
	global_load_dwordx4 v[142:145], v2, s[98:99]
	v_pk_fma_f32 v[0:1], v[6:7], v[100:101], v[0:1]
	v_readlane_b32 s12, v106, 42
	v_pk_fma_f32 v[0:1], v[8:9], v[104:105], v[0:1]
	v_readlane_b32 s13, v107, 42
	v_pk_fma_f32 v[0:1], v[10:11], v[102:103], v[0:1]
	s_nop 0
	v_pk_fma_f32 v[0:1], v[12:13], v[98:99], v[0:1]
	s_nop 0
	v_pk_fma_f32 v[0:1], v[14:15], v[96:97], v[0:1]
	s_nop 0
	v_pk_fma_f32 v[0:1], v[16:17], v[90:91], v[0:1]
	s_nop 0
	v_pk_fma_f32 v[0:1], v[18:19], v[88:89], v[0:1]
	s_nop 0
	v_pk_fma_f32 v[0:1], v[20:21], v[84:85], v[0:1]
	s_nop 0
	v_pk_fma_f32 v[0:1], v[22:23], v[82:83], v[0:1]
	s_nop 0
	v_pk_fma_f32 v[0:1], v[24:25], v[78:79], v[0:1]
	s_nop 0
	v_pk_fma_f32 v[0:1], v[26:27], v[76:77], v[0:1]
	s_nop 0
	v_pk_fma_f32 v[0:1], v[28:29], v[74:75], v[0:1]
	s_nop 0
	v_pk_fma_f32 v[0:1], v[30:31], v[80:81], v[0:1]
	s_nop 0
	v_add_f32_e32 v134, v0, v1
	v_mov_b32_e32 v0, s13
	v_mov_b32_e32 v1, s12
	v_cndmask_b32_e64 v0, v0, v1, s[0:1]
	v_mad_u32_u24 v0, v0, s23, v251
	global_load_dwordx2 v[152:153], v0, s[98:99] offset:16
	global_load_dwordx4 v[148:151], v0, s[98:99]
	v_readlane_b32 s12, v106, 43
	v_readlane_b32 s13, v107, 43
	s_nop 0
	v_mov_b32_e32 v1, s12
	v_mov_b32_e32 v0, s13
	v_cndmask_b32_e64 v0, v0, v1, s[0:1]
	v_mad_u32_u24 v0, v0, s23, v251
	global_load_dwordx2 v[158:159], v0, s[98:99] offset:16
	global_load_dwordx4 v[154:157], v0, s[98:99]
	v_readlane_b32 s12, v106, 44
	v_readlane_b32 s13, v107, 44
	s_nop 0
	v_mov_b32_e32 v1, s12
	v_mov_b32_e32 v0, s13
	v_cndmask_b32_e64 v0, v0, v1, s[0:1]
	v_mad_u32_u24 v0, v0, s23, v251
	global_load_dwordx2 v[164:165], v0, s[98:99] offset:16
	global_load_dwordx4 v[160:163], v0, s[98:99]
	v_readlane_b32 s12, v106, 45
	v_readlane_b32 s13, v107, 45
	s_nop 0
	v_mov_b32_e32 v1, s12
	v_mov_b32_e32 v0, s13
	v_cndmask_b32_e64 v0, v0, v1, s[0:1]
	v_mad_u32_u24 v0, v0, s23, v251
	v_readlane_b32 s12, v106, 46
	v_readlane_b32 s13, v107, 46
	global_load_dwordx2 v[48:49], v0, s[98:99] offset:16
	global_load_dwordx4 v[44:47], v0, s[98:99]
	v_mov_b32_e32 v0, s13
	v_mov_b32_e32 v1, s12
	v_cndmask_b32_e64 v0, v0, v1, s[0:1]
	v_mad_u32_u24 v0, v0, s23, v251
	v_readlane_b32 s12, v106, 47
	v_readlane_b32 s13, v107, 47
	global_load_dwordx2 v[42:43], v0, s[98:99] offset:16
	global_load_dwordx4 v[38:41], v0, s[98:99]
	v_mov_b32_e32 v0, s13
	v_mov_b32_e32 v1, s12
	v_cndmask_b32_e64 v0, v0, v1, s[0:1]
	v_mad_u32_u24 v0, v0, s23, v251
	global_load_dwordx2 v[36:37], v0, s[98:99] offset:16
	global_load_dwordx4 v[32:35], v0, s[98:99]
	s_waitcnt vmcnt(14)
; DI void phase_peer_out(const Params& p, char* lds) {
;     ...
; #pragma unroll
;         for (int k = 0; k < 8; ++k) {
;           const v32f f = __builtin_amdgcn_cvt_scalef32_pk32_f32_fp6(qb[k], 1.0f);
;           f32x2 a = f32x2{f[0], f[1]} * x2[0];
; #pragma unroll
;           for (int i = 1; i < 16; ++i) a = f32x2{f[2 * i], f[2 * i + 1]} * x2[i] + a;
;           pd[kb * 8 + k] = a.x + a.y;
	v_cvt_scalef32_pk32_f32_fp6 v[0:31], v[136:141], 1.0
	v_pk_mul_f32 v[2:3], v[2:3], v[92:93]
	v_readlane_b32 s12, v106, 48
	v_pk_fma_f32 v[0:1], v[0:1], v[94:95], v[2:3]
	v_readlane_b32 s13, v107, 48
	v_pk_fma_f32 v[0:1], v[4:5], v[86:87], v[0:1]
	s_nop 0
	v_pk_fma_f32 v[0:1], v[6:7], v[100:101], v[0:1]
	s_nop 0
	v_pk_fma_f32 v[0:1], v[8:9], v[104:105], v[0:1]
	s_nop 0
	v_pk_fma_f32 v[0:1], v[10:11], v[102:103], v[0:1]
	s_nop 0
	v_pk_fma_f32 v[0:1], v[12:13], v[98:99], v[0:1]
	s_nop 0
	v_pk_fma_f32 v[0:1], v[14:15], v[96:97], v[0:1]
	s_nop 0
	v_pk_fma_f32 v[0:1], v[16:17], v[90:91], v[0:1]
	s_nop 0
	v_pk_fma_f32 v[0:1], v[18:19], v[88:89], v[0:1]
	s_nop 0
	v_pk_fma_f32 v[0:1], v[20:21], v[84:85], v[0:1]
	s_nop 0
	v_pk_fma_f32 v[0:1], v[22:23], v[82:83], v[0:1]
	s_nop 0
	v_pk_fma_f32 v[0:1], v[24:25], v[78:79], v[0:1]
	s_nop 0
	v_pk_fma_f32 v[0:1], v[26:27], v[76:77], v[0:1]
	s_nop 0
	v_pk_fma_f32 v[0:1], v[28:29], v[74:75], v[0:1]
	s_nop 0
	v_pk_fma_f32 v[0:1], v[30:31], v[80:81], v[0:1]
	s_nop 0
	v_add_f32_e32 v135, v0, v1
	s_waitcnt vmcnt(12)
	v_cvt_scalef32_pk32_f32_fp6 v[0:31], v[142:147], 1.0
	v_pk_mul_f32 v[2:3], v[2:3], v[92:93]
	s_nop 0
	v_pk_fma_f32 v[0:1], v[0:1], v[94:95], v[2:3]
	s_nop 0
	v_pk_fma_f32 v[0:1], v[4:5], v[86:87], v[0:1]
	s_nop 0
	v_pk_fma_f32 v[0:1], v[6:7], v[100:101], v[0:1]
	s_nop 0
	v_pk_fma_f32 v[0:1], v[8:9], v[104:105], v[0:1]
	s_nop 0
	v_pk_fma_f32 v[0:1], v[10:11], v[102:103], v[0:1]
	s_nop 0
	v_pk_fma_f32 v[0:1], v[12:13], v[98:99], v[0:1]
	s_nop 0
	v_pk_fma_f32 v[0:1], v[14:15], v[96:97], v[0:1]
	s_nop 0
	v_pk_fma_f32 v[0:1], v[16:17], v[90:91], v[0:1]
	s_nop 0
	v_pk_fma_f32 v[0:1], v[18:19], v[88:89], v[0:1]
	s_nop 0
	v_pk_fma_f32 v[0:1], v[20:21], v[84:85], v[0:1]
	s_nop 0
	v_pk_fma_f32 v[0:1], v[22:23], v[82:83], v[0:1]
	s_nop 0
	v_pk_fma_f32 v[0:1], v[24:25], v[78:79], v[0:1]
	s_nop 0
	v_pk_fma_f32 v[0:1], v[26:27], v[76:77], v[0:1]
	s_nop 0
	v_pk_fma_f32 v[0:1], v[28:29], v[74:75], v[0:1]
	s_nop 0
	v_pk_fma_f32 v[0:1], v[30:31], v[80:81], v[0:1]
	s_nop 0
	v_add_f32_e32 v136, v0, v1
	s_waitcnt vmcnt(10)
	v_cvt_scalef32_pk32_f32_fp6 v[0:31], v[148:153], 1.0
	v_pk_mul_f32 v[2:3], v[2:3], v[92:93]
	s_nop 0
	v_pk_fma_f32 v[0:1], v[0:1], v[94:95], v[2:3]
	s_nop 0
	v_pk_fma_f32 v[0:1], v[4:5], v[86:87], v[0:1]
	s_nop 0
	v_pk_fma_f32 v[0:1], v[6:7], v[100:101], v[0:1]
	s_nop 0
	v_pk_fma_f32 v[0:1], v[8:9], v[104:105], v[0:1]
	s_nop 0
	v_pk_fma_f32 v[0:1], v[10:11], v[102:103], v[0:1]
	s_nop 0
	v_pk_fma_f32 v[0:1], v[12:13], v[98:99], v[0:1]
	s_nop 0
	v_pk_fma_f32 v[0:1], v[14:15], v[96:97], v[0:1]
	s_nop 0
	v_pk_fma_f32 v[0:1], v[16:17], v[90:91], v[0:1]
	s_nop 0
	v_pk_fma_f32 v[0:1], v[18:19], v[88:89], v[0:1]
	s_nop 0
	v_pk_fma_f32 v[0:1], v[20:21], v[84:85], v[0:1]
	s_nop 0
	v_pk_fma_f32 v[0:1], v[22:23], v[82:83], v[0:1]
	s_nop 0
	v_pk_fma_f32 v[0:1], v[24:25], v[78:79], v[0:1]
	s_nop 0
	v_pk_fma_f32 v[0:1], v[26:27], v[76:77], v[0:1]
	s_nop 0
	v_pk_fma_f32 v[0:1], v[28:29], v[74:75], v[0:1]
	s_nop 0
	v_pk_fma_f32 v[0:1], v[30:31], v[80:81], v[0:1]
	s_nop 0
	v_add_f32_e32 v137, v0, v1
	s_waitcnt vmcnt(8)
	v_cvt_scalef32_pk32_f32_fp6 v[0:31], v[154:159], 1.0
	v_pk_mul_f32 v[2:3], v[2:3], v[92:93]
	s_nop 0
	v_pk_fma_f32 v[0:1], v[0:1], v[94:95], v[2:3]
	s_nop 0
	v_pk_fma_f32 v[0:1], v[4:5], v[86:87], v[0:1]
	s_nop 0
	v_pk_fma_f32 v[0:1], v[6:7], v[100:101], v[0:1]
	s_nop 0
	v_pk_fma_f32 v[0:1], v[8:9], v[104:105], v[0:1]
	s_nop 0
	v_pk_fma_f32 v[0:1], v[10:11], v[102:103], v[0:1]
	s_nop 0
	v_pk_fma_f32 v[0:1], v[12:13], v[98:99], v[0:1]
	s_nop 0
	v_pk_fma_f32 v[0:1], v[14:15], v[96:97], v[0:1]
	s_nop 0
	v_pk_fma_f32 v[0:1], v[16:17], v[90:91], v[0:1]
	s_nop 0
	v_pk_fma_f32 v[0:1], v[18:19], v[88:89], v[0:1]
	s_nop 0
	v_pk_fma_f32 v[0:1], v[20:21], v[84:85], v[0:1]
	s_nop 0
	v_pk_fma_f32 v[0:1], v[22:23], v[82:83], v[0:1]
	s_nop 0
	v_pk_fma_f32 v[0:1], v[24:25], v[78:79], v[0:1]
	s_nop 0
	v_pk_fma_f32 v[0:1], v[26:27], v[76:77], v[0:1]
	s_nop 0
	v_pk_fma_f32 v[0:1], v[28:29], v[74:75], v[0:1]
	s_nop 0
	v_pk_fma_f32 v[0:1], v[30:31], v[80:81], v[0:1]
	s_nop 0
	v_add_f32_e32 v138, v0, v1
	s_waitcnt vmcnt(6)
	v_cvt_scalef32_pk32_f32_fp6 v[0:31], v[160:165], 1.0
	v_pk_mul_f32 v[2:3], v[2:3], v[92:93]
	s_nop 0
	v_pk_fma_f32 v[0:1], v[0:1], v[94:95], v[2:3]
	s_nop 0
	v_pk_fma_f32 v[0:1], v[4:5], v[86:87], v[0:1]
	s_nop 0
	v_pk_fma_f32 v[0:1], v[6:7], v[100:101], v[0:1]
	s_nop 0
	v_pk_fma_f32 v[0:1], v[8:9], v[104:105], v[0:1]
	s_nop 0
	v_pk_fma_f32 v[0:1], v[10:11], v[102:103], v[0:1]
	s_nop 0
	v_pk_fma_f32 v[0:1], v[12:13], v[98:99], v[0:1]
	s_nop 0
	v_pk_fma_f32 v[0:1], v[14:15], v[96:97], v[0:1]
	s_nop 0
	v_pk_fma_f32 v[0:1], v[16:17], v[90:91], v[0:1]
	s_nop 0
	v_pk_fma_f32 v[0:1], v[18:19], v[88:89], v[0:1]
	s_nop 0
	v_pk_fma_f32 v[0:1], v[20:21], v[84:85], v[0:1]
	s_nop 0
	v_pk_fma_f32 v[0:1], v[22:23], v[82:83], v[0:1]
	s_nop 0
	v_pk_fma_f32 v[0:1], v[24:25], v[78:79], v[0:1]
	s_nop 0
	v_pk_fma_f32 v[0:1], v[26:27], v[76:77], v[0:1]
	s_nop 0
	v_pk_fma_f32 v[0:1], v[28:29], v[74:75], v[0:1]
	s_nop 0
	v_pk_fma_f32 v[0:1], v[30:31], v[80:81], v[0:1]
	s_nop 0
	v_add_f32_e32 v139, v0, v1
	s_waitcnt vmcnt(4)
; DI void phase_peer_out(const Params& p, char* lds) {
;     ...
;       for (int kb = 0; kb < 4; ++kb) {
;         v6u qb[8];
; #pragma unroll
;         for (int k = 0; k < 8; ++k) {
;           const int e0 = __builtin_amdgcn_readlane(el[0], hf * 32 + kb * 8 + k), e1 = __builtin_amdgcn_readlane(el[1], hf * 32 + kb * 8 + k);
;           qb[k] = load6(U6 + (size_t)(hb ? e1 : e0) * 768);
;         }
; #pragma unroll
;         for (int k = 0; k < 8; ++k) {
;           const v32f f = __builtin_amdgcn_cvt_scalef32_pk32_f32_fp6(qb[k], 1.0f);
;           f32x2 a = f32x2{f[0], f[1]} * x2[0];
; #pragma unroll
;           for (int i = 1; i < 16; ++i) a = f32x2{f[2 * i], f[2 * i + 1]} * x2[i] + a;
;           pd[kb * 8 + k] = a.x + a.y;
	v_cvt_scalef32_pk32_f32_fp6 v[0:31], v[44:49], 1.0
	v_pk_mul_f32 v[2:3], v[2:3], v[92:93]
	s_nop 0
	v_pk_fma_f32 v[0:1], v[0:1], v[94:95], v[2:3]
	s_nop 0
	v_pk_fma_f32 v[0:1], v[4:5], v[86:87], v[0:1]
	s_nop 0
	v_pk_fma_f32 v[0:1], v[6:7], v[100:101], v[0:1]
	s_nop 0
	v_pk_fma_f32 v[0:1], v[8:9], v[104:105], v[0:1]
	s_nop 0
	v_pk_fma_f32 v[0:1], v[10:11], v[102:103], v[0:1]
	s_nop 0
	v_pk_fma_f32 v[0:1], v[12:13], v[98:99], v[0:1]
	s_nop 0
	v_pk_fma_f32 v[0:1], v[14:15], v[96:97], v[0:1]
	s_nop 0
	v_pk_fma_f32 v[0:1], v[16:17], v[90:91], v[0:1]
	s_nop 0
	v_pk_fma_f32 v[0:1], v[18:19], v[88:89], v[0:1]
	s_nop 0
	v_pk_fma_f32 v[0:1], v[20:21], v[84:85], v[0:1]
	s_nop 0
	v_pk_fma_f32 v[0:1], v[22:23], v[82:83], v[0:1]
	s_nop 0
	v_pk_fma_f32 v[0:1], v[24:25], v[78:79], v[0:1]
	s_nop 0
	v_pk_fma_f32 v[0:1], v[26:27], v[76:77], v[0:1]
	s_nop 0
	v_pk_fma_f32 v[0:1], v[28:29], v[74:75], v[0:1]
	s_nop 0
	v_pk_fma_f32 v[0:1], v[30:31], v[80:81], v[0:1]
	s_nop 0
	v_add_f32_e32 v141, v0, v1
	s_waitcnt vmcnt(2)
	v_cvt_scalef32_pk32_f32_fp6 v[0:31], v[38:43], 1.0
	v_pk_mul_f32 v[2:3], v[2:3], v[92:93]
	s_nop 0
	v_pk_fma_f32 v[0:1], v[0:1], v[94:95], v[2:3]
	s_nop 0
	v_pk_fma_f32 v[0:1], v[4:5], v[86:87], v[0:1]
	s_nop 0
	v_pk_fma_f32 v[0:1], v[6:7], v[100:101], v[0:1]
	s_nop 0
	v_pk_fma_f32 v[0:1], v[8:9], v[104:105], v[0:1]
	s_nop 0
	v_pk_fma_f32 v[0:1], v[10:11], v[102:103], v[0:1]
	s_nop 0
	v_pk_fma_f32 v[0:1], v[12:13], v[98:99], v[0:1]
	s_nop 0
	v_pk_fma_f32 v[0:1], v[14:15], v[96:97], v[0:1]
	s_nop 0
	v_pk_fma_f32 v[0:1], v[16:17], v[90:91], v[0:1]
	s_nop 0
	v_pk_fma_f32 v[0:1], v[18:19], v[88:89], v[0:1]
	s_nop 0
	v_pk_fma_f32 v[0:1], v[20:21], v[84:85], v[0:1]
	s_nop 0
	v_pk_fma_f32 v[0:1], v[22:23], v[82:83], v[0:1]
	s_nop 0
	v_pk_fma_f32 v[0:1], v[24:25], v[78:79], v[0:1]
	s_nop 0
	v_pk_fma_f32 v[0:1], v[26:27], v[76:77], v[0:1]
	s_nop 0
	v_pk_fma_f32 v[0:1], v[28:29], v[74:75], v[0:1]
	s_nop 0
	v_pk_fma_f32 v[0:1], v[30:31], v[80:81], v[0:1]
	s_nop 0
	v_add_f32_e32 v140, v0, v1
	s_waitcnt vmcnt(0)
	v_cvt_scalef32_pk32_f32_fp6 v[0:31], v[32:37], 1.0
	v_mov_b32_e32 v32, s13
	v_mov_b32_e32 v33, s12
	v_cndmask_b32_e64 v32, v32, v33, s[0:1]
	v_mad_u32_u24 v32, v32, s23, v251
	global_load_dwordx2 v[148:149], v32, s[98:99] offset:16
	global_load_dwordx4 v[144:147], v32, s[98:99]
	v_pk_mul_f32 v[2:3], v[2:3], v[92:93]
	v_readlane_b32 s12, v106, 49
	v_readlane_b32 s13, v107, 49
	v_pk_fma_f32 v[0:1], v[0:1], v[94:95], v[2:3]
	v_mov_b32_e32 v3, s12
	v_mov_b32_e32 v2, s13
	v_cndmask_b32_e64 v2, v2, v3, s[0:1]
	v_mad_u32_u24 v2, v2, s23, v251
	v_pk_fma_f32 v[0:1], v[4:5], v[86:87], v[0:1]
	global_load_dwordx2 v[154:155], v2, s[98:99] offset:16
	global_load_dwordx4 v[150:153], v2, s[98:99]
	v_pk_fma_f32 v[0:1], v[6:7], v[100:101], v[0:1]
	v_readlane_b32 s12, v106, 50
	v_pk_fma_f32 v[0:1], v[8:9], v[104:105], v[0:1]
	v_readlane_b32 s13, v107, 50
	v_pk_fma_f32 v[0:1], v[10:11], v[102:103], v[0:1]
	s_nop 0
	v_pk_fma_f32 v[0:1], v[12:13], v[98:99], v[0:1]
	s_nop 0
	v_pk_fma_f32 v[0:1], v[14:15], v[96:97], v[0:1]
	s_nop 0
	v_pk_fma_f32 v[0:1], v[16:17], v[90:91], v[0:1]
	s_nop 0
	v_pk_fma_f32 v[0:1], v[18:19], v[88:89], v[0:1]
	s_nop 0
	v_pk_fma_f32 v[0:1], v[20:21], v[84:85], v[0:1]
	s_nop 0
	v_pk_fma_f32 v[0:1], v[22:23], v[82:83], v[0:1]
	s_nop 0
	v_pk_fma_f32 v[0:1], v[24:25], v[78:79], v[0:1]
	s_nop 0
	v_pk_fma_f32 v[0:1], v[26:27], v[76:77], v[0:1]
	s_nop 0
	v_pk_fma_f32 v[0:1], v[28:29], v[74:75], v[0:1]
	s_nop 0
	v_pk_fma_f32 v[0:1], v[30:31], v[80:81], v[0:1]
	s_nop 0
	v_add_f32_e32 v142, v0, v1
	v_mov_b32_e32 v0, s13
	v_mov_b32_e32 v1, s12
	v_cndmask_b32_e64 v0, v0, v1, s[0:1]
	v_mad_u32_u24 v0, v0, s23, v251
	global_load_dwordx2 v[160:161], v0, s[98:99] offset:16
	global_load_dwordx4 v[156:159], v0, s[98:99]
	v_readlane_b32 s12, v106, 51
	v_readlane_b32 s13, v107, 51
	s_nop 0
	v_mov_b32_e32 v1, s12
	v_mov_b32_e32 v0, s13
	v_cndmask_b32_e64 v0, v0, v1, s[0:1]
	v_mad_u32_u24 v0, v0, s23, v251
	global_load_dwordx2 v[166:167], v0, s[98:99] offset:16
	global_load_dwordx4 v[162:165], v0, s[98:99]
	v_readlane_b32 s12, v106, 52
	v_readlane_b32 s13, v107, 52
	s_nop 0
	v_mov_b32_e32 v1, s12
	v_mov_b32_e32 v0, s13
	v_cndmask_b32_e64 v0, v0, v1, s[0:1]
	v_mad_u32_u24 v0, v0, s23, v251
	global_load_dwordx2 v[172:173], v0, s[98:99] offset:16
	global_load_dwordx4 v[168:171], v0, s[98:99]
	v_readlane_b32 s12, v106, 53
	v_readlane_b32 s13, v107, 53
	s_nop 0
	v_mov_b32_e32 v1, s12
	v_mov_b32_e32 v0, s13
	v_cndmask_b32_e64 v0, v0, v1, s[0:1]
	v_mad_u32_u24 v0, v0, s23, v251
	v_readlane_b32 s12, v106, 54
	v_readlane_b32 s13, v107, 54
	global_load_dwordx2 v[48:49], v0, s[98:99] offset:16
	global_load_dwordx4 v[44:47], v0, s[98:99]
	v_mov_b32_e32 v0, s13
	v_mov_b32_e32 v1, s12
	v_cndmask_b32_e64 v0, v0, v1, s[0:1]
	v_mad_u32_u24 v0, v0, s23, v251
	v_readlane_b32 s12, v106, 55
	v_readlane_b32 s13, v107, 55
	global_load_dwordx2 v[42:43], v0, s[98:99] offset:16
	global_load_dwordx4 v[38:41], v0, s[98:99]
	v_mov_b32_e32 v0, s13
	v_mov_b32_e32 v1, s12
	v_cndmask_b32_e64 v0, v0, v1, s[0:1]
	v_mad_u32_u24 v0, v0, s23, v251
	global_load_dwordx2 v[36:37], v0, s[98:99] offset:16
	global_load_dwordx4 v[32:35], v0, s[98:99]
	s_waitcnt vmcnt(14)
; DI void phase_peer_out(const Params& p, char* lds) {
;     ...
; #pragma unroll
;         for (int k = 0; k < 8; ++k) {
;           const v32f f = __builtin_amdgcn_cvt_scalef32_pk32_f32_fp6(qb[k], 1.0f);
;           f32x2 a = f32x2{f[0], f[1]} * x2[0];
; #pragma unroll
;           for (int i = 1; i < 16; ++i) a = f32x2{f[2 * i], f[2 * i + 1]} * x2[i] + a;
;           pd[kb * 8 + k] = a.x + a.y;
	v_cvt_scalef32_pk32_f32_fp6 v[0:31], v[144:149], 1.0
	v_pk_mul_f32 v[2:3], v[2:3], v[92:93]
	v_readlane_b32 s12, v106, 56
	v_pk_fma_f32 v[0:1], v[0:1], v[94:95], v[2:3]
	v_readlane_b32 s13, v107, 56
	v_pk_fma_f32 v[0:1], v[4:5], v[86:87], v[0:1]
	s_nop 0
	v_pk_fma_f32 v[0:1], v[6:7], v[100:101], v[0:1]
	s_nop 0
	v_pk_fma_f32 v[0:1], v[8:9], v[104:105], v[0:1]
	s_nop 0
	v_pk_fma_f32 v[0:1], v[10:11], v[102:103], v[0:1]
	s_nop 0
	v_pk_fma_f32 v[0:1], v[12:13], v[98:99], v[0:1]
	s_nop 0
	v_pk_fma_f32 v[0:1], v[14:15], v[96:97], v[0:1]
	s_nop 0
	v_pk_fma_f32 v[0:1], v[16:17], v[90:91], v[0:1]
	s_nop 0
	v_pk_fma_f32 v[0:1], v[18:19], v[88:89], v[0:1]
	s_nop 0
	v_pk_fma_f32 v[0:1], v[20:21], v[84:85], v[0:1]
	s_nop 0
	v_pk_fma_f32 v[0:1], v[22:23], v[82:83], v[0:1]
	s_nop 0
	v_pk_fma_f32 v[0:1], v[24:25], v[78:79], v[0:1]
	s_nop 0
	v_pk_fma_f32 v[0:1], v[26:27], v[76:77], v[0:1]
	s_nop 0
	v_pk_fma_f32 v[0:1], v[28:29], v[74:75], v[0:1]
	s_nop 0
	v_pk_fma_f32 v[0:1], v[30:31], v[80:81], v[0:1]
	s_nop 0
	v_add_f32_e32 v143, v0, v1
	s_waitcnt vmcnt(12)
	v_cvt_scalef32_pk32_f32_fp6 v[0:31], v[150:155], 1.0
	v_pk_mul_f32 v[2:3], v[2:3], v[92:93]
	s_nop 0
	v_pk_fma_f32 v[0:1], v[0:1], v[94:95], v[2:3]
	s_nop 0
	v_pk_fma_f32 v[0:1], v[4:5], v[86:87], v[0:1]
	s_nop 0
	v_pk_fma_f32 v[0:1], v[6:7], v[100:101], v[0:1]
	s_nop 0
	v_pk_fma_f32 v[0:1], v[8:9], v[104:105], v[0:1]
	s_nop 0
	v_pk_fma_f32 v[0:1], v[10:11], v[102:103], v[0:1]
	s_nop 0
	v_pk_fma_f32 v[0:1], v[12:13], v[98:99], v[0:1]
	s_nop 0
	v_pk_fma_f32 v[0:1], v[14:15], v[96:97], v[0:1]
	s_nop 0
	v_pk_fma_f32 v[0:1], v[16:17], v[90:91], v[0:1]
	s_nop 0
	v_pk_fma_f32 v[0:1], v[18:19], v[88:89], v[0:1]
	s_nop 0
	v_pk_fma_f32 v[0:1], v[20:21], v[84:85], v[0:1]
	s_nop 0
	v_pk_fma_f32 v[0:1], v[22:23], v[82:83], v[0:1]
	s_nop 0
	v_pk_fma_f32 v[0:1], v[24:25], v[78:79], v[0:1]
	s_nop 0
	v_pk_fma_f32 v[0:1], v[26:27], v[76:77], v[0:1]
	s_nop 0
	v_pk_fma_f32 v[0:1], v[28:29], v[74:75], v[0:1]
	s_nop 0
	v_pk_fma_f32 v[0:1], v[30:31], v[80:81], v[0:1]
	s_nop 0
	v_add_f32_e32 v144, v0, v1
	s_waitcnt vmcnt(10)
	v_cvt_scalef32_pk32_f32_fp6 v[0:31], v[156:161], 1.0
	v_pk_mul_f32 v[2:3], v[2:3], v[92:93]
	s_nop 0
	v_pk_fma_f32 v[0:1], v[0:1], v[94:95], v[2:3]
	s_nop 0
	v_pk_fma_f32 v[0:1], v[4:5], v[86:87], v[0:1]
	s_nop 0
	v_pk_fma_f32 v[0:1], v[6:7], v[100:101], v[0:1]
	s_nop 0
	v_pk_fma_f32 v[0:1], v[8:9], v[104:105], v[0:1]
	s_nop 0
	v_pk_fma_f32 v[0:1], v[10:11], v[102:103], v[0:1]
	s_nop 0
	v_pk_fma_f32 v[0:1], v[12:13], v[98:99], v[0:1]
	s_nop 0
	v_pk_fma_f32 v[0:1], v[14:15], v[96:97], v[0:1]
	s_nop 0
	v_pk_fma_f32 v[0:1], v[16:17], v[90:91], v[0:1]
	s_nop 0
	v_pk_fma_f32 v[0:1], v[18:19], v[88:89], v[0:1]
	s_nop 0
	v_pk_fma_f32 v[0:1], v[20:21], v[84:85], v[0:1]
	s_nop 0
	v_pk_fma_f32 v[0:1], v[22:23], v[82:83], v[0:1]
	s_nop 0
	v_pk_fma_f32 v[0:1], v[24:25], v[78:79], v[0:1]
	s_nop 0
	v_pk_fma_f32 v[0:1], v[26:27], v[76:77], v[0:1]
	s_nop 0
	v_pk_fma_f32 v[0:1], v[28:29], v[74:75], v[0:1]
	s_nop 0
	v_pk_fma_f32 v[0:1], v[30:31], v[80:81], v[0:1]
	s_nop 0
	v_add_f32_e32 v145, v0, v1
	s_waitcnt vmcnt(8)
	v_cvt_scalef32_pk32_f32_fp6 v[0:31], v[162:167], 1.0
	v_pk_mul_f32 v[2:3], v[2:3], v[92:93]
	s_nop 0
	v_pk_fma_f32 v[0:1], v[0:1], v[94:95], v[2:3]
	s_nop 0
	v_pk_fma_f32 v[0:1], v[4:5], v[86:87], v[0:1]
	s_nop 0
	v_pk_fma_f32 v[0:1], v[6:7], v[100:101], v[0:1]
	s_nop 0
	v_pk_fma_f32 v[0:1], v[8:9], v[104:105], v[0:1]
	s_nop 0
	v_pk_fma_f32 v[0:1], v[10:11], v[102:103], v[0:1]
	s_nop 0
	v_pk_fma_f32 v[0:1], v[12:13], v[98:99], v[0:1]
	s_nop 0
	v_pk_fma_f32 v[0:1], v[14:15], v[96:97], v[0:1]
	s_nop 0
	v_pk_fma_f32 v[0:1], v[16:17], v[90:91], v[0:1]
	s_nop 0
	v_pk_fma_f32 v[0:1], v[18:19], v[88:89], v[0:1]
	s_nop 0
	v_pk_fma_f32 v[0:1], v[20:21], v[84:85], v[0:1]
	s_nop 0
	v_pk_fma_f32 v[0:1], v[22:23], v[82:83], v[0:1]
	s_nop 0
	v_pk_fma_f32 v[0:1], v[24:25], v[78:79], v[0:1]
	s_nop 0
	v_pk_fma_f32 v[0:1], v[26:27], v[76:77], v[0:1]
	s_nop 0
	v_pk_fma_f32 v[0:1], v[28:29], v[74:75], v[0:1]
	s_nop 0
	v_pk_fma_f32 v[0:1], v[30:31], v[80:81], v[0:1]
	s_nop 0
	v_add_f32_e32 v146, v0, v1
	s_waitcnt vmcnt(6)
	v_cvt_scalef32_pk32_f32_fp6 v[0:31], v[168:173], 1.0
	v_pk_mul_f32 v[2:3], v[2:3], v[92:93]
	s_nop 0
	v_pk_fma_f32 v[0:1], v[0:1], v[94:95], v[2:3]
	s_nop 0
	v_pk_fma_f32 v[0:1], v[4:5], v[86:87], v[0:1]
	s_nop 0
	v_pk_fma_f32 v[0:1], v[6:7], v[100:101], v[0:1]
	s_nop 0
	v_pk_fma_f32 v[0:1], v[8:9], v[104:105], v[0:1]
	s_nop 0
	v_pk_fma_f32 v[0:1], v[10:11], v[102:103], v[0:1]
	s_nop 0
	v_pk_fma_f32 v[0:1], v[12:13], v[98:99], v[0:1]
	s_nop 0
	v_pk_fma_f32 v[0:1], v[14:15], v[96:97], v[0:1]
	s_nop 0
	v_pk_fma_f32 v[0:1], v[16:17], v[90:91], v[0:1]
	s_nop 0
	v_pk_fma_f32 v[0:1], v[18:19], v[88:89], v[0:1]
	s_nop 0
	v_pk_fma_f32 v[0:1], v[20:21], v[84:85], v[0:1]
	s_nop 0
	v_pk_fma_f32 v[0:1], v[22:23], v[82:83], v[0:1]
	s_nop 0
	v_pk_fma_f32 v[0:1], v[24:25], v[78:79], v[0:1]
	s_nop 0
	v_pk_fma_f32 v[0:1], v[26:27], v[76:77], v[0:1]
	s_nop 0
	v_pk_fma_f32 v[0:1], v[28:29], v[74:75], v[0:1]
	s_nop 0
	v_pk_fma_f32 v[0:1], v[30:31], v[80:81], v[0:1]
	s_nop 0
	v_add_f32_e32 v147, v0, v1
	s_waitcnt vmcnt(4)
; DI void phase_peer_out(const Params& p, char* lds) {
;     ...
;       for (int kb = 0; kb < 4; ++kb) {
;         v6u qb[8];
; #pragma unroll
;         for (int k = 0; k < 8; ++k) {
;           const int e0 = __builtin_amdgcn_readlane(el[0], hf * 32 + kb * 8 + k), e1 = __builtin_amdgcn_readlane(el[1], hf * 32 + kb * 8 + k);
;           qb[k] = load6(U6 + (size_t)(hb ? e1 : e0) * 768);
;         }
; #pragma unroll
;         for (int k = 0; k < 8; ++k) {
;           const v32f f = __builtin_amdgcn_cvt_scalef32_pk32_f32_fp6(qb[k], 1.0f);
;           f32x2 a = f32x2{f[0], f[1]} * x2[0];
; #pragma unroll
;           for (int i = 1; i < 16; ++i) a = f32x2{f[2 * i], f[2 * i + 1]} * x2[i] + a;
;           pd[kb * 8 + k] = a.x + a.y;
	v_cvt_scalef32_pk32_f32_fp6 v[0:31], v[44:49], 1.0
	v_pk_mul_f32 v[2:3], v[2:3], v[92:93]
	s_nop 0
	v_pk_fma_f32 v[0:1], v[0:1], v[94:95], v[2:3]
	s_nop 0
	v_pk_fma_f32 v[0:1], v[4:5], v[86:87], v[0:1]
	s_nop 0
	v_pk_fma_f32 v[0:1], v[6:7], v[100:101], v[0:1]
	s_nop 0
	v_pk_fma_f32 v[0:1], v[8:9], v[104:105], v[0:1]
	s_nop 0
	v_pk_fma_f32 v[0:1], v[10:11], v[102:103], v[0:1]
	s_nop 0
	v_pk_fma_f32 v[0:1], v[12:13], v[98:99], v[0:1]
	s_nop 0
	v_pk_fma_f32 v[0:1], v[14:15], v[96:97], v[0:1]
	s_nop 0
	v_pk_fma_f32 v[0:1], v[16:17], v[90:91], v[0:1]
	s_nop 0
	v_pk_fma_f32 v[0:1], v[18:19], v[88:89], v[0:1]
	s_nop 0
	v_pk_fma_f32 v[0:1], v[20:21], v[84:85], v[0:1]
	s_nop 0
	v_pk_fma_f32 v[0:1], v[22:23], v[82:83], v[0:1]
	s_nop 0
	v_pk_fma_f32 v[0:1], v[24:25], v[78:79], v[0:1]
	s_nop 0
	v_pk_fma_f32 v[0:1], v[26:27], v[76:77], v[0:1]
	s_nop 0
	v_pk_fma_f32 v[0:1], v[28:29], v[74:75], v[0:1]
	s_nop 0
	v_pk_fma_f32 v[0:1], v[30:31], v[80:81], v[0:1]
	s_nop 0
	v_add_f32_e32 v148, v0, v1
	s_waitcnt vmcnt(2)
	v_cvt_scalef32_pk32_f32_fp6 v[0:31], v[38:43], 1.0
	v_pk_mul_f32 v[2:3], v[2:3], v[92:93]
	s_nop 0
	v_pk_fma_f32 v[0:1], v[0:1], v[94:95], v[2:3]
	s_nop 0
	v_pk_fma_f32 v[0:1], v[4:5], v[86:87], v[0:1]
	s_nop 0
	v_pk_fma_f32 v[0:1], v[6:7], v[100:101], v[0:1]
	s_nop 0
	v_pk_fma_f32 v[0:1], v[8:9], v[104:105], v[0:1]
	s_nop 0
	v_pk_fma_f32 v[0:1], v[10:11], v[102:103], v[0:1]
	s_nop 0
	v_pk_fma_f32 v[0:1], v[12:13], v[98:99], v[0:1]
	s_nop 0
	v_pk_fma_f32 v[0:1], v[14:15], v[96:97], v[0:1]
	s_nop 0
	v_pk_fma_f32 v[0:1], v[16:17], v[90:91], v[0:1]
	s_nop 0
	v_pk_fma_f32 v[0:1], v[18:19], v[88:89], v[0:1]
	s_nop 0
	v_pk_fma_f32 v[0:1], v[20:21], v[84:85], v[0:1]
	s_nop 0
	v_pk_fma_f32 v[0:1], v[22:23], v[82:83], v[0:1]
	s_nop 0
	v_pk_fma_f32 v[0:1], v[24:25], v[78:79], v[0:1]
	s_nop 0
	v_pk_fma_f32 v[0:1], v[26:27], v[76:77], v[0:1]
	s_nop 0
	v_pk_fma_f32 v[0:1], v[28:29], v[74:75], v[0:1]
	s_nop 0
	v_pk_fma_f32 v[0:1], v[30:31], v[80:81], v[0:1]
	s_nop 0
	v_add_f32_e32 v149, v0, v1
	s_waitcnt vmcnt(0)
	v_cvt_scalef32_pk32_f32_fp6 v[0:31], v[32:37], 1.0
	v_mov_b32_e32 v32, s13
	v_mov_b32_e32 v33, s12
	v_cndmask_b32_e64 v32, v32, v33, s[0:1]
	v_mad_u32_u24 v32, v32, s23, v251
	global_load_dwordx2 v[156:157], v32, s[98:99] offset:16
	global_load_dwordx4 v[152:155], v32, s[98:99]
	v_pk_mul_f32 v[2:3], v[2:3], v[92:93]
	v_readlane_b32 s12, v106, 57
	v_readlane_b32 s13, v107, 57
	v_pk_fma_f32 v[0:1], v[0:1], v[94:95], v[2:3]
	v_mov_b32_e32 v3, s12
	v_mov_b32_e32 v2, s13
	v_cndmask_b32_e64 v2, v2, v3, s[0:1]
	v_mad_u32_u24 v2, v2, s23, v251
	v_pk_fma_f32 v[0:1], v[4:5], v[86:87], v[0:1]
	global_load_dwordx2 v[162:163], v2, s[98:99] offset:16
	global_load_dwordx4 v[158:161], v2, s[98:99]
	v_pk_fma_f32 v[0:1], v[6:7], v[100:101], v[0:1]
	v_readlane_b32 s12, v106, 58
	v_pk_fma_f32 v[0:1], v[8:9], v[104:105], v[0:1]
	v_readlane_b32 s13, v107, 58
	v_pk_fma_f32 v[0:1], v[10:11], v[102:103], v[0:1]
	s_nop 0
	v_pk_fma_f32 v[0:1], v[12:13], v[98:99], v[0:1]
	s_nop 0
	v_pk_fma_f32 v[0:1], v[14:15], v[96:97], v[0:1]
	s_nop 0
	v_pk_fma_f32 v[0:1], v[16:17], v[90:91], v[0:1]
	s_nop 0
	v_pk_fma_f32 v[0:1], v[18:19], v[88:89], v[0:1]
	s_nop 0
	v_pk_fma_f32 v[0:1], v[20:21], v[84:85], v[0:1]
	s_nop 0
	v_pk_fma_f32 v[0:1], v[22:23], v[82:83], v[0:1]
	s_nop 0
	v_pk_fma_f32 v[0:1], v[24:25], v[78:79], v[0:1]
	s_nop 0
	v_pk_fma_f32 v[0:1], v[26:27], v[76:77], v[0:1]
	s_nop 0
	v_pk_fma_f32 v[0:1], v[28:29], v[74:75], v[0:1]
	s_nop 0
	v_pk_fma_f32 v[0:1], v[30:31], v[80:81], v[0:1]
	s_nop 0
	v_add_f32_e32 v150, v0, v1
	v_mov_b32_e32 v0, s13
	v_mov_b32_e32 v1, s12
	v_cndmask_b32_e64 v0, v0, v1, s[0:1]
	v_mad_u32_u24 v0, v0, s23, v251
	global_load_dwordx2 v[168:169], v0, s[98:99] offset:16
	global_load_dwordx4 v[164:167], v0, s[98:99]
	v_readlane_b32 s12, v106, 59
	v_readlane_b32 s13, v107, 59
	s_nop 0
	v_mov_b32_e32 v1, s12
	v_mov_b32_e32 v0, s13
	v_cndmask_b32_e64 v0, v0, v1, s[0:1]
	v_mad_u32_u24 v0, v0, s23, v251
	global_load_dwordx2 v[174:175], v0, s[98:99] offset:16
	global_load_dwordx4 v[170:173], v0, s[98:99]
	v_readlane_b32 s12, v106, 60
	v_readlane_b32 s13, v107, 60
	s_nop 0
	v_mov_b32_e32 v1, s12
	v_mov_b32_e32 v0, s13
	v_cndmask_b32_e64 v0, v0, v1, s[0:1]
	v_mad_u32_u24 v0, v0, s23, v251
	global_load_dwordx2 v[180:181], v0, s[98:99] offset:16
	global_load_dwordx4 v[176:179], v0, s[98:99]
	v_readlane_b32 s12, v106, 61
	v_readlane_b32 s13, v107, 61
	s_nop 0
	v_mov_b32_e32 v1, s12
	v_mov_b32_e32 v0, s13
	v_cndmask_b32_e64 v0, v0, v1, s[0:1]
	v_mad_u32_u24 v0, v0, s23, v251
	v_readlane_b32 s12, v106, 62
	v_readlane_b32 s13, v107, 62
	global_load_dwordx2 v[48:49], v0, s[98:99] offset:16
	global_load_dwordx4 v[44:47], v0, s[98:99]
	v_mov_b32_e32 v0, s13
	v_mov_b32_e32 v1, s12
	v_cndmask_b32_e64 v0, v0, v1, s[0:1]
	v_mad_u32_u24 v0, v0, s23, v251
	v_readlane_b32 s12, v106, 63
	v_readlane_b32 s13, v107, 63
	global_load_dwordx2 v[42:43], v0, s[98:99] offset:16
	global_load_dwordx4 v[38:41], v0, s[98:99]
	v_mov_b32_e32 v0, s13
	v_mov_b32_e32 v1, s12
	v_cndmask_b32_e64 v0, v0, v1, s[0:1]
	v_mad_u32_u24 v0, v0, s23, v251
	global_load_dwordx2 v[36:37], v0, s[98:99] offset:16
	global_load_dwordx4 v[32:35], v0, s[98:99]
	s_waitcnt vmcnt(14)
; DI void phase_peer_out(const Params& p, char* lds) {
;     ...
; #pragma unroll
;         for (int k = 0; k < 8; ++k) {
;           const v32f f = __builtin_amdgcn_cvt_scalef32_pk32_f32_fp6(qb[k], 1.0f);
;           f32x2 a = f32x2{f[0], f[1]} * x2[0];
; #pragma unroll
;           for (int i = 1; i < 16; ++i) a = f32x2{f[2 * i], f[2 * i + 1]} * x2[i] + a;
;           pd[kb * 8 + k] = a.x + a.y;
	v_cvt_scalef32_pk32_f32_fp6 v[0:31], v[152:157], 1.0
	v_pk_mul_f32 v[2:3], v[2:3], v[92:93]
	s_nop 0
	v_pk_fma_f32 v[0:1], v[0:1], v[94:95], v[2:3]
	s_nop 0
	v_pk_fma_f32 v[0:1], v[4:5], v[86:87], v[0:1]
	s_nop 0
	v_pk_fma_f32 v[0:1], v[6:7], v[100:101], v[0:1]
	s_nop 0
	v_pk_fma_f32 v[0:1], v[8:9], v[104:105], v[0:1]
	s_nop 0
	v_pk_fma_f32 v[0:1], v[10:11], v[102:103], v[0:1]
	s_nop 0
	v_pk_fma_f32 v[0:1], v[12:13], v[98:99], v[0:1]
	s_nop 0
	v_pk_fma_f32 v[0:1], v[14:15], v[96:97], v[0:1]
	s_nop 0
	v_pk_fma_f32 v[0:1], v[16:17], v[90:91], v[0:1]
	s_nop 0
	v_pk_fma_f32 v[0:1], v[18:19], v[88:89], v[0:1]
	s_nop 0
	v_pk_fma_f32 v[0:1], v[20:21], v[84:85], v[0:1]
	s_nop 0
	v_pk_fma_f32 v[0:1], v[22:23], v[82:83], v[0:1]
	s_nop 0
	v_pk_fma_f32 v[0:1], v[24:25], v[78:79], v[0:1]
	s_nop 0
	v_pk_fma_f32 v[0:1], v[26:27], v[76:77], v[0:1]
	s_nop 0
	v_pk_fma_f32 v[0:1], v[28:29], v[74:75], v[0:1]
	s_nop 0
	v_pk_fma_f32 v[0:1], v[30:31], v[80:81], v[0:1]
	s_nop 0
	v_add_f32_e32 v106, v0, v1
	s_waitcnt vmcnt(12)
	v_cvt_scalef32_pk32_f32_fp6 v[0:31], v[158:163], 1.0
	v_pk_mul_f32 v[2:3], v[2:3], v[92:93]
	s_nop 0
	v_pk_fma_f32 v[0:1], v[0:1], v[94:95], v[2:3]
	s_nop 0
	v_pk_fma_f32 v[0:1], v[4:5], v[86:87], v[0:1]
	s_nop 0
	v_pk_fma_f32 v[0:1], v[6:7], v[100:101], v[0:1]
	s_nop 0
	v_pk_fma_f32 v[0:1], v[8:9], v[104:105], v[0:1]
	s_nop 0
	v_pk_fma_f32 v[0:1], v[10:11], v[102:103], v[0:1]
	s_nop 0
	v_pk_fma_f32 v[0:1], v[12:13], v[98:99], v[0:1]
	s_nop 0
	v_pk_fma_f32 v[0:1], v[14:15], v[96:97], v[0:1]
	s_nop 0
	v_pk_fma_f32 v[0:1], v[16:17], v[90:91], v[0:1]
	s_nop 0
	v_pk_fma_f32 v[0:1], v[18:19], v[88:89], v[0:1]
	s_nop 0
	v_pk_fma_f32 v[0:1], v[20:21], v[84:85], v[0:1]
	s_nop 0
	v_pk_fma_f32 v[0:1], v[22:23], v[82:83], v[0:1]
	s_nop 0
	v_pk_fma_f32 v[0:1], v[24:25], v[78:79], v[0:1]
	s_nop 0
	v_pk_fma_f32 v[0:1], v[26:27], v[76:77], v[0:1]
	s_nop 0
	v_pk_fma_f32 v[0:1], v[28:29], v[74:75], v[0:1]
	s_nop 0
	v_pk_fma_f32 v[0:1], v[30:31], v[80:81], v[0:1]
	s_nop 0
	v_add_f32_e32 v151, v0, v1
	s_waitcnt vmcnt(10)
	v_cvt_scalef32_pk32_f32_fp6 v[0:31], v[164:169], 1.0
	v_pk_mul_f32 v[2:3], v[2:3], v[92:93]
	s_nop 0
	v_pk_fma_f32 v[0:1], v[0:1], v[94:95], v[2:3]
	s_nop 0
	v_pk_fma_f32 v[0:1], v[4:5], v[86:87], v[0:1]
	s_nop 0
	v_pk_fma_f32 v[0:1], v[6:7], v[100:101], v[0:1]
	s_nop 0
	v_pk_fma_f32 v[0:1], v[8:9], v[104:105], v[0:1]
	s_nop 0
	v_pk_fma_f32 v[0:1], v[10:11], v[102:103], v[0:1]
	s_nop 0
	v_pk_fma_f32 v[0:1], v[12:13], v[98:99], v[0:1]
	s_nop 0
	v_pk_fma_f32 v[0:1], v[14:15], v[96:97], v[0:1]
	s_nop 0
	v_pk_fma_f32 v[0:1], v[16:17], v[90:91], v[0:1]
	s_nop 0
	v_pk_fma_f32 v[0:1], v[18:19], v[88:89], v[0:1]
	s_nop 0
	v_pk_fma_f32 v[0:1], v[20:21], v[84:85], v[0:1]
	s_nop 0
	v_pk_fma_f32 v[0:1], v[22:23], v[82:83], v[0:1]
	s_nop 0
	v_pk_fma_f32 v[0:1], v[24:25], v[78:79], v[0:1]
	s_nop 0
	v_pk_fma_f32 v[0:1], v[26:27], v[76:77], v[0:1]
	s_nop 0
	v_pk_fma_f32 v[0:1], v[28:29], v[74:75], v[0:1]
	s_nop 0
	v_pk_fma_f32 v[0:1], v[30:31], v[80:81], v[0:1]
	s_nop 0
	v_add_f32_e32 v152, v0, v1
	s_waitcnt vmcnt(8)
	v_cvt_scalef32_pk32_f32_fp6 v[0:31], v[170:175], 1.0
	v_pk_mul_f32 v[2:3], v[2:3], v[92:93]
	s_nop 0
	v_pk_fma_f32 v[0:1], v[0:1], v[94:95], v[2:3]
	s_nop 0
	v_pk_fma_f32 v[0:1], v[4:5], v[86:87], v[0:1]
	s_nop 0
	v_pk_fma_f32 v[0:1], v[6:7], v[100:101], v[0:1]
	s_nop 0
	v_pk_fma_f32 v[0:1], v[8:9], v[104:105], v[0:1]
	s_nop 0
	v_pk_fma_f32 v[0:1], v[10:11], v[102:103], v[0:1]
	s_nop 0
	v_pk_fma_f32 v[0:1], v[12:13], v[98:99], v[0:1]
	s_nop 0
	v_pk_fma_f32 v[0:1], v[14:15], v[96:97], v[0:1]
	s_nop 0
	v_pk_fma_f32 v[0:1], v[16:17], v[90:91], v[0:1]
	s_nop 0
	v_pk_fma_f32 v[0:1], v[18:19], v[88:89], v[0:1]
	s_nop 0
	v_pk_fma_f32 v[0:1], v[20:21], v[84:85], v[0:1]
	s_nop 0
	v_pk_fma_f32 v[0:1], v[22:23], v[82:83], v[0:1]
	s_nop 0
	v_pk_fma_f32 v[0:1], v[24:25], v[78:79], v[0:1]
	s_nop 0
	v_pk_fma_f32 v[0:1], v[26:27], v[76:77], v[0:1]
	s_nop 0
	v_pk_fma_f32 v[0:1], v[28:29], v[74:75], v[0:1]
	s_nop 0
	v_pk_fma_f32 v[0:1], v[30:31], v[80:81], v[0:1]
	s_nop 0
	v_add_f32_e32 v153, v0, v1
	s_waitcnt vmcnt(6)
	v_cvt_scalef32_pk32_f32_fp6 v[0:31], v[176:181], 1.0
	v_pk_mul_f32 v[2:3], v[2:3], v[92:93]
	s_nop 0
	v_pk_fma_f32 v[0:1], v[0:1], v[94:95], v[2:3]
	s_nop 0
	v_pk_fma_f32 v[0:1], v[4:5], v[86:87], v[0:1]
	s_nop 0
	v_pk_fma_f32 v[0:1], v[6:7], v[100:101], v[0:1]
	s_nop 0
	v_pk_fma_f32 v[0:1], v[8:9], v[104:105], v[0:1]
	s_nop 0
	v_pk_fma_f32 v[0:1], v[10:11], v[102:103], v[0:1]
	s_nop 0
	v_pk_fma_f32 v[0:1], v[12:13], v[98:99], v[0:1]
	s_nop 0
	v_pk_fma_f32 v[0:1], v[14:15], v[96:97], v[0:1]
	s_nop 0
	v_pk_fma_f32 v[0:1], v[16:17], v[90:91], v[0:1]
	s_nop 0
	v_pk_fma_f32 v[0:1], v[18:19], v[88:89], v[0:1]
	s_nop 0
	v_pk_fma_f32 v[0:1], v[20:21], v[84:85], v[0:1]
	s_nop 0
	v_pk_fma_f32 v[0:1], v[22:23], v[82:83], v[0:1]
	s_nop 0
	v_pk_fma_f32 v[0:1], v[24:25], v[78:79], v[0:1]
	s_nop 0
	v_pk_fma_f32 v[0:1], v[26:27], v[76:77], v[0:1]
	s_nop 0
	v_pk_fma_f32 v[0:1], v[28:29], v[74:75], v[0:1]
	s_nop 0
	v_pk_fma_f32 v[0:1], v[30:31], v[80:81], v[0:1]
	s_nop 0
	v_add_f32_e32 v154, v0, v1
	s_waitcnt vmcnt(4)
	v_cvt_scalef32_pk32_f32_fp6 v[0:31], v[44:49], 1.0
	v_pk_mul_f32 v[2:3], v[2:3], v[92:93]
	s_nop 0
	v_pk_fma_f32 v[0:1], v[0:1], v[94:95], v[2:3]
	s_nop 0
	v_pk_fma_f32 v[0:1], v[4:5], v[86:87], v[0:1]
	s_nop 0
	v_pk_fma_f32 v[0:1], v[6:7], v[100:101], v[0:1]
	s_nop 0
	v_pk_fma_f32 v[0:1], v[8:9], v[104:105], v[0:1]
	s_nop 0
	v_pk_fma_f32 v[0:1], v[10:11], v[102:103], v[0:1]
	s_nop 0
	v_pk_fma_f32 v[0:1], v[12:13], v[98:99], v[0:1]
	s_nop 0
	v_pk_fma_f32 v[0:1], v[14:15], v[96:97], v[0:1]
	s_nop 0
	v_pk_fma_f32 v[0:1], v[16:17], v[90:91], v[0:1]
	s_nop 0
	v_pk_fma_f32 v[0:1], v[18:19], v[88:89], v[0:1]
	s_nop 0
	v_pk_fma_f32 v[0:1], v[20:21], v[84:85], v[0:1]
	s_nop 0
	v_pk_fma_f32 v[0:1], v[22:23], v[82:83], v[0:1]
	s_nop 0
	v_pk_fma_f32 v[0:1], v[24:25], v[78:79], v[0:1]
	s_nop 0
	v_pk_fma_f32 v[0:1], v[26:27], v[76:77], v[0:1]
	s_nop 0
	v_pk_fma_f32 v[0:1], v[28:29], v[74:75], v[0:1]
	s_nop 0
	v_pk_fma_f32 v[0:1], v[30:31], v[80:81], v[0:1]
	s_nop 0
	v_add_f32_e32 v44, v0, v1
	s_waitcnt vmcnt(2)
; DI void phase_peer_out(const Params& p, char* lds) {
;     ...
;         for (int k = 0; k < 8; ++k) {
;           const v32f f = __builtin_amdgcn_cvt_scalef32_pk32_f32_fp6(qb[k], 1.0f);
;           f32x2 a = f32x2{f[0], f[1]} * x2[0];
; #pragma unroll
;           for (int i = 1; i < 16; ++i) a = f32x2{f[2 * i], f[2 * i + 1]} * x2[i] + a;
;           pd[kb * 8 + k] = a.x + a.y;
;         }
;       }
; #pragma unroll
;       for (int off = 16; off >= 1; off >>= 1) {
;         const bool up = (lane & off) != 0;
; #pragma unroll
;         for (int i = 0; i < off; ++i) {
;           const float send = up ? pd[i] : pd[i + off];
;           const float keep = up ? pd[i + off] : pd[i];
;           pd[i] = keep + __shfl_xor(send, off);
;         }
;       }
	v_cvt_scalef32_pk32_f32_fp6 v[0:31], v[38:43], 1.0
	v_pk_mul_f32 v[2:3], v[2:3], v[92:93]
	s_nop 0
	v_pk_fma_f32 v[0:1], v[0:1], v[94:95], v[2:3]
	s_nop 0
	v_pk_fma_f32 v[0:1], v[4:5], v[86:87], v[0:1]
	s_nop 0
	v_pk_fma_f32 v[0:1], v[6:7], v[100:101], v[0:1]
	s_nop 0
	v_pk_fma_f32 v[0:1], v[8:9], v[104:105], v[0:1]
	s_nop 0
	v_pk_fma_f32 v[0:1], v[10:11], v[102:103], v[0:1]
	s_nop 0
	v_pk_fma_f32 v[0:1], v[12:13], v[98:99], v[0:1]
	s_nop 0
	v_pk_fma_f32 v[0:1], v[14:15], v[96:97], v[0:1]
	s_nop 0
	v_pk_fma_f32 v[0:1], v[16:17], v[90:91], v[0:1]
	s_nop 0
	v_pk_fma_f32 v[0:1], v[18:19], v[88:89], v[0:1]
	s_nop 0
	v_pk_fma_f32 v[0:1], v[20:21], v[84:85], v[0:1]
	s_nop 0
	v_pk_fma_f32 v[0:1], v[22:23], v[82:83], v[0:1]
	s_nop 0
	v_pk_fma_f32 v[0:1], v[24:25], v[78:79], v[0:1]
	s_nop 0
	v_pk_fma_f32 v[0:1], v[26:27], v[76:77], v[0:1]
	s_nop 0
	v_pk_fma_f32 v[0:1], v[28:29], v[74:75], v[0:1]
	s_nop 0
	v_pk_fma_f32 v[0:1], v[30:31], v[80:81], v[0:1]
	s_nop 0
	v_add_f32_e32 v38, v0, v1
	s_waitcnt vmcnt(0)
	v_cvt_scalef32_pk32_f32_fp6 v[0:31], v[32:37], 1.0
	v_pk_mul_f32 v[2:3], v[2:3], v[92:93]
	s_nop 0
	v_pk_fma_f32 v[0:1], v[0:1], v[94:95], v[2:3]
	v_cndmask_b32_e64 v2, v54, v143, s[2:3]
	v_pk_fma_f32 v[0:1], v[4:5], v[86:87], v[0:1]
	ds_bpermute_b32 v2, v118, v2
	v_pk_fma_f32 v[0:1], v[6:7], v[100:101], v[0:1]
	v_cndmask_b32_e64 v4, v129, v145, s[2:3]
	v_pk_fma_f32 v[0:1], v[8:9], v[104:105], v[0:1]
	ds_bpermute_b32 v4, v118, v4
	v_pk_fma_f32 v[0:1], v[10:11], v[102:103], v[0:1]
	v_cndmask_b32_e64 v5, v130, v146, s[2:3]
	v_pk_fma_f32 v[0:1], v[12:13], v[98:99], v[0:1]
	ds_bpermute_b32 v5, v118, v5
	v_pk_fma_f32 v[0:1], v[14:15], v[96:97], v[0:1]
	v_cndmask_b32_e64 v7, v132, v148, s[2:3]
	v_pk_fma_f32 v[0:1], v[16:17], v[90:91], v[0:1]
	ds_bpermute_b32 v7, v118, v7
	v_pk_fma_f32 v[0:1], v[18:19], v[88:89], v[0:1]
	v_cndmask_b32_e64 v8, v133, v149, s[2:3]
	v_pk_fma_f32 v[0:1], v[20:21], v[84:85], v[0:1]
	ds_bpermute_b32 v8, v118, v8
	v_pk_fma_f32 v[0:1], v[22:23], v[82:83], v[0:1]
	v_cndmask_b32_e64 v10, v135, v106, s[2:3]
	v_pk_fma_f32 v[0:1], v[24:25], v[78:79], v[0:1]
	ds_bpermute_b32 v10, v118, v10
	v_pk_fma_f32 v[0:1], v[26:27], v[76:77], v[0:1]
	v_cndmask_b32_e64 v11, v136, v151, s[2:3]
	v_pk_fma_f32 v[0:1], v[28:29], v[74:75], v[0:1]
	ds_bpermute_b32 v11, v118, v11
	v_pk_fma_f32 v[0:1], v[30:31], v[80:81], v[0:1]
	v_cndmask_b32_e64 v13, v138, v153, s[2:3]
	v_add_f32_e32 v3, v0, v1
	v_cndmask_b32_e64 v0, v143, v54, s[2:3]
	s_waitcnt lgkmcnt(6)
	v_add_f32_e32 v2, v0, v2
	v_cndmask_b32_e64 v0, v55, v144, s[2:3]
	ds_bpermute_b32 v0, v118, v0
	v_cndmask_b32_e64 v1, v144, v55, s[2:3]
	ds_bpermute_b32 v13, v118, v13
	v_cndmask_b32_e64 v14, v139, v154, s[2:3]
	ds_bpermute_b32 v14, v118, v14
	s_waitcnt lgkmcnt(2)
	v_add_f32_e32 v6, v1, v0
	v_cndmask_b32_e64 v0, v145, v129, s[2:3]
	v_add_f32_e32 v4, v0, v4
	v_cndmask_b32_e64 v0, v146, v130, s[2:3]
	v_add_f32_e32 v5, v0, v5
	v_cndmask_b32_e64 v0, v131, v147, s[2:3]
	ds_bpermute_b32 v0, v118, v0
	v_cndmask_b32_e64 v1, v147, v131, s[2:3]
	v_cndmask_b32_e64 v16, v44, v141, s[2:3]
	v_cndmask_b32_e64 v18, v142, v3, s[2:3]
	ds_bpermute_b32 v18, v118, v18
	s_waitcnt lgkmcnt(1)
	v_add_f32_e32 v9, v1, v0
	v_cndmask_b32_e64 v0, v148, v132, s[2:3]
	v_add_f32_e32 v7, v0, v7
	v_cndmask_b32_e64 v0, v149, v133, s[2:3]
	v_add_f32_e32 v8, v0, v8
	v_cndmask_b32_e64 v0, v134, v150, s[2:3]
	ds_bpermute_b32 v0, v118, v0
	v_cndmask_b32_e64 v1, v150, v134, s[2:3]
	v_cndmask_b32_e64 v3, v3, v142, s[2:3]
	s_waitcnt lgkmcnt(1)
	v_add_f32_e32 v3, v3, v18
	s_waitcnt lgkmcnt(0)
	v_add_f32_e32 v12, v1, v0
	v_cndmask_b32_e64 v0, v106, v135, s[2:3]
	v_add_f32_e32 v10, v0, v10
	v_cndmask_b32_e64 v0, v151, v136, s[2:3]
	v_add_f32_e32 v11, v0, v11
	v_cndmask_b32_e64 v0, v137, v152, s[2:3]
	ds_bpermute_b32 v0, v118, v0
	v_cndmask_b32_e64 v1, v152, v137, s[2:3]
	s_waitcnt lgkmcnt(0)
; DI void phase_peer_out(const Params& p, char* lds) {
;     ...
; #pragma unroll
;       for (int off = 16; off >= 1; off >>= 1) {
;         const bool up = (lane & off) != 0;
; #pragma unroll
;         for (int i = 0; i < off; ++i) {
;           const float send = up ? pd[i] : pd[i + off];
;           const float keep = up ? pd[i + off] : pd[i];
;           pd[i] = keep + __shfl_xor(send, off);
;         }
;       }
;       sw[hb * 64 + hf * 32 + l5] = pd[0];
;     }
;     float coefv[2];
; #pragma unroll
;     for (int grp = 0; grp < 2; ++grp) {
;       const float dt = sw[grp * 64 + lane] * USC[el[grp]];
;       const float ge = 0.5f * dt * (1.f + erff(dt * 0.7071067811865476f));
	v_add_f32_e32 v15, v1, v0
	v_cndmask_b32_e64 v0, v153, v138, s[2:3]
	v_add_f32_e32 v13, v0, v13
	v_cndmask_b32_e64 v0, v154, v139, s[2:3]
	v_add_f32_e32 v14, v0, v14
	v_cndmask_b32_e64 v0, v141, v44, s[2:3]
	ds_bpermute_b32 v17, v118, v0
	v_lshl_add_u64 v[0:1], v[108:109], 2, s[54:55]
	global_load_dword v0, v[0:1], off
	v_cndmask_b32_e64 v1, v140, v38, s[2:3]
	ds_bpermute_b32 v1, v118, v1
	s_waitcnt lgkmcnt(1)
	v_add_f32_e32 v16, v16, v17
	v_cndmask_b32_e64 v17, v38, v140, s[2:3]
	v_cndmask_b32_e64 v18, v4, v15, s[4:5]
	ds_bpermute_b32 v18, v114, v18
	s_waitcnt lgkmcnt(1)
	v_add_f32_e32 v1, v17, v1
	v_cndmask_b32_e64 v17, v2, v10, s[4:5]
	v_cndmask_b32_e64 v2, v10, v2, s[4:5]
	ds_bpermute_b32 v10, v114, v17
	v_cndmask_b32_e64 v17, v6, v11, s[4:5]
	ds_bpermute_b32 v17, v114, v17
	v_cndmask_b32_e64 v6, v11, v6, s[4:5]
	v_cndmask_b32_e64 v11, v9, v14, s[4:5]
	s_waitcnt lgkmcnt(1)
	v_add_f32_e32 v2, v2, v10
	v_cndmask_b32_e64 v10, v5, v13, s[4:5]
	ds_bpermute_b32 v10, v114, v10
	v_cndmask_b32_e64 v5, v13, v5, s[4:5]
	v_cndmask_b32_e64 v13, v7, v16, s[4:5]
	ds_bpermute_b32 v13, v114, v13
	ds_bpermute_b32 v11, v114, v11
	s_waitcnt lgkmcnt(2)
	v_add_f32_e32 v5, v5, v10
	v_cndmask_b32_e64 v10, v8, v1, s[4:5]
	v_cndmask_b32_e64 v1, v1, v8, s[4:5]
	ds_bpermute_b32 v8, v114, v10
	v_cndmask_b32_e64 v10, v12, v3, s[4:5]
	ds_bpermute_b32 v10, v114, v10
	v_cndmask_b32_e64 v7, v16, v7, s[4:5]
	v_add_f32_e32 v6, v6, v17
	v_cndmask_b32_e64 v4, v15, v4, s[4:5]
	v_cndmask_b32_e64 v9, v14, v9, s[4:5]
	s_waitcnt lgkmcnt(3)
	v_add_f32_e32 v7, v7, v13
	v_cndmask_b32_e64 v3, v3, v12, s[4:5]
	v_add_f32_e32 v4, v4, v18
	s_waitcnt lgkmcnt(2)
	v_add_f32_e32 v9, v9, v11
	s_waitcnt lgkmcnt(1)
	v_add_f32_e32 v1, v1, v8
	s_waitcnt lgkmcnt(0)
	v_add_f32_e32 v3, v3, v10
	v_cndmask_b32_e64 v8, v6, v7, s[6:7]
	v_cndmask_b32_e64 v11, v2, v9, s[6:7]
	v_cndmask_b32_e64 v2, v9, v2, s[6:7]
	v_cndmask_b32_e64 v6, v7, v6, s[6:7]
	ds_bpermute_b32 v7, v115, v8
	v_cndmask_b32_e64 v8, v4, v1, s[6:7]
	v_cndmask_b32_e64 v9, v5, v3, s[6:7]
	ds_bpermute_b32 v11, v115, v11
	ds_bpermute_b32 v8, v115, v8
	ds_bpermute_b32 v9, v115, v9
	v_cndmask_b32_e64 v1, v1, v4, s[6:7]
	v_cndmask_b32_e64 v3, v3, v5, s[6:7]
	s_waitcnt lgkmcnt(2)
	v_add_f32_e32 v2, v2, v11
	v_add_f32_e32 v6, v6, v7
	s_waitcnt lgkmcnt(1)
	v_add_f32_e32 v1, v1, v8
	s_waitcnt lgkmcnt(0)
	v_add_f32_e32 v3, v3, v9
	v_cndmask_b32_e64 v4, v2, v1, s[8:9]
	v_cndmask_b32_e64 v5, v6, v3, s[8:9]
	ds_bpermute_b32 v4, v116, v4
	ds_bpermute_b32 v5, v116, v5
	v_cndmask_b32_e64 v1, v1, v2, s[8:9]
	v_cndmask_b32_e64 v2, v3, v6, s[8:9]
	ds_bpermute_b32 v7, v117, v53
	s_waitcnt lgkmcnt(2)
	v_add_f32_e32 v1, v1, v4
	s_waitcnt lgkmcnt(1)
	v_add_f32_e32 v2, v2, v5
	v_cndmask_b32_e64 v3, v1, v2, s[10:11]
	ds_bpermute_b32 v3, v117, v3
	ds_bpermute_b32 v4, v116, v50
	v_cndmask_b32_e64 v5, v52, v51, s[10:11]
	v_cndmask_b32_e64 v1, v2, v1, s[10:11]
	s_waitcnt lgkmcnt(2)
	v_add_f32_e32 v5, v5, v7
	s_waitcnt lgkmcnt(1)
	v_add_f32_e32 v1, v1, v3
	ds_write2_b32 v121, v5, v1 offset0:128 offset1:160
	ds_read_b32 v1, v112 offset:512
	s_waitcnt lgkmcnt(2)
	v_add_f32_e32 v3, v50, v4
	ds_bpermute_b32 v5, v117, v128
	ds_bpermute_b32 v4, v117, v3
	s_waitcnt vmcnt(0) lgkmcnt(2)
	v_mul_f32_e32 v6, v1, v0
	v_mul_f32_e32 v7, 0x3f3504f3, v6
	v_cmp_nlt_f32_e64 s[12:13], |v7|, 1.0
	s_and_saveexec_b64 s[16:17], s[12:13]
	s_xor_b64 s[16:17], exec, s[16:17]
	s_cbranch_execz .LBB0_1205
	v_fma_f32 v0, |v7|, s24, v124
	v_fma_f32 v0, |v7|, v0, s25
	v_fma_f32 v0, |v7|, v0, s26
	v_fma_f32 v0, |v7|, v0, s27
	v_fma_f32 v0, |v7|, v0, s28
	v_fma_f32 v0, |v7|, v0, s29
	v_fma_f32 v0, |v7|, v0, |v7|
	v_mul_f32_e32 v1, 0xbfb8aa3b, v0
	v_fma_f32 v2, v0, s30, -v1
	v_rndne_f32_e32 v8, v1
	v_fmac_f32_e32 v2, 0xb2a5705f, v0
	v_sub_f32_e32 v1, v1, v8
	v_add_f32_e32 v1, v1, v2
	v_cvt_i32_f32_e32 v2, v8
	v_exp_f32_e32 v1, v1
	v_cmp_nlt_f32_e64 s[12:13], s31, v0
	v_ldexp_f32 v1, v1, v2
	s_nop 0
	v_cndmask_b32_e64 v1, 0, v1, s[12:13]
	v_cmp_ngt_f32_e64 s[12:13], s33, v0
	s_nop 1
	v_cndmask_b32_e64 v0, v125, v1, s[12:13]
	v_sub_f32_e32 v8, 1.0, v0

; __global__ void __launch_bounds__(512) mega(Params p) {
;   extern __shared__ __attribute__((aligned(16))) char lds[];
	.amdhsa_kernel _Z4mega6Params
		.amdhsa_group_segment_fixed_size 0
		.amdhsa_private_segment_fixed_size 0
		.amdhsa_kernarg_size 472
		.amdhsa_user_sgpr_count 2
		.amdhsa_user_sgpr_dispatch_ptr 0
		.amdhsa_user_sgpr_queue_ptr 0
		.amdhsa_user_sgpr_kernarg_segment_ptr 1
		.amdhsa_user_sgpr_dispatch_id 0
		.amdhsa_user_sgpr_kernarg_preload_length 0
		.amdhsa_user_sgpr_kernarg_preload_offset 0
		.amdhsa_user_sgpr_private_segment_size 0
		.amdhsa_uses_dynamic_stack 0
		.amdhsa_enable_private_segment 0
		.amdhsa_system_sgpr_workgroup_id_x 1
		.amdhsa_system_sgpr_workgroup_id_y 0
		.amdhsa_system_sgpr_workgroup_id_z 0
		.amdhsa_system_sgpr_workgroup_info 0
		.amdhsa_system_vgpr_workitem_id 2
		.amdhsa_next_free_vgpr 256
		.amdhsa_next_free_sgpr 102
		.amdhsa_accum_offset 256
		.amdhsa_reserve_vcc 1
		.amdhsa_float_round_mode_32 0
		.amdhsa_float_round_mode_16_64 0
		.amdhsa_float_denorm_mode_32 3
		.amdhsa_float_denorm_mode_16_64 3
		.amdhsa_dx10_clamp 1
		.amdhsa_ieee_mode 1
		.amdhsa_fp16_overflow 0
		.amdhsa_tg_split 0
		.amdhsa_exception_fp_ieee_invalid_op 0
		.amdhsa_exception_fp_denorm_src 0
		.amdhsa_exception_fp_ieee_div_zero 0
		.amdhsa_exception_fp_ieee_overflow 0
		.amdhsa_exception_fp_ieee_underflow 0
		.amdhsa_exception_fp_ieee_inexact 0
		.amdhsa_exception_int_div_zero 0
	.end_amdhsa_kernel

; __global__ void __launch_bounds__(512) mega(Params p) {
amdhsa.kernels:
  - .agpr_count:     0
    .args:
      - .offset:         0
        .size:           216
        .value_kind:     by_value
      - .offset:         216
        .size:           4
        .value_kind:     hidden_block_count_x
      - .offset:         220
        .size:           4
        .value_kind:     hidden_block_count_y
      - .offset:         224
        .size:           4
        .value_kind:     hidden_block_count_z
      - .offset:         228
        .size:           2
        .value_kind:     hidden_group_size_x
      - .offset:         230
        .size:           2
        .value_kind:     hidden_group_size_y
      - .offset:         232
        .size:           2
        .value_kind:     hidden_group_size_z
      - .offset:         234
        .size:           2
        .value_kind:     hidden_remainder_x
      - .offset:         236
        .size:           2
        .value_kind:     hidden_remainder_y
      - .offset:         238
        .size:           2
        .value_kind:     hidden_remainder_z
      - .offset:         256
        .size:           8
        .value_kind:     hidden_global_offset_x
      - .offset:         264
        .size:           8
        .value_kind:     hidden_global_offset_y
      - .offset:         272
        .size:           8
        .value_kind:     hidden_global_offset_z
      - .offset:         280
        .size:           2
        .value_kind:     hidden_grid_dims
      - .offset:         304
        .size:           8
        .value_kind:     hidden_multigrid_sync_arg
      - .offset:         336
        .size:           4
        .value_kind:     hidden_dynamic_lds_size
    .group_segment_fixed_size: 0
    .kernarg_segment_align: 8
    .kernarg_segment_size: 472
    .language:       OpenCL C
    .language_version:
      - 2
      - 0
    .max_flat_workgroup_size: 512
    .name:           _Z4mega6Params
    .private_segment_fixed_size: 0
    .sgpr_count:     108
    .sgpr_spill_count: 60
    .symbol:         _Z4mega6Params.kd
    .uniform_work_group_size: 1
    .uses_dynamic_stack: false
    .vgpr_count:     256
    .vgpr_spill_count: 0
    .wavefront_size: 64
